# f32 to bf16 rounding: bit trick replaced by v_cvt_pk_bf16_f32 at 754 high-half-only sites, the v_bfe deleted where no wait-state depends on its slot (735)
# speedup vs baseline: 1.0104x; 1.0104x over previous
.LBB0_436:
	s_mul_hi_i32 s12, s91, 0x2aaaaaab
	s_lshr_b32 s13, s12, 31
	s_ashr_i32 s12, s12, 2
	s_add_i32 s82, s12, s13
	s_mul_i32 s12, s82, 0xffffffe8
	s_add_i32 s76, s91, s12
	s_mov_b64 s[12:13], -1
	s_cmp_gt_i32 s76, 15
	v_lshl_add_u32 v103, s82, 5, v67
	s_cbranch_scc0 .LBB0_510
	v_mov_b32_e32 v155, v97
	s_add_i32 s12, s76, -16
	s_lshr_b32 s38, s12, 1
	s_and_b32 s28, s94, 2
	v_or_b32_e32 v146, s28, v63
	s_movk_i32 s26, 0x810
	v_cmp_gt_i32_e64 s[14:15], s26, v103
	s_mul_i32 s33, s38, 0x810
	s_nop 1
	v_cndmask_b32_e64 v140, 0, v103, s[14:15]
	v_add_u32_e32 v142, s33, v140
	v_mov_b64_e32 v[140:141], s[54:55]
	v_mad_i64_i32 v[144:145], s[16:17], v142, s44, v[140:141]
	v_lshlrev_b32_e32 v142, 1, v62
	v_lshl_or_b32 v142, v146, 7, v142
	v_or_b32_e32 v154, 0x2200, v142
	v_lshl_add_u64 v[146:147], v[144:145], 0, v[154:155]
	v_mov_b32_e32 v143, v155
	s_mov_b64 s[86:87], 0x2a00
	global_load_ushort v139, v[146:147], off
	v_lshl_add_u64 v[146:147], v[144:145], 0, v[142:143]
	v_lshl_add_u64 v[152:153], v[144:145], 0, s[86:87]
	v_add_co_u32_e32 v144, vcc, s74, v144
	s_nop 1
	v_addc_co_u32_e32 v145, vcc, 0, v145, vcc
	global_load_dwordx4 v[160:163], v[144:145], off offset:2560
	global_load_dwordx4 v[164:167], v[152:153], off offset:16
	v_or_b32_e32 v156, 2, v103
	v_cmp_gt_i32_e64 s[12:13], s26, v156
	v_or_b32_e32 v150, 3, v103
	v_or_b32_e32 v144, 1, v103
	v_cmp_gt_i32_e64 s[18:19], s26, v144
	v_cmp_gt_i32_e64 s[16:17], s26, v150
	s_nop 1
	v_cndmask_b32_e64 v144, 0, v144, s[18:19]
	v_add_u32_e32 v157, s33, v144
	v_mad_i64_i32 v[148:149], s[20:21], v157, s44, v[140:141]
	v_lshl_add_u64 v[144:145], v[148:149], 0, v[154:155]
	global_load_ushort v159, v[144:145], off
	v_lshl_add_u64 v[144:145], v[148:149], 0, v[142:143]
	v_lshl_add_u64 v[152:153], v[148:149], 0, s[86:87]
	v_add_co_u32_e32 v148, vcc, s74, v148
	s_nop 1
	v_addc_co_u32_e32 v149, vcc, 0, v149, vcc
	global_load_dwordx4 v[168:171], v[148:149], off offset:2560
	global_load_dwordx4 v[172:175], v[152:153], off offset:16
	v_cndmask_b32_e64 v148, 0, v156, s[12:13]
	v_add_u32_e32 v148, s33, v148
	v_mad_i64_i32 v[148:149], s[20:21], v148, s44, v[140:141]
	v_add_co_u32_e32 v146, vcc, s74, v146
	v_lshl_add_u64 v[152:153], v[148:149], 0, v[154:155]
	s_nop 1
	v_addc_co_u32_e32 v147, vcc, 0, v147, vcc
	global_load_ushort v176, v[152:153], off
	global_load_ushort v177, v[146:147], off offset:1024
	v_lshl_add_u64 v[152:153], v[148:149], 0, v[142:143]
	v_add_co_u32_e32 v146, vcc, s74, v152
	s_nop 1
	v_addc_co_u32_e32 v147, vcc, 0, v153, vcc
	global_load_ushort v178, v[146:147], off offset:1024
	v_lshl_add_u64 v[146:147], v[148:149], 0, s[86:87]
	v_add_co_u32_e32 v148, vcc, s74, v148
	s_nop 1
	v_addc_co_u32_e32 v149, vcc, 0, v149, vcc
	global_load_dwordx4 v[180:183], v[148:149], off offset:2560
	global_load_dwordx4 v[184:187], v[146:147], off offset:16
	v_cndmask_b32_e64 v146, 0, v150, s[16:17]
	v_add_u32_e32 v158, s33, v146
	v_mad_i64_i32 v[146:147], s[20:21], v158, s44, v[140:141]
	v_lshl_add_u64 v[150:151], v[146:147], 0, v[154:155]
	global_load_ushort v179, v[150:151], off
	v_lshl_add_u64 v[150:151], v[146:147], 0, v[142:143]
	v_add_co_u32_e32 v150, vcc, s74, v150
	s_nop 1
	v_addc_co_u32_e32 v151, vcc, 0, v151, vcc
	v_add_co_u32_e32 v144, vcc, s74, v144
	global_load_ushort v188, v[150:151], off offset:1024
	s_nop 1
	v_addc_co_u32_e32 v145, vcc, 0, v145, vcc
	global_load_ushort v189, v[144:145], off offset:1024
	v_lshl_add_u64 v[150:151], v[146:147], 0, s[86:87]
	v_add_co_u32_e32 v144, vcc, s74, v146
	s_nop 1
	v_addc_co_u32_e32 v145, vcc, 0, v147, vcc
	global_load_dwordx4 v[190:193], v[144:145], off offset:2560
	global_load_dwordx4 v[194:197], v[150:151], off offset:16
	s_add_i32 s12, s76, -16
	s_lshr_b32 s38, s12, 1
	s_and_b32 s28, s94, 2
	s_lshl_b32 s60, s38, 2
	v_or_b32_e32 v6, s28, v63
	s_add_i32 s60, s60, 32
	s_ashr_i32 s83, s82, 31
	v_or_b32_e32 v2, s60, v6
	v_mov_b64_e32 v[0:1], s[82:83]
	v_mad_u64_u32 v[0:1], s[12:13], v2, s79, v[0:1]
	v_mov_b64_e32 v[2:3], s[56:57]
	v_mad_u64_u32 v[38:39], s[12:13], v0, s44, v[2:3]
	v_lshlrev_b32_e32 v96, 8, v6
	v_mad_i32_i24 v39, v1, s44, v39
	v_lshl_add_u64 v[0:1], v[10:11], 0, v[96:97]
	global_load_dword v107, v[0:1], off
	v_lshl_add_u64 v[0:1], v[12:13], 0, v[96:97]
	s_movk_i32 s12, 0x1000
	v_add_co_u32_e32 v2, vcc, s12, v0
	global_load_dword v44, v[0:1], off
	global_load_dword v46, v[0:1], off offset:1024
	global_load_dword v42, v[0:1], off offset:2048
	global_load_dword v40, v[0:1], off offset:3072
	v_addc_co_u32_e32 v3, vcc, 0, v1, vcc
	v_add_co_u32_e32 v4, vcc, s74, v0
	s_movk_i32 s26, 0x810
	s_nop 0
	v_addc_co_u32_e32 v5, vcc, 0, v1, vcc
	v_add_co_u32_e32 v0, vcc, s44, v0
	v_cmp_gt_i32_e64 s[14:15], s26, v103
	s_nop 0
	v_addc_co_u32_e32 v1, vcc, 0, v1, vcc
	global_load_dword v54, v[4:5], off offset:-4096
	global_load_dword v52, v[2:3], off offset:1024
	global_load_dword v50, v[2:3], off offset:2048
	global_load_dword v48, v[2:3], off offset:3072
	global_load_dword v45, v[4:5], off
	global_load_dword v47, v[4:5], off offset:1024
	global_load_dword v43, v[4:5], off offset:2048
	global_load_dword v41, v[4:5], off offset:3072
	global_load_dword v55, v[0:1], off
	global_load_dword v53, v[0:1], off offset:1024
	global_load_dword v51, v[0:1], off offset:2048
	global_load_dword v49, v[0:1], off offset:3072
	s_mul_i32 s33, s38, 0x810
	v_cndmask_b32_e64 v0, 0, v103, s[14:15]
	v_add_u32_e32 v2, s33, v0
	v_mov_b64_e32 v[0:1], s[54:55]
	v_mad_i64_i32 v[4:5], s[16:17], v2, s44, v[0:1]
	v_lshlrev_b32_e32 v2, 1, v62
	v_lshl_or_b32 v2, v6, 7, v2
	v_or_b32_e32 v96, 0x2200, v2
	v_lshl_add_u64 v[6:7], v[4:5], 0, v[96:97]
	v_mov_b32_e32 v3, v97
	s_mov_b64 s[86:87], 0x2a00
	s_waitcnt vmcnt(0)
	v_mov_b32_e32 v106, v139
	v_lshl_add_u64 v[6:7], v[4:5], 0, v[2:3]
	v_lshl_add_u64 v[60:61], v[4:5], 0, s[86:87]
	v_add_co_u32_e32 v4, vcc, s74, v4
	s_mov_b32 s29, 0xbfb8aa3b
	s_nop 0
	v_addc_co_u32_e32 v5, vcc, 0, v5, vcc
	v_mov_b64_e32 v[56:57], v[160:161]
	v_mov_b64_e32 v[58:59], v[162:163]
	v_mov_b64_e32 v[108:109], v[164:165]
	v_mov_b64_e32 v[110:111], v[166:167]
	s_mov_b32 s49, 0x3f317217
	s_mov_b32 s61, 0x7f800000
	v_mov_b32_e32 v136, 0x41b17218
	v_or_b32_e32 v104, 2, v103
	v_cmp_gt_i32_e64 s[12:13], s26, v104
	s_waitcnt vmcnt(0)
	v_and_b32_e32 v60, 0xffff0000, v56
	v_and_b32_e32 v61, 0xffff0000, v108
	v_lshlrev_b32_e32 v4, 16, v56
	v_lshlrev_b32_e32 v5, 16, v108
	v_pk_mul_f32 v[60:61], v[46:47], v[60:61]
	v_lshlrev_b32_e32 v56, 16, v58
	v_pk_fma_f32 v[4:5], v[44:45], v[4:5], v[60:61]
	v_lshlrev_b32_e32 v60, 16, v57
	v_lshlrev_b32_e32 v61, 16, v109
	v_pk_fma_f32 v[4:5], v[42:43], v[60:61], v[4:5]
	v_and_b32_e32 v61, 0xffff0000, v109
	v_and_b32_e32 v60, 0xffff0000, v57
	v_pk_fma_f32 v[4:5], v[40:41], v[60:61], v[4:5]
	v_lshlrev_b32_e32 v57, 16, v110
	v_pk_fma_f32 v[4:5], v[54:55], v[56:57], v[4:5]
	v_and_b32_e32 v57, 0xffff0000, v110
	v_and_b32_e32 v56, 0xffff0000, v58
	v_pk_fma_f32 v[4:5], v[52:53], v[56:57], v[4:5]
	v_lshlrev_b32_e32 v56, 16, v59
	v_lshlrev_b32_e32 v57, 16, v111
	v_pk_fma_f32 v[4:5], v[50:51], v[56:57], v[4:5]
	v_and_b32_e32 v57, 0xffff0000, v111
	v_and_b32_e32 v56, 0xffff0000, v59
	v_pk_fma_f32 v[4:5], v[48:49], v[56:57], v[4:5]
	v_or_b32_e32 v58, 3, v103
	v_add_f32_e32 v4, v107, v4
	v_add_f32_e32 v4, v4, v5
	v_min_f32_e32 v5, 0, v4
	v_mul_f32_e64 v4, |v4|, s29
	v_exp_f32_e32 v4, v4
	s_nop 0
	v_add_f32_e32 v4, 1.0, v4
	v_cmp_gt_f32_e32 vcc, s45, v4
	s_nop 1
	v_cndmask_b32_e64 v56, 0, 32, vcc
	v_ldexp_f32 v4, v4, v56
	v_log_f32_e32 v4, v4
	s_nop 0
	v_mul_f32_e32 v56, 0x3f317217, v4
	v_fma_f32 v56, v4, s49, -v56
	v_fmac_f32_e32 v56, 0x3377d1cf, v4
	v_fmac_f32_e32 v56, 0x3f317217, v4
	v_cmp_lt_f32_e64 s[16:17], |v4|, s61
	s_nop 1
	v_cndmask_b32_e64 v4, v4, v56, s[16:17]
	v_cndmask_b32_e32 v56, 0, v136, vcc
	v_sub_f32_e32 v4, v4, v56
	v_sub_f32_e32 v4, v5, v4
	s_mov_b32 s16, 0x3d800000
	v_fma_f32 v4, v4, s16, 0
	v_cndmask_b32_e64 v108, 0, v4, s[14:15]
	v_or_b32_e32 v4, 1, v103
	v_cmp_gt_i32_e64 s[18:19], s26, v4
	v_cmp_gt_i32_e64 s[16:17], s26, v58
	s_nop 0
	v_cndmask_b32_e64 v4, 0, v4, s[18:19]
	v_add_u32_e32 v105, s33, v4
	v_mad_i64_i32 v[56:57], s[20:21], v105, s44, v[0:1]
	v_lshl_add_u64 v[4:5], v[56:57], 0, v[96:97]
	v_mov_b32_e32 v109, v159
	v_lshl_add_u64 v[4:5], v[56:57], 0, v[2:3]
	v_lshl_add_u64 v[60:61], v[56:57], 0, s[86:87]
	v_add_co_u32_e32 v56, vcc, s74, v56
	s_nop 1
	v_addc_co_u32_e32 v57, vcc, 0, v57, vcc
	v_mov_b64_e32 v[110:111], v[168:169]
	v_mov_b64_e32 v[112:113], v[170:171]
	v_mov_b64_e32 v[114:115], v[172:173]
	v_mov_b64_e32 v[116:117], v[174:175]
	s_waitcnt vmcnt(0)
	v_and_b32_e32 v60, 0xffff0000, v110
	s_waitcnt vmcnt(0)
	v_and_b32_e32 v61, 0xffff0000, v114
	v_lshlrev_b32_e32 v56, 16, v110
	v_lshlrev_b32_e32 v57, 16, v114
	v_pk_mul_f32 v[60:61], v[46:47], v[60:61]
	s_nop 0
	v_pk_fma_f32 v[56:57], v[44:45], v[56:57], v[60:61]
	v_lshlrev_b32_e32 v60, 16, v111
	v_lshlrev_b32_e32 v61, 16, v115
	v_pk_fma_f32 v[56:57], v[42:43], v[60:61], v[56:57]
	v_and_b32_e32 v61, 0xffff0000, v115
	v_and_b32_e32 v60, 0xffff0000, v111
	v_pk_fma_f32 v[56:57], v[40:41], v[60:61], v[56:57]
	v_lshlrev_b32_e32 v60, 16, v112
	v_lshlrev_b32_e32 v61, 16, v116
	v_pk_fma_f32 v[56:57], v[54:55], v[60:61], v[56:57]
	v_and_b32_e32 v61, 0xffff0000, v116
	v_and_b32_e32 v60, 0xffff0000, v112
	v_pk_fma_f32 v[56:57], v[52:53], v[60:61], v[56:57]
	v_lshlrev_b32_e32 v60, 16, v113
	v_lshlrev_b32_e32 v61, 16, v117
	v_pk_fma_f32 v[56:57], v[50:51], v[60:61], v[56:57]
	v_and_b32_e32 v61, 0xffff0000, v117
	v_and_b32_e32 v60, 0xffff0000, v113
	v_pk_fma_f32 v[56:57], v[48:49], v[60:61], v[56:57]
	s_nop 0
	v_add_f32_e32 v56, v107, v56
	v_add_f32_e32 v56, v56, v57
	v_min_f32_e32 v57, 0, v56
	v_mul_f32_e64 v56, |v56|, s29
	v_exp_f32_e32 v56, v56
	s_nop 0
	v_add_f32_e32 v56, 1.0, v56
	v_cmp_gt_f32_e32 vcc, s45, v56
	s_nop 1
	v_cndmask_b32_e64 v59, 0, 32, vcc
	v_ldexp_f32 v56, v56, v59
	v_log_f32_e32 v56, v56
	s_nop 0
	v_mul_f32_e32 v59, 0x3f317217, v56
	v_fma_f32 v59, v56, s49, -v59
	v_fmac_f32_e32 v59, 0x3377d1cf, v56
	v_fmac_f32_e32 v59, 0x3f317217, v56
	v_cmp_lt_f32_e64 s[20:21], |v56|, s61
	s_nop 1
	v_cndmask_b32_e64 v56, v56, v59, s[20:21]
	v_cndmask_b32_e32 v59, 0, v136, vcc
	v_sub_f32_e32 v56, v56, v59
	v_sub_f32_e32 v56, v57, v56
	v_mul_f32_e32 v56, 0x3d800000, v56
	v_cndmask_b32_e64 v56, 0, v56, s[18:19]
	v_add_f32_e32 v112, v108, v56
	v_cndmask_b32_e64 v56, 0, v104, s[12:13]
	v_add_u32_e32 v56, s33, v56
	v_mad_i64_i32 v[56:57], s[20:21], v56, s44, v[0:1]
	v_add_co_u32_e32 v6, vcc, s74, v6
	v_lshl_add_u64 v[60:61], v[56:57], 0, v[96:97]
	s_nop 0
	v_addc_co_u32_e32 v7, vcc, 0, v7, vcc
	v_mov_b32_e32 v113, v176
	v_mov_b32_e32 v59, v177
	v_lshl_add_u64 v[60:61], v[56:57], 0, v[2:3]
	v_add_co_u32_e32 v6, vcc, s74, v60
	s_waitcnt vmcnt(0)
	v_lshlrev_b32_e32 v59, 16, v59
	v_addc_co_u32_e32 v7, vcc, 0, v61, vcc
	v_mov_b32_e32 v6, v178
	s_waitcnt vmcnt(0)
	v_lshlrev_b32_e32 v60, 16, v6
	v_lshl_add_u64 v[6:7], v[56:57], 0, s[86:87]
	v_add_co_u32_e32 v56, vcc, s74, v56
	s_nop 1
	v_addc_co_u32_e32 v57, vcc, 0, v57, vcc
	v_mov_b64_e32 v[114:115], v[180:181]
	v_mov_b64_e32 v[116:117], v[182:183]
	v_mov_b64_e32 v[118:119], v[184:185]
	v_mov_b64_e32 v[120:121], v[186:187]
	s_waitcnt vmcnt(0)
	v_and_b32_e32 v56, 0xffff0000, v114
	s_waitcnt vmcnt(0)
	v_and_b32_e32 v57, 0xffff0000, v118
	v_lshlrev_b32_e32 v6, 16, v114
	v_lshlrev_b32_e32 v7, 16, v118
	v_pk_mul_f32 v[56:57], v[46:47], v[56:57]
	s_nop 0
	v_pk_fma_f32 v[6:7], v[44:45], v[6:7], v[56:57]
	v_lshlrev_b32_e32 v56, 16, v115
	v_lshlrev_b32_e32 v57, 16, v119
	v_pk_fma_f32 v[6:7], v[42:43], v[56:57], v[6:7]
	v_and_b32_e32 v57, 0xffff0000, v119
	v_and_b32_e32 v56, 0xffff0000, v115
	v_pk_fma_f32 v[6:7], v[40:41], v[56:57], v[6:7]
	v_lshlrev_b32_e32 v56, 16, v116
	v_lshlrev_b32_e32 v57, 16, v120
	v_pk_fma_f32 v[6:7], v[54:55], v[56:57], v[6:7]
	v_and_b32_e32 v57, 0xffff0000, v120
	v_and_b32_e32 v56, 0xffff0000, v116
	v_pk_fma_f32 v[6:7], v[52:53], v[56:57], v[6:7]
	v_lshlrev_b32_e32 v56, 16, v117
	v_lshlrev_b32_e32 v57, 16, v121
	v_pk_fma_f32 v[6:7], v[50:51], v[56:57], v[6:7]
	v_and_b32_e32 v57, 0xffff0000, v121
	v_and_b32_e32 v56, 0xffff0000, v117
	v_pk_fma_f32 v[6:7], v[48:49], v[56:57], v[6:7]
	v_cndmask_b32_e64 v57, 0, v60, s[12:13]
	v_add_f32_e32 v6, v107, v6
	v_add_f32_e32 v6, v6, v7
	v_min_f32_e32 v7, 0, v6
	v_mul_f32_e64 v6, |v6|, s29
	v_exp_f32_e32 v6, v6
	s_nop 0
	v_add_f32_e32 v6, 1.0, v6
	v_cmp_gt_f32_e32 vcc, s45, v6
	s_nop 1
	v_cndmask_b32_e64 v56, 0, 32, vcc
	v_ldexp_f32 v6, v6, v56
	v_log_f32_e32 v6, v6
	s_nop 0
	v_mul_f32_e32 v56, 0x3f317217, v6
	v_fma_f32 v56, v6, s49, -v56
	v_fmac_f32_e32 v56, 0x3377d1cf, v6
	v_fmac_f32_e32 v56, 0x3f317217, v6
	v_cmp_lt_f32_e64 s[20:21], |v6|, s61
	s_nop 1
	v_cndmask_b32_e64 v6, v6, v56, s[20:21]
	v_cndmask_b32_e32 v56, 0, v136, vcc
	v_sub_f32_e32 v6, v6, v56
	v_sub_f32_e32 v6, v7, v6
	v_mul_f32_e32 v6, 0x3d800000, v6
	v_cndmask_b32_e64 v6, 0, v6, s[12:13]
	v_add_f32_e32 v116, v112, v6
	v_cndmask_b32_e64 v6, 0, v58, s[16:17]
	v_add_u32_e32 v110, s33, v6
	v_mad_i64_i32 v[6:7], s[20:21], v110, s44, v[0:1]
	v_cndmask_b32_e64 v56, 0, v59, s[14:15]
	v_lshl_add_u64 v[58:59], v[6:7], 0, v[96:97]
	v_mov_b32_e32 v115, v179
	v_lshl_add_u64 v[58:59], v[6:7], 0, v[2:3]
	v_add_co_u32_e32 v58, vcc, s74, v58
	s_nop 1
	v_addc_co_u32_e32 v59, vcc, 0, v59, vcc
	v_add_co_u32_e32 v4, vcc, s74, v4
	v_mov_b32_e32 v58, v188
	s_nop 0
	v_addc_co_u32_e32 v5, vcc, 0, v5, vcc
	v_mov_b32_e32 v4, v189
	s_waitcnt vmcnt(0)
	v_lshlrev_b32_e32 v114, 16, v58
	v_lshl_add_u64 v[58:59], v[6:7], 0, s[86:87]
	s_waitcnt vmcnt(0)
	v_lshlrev_b32_e32 v111, 16, v4
	v_add_co_u32_e32 v4, vcc, s74, v6
	s_nop 1
	v_addc_co_u32_e32 v5, vcc, 0, v7, vcc
	v_mov_b64_e32 v[4:5], v[190:191]
	v_mov_b64_e32 v[6:7], v[192:193]
	s_nop 0
	v_mov_b64_e32 v[58:59], v[194:195]
	v_mov_b64_e32 v[60:61], v[196:197]
	v_mov_b32_e32 v140, v0
	v_mov_b32_e32 v141, v1
	v_mov_b32_e32 v142, v2
	v_mov_b32_e32 v143, v3
	v_or_b32_e32 v150, 4, v103
	v_cmp_gt_i32_e64 s[22:23], s26, v150
	v_or_b32_e32 v139, 6, v103
	s_nop 1
	v_cndmask_b32_e64 v144, 0, v150, s[22:23]
	v_add_u32_e32 v144, s33, v144
	v_mad_i64_i32 v[146:147], s[24:25], v144, s44, v[140:141]
	v_lshl_add_u64 v[144:145], v[146:147], 0, v[96:97]
	global_load_ushort v152, v[144:145], off
	v_lshl_add_u64 v[144:145], v[146:147], 0, v[142:143]
	v_lshl_add_u64 v[148:149], v[146:147], 0, s[86:87]
	v_add_co_u32_e32 v146, vcc, s74, v146
	v_cmp_gt_i32_e64 s[20:21], s26, v139
	s_nop 1
	v_addc_co_u32_e32 v147, vcc, 0, v147, vcc
	global_load_dwordx4 v[158:161], v[146:147], off offset:2560
	global_load_dwordx4 v[162:165], v[148:149], off offset:16
	v_or_b32_e32 v153, 7, v103
	v_or_b32_e32 v146, 5, v103
	v_cmp_gt_i32_e64 s[24:25], s26, v153
	v_cmp_gt_i32_e64 s[98:99], s26, v146
	s_nop 1
	v_cndmask_b32_e64 v146, 0, v146, s[98:99]
	v_add_u32_e32 v151, s33, v146
	v_mad_i64_i32 v[148:149], s[30:31], v151, s44, v[140:141]
	v_lshl_add_u64 v[146:147], v[148:149], 0, v[96:97]
	global_load_ushort v166, v[146:147], off
	v_lshl_add_u64 v[146:147], v[148:149], 0, v[142:143]
	v_lshl_add_u64 v[156:157], v[148:149], 0, s[86:87]
	v_add_co_u32_e32 v148, vcc, s74, v148
	s_nop 1
	v_addc_co_u32_e32 v149, vcc, 0, v149, vcc
	global_load_dwordx4 v[168:171], v[148:149], off offset:2560
	global_load_dwordx4 v[172:175], v[156:157], off offset:16
	v_cndmask_b32_e64 v148, 0, v139, s[20:21]
	v_add_u32_e32 v148, s33, v148
	v_mad_i64_i32 v[148:149], s[30:31], v148, s44, v[140:141]
	v_lshl_add_u64 v[154:155], v[148:149], 0, v[96:97]
	global_load_ushort v167, v[154:155], off
	v_lshl_add_u64 v[154:155], v[148:149], 0, v[142:143]
	v_add_co_u32_e32 v154, vcc, s74, v154
	s_nop 1
	v_addc_co_u32_e32 v155, vcc, 0, v155, vcc
	v_add_co_u32_e32 v144, vcc, s74, v144
	global_load_ushort v176, v[154:155], off offset:1024
	s_nop 1
	v_addc_co_u32_e32 v145, vcc, 0, v145, vcc
	global_load_ushort v177, v[144:145], off offset:1024
	v_lshl_add_u64 v[144:145], v[148:149], 0, s[86:87]
	v_add_co_u32_e32 v148, vcc, s74, v148
	s_nop 1
	v_addc_co_u32_e32 v149, vcc, 0, v149, vcc
	global_load_dwordx4 v[178:181], v[148:149], off offset:2560
	global_load_dwordx4 v[182:185], v[144:145], off offset:16
	v_cndmask_b32_e64 v144, 0, v153, s[24:25]
	v_add_u32_e32 v153, s33, v144
	v_mad_i64_i32 v[140:141], s[30:31], v153, s44, v[140:141]
	v_lshl_add_u64 v[142:143], v[140:141], 0, v[142:143]
	v_add_co_u32_e32 v142, vcc, s74, v142
	v_lshl_add_u64 v[144:145], v[140:141], 0, v[96:97]
	s_nop 1
	v_addc_co_u32_e32 v143, vcc, 0, v143, vcc
	global_load_ushort v186, v[144:145], off
	global_load_ushort v187, v[142:143], off offset:1024
	v_add_co_u32_e32 v142, vcc, s74, v146
	s_nop 1
	v_addc_co_u32_e32 v143, vcc, 0, v147, vcc
	global_load_ushort v188, v[142:143], off offset:1024
	v_lshl_add_u64 v[144:145], v[140:141], 0, s[86:87]
	v_add_co_u32_e32 v140, vcc, s74, v140
	s_nop 1
	v_addc_co_u32_e32 v141, vcc, 0, v141, vcc
	global_load_dwordx4 v[190:193], v[140:141], off offset:2560
	global_load_dwordx4 v[194:197], v[144:145], off offset:16
	s_waitcnt vmcnt(0)
	v_and_b32_e32 v120, 0xffff0000, v4
	s_waitcnt vmcnt(0)
	v_and_b32_e32 v121, 0xffff0000, v58
	v_lshlrev_b32_e32 v118, 16, v4
	v_lshlrev_b32_e32 v119, 16, v58
	v_pk_mul_f32 v[120:121], v[46:47], v[120:121]
	v_and_b32_e32 v58, 0xffff0000, v5
	v_pk_fma_f32 v[118:119], v[44:45], v[118:119], v[120:121]
	v_lshlrev_b32_e32 v120, 16, v5
	v_lshlrev_b32_e32 v121, 16, v59
	v_pk_fma_f32 v[118:119], v[42:43], v[120:121], v[118:119]
	v_and_b32_e32 v59, 0xffff0000, v59
	v_pk_fma_f32 v[4:5], v[40:41], v[58:59], v[118:119]
	v_lshlrev_b32_e32 v58, 16, v6
	v_lshlrev_b32_e32 v59, 16, v60
	v_pk_fma_f32 v[4:5], v[54:55], v[58:59], v[4:5]
	v_and_b32_e32 v59, 0xffff0000, v60
	v_and_b32_e32 v58, 0xffff0000, v6
	v_pk_fma_f32 v[4:5], v[52:53], v[58:59], v[4:5]
	v_lshlrev_b32_e32 v58, 16, v7
	v_lshlrev_b32_e32 v59, 16, v61
	v_pk_fma_f32 v[4:5], v[50:51], v[58:59], v[4:5]
	v_and_b32_e32 v59, 0xffff0000, v61
	v_and_b32_e32 v58, 0xffff0000, v7
	v_pk_fma_f32 v[4:5], v[48:49], v[58:59], v[4:5]
	v_cndmask_b32_e64 v59, 0, v114, s[16:17]
	v_add_f32_e32 v4, v107, v4
	v_add_f32_e32 v4, v4, v5
	v_min_f32_e32 v5, 0, v4
	v_mul_f32_e64 v4, |v4|, s29
	v_exp_f32_e32 v4, v4
	v_or_b32_e32 v114, 4, v103
	v_cmp_gt_i32_e64 s[22:23], s26, v114
	v_cndmask_b32_e64 v58, 0, v111, s[18:19]
	v_add_f32_e32 v4, 1.0, v4
	v_cmp_gt_f32_e32 vcc, s45, v4
	v_or_b32_e32 v111, 6, v103
	s_nop 0
	v_cndmask_b32_e64 v6, 0, 32, vcc
	v_ldexp_f32 v4, v4, v6
	v_log_f32_e32 v4, v4
	s_nop 0
	v_mul_f32_e32 v6, 0x3f317217, v4
	v_fma_f32 v6, v4, s49, -v6
	v_fmac_f32_e32 v6, 0x3377d1cf, v4
	v_fmac_f32_e32 v6, 0x3f317217, v4
	v_cmp_lt_f32_e64 s[20:21], |v4|, s61
	s_nop 1
	v_cndmask_b32_e64 v4, v4, v6, s[20:21]
	v_cndmask_b32_e32 v6, 0, v136, vcc
	v_sub_f32_e32 v4, v4, v6
	v_sub_f32_e32 v4, v5, v4
	v_mul_f32_e32 v4, 0x3d800000, v4
	v_cndmask_b32_e64 v4, 0, v4, s[16:17]
	v_add_f32_e32 v119, v116, v4
	v_cndmask_b32_e64 v4, 0, v114, s[22:23]
	v_add_u32_e32 v4, s33, v4
	v_mad_i64_i32 v[6:7], s[24:25], v4, s44, v[0:1]
	v_lshl_add_u64 v[4:5], v[6:7], 0, v[96:97]
	s_waitcnt vmcnt(0)
	v_mov_b32_e32 v118, v152
	v_lshl_add_u64 v[4:5], v[6:7], 0, v[2:3]
	v_lshl_add_u64 v[60:61], v[6:7], 0, s[86:87]
	v_add_co_u32_e32 v6, vcc, s74, v6
	v_cmp_gt_i32_e64 s[20:21], s26, v111
	s_nop 0
	v_addc_co_u32_e32 v7, vcc, 0, v7, vcc
	v_mov_b64_e32 v[120:121], v[158:159]
	v_mov_b64_e32 v[122:123], v[160:161]
	v_mov_b64_e32 v[124:125], v[162:163]
	v_mov_b64_e32 v[126:127], v[164:165]
	s_waitcnt vmcnt(0)
	v_and_b32_e32 v60, 0xffff0000, v120
	s_waitcnt vmcnt(0)
	v_and_b32_e32 v61, 0xffff0000, v124
	v_lshlrev_b32_e32 v6, 16, v120
	v_lshlrev_b32_e32 v7, 16, v124
	v_pk_mul_f32 v[60:61], v[46:47], v[60:61]
	s_nop 0
	v_pk_fma_f32 v[6:7], v[44:45], v[6:7], v[60:61]
	v_lshlrev_b32_e32 v60, 16, v121
	v_lshlrev_b32_e32 v61, 16, v125
	v_pk_fma_f32 v[6:7], v[42:43], v[60:61], v[6:7]
	v_and_b32_e32 v61, 0xffff0000, v125
	v_and_b32_e32 v60, 0xffff0000, v121
	v_pk_fma_f32 v[6:7], v[40:41], v[60:61], v[6:7]
	v_lshlrev_b32_e32 v60, 16, v122
	v_lshlrev_b32_e32 v61, 16, v126
	v_pk_fma_f32 v[6:7], v[54:55], v[60:61], v[6:7]
	v_and_b32_e32 v61, 0xffff0000, v126
	v_and_b32_e32 v60, 0xffff0000, v122
	v_pk_fma_f32 v[6:7], v[52:53], v[60:61], v[6:7]
	v_lshlrev_b32_e32 v60, 16, v123
	v_lshlrev_b32_e32 v61, 16, v127
	v_pk_fma_f32 v[6:7], v[50:51], v[60:61], v[6:7]
	v_and_b32_e32 v61, 0xffff0000, v127
	v_and_b32_e32 v60, 0xffff0000, v123
	v_pk_fma_f32 v[6:7], v[48:49], v[60:61], v[6:7]
	v_or_b32_e32 v123, 7, v103
	v_add_f32_e32 v6, v107, v6
	v_add_f32_e32 v6, v6, v7
	v_min_f32_e32 v7, 0, v6
	v_mul_f32_e64 v6, |v6|, s29
	v_exp_f32_e32 v6, v6
	s_nop 0
	v_add_f32_e32 v6, 1.0, v6
	v_cmp_gt_f32_e32 vcc, s45, v6
	s_nop 1
	v_cndmask_b32_e64 v60, 0, 32, vcc
	v_ldexp_f32 v6, v6, v60
	v_log_f32_e32 v6, v6
	s_nop 0
	v_mul_f32_e32 v60, 0x3f317217, v6
	v_fma_f32 v60, v6, s49, -v60
	v_fmac_f32_e32 v60, 0x3377d1cf, v6
	v_fmac_f32_e32 v60, 0x3f317217, v6
	v_cmp_lt_f32_e64 s[24:25], |v6|, s61
	s_nop 1
	v_cndmask_b32_e64 v6, v6, v60, s[24:25]
	v_cndmask_b32_e32 v60, 0, v136, vcc
	v_sub_f32_e32 v6, v6, v60
	v_sub_f32_e32 v6, v7, v6
	v_mul_f32_e32 v6, 0x3d800000, v6
	v_cndmask_b32_e64 v122, 0, v6, s[22:23]
	v_or_b32_e32 v6, 5, v103
	v_cmp_gt_i32_e64 s[24:25], s26, v123
	v_cmp_gt_i32_e64 s[26:27], s26, v6
	s_nop 1
	v_cndmask_b32_e64 v6, 0, v6, s[26:27]
	v_add_u32_e32 v117, s33, v6
	v_mad_i64_i32 v[60:61], s[30:31], v117, s44, v[0:1]
	v_lshl_add_u64 v[6:7], v[60:61], 0, v[96:97]
	v_mov_b32_e32 v120, v166
	v_lshl_add_u64 v[6:7], v[60:61], 0, v[2:3]
	v_lshl_add_u64 v[128:129], v[60:61], 0, s[86:87]
	v_add_co_u32_e32 v60, vcc, s74, v60
	s_nop 1
	v_addc_co_u32_e32 v61, vcc, 0, v61, vcc
	v_mov_b64_e32 v[124:125], v[168:169]
	v_mov_b64_e32 v[126:127], v[170:171]
	s_nop 0
	v_mov_b64_e32 v[128:129], v[172:173]
	v_mov_b64_e32 v[130:131], v[174:175]
	s_waitcnt vmcnt(0)
	v_and_b32_e32 v132, 0xffff0000, v124
	s_waitcnt vmcnt(0)
	v_and_b32_e32 v133, 0xffff0000, v128
	v_lshlrev_b32_e32 v60, 16, v124
	v_lshlrev_b32_e32 v61, 16, v128
	v_pk_mul_f32 v[132:133], v[46:47], v[132:133]
	v_and_b32_e32 v128, 0xffff0000, v125
	v_pk_fma_f32 v[60:61], v[44:45], v[60:61], v[132:133]
	v_lshlrev_b32_e32 v132, 16, v125
	v_lshlrev_b32_e32 v133, 16, v129
	v_pk_fma_f32 v[60:61], v[42:43], v[132:133], v[60:61]
	v_and_b32_e32 v129, 0xffff0000, v129
	v_pk_fma_f32 v[60:61], v[40:41], v[128:129], v[60:61]
	v_lshlrev_b32_e32 v124, 16, v126
	v_lshlrev_b32_e32 v125, 16, v130
	v_pk_fma_f32 v[60:61], v[54:55], v[124:125], v[60:61]
	v_and_b32_e32 v125, 0xffff0000, v130
	v_and_b32_e32 v124, 0xffff0000, v126
	v_pk_fma_f32 v[60:61], v[52:53], v[124:125], v[60:61]
	v_lshlrev_b32_e32 v124, 16, v127
	v_lshlrev_b32_e32 v125, 16, v131
	v_pk_fma_f32 v[60:61], v[50:51], v[124:125], v[60:61]
	v_and_b32_e32 v125, 0xffff0000, v131
	v_and_b32_e32 v124, 0xffff0000, v127
	v_pk_fma_f32 v[60:61], v[48:49], v[124:125], v[60:61]
	s_nop 0
	v_add_f32_e32 v60, v107, v60
	v_add_f32_e32 v60, v60, v61
	v_min_f32_e32 v61, 0, v60
	v_mul_f32_e64 v60, |v60|, s29
	v_exp_f32_e32 v60, v60
	s_nop 0
	v_add_f32_e32 v60, 1.0, v60
	v_cmp_gt_f32_e32 vcc, s45, v60
	s_nop 1
	v_cndmask_b32_e64 v121, 0, 32, vcc
	v_ldexp_f32 v60, v60, v121
	v_log_f32_e32 v60, v60
	s_nop 0
	v_mul_f32_e32 v121, 0x3f317217, v60
	v_fma_f32 v121, v60, s49, -v121
	v_fmac_f32_e32 v121, 0x3377d1cf, v60
	v_fmac_f32_e32 v121, 0x3f317217, v60
	v_cmp_lt_f32_e64 s[30:31], |v60|, s61
	s_nop 1
	v_cndmask_b32_e64 v60, v60, v121, s[30:31]
	v_cndmask_b32_e32 v121, 0, v136, vcc
	v_sub_f32_e32 v60, v60, v121
	v_sub_f32_e32 v60, v61, v60
	v_mul_f32_e32 v60, 0x3d800000, v60
	v_cndmask_b32_e64 v124, 0, v60, s[26:27]
	v_cndmask_b32_e64 v60, 0, v111, s[20:21]
	v_add_u32_e32 v60, s33, v60
	v_mad_i64_i32 v[60:61], s[30:31], v60, s44, v[0:1]
	v_lshl_add_u64 v[126:127], v[60:61], 0, v[96:97]
	v_mov_b32_e32 v121, v167
	v_lshl_add_u64 v[126:127], v[60:61], 0, v[2:3]
	v_add_co_u32_e32 v126, vcc, s74, v126
	s_nop 1
	v_addc_co_u32_e32 v127, vcc, 0, v127, vcc
	v_add_co_u32_e32 v4, vcc, s74, v4
	v_mov_b32_e32 v125, v176
	s_nop 0
	v_addc_co_u32_e32 v5, vcc, 0, v5, vcc
	v_mov_b32_e32 v4, v177
	s_waitcnt vmcnt(0)
	v_lshlrev_b32_e32 v135, 16, v125
	s_waitcnt vmcnt(0)
	v_lshlrev_b32_e32 v134, 16, v4
	v_lshl_add_u64 v[4:5], v[60:61], 0, s[86:87]
	v_add_co_u32_e32 v60, vcc, s74, v60
	s_nop 1
	v_addc_co_u32_e32 v61, vcc, 0, v61, vcc
	v_mov_b64_e32 v[126:127], v[178:179]
	v_mov_b64_e32 v[128:129], v[180:181]
	v_mov_b64_e32 v[130:131], v[182:183]
	v_mov_b64_e32 v[132:133], v[184:185]
	s_waitcnt vmcnt(0)
	v_and_b32_e32 v60, 0xffff0000, v126
	s_waitcnt vmcnt(0)
	v_and_b32_e32 v61, 0xffff0000, v130
	v_lshlrev_b32_e32 v4, 16, v126
	v_lshlrev_b32_e32 v5, 16, v130
	v_pk_mul_f32 v[60:61], v[46:47], v[60:61]
	s_nop 0
	v_pk_fma_f32 v[4:5], v[44:45], v[4:5], v[60:61]
	v_lshlrev_b32_e32 v60, 16, v127
	v_lshlrev_b32_e32 v61, 16, v131
	v_pk_fma_f32 v[4:5], v[42:43], v[60:61], v[4:5]
	v_and_b32_e32 v61, 0xffff0000, v131
	v_and_b32_e32 v60, 0xffff0000, v127
	v_pk_fma_f32 v[4:5], v[40:41], v[60:61], v[4:5]
	v_lshlrev_b32_e32 v60, 16, v128
	v_lshlrev_b32_e32 v61, 16, v132
	v_pk_fma_f32 v[4:5], v[54:55], v[60:61], v[4:5]
	v_and_b32_e32 v61, 0xffff0000, v132
	v_and_b32_e32 v60, 0xffff0000, v128
	v_pk_fma_f32 v[4:5], v[52:53], v[60:61], v[4:5]
	v_lshlrev_b32_e32 v60, 16, v129
	v_lshlrev_b32_e32 v61, 16, v133
	v_pk_fma_f32 v[4:5], v[50:51], v[60:61], v[4:5]
	v_and_b32_e32 v61, 0xffff0000, v133
	v_and_b32_e32 v60, 0xffff0000, v129
	v_pk_fma_f32 v[4:5], v[48:49], v[60:61], v[4:5]
	v_cndmask_b32_e64 v61, 0, v135, s[20:21]
	v_add_f32_e32 v4, v107, v4
	v_add_f32_e32 v4, v4, v5
	v_min_f32_e32 v5, 0, v4
	v_mul_f32_e64 v4, |v4|, s29
	v_exp_f32_e32 v4, v4
	s_nop 0
	v_add_f32_e32 v4, 1.0, v4
	v_cmp_gt_f32_e32 vcc, s45, v4
	s_nop 1
	v_cndmask_b32_e64 v60, 0, 32, vcc
	v_ldexp_f32 v4, v4, v60
	v_log_f32_e32 v4, v4
	s_nop 0
	v_mul_f32_e32 v60, 0x3f317217, v4
	v_fma_f32 v60, v4, s49, -v60
	v_fmac_f32_e32 v60, 0x3377d1cf, v4
	v_fmac_f32_e32 v60, 0x3f317217, v4
	v_cmp_lt_f32_e64 s[30:31], |v4|, s61
	s_nop 1
	v_cndmask_b32_e64 v4, v4, v60, s[30:31]
	v_cndmask_b32_e32 v60, 0, v136, vcc
	v_sub_f32_e32 v4, v4, v60
	v_sub_f32_e32 v4, v5, v4
	v_mul_f32_e32 v4, 0x3d800000, v4
	v_cndmask_b32_e64 v125, 0, v4, s[20:21]
	v_cndmask_b32_e64 v4, 0, v123, s[24:25]
	v_add_u32_e32 v123, s33, v4
	v_mad_i64_i32 v[0:1], s[30:31], v123, s44, v[0:1]
	v_lshl_add_u64 v[2:3], v[0:1], 0, v[2:3]
	v_add_co_u32_e32 v2, vcc, s74, v2
	v_lshl_add_u64 v[4:5], v[0:1], 0, v[96:97]
	s_nop 0
	v_addc_co_u32_e32 v3, vcc, 0, v3, vcc
	v_mov_b32_e32 v96, v186
	v_cndmask_b32_e64 v60, 0, v134, s[22:23]
	v_mov_b32_e32 v4, v187
	v_add_co_u32_e32 v2, vcc, s74, v6
	s_waitcnt vmcnt(0)
	v_lshlrev_b32_e32 v131, 16, v4
	v_addc_co_u32_e32 v3, vcc, 0, v7, vcc
	v_mov_b32_e32 v2, v188
	v_lshl_add_u64 v[4:5], v[0:1], 0, s[86:87]
	v_add_co_u32_e32 v0, vcc, s74, v0
	s_waitcnt vmcnt(0)
	v_lshlrev_b32_e32 v130, 16, v2
	v_addc_co_u32_e32 v1, vcc, 0, v1, vcc
	v_mov_b64_e32 v[0:1], v[190:191]
	v_mov_b64_e32 v[2:3], v[192:193]
	s_nop 0
	v_mov_b64_e32 v[4:5], v[194:195]
	v_mov_b64_e32 v[6:7], v[196:197]
	s_barrier
	s_waitcnt vmcnt(1)
	v_and_b32_e32 v128, 0xffff0000, v0
	s_waitcnt vmcnt(0)
	v_and_b32_e32 v129, 0xffff0000, v4
	v_lshlrev_b32_e32 v126, 16, v0
	v_lshlrev_b32_e32 v127, 16, v4
	v_pk_mul_f32 v[46:47], v[46:47], v[128:129]
	v_and_b32_e32 v4, 0xffff0000, v1
	v_pk_fma_f32 v[44:45], v[44:45], v[126:127], v[46:47]
	v_lshlrev_b32_e32 v46, 16, v1
	v_lshlrev_b32_e32 v47, 16, v5
	v_pk_fma_f32 v[42:43], v[42:43], v[46:47], v[44:45]
	v_and_b32_e32 v5, 0xffff0000, v5
	v_pk_fma_f32 v[0:1], v[40:41], v[4:5], v[42:43]
	v_lshlrev_b32_e32 v4, 16, v2
	v_lshlrev_b32_e32 v5, 16, v6
	v_pk_fma_f32 v[0:1], v[54:55], v[4:5], v[0:1]
	v_and_b32_e32 v5, 0xffff0000, v6
	v_and_b32_e32 v4, 0xffff0000, v2
	v_pk_fma_f32 v[0:1], v[52:53], v[4:5], v[0:1]
	v_lshlrev_b32_e32 v4, 16, v3
	v_lshlrev_b32_e32 v5, 16, v7
	v_pk_fma_f32 v[0:1], v[50:51], v[4:5], v[0:1]
	v_and_b32_e32 v5, 0xffff0000, v7
	v_and_b32_e32 v4, 0xffff0000, v3
	v_pk_fma_f32 v[0:1], v[48:49], v[4:5], v[0:1]
	v_add_f32_e32 v52, v119, v122
	v_add_f32_e32 v0, v107, v0
	v_add_f32_e32 v0, v0, v1
	v_min_f32_e32 v1, 0, v0
	v_mul_f32_e64 v0, |v0|, s29
	v_exp_f32_e32 v0, v0
	v_add_f32_e32 v53, v52, v124
	v_add_f32_e32 v54, v53, v125
	v_add_f32_e32 v0, 1.0, v0
	v_cmp_gt_f32_e32 vcc, s45, v0
	s_nop 1
	v_cndmask_b32_e64 v2, 0, 32, vcc
	v_ldexp_f32 v0, v0, v2
	v_log_f32_e32 v0, v0
	s_nop 0
	v_mul_f32_e32 v2, 0x3f317217, v0
	v_fma_f32 v2, v0, s49, -v2
	v_fmac_f32_e32 v2, 0x3377d1cf, v0
	v_fmac_f32_e32 v2, 0x3f317217, v0
	v_cmp_lt_f32_e64 s[30:31], |v0|, s61
	s_nop 1
	v_cndmask_b32_e64 v0, v0, v2, s[30:31]
	v_cndmask_b32_e32 v2, 0, v136, vcc
	v_sub_f32_e32 v0, v0, v2
	v_sub_f32_e32 v0, v1, v0
	v_mul_f32_e32 v0, 0x3d800000, v0
	v_cndmask_b32_e64 v2, 0, v0, s[24:25]
	v_add_f32_e32 v5, v54, v2
	ds_write_b32 v68, v5
	s_waitcnt lgkmcnt(0)
	s_barrier
	ds_read2st64_b32 v[6:7], v69 offset1:2
	ds_read2st64_b32 v[2:3], v69 offset0:4 offset1:6
	v_cndmask_b32_e64 v1, 0, v131, s[24:25]
	v_cndmask_b32_e64 v0, 0, v130, s[26:27]
	s_waitcnt lgkmcnt(1)
	v_add_f32_e32 v7, v6, v7
	s_waitcnt lgkmcnt(0)
	v_add_f32_e32 v4, v7, v2
	v_cndmask_b32_e64 v2, v4, v7, s[4:5]
	v_cndmask_b32_e64 v2, v2, v6, s[2:3]
	v_cndmask_b32_e64 v47, v2, 0, s[0:1]
	v_mov_b32_e32 v46, v3
	v_add_f32_e32 v45, v108, v47
	v_pk_add_f32 v[2:3], v[4:5], v[46:47]
	v_add_f32_e32 v44, v112, v47
	v_sub_f32_e32 v5, v2, v45
	v_mul_f32_e32 v5, 0x3fb8aa3b, v5
	v_exp_f32_e32 v40, v5
	v_sub_f32_e32 v5, v2, v44
	v_mul_f32_e32 v5, 0x3fb8aa3b, v5
	v_add_f32_e32 v43, v116, v47
	v_exp_f32_e32 v48, v5
	v_sub_f32_e32 v5, v2, v43
	v_mul_f32_e32 v5, 0x3fb8aa3b, v5
	v_exp_f32_e32 v41, v5
	v_add_f32_e32 v42, v119, v47
	v_sub_f32_e32 v5, v2, v42
	v_mul_f32_e32 v5, 0x3fb8aa3b, v5
	v_pk_mul_f32 v[50:51], v[56:57], v[40:41]
	v_add_f32_e32 v41, v52, v47
	v_exp_f32_e32 v49, v5
	v_sub_f32_e32 v5, v2, v41
	v_add_f32_e32 v40, v53, v47
	v_mul_f32_e32 v5, 0x3fb8aa3b, v5
	v_exp_f32_e32 v46, v5
	v_sub_f32_e32 v5, v2, v40
	v_mul_f32_e32 v5, 0x3fb8aa3b, v5
	v_exp_f32_e32 v52, v5
	v_add_f32_e32 v5, v47, v54
	v_sub_f32_e32 v53, v2, v3
	v_sub_f32_e32 v47, v2, v5
	v_mul_f32_e32 v53, 0x3fb8aa3b, v53
	v_mul_f32_e32 v47, 0x3fb8aa3b, v47
	v_exp_f32_e32 v53, v53
	v_exp_f32_e32 v47, v47
	v_pk_mul_f32 v[48:49], v[58:59], v[48:49]
	v_pk_mul_f32 v[52:53], v[0:1], v[52:53]
	v_pk_mul_f32 v[46:47], v[60:61], v[46:47]
	v_cvt_pk_bf16_f32 v52, v52, v52
	v_cvt_pk_bf16_f32 v53, v53, v53
	v_cvt_pk_bf16_f32 v54, v48, v48
	v_cvt_pk_bf16_f32 v55, v49, v49
	v_cvt_pk_bf16_f32 v47, v47, v47
	v_cvt_pk_bf16_f32 v46, v46, v46
	v_cvt_pk_bf16_f32 v48, v51, v51
	v_cvt_pk_bf16_f32 v49, v50, v50
	v_lshrrev_b32_e32 v46, 16, v46
	v_lshrrev_b32_e32 v47, 16, v47
	v_lshrrev_b32_e32 v50, 16, v49
	v_lshrrev_b32_e32 v51, 16, v48
	v_and_or_b32 v49, v53, s36, v47
	v_and_or_b32 v48, v52, s36, v46
	v_and_or_b32 v47, v55, s36, v51
	v_and_or_b32 v46, v54, s36, v50
	v_lshl_add_u64 v[50:51], v[38:39], 0, v[14:15]
	v_add_co_u32_e32 v50, vcc, 0x1000, v50
	s_nop 1
	v_addc_co_u32_e32 v51, vcc, 0, v51, vcc
	global_store_dwordx4 v[50:51], v[46:49], off
	s_and_saveexec_b64 s[30:31], s[8:9]
	s_cbranch_execz .LBB0_439
	v_mul_f32_e32 v2, 0x3fb8aa3b, v2
	v_exp_f32_e32 v2, v2
	v_lshl_add_u64 v[38:39], v[38:39], 0, v[8:9]
	v_add_co_u32_e32 v38, vcc, 0x2000, v38
	s_nop 1
	v_addc_co_u32_e32 v39, vcc, 0, v39, vcc
	global_store_dword v[38:39], v2, off offset:2048
.LBB0_439:
	s_or_b64 exec, exec, s[30:31]
	v_lshlrev_b32_e32 v2, 16, v106
	v_mul_f32_e32 v2, 0x3e000000, v2
	v_cndmask_b32_e64 v38, 0, v2, s[14:15]
	v_cndmask_b32_e64 v2, v4, v6, s[6:7]
	v_mul_f32_e32 v4, 0x3fb8aa3b, v45
	v_exp_f32_e32 v4, v4
	s_nop 0
	v_mul_f32_e32 v4, v38, v4
	v_cvt_pk_bf16_f32 v4, v4, v4
	v_add_u32_e32 v6, v71, v72
	ds_write_b16_d16_hi v6, v4 offset:2048
	v_sub_f32_e32 v4, v45, v2
	v_mul_f32_e32 v4, 0x3fb8aa3b, v4
	v_exp_f32_e32 v4, v4
	s_nop 0
	v_mul_f32_e32 v4, v38, v4
	v_cvt_pk_bf16_f32 v4, v4, v4
	ds_write_b16_d16_hi v73, v4 offset:10240
	v_sub_f32_e32 v4, v2, v45
	v_mul_f32_e32 v4, 0x3fb8aa3b, v4
	v_exp_f32_e32 v4, v4
	s_nop 0
	v_mul_f32_e32 v4, v56, v4
	v_cvt_pk_bf16_f32 v4, v4, v4
	ds_write_b16_d16_hi v73, v4 offset:18944
	s_and_saveexec_b64 s[30:31], s[6:7]
	s_xor_b64 s[30:31], exec, s[30:31]
	s_cbranch_execz .LBB0_441
	v_sub_f32_e32 v4, v7, v45
	v_mul_f32_e32 v4, 0x3fb8aa3b, v4
	v_exp_f32_e32 v4, v4
	s_nop 0
	v_mul_f32_e32 v4, v56, v4
	v_cvt_pk_bf16_f32 v4, v4, v4
	ds_write_b16_d16_hi v73, v4 offset:32000
.LBB0_441:
	s_andn2_saveexec_b64 s[30:31], s[30:31]
	s_cbranch_execz .LBB0_443
	v_sub_f32_e32 v4, v45, v7
	v_mul_f32_e32 v4, 0x3fb8aa3b, v4
	v_exp_f32_e32 v4, v4
	s_nop 0
	v_mul_f32_e32 v4, v38, v4
	v_cvt_pk_bf16_f32 v4, v4, v4
	ds_write_b16_d16_hi v74, v4 offset:23296
.LBB0_443:
	s_or_b64 exec, exec, s[30:31]
	v_mul_f32_e32 v6, 0x3fb8aa3b, v44
	v_exp_f32_e32 v6, v6
	v_lshlrev_b32_e32 v4, 16, v109
	v_mul_f32_e32 v4, 0x3e000000, v4
	v_cndmask_b32_e64 v4, 0, v4, s[18:19]
	v_mul_f32_e32 v6, v4, v6
	v_cvt_pk_bf16_f32 v6, v6, v6
	v_add_u32_e32 v38, v71, v75
	ds_write_b16_d16_hi v38, v6 offset:2048
	v_sub_f32_e32 v6, v44, v2
	v_mul_f32_e32 v6, 0x3fb8aa3b, v6
	v_exp_f32_e32 v6, v6
	s_nop 0
	v_mul_f32_e32 v6, v4, v6
	v_cvt_pk_bf16_f32 v6, v6, v6
	ds_write_b16_d16_hi v76, v6 offset:10240
	v_sub_f32_e32 v6, v2, v44
	v_mul_f32_e32 v6, 0x3fb8aa3b, v6
	v_exp_f32_e32 v6, v6
	s_nop 0
	v_mul_f32_e32 v6, v58, v6
	v_cvt_pk_bf16_f32 v6, v6, v6
	ds_write_b16_d16_hi v76, v6 offset:18944
	s_and_saveexec_b64 s[30:31], s[6:7]
	s_xor_b64 s[30:31], exec, s[30:31]
	s_cbranch_execz .LBB0_445
	v_sub_f32_e32 v4, v7, v44
	v_mul_f32_e32 v4, 0x3fb8aa3b, v4
	v_exp_f32_e32 v4, v4
	s_nop 0
	v_mul_f32_e32 v4, v58, v4
	v_bfe_u32 v6, v4, 16, 1
	v_add3_u32 v4, v4, v6, s48
	ds_write_b16_d16_hi v76, v4 offset:32000
.LBB0_445:
	s_andn2_saveexec_b64 s[30:31], s[30:31]
	s_cbranch_execz .LBB0_447
	v_sub_f32_e32 v6, v44, v7
	v_mul_f32_e32 v6, 0x3fb8aa3b, v6
	v_exp_f32_e32 v6, v6
	s_nop 0
	v_mul_f32_e32 v4, v4, v6
	v_cvt_pk_bf16_f32 v4, v4, v4
	ds_write_b16_d16_hi v77, v4 offset:23296
.LBB0_447:
	s_or_b64 exec, exec, s[30:31]
	v_mul_f32_e32 v6, 0x3fb8aa3b, v43
	v_exp_f32_e32 v6, v6
	v_lshlrev_b32_e32 v4, 16, v113
	v_mul_f32_e32 v4, 0x3e000000, v4
	v_cndmask_b32_e64 v4, 0, v4, s[12:13]
	v_mul_f32_e32 v6, v4, v6
	v_cvt_pk_bf16_f32 v6, v6, v6
	v_add_u32_e32 v38, v71, v78
	ds_write_b16_d16_hi v38, v6 offset:2048
	v_sub_f32_e32 v6, v43, v2
	v_mul_f32_e32 v6, 0x3fb8aa3b, v6
	v_exp_f32_e32 v6, v6
	s_nop 0
	v_mul_f32_e32 v6, v4, v6
	v_cvt_pk_bf16_f32 v6, v6, v6
	ds_write_b16_d16_hi v79, v6 offset:10240
	v_sub_f32_e32 v6, v2, v43
	v_mul_f32_e32 v6, 0x3fb8aa3b, v6
	v_exp_f32_e32 v6, v6
	s_nop 0
	v_mul_f32_e32 v6, v57, v6
	v_cvt_pk_bf16_f32 v6, v6, v6
	ds_write_b16_d16_hi v79, v6 offset:18944
	s_and_saveexec_b64 s[30:31], s[6:7]
	s_xor_b64 s[30:31], exec, s[30:31]
	s_cbranch_execz .LBB0_449
	v_sub_f32_e32 v4, v7, v43
	v_mul_f32_e32 v4, 0x3fb8aa3b, v4
	v_exp_f32_e32 v4, v4
	s_nop 0
	v_mul_f32_e32 v4, v57, v4
	v_bfe_u32 v6, v4, 16, 1
	v_add3_u32 v4, v4, v6, s48
	ds_write_b16_d16_hi v79, v4 offset:32000
.LBB0_449:
	s_andn2_saveexec_b64 s[30:31], s[30:31]
	s_cbranch_execz .LBB0_451
	v_sub_f32_e32 v6, v43, v7
	v_mul_f32_e32 v6, 0x3fb8aa3b, v6
	v_exp_f32_e32 v6, v6
	s_nop 0
	v_mul_f32_e32 v4, v4, v6
	v_cvt_pk_bf16_f32 v4, v4, v4
	ds_write_b16_d16_hi v80, v4 offset:23296
.LBB0_451:
	s_or_b64 exec, exec, s[30:31]
	v_mul_f32_e32 v6, 0x3fb8aa3b, v42
	v_exp_f32_e32 v6, v6
	v_lshlrev_b32_e32 v4, 16, v115
	v_mul_f32_e32 v4, 0x3e000000, v4
	v_cndmask_b32_e64 v4, 0, v4, s[16:17]
	v_mul_f32_e32 v6, v4, v6
	v_cvt_pk_bf16_f32 v6, v6, v6
	v_add_u32_e32 v38, v71, v81
	ds_write_b16_d16_hi v38, v6 offset:2048
	v_sub_f32_e32 v6, v42, v2
	v_mul_f32_e32 v6, 0x3fb8aa3b, v6
	v_exp_f32_e32 v6, v6
	s_nop 0
	v_mul_f32_e32 v6, v4, v6
	v_cvt_pk_bf16_f32 v6, v6, v6
	ds_write_b16_d16_hi v82, v6 offset:10240
	v_sub_f32_e32 v6, v2, v42
	v_mul_f32_e32 v6, 0x3fb8aa3b, v6
	v_exp_f32_e32 v6, v6
	s_nop 0
	v_mul_f32_e32 v6, v59, v6
	v_cvt_pk_bf16_f32 v6, v6, v6
	ds_write_b16_d16_hi v82, v6 offset:18944
	s_and_saveexec_b64 s[30:31], s[6:7]
	s_xor_b64 s[30:31], exec, s[30:31]
	s_cbranch_execz .LBB0_453
	v_sub_f32_e32 v4, v7, v42
	v_mul_f32_e32 v4, 0x3fb8aa3b, v4
	v_exp_f32_e32 v4, v4
	s_nop 0
	v_mul_f32_e32 v4, v59, v4
	v_bfe_u32 v6, v4, 16, 1
	v_add3_u32 v4, v4, v6, s48
	ds_write_b16_d16_hi v82, v4 offset:32000
.LBB0_453:
	s_andn2_saveexec_b64 s[30:31], s[30:31]
	s_cbranch_execz .LBB0_455
	v_sub_f32_e32 v6, v42, v7
	v_mul_f32_e32 v6, 0x3fb8aa3b, v6
	v_exp_f32_e32 v6, v6
	s_nop 0
	v_mul_f32_e32 v4, v4, v6
	v_cvt_pk_bf16_f32 v4, v4, v4
	ds_write_b16_d16_hi v83, v4 offset:23296
.LBB0_455:
	s_or_b64 exec, exec, s[30:31]
	v_mul_f32_e32 v6, 0x3fb8aa3b, v41
	v_exp_f32_e32 v6, v6
	v_lshlrev_b32_e32 v4, 16, v118
	v_mul_f32_e32 v4, 0x3e000000, v4
	v_cndmask_b32_e64 v4, 0, v4, s[22:23]
	v_mul_f32_e32 v6, v4, v6
	v_cvt_pk_bf16_f32 v6, v6, v6
	v_add_u32_e32 v38, v71, v84
	ds_write_b16_d16_hi v38, v6 offset:2048
	v_sub_f32_e32 v6, v41, v2
	v_mul_f32_e32 v6, 0x3fb8aa3b, v6
	v_exp_f32_e32 v6, v6
	s_nop 0
	v_mul_f32_e32 v6, v4, v6
	v_cvt_pk_bf16_f32 v6, v6, v6
	ds_write_b16_d16_hi v85, v6 offset:10240
	v_sub_f32_e32 v6, v2, v41
	v_mul_f32_e32 v6, 0x3fb8aa3b, v6
	v_exp_f32_e32 v6, v6
	s_nop 0
	v_mul_f32_e32 v6, v60, v6
	v_cvt_pk_bf16_f32 v6, v6, v6
	ds_write_b16_d16_hi v85, v6 offset:18944
	s_and_saveexec_b64 s[30:31], s[6:7]
	s_xor_b64 s[30:31], exec, s[30:31]
	s_cbranch_execz .LBB0_457
	v_sub_f32_e32 v4, v7, v41
	v_mul_f32_e32 v4, 0x3fb8aa3b, v4
	v_exp_f32_e32 v4, v4
	s_nop 0
	v_mul_f32_e32 v4, v60, v4
	v_bfe_u32 v6, v4, 16, 1
	v_add3_u32 v4, v4, v6, s48
	ds_write_b16_d16_hi v85, v4 offset:32000
.LBB0_457:
	s_andn2_saveexec_b64 s[30:31], s[30:31]
	s_cbranch_execz .LBB0_459
	v_sub_f32_e32 v6, v41, v7
	v_mul_f32_e32 v6, 0x3fb8aa3b, v6
	v_exp_f32_e32 v6, v6
	s_nop 0
	v_mul_f32_e32 v4, v4, v6
	v_cvt_pk_bf16_f32 v4, v4, v4
	ds_write_b16_d16_hi v86, v4 offset:23296
.LBB0_459:
	s_or_b64 exec, exec, s[30:31]
	v_mul_f32_e32 v6, 0x3fb8aa3b, v40
	v_exp_f32_e32 v6, v6
	v_lshlrev_b32_e32 v4, 16, v120
	v_mul_f32_e32 v4, 0x3e000000, v4
	v_cndmask_b32_e64 v4, 0, v4, s[26:27]
	v_mul_f32_e32 v6, v4, v6
	v_cvt_pk_bf16_f32 v6, v6, v6
	v_add_u32_e32 v38, v71, v87
	ds_write_b16_d16_hi v38, v6 offset:2048
	v_sub_f32_e32 v6, v40, v2
	v_mul_f32_e32 v6, 0x3fb8aa3b, v6
	v_exp_f32_e32 v6, v6
	s_nop 0
	v_mul_f32_e32 v6, v4, v6
	v_cvt_pk_bf16_f32 v6, v6, v6
	ds_write_b16_d16_hi v88, v6 offset:10240
	v_sub_f32_e32 v6, v2, v40
	v_mul_f32_e32 v6, 0x3fb8aa3b, v6
	v_exp_f32_e32 v6, v6
	s_nop 0
	v_mul_f32_e32 v6, v0, v6
	v_cvt_pk_bf16_f32 v6, v6, v6
	ds_write_b16_d16_hi v88, v6 offset:18944
	s_and_saveexec_b64 s[30:31], s[6:7]
	s_xor_b64 s[30:31], exec, s[30:31]
	s_cbranch_execz .LBB0_461
	v_sub_f32_e32 v4, v7, v40
	v_mul_f32_e32 v4, 0x3fb8aa3b, v4
	v_exp_f32_e32 v4, v4
	s_nop 0
	v_mul_f32_e32 v0, v0, v4
	v_cvt_pk_bf16_f32 v0, v0, v0
	ds_write_b16_d16_hi v88, v0 offset:32000
.LBB0_461:
	s_andn2_saveexec_b64 s[30:31], s[30:31]
	s_cbranch_execz .LBB0_463
	v_sub_f32_e32 v0, v40, v7
	v_mul_f32_e32 v0, 0x3fb8aa3b, v0
	v_exp_f32_e32 v0, v0
	s_nop 0
	v_mul_f32_e32 v0, v4, v0
	v_cvt_pk_bf16_f32 v0, v0, v0
	ds_write_b16_d16_hi v89, v0 offset:23296
.LBB0_463:
	s_or_b64 exec, exec, s[30:31]
	v_mul_f32_e32 v4, 0x3fb8aa3b, v5
	v_exp_f32_e32 v4, v4
	v_lshlrev_b32_e32 v0, 16, v121
	v_mul_f32_e32 v0, 0x3e000000, v0
	v_cndmask_b32_e64 v0, 0, v0, s[20:21]
	v_mul_f32_e32 v4, v0, v4
	v_cvt_pk_bf16_f32 v4, v4, v4
	v_add_u32_e32 v6, v71, v90
	ds_write_b16_d16_hi v6, v4 offset:2048
	v_sub_f32_e32 v4, v5, v2
	v_mul_f32_e32 v4, 0x3fb8aa3b, v4
	v_exp_f32_e32 v4, v4
	s_nop 0
	v_mul_f32_e32 v4, v0, v4
	v_cvt_pk_bf16_f32 v4, v4, v4
	ds_write_b16_d16_hi v91, v4 offset:10240
	v_sub_f32_e32 v4, v2, v5
	v_mul_f32_e32 v4, 0x3fb8aa3b, v4
	v_exp_f32_e32 v4, v4
	s_nop 0
	v_mul_f32_e32 v4, v61, v4
	v_cvt_pk_bf16_f32 v4, v4, v4
	ds_write_b16_d16_hi v91, v4 offset:18944
	s_and_saveexec_b64 s[30:31], s[6:7]
	s_xor_b64 s[30:31], exec, s[30:31]
	s_cbranch_execz .LBB0_465
	v_sub_f32_e32 v0, v7, v5
	v_mul_f32_e32 v0, 0x3fb8aa3b, v0
	v_exp_f32_e32 v0, v0
	s_nop 0
	v_mul_f32_e32 v0, v61, v0
	v_bfe_u32 v4, v0, 16, 1
	v_add3_u32 v0, v0, v4, s48
	ds_write_b16_d16_hi v91, v0 offset:32000
.LBB0_465:
	s_andn2_saveexec_b64 s[30:31], s[30:31]
	s_cbranch_execz .LBB0_467
	v_sub_f32_e32 v4, v5, v7
	v_mul_f32_e32 v4, 0x3fb8aa3b, v4
	v_exp_f32_e32 v4, v4
	s_nop 0
	v_mul_f32_e32 v0, v0, v4
	v_cvt_pk_bf16_f32 v0, v0, v0
	ds_write_b16_d16_hi v92, v0 offset:23296
.LBB0_467:
	s_or_b64 exec, exec, s[30:31]
	v_mul_f32_e32 v4, 0x3fb8aa3b, v3
	v_exp_f32_e32 v4, v4
	v_lshlrev_b32_e32 v0, 16, v96
	v_mul_f32_e32 v0, 0x3e000000, v0
	v_cndmask_b32_e64 v0, 0, v0, s[24:25]
	v_mul_f32_e32 v4, v0, v4
	v_cvt_pk_bf16_f32 v4, v4, v4
	v_add_u32_e32 v5, v71, v93
	ds_write_b16_d16_hi v5, v4 offset:2048
	v_sub_f32_e32 v4, v3, v2
	v_mul_f32_e32 v4, 0x3fb8aa3b, v4
	v_exp_f32_e32 v4, v4
	v_sub_f32_e32 v2, v2, v3
	v_mul_f32_e32 v2, 0x3fb8aa3b, v2
	v_exp_f32_e32 v2, v2
	v_mul_f32_e32 v4, v0, v4
	v_cvt_pk_bf16_f32 v4, v4, v4
	v_mul_f32_e32 v2, v1, v2
	ds_write_b16_d16_hi v94, v4 offset:10240
	v_cvt_pk_bf16_f32 v2, v2, v2
	ds_write_b16_d16_hi v94, v2 offset:18944
	s_and_saveexec_b64 s[30:31], s[6:7]
	s_xor_b64 s[30:31], exec, s[30:31]
	s_cbranch_execz .LBB0_469
	v_sub_f32_e32 v0, v7, v3
	v_mul_f32_e32 v0, 0x3fb8aa3b, v0
	v_exp_f32_e32 v0, v0
	s_nop 0
	v_mul_f32_e32 v0, v1, v0
	v_bfe_u32 v1, v0, 16, 1
	v_add3_u32 v0, v0, v1, s48
	ds_write_b16_d16_hi v94, v0 offset:32000
.LBB0_469:
	s_andn2_saveexec_b64 s[30:31], s[30:31]
	s_cbranch_execz .LBB0_471
	v_sub_f32_e32 v1, v3, v7
	v_mul_f32_e32 v1, 0x3fb8aa3b, v1
	v_exp_f32_e32 v1, v1
	s_nop 0
	v_mul_f32_e32 v0, v0, v1
	v_cvt_pk_bf16_f32 v0, v0, v0
	ds_write_b16_d16_hi v95, v0 offset:23296

.LBB0_503:
	s_or_b64 exec, exec, s[12:13]
	s_or_b32 s12, s30, s49
	s_mul_hi_u32 s13, s12, 0x41
	s_add_i32 s13, s13, s31
	s_mulk_i32 s12, 0x41
	s_add_u32 s12, s12, s33
	s_addc_u32 s13, s13, s38
	s_or_b32 s14, s60, s28
	s_waitcnt vmcnt(0)
	v_or_b32_e32 v41, v5, v4
	s_lshl_b64 s[12:13], s[12:13], 13
	v_add_u32_e32 v6, s14, v70
	v_mov_b64_e32 v[4:5], s[82:83]
	v_or_b32_e32 v39, v1, v0
	v_lshl_add_u64 v[0:1], v[16:17], 0, s[12:13]
	v_mad_i64_i32 v[4:5], s[12:13], v6, s79, v[4:5]
	v_mad_u64_u32 v[6:7], s[12:13], v4, s44, v[20:21]
	s_add_i32 s12, s14, s93
	s_mul_hi_i32 s13, s12, 0x41
	s_mulk_i32 s12, 0x41
	s_add_u32 s12, s12, s82
	v_or_b32_e32 v38, v49, v48
	v_or_b32_e32 v40, v3, v2
	s_addc_u32 s13, s13, s83
	global_store_dwordx4 v[0:1], v[38:41], off
	v_add_u32_e32 v0, v99, v18
	s_mulk_i32 s13, 0x3000
	s_mul_hi_u32 s14, s12, 0x3000
	s_waitcnt lgkmcnt(0)
	s_barrier
	ds_read_b128 v[0:3], v0 offset:2048
	s_add_i32 s14, s14, s13
	s_mulk_i32 s12, 0x3000
	s_add_u32 s12, s34, s12
	s_addc_u32 s13, s35, s14
	s_add_u32 s12, s12, 0x2e894000
	v_mad_i32_i24 v7, v5, s44, v7
	s_addc_u32 s13, s13, 0
	s_andn2_b64 vcc, exec, s[58:59]
	s_mov_b64 s[14:15], -1
	s_waitcnt lgkmcnt(0)
	global_store_dwordx4 v[6:7], v[0:3], off
	s_cbranch_vccnz .LBB0_505
	ds_read_b128 v[0:3], v100
	ds_read_b128 v[4:7], v102
	s_mov_b64 s[14:15], 0
	s_waitcnt lgkmcnt(0)
	v_mfma_f32_16x16x32_bf16 v[0:3], v[0:3], v[4:7], 0
	ds_read_b128 v[4:7], v100 offset:64
	ds_read_b128 v[38:41], v102 offset:64
	s_waitcnt lgkmcnt(0)
	v_mfma_f32_16x16x32_bf16 v[0:3], v[4:7], v[38:41], v[0:3]
	v_lshl_add_u64 v[4:5], s[12:13], 0, v[22:23]
	s_nop 6
	v_cndmask_b32_e64 v0, v0, 0, s[80:81]
	s_nop 0
	v_cvt_pk_bf16_f32 v0, v0, v0
	v_lshl_add_u64 v[6:7], v[4:5], 0, v[24:25]
	global_store_short_d16_hi v[6:7], v0, off
	v_cndmask_b32_e64 v0, v1, 0, s[62:63]
	v_bfe_u32 v1, v0, 16, 1
	v_add3_u32 v6, v0, v1, s48
	v_lshl_add_u64 v[0:1], v[4:5], 0, v[26:27]
	global_store_short_d16_hi v[0:1], v6, off
	v_cndmask_b32_e64 v0, v2, 0, s[64:65]
	v_cvt_pk_bf16_f32 v2, v0, v0
	v_lshl_add_u64 v[0:1], v[4:5], 0, v[28:29]
	global_store_short_d16_hi v[0:1], v2, off
	v_cndmask_b32_e64 v0, v3, 0, s[66:67]
	v_bfe_u32 v1, v0, 16, 1
	v_add3_u32 v2, v0, v1, s48
	v_lshl_add_u64 v[0:1], v[4:5], 0, v[30:31]
	global_store_short_d16_hi v[0:1], v2, off

.LBB0_510:
	s_and_b64 vcc, exec, s[12:13]
	s_cbranch_vccz .LBB0_435
	s_movk_i32 s29, 0x810
	v_or_b32_e32 v38, 1, v103
	s_ashr_i32 s33, s76, 2
	v_cmp_gt_i32_e64 s[12:13], s29, v103
	v_cmp_gt_i32_e64 s[16:17], s29, v38
	s_mul_i32 s60, s33, 0x810
	v_cndmask_b32_e64 v0, 0, v103, s[12:13]
	v_cndmask_b32_e64 v38, 0, v38, s[16:17]
	v_add_u32_e32 v0, s60, v0
	v_mov_b64_e32 v[2:3], s[54:55]
	v_add_u32_e32 v47, s60, v38
	v_or_b32_e32 v46, 2, v103
	v_mad_i64_i32 v[4:5], s[14:15], v0, s44, v[2:3]
	v_mad_i64_i32 v[38:39], s[14:15], v47, s44, v[2:3]
	s_and_b32 s28, s76, 3
	v_cmp_gt_i32_e64 s[14:15], s29, v46
	s_lshl_b32 s61, s28, 7
	v_add_lshl_u32 v0, s61, v65, 1
	v_cndmask_b32_e64 v42, 0, v46, s[14:15]
	v_mov_b32_e32 v1, v97
	v_add_u32_e32 v42, s60, v42
	v_lshl_add_u64 v[6:7], v[4:5], 0, v[0:1]
	v_mad_i64_i32 v[42:43], s[18:19], v42, s44, v[2:3]
	v_lshl_add_u64 v[40:41], v[38:39], 0, v[0:1]
	v_lshl_add_u64 v[44:45], v[42:43], 0, v[0:1]
	global_load_ushort v54, v[6:7], off
	global_load_ushort v55, v[40:41], off
	global_load_ushort v56, v[44:45], off
	s_lshl_b32 s38, s28, 9
	v_lshl_add_u64 v[6:7], v[34:35], 0, s[38:39]
	global_load_dword v58, v[6:7], off
	v_or_b32_e32 v40, 3, v103
	v_or_b32_e32 v48, 4, v103
	v_cmp_gt_i32_e64 s[20:21], s29, v40
	s_lshl_b32 s22, s28, 1
	s_lshl_b32 s76, s33, 3
	v_cndmask_b32_e64 v40, 0, v40, s[20:21]
	v_cmp_gt_i32_e64 s[18:19], s29, v48
	s_or_b32 s38, s22, s76
	v_add_u32_e32 v49, s60, v40
	v_cndmask_b32_e64 v41, 0, v48, s[18:19]
	v_add_lshl_u32 v96, s61, v64, 1
	v_add_u32_e32 v44, s60, v41
	v_or_b32_e32 v50, s38, v63
	v_mad_i64_i32 v[40:41], s[22:23], v49, s44, v[2:3]
	v_mad_i64_i32 v[44:45], s[22:23], v44, s44, v[2:3]
	v_lshl_add_u32 v57, v50, 6, v50
	v_lshl_add_u64 v[4:5], v[4:5], 0, v[96:97]
	v_lshl_add_u64 v[50:51], v[40:41], 0, v[96:97]
	v_lshl_add_u64 v[38:39], v[38:39], 0, v[96:97]
	v_lshl_add_u64 v[42:43], v[42:43], 0, v[96:97]
	v_lshl_add_u64 v[40:41], v[40:41], 0, v[0:1]
	v_lshl_add_u64 v[52:53], v[44:45], 0, v[0:1]
	v_add_u32_e32 v59, s82, v57
	global_load_ushort v57, v[50:51], off
	global_load_ushort v60, v[42:43], off
	global_load_ushort v104, v[38:39], off
	global_load_ushort v105, v[4:5], off
	global_load_ushort v61, v[40:41], off
	global_load_ushort v106, v[52:53], off
	v_mov_b64_e32 v[6:7], s[56:57]
	v_mad_i64_i32 v[40:41], s[22:23], v59, s44, v[6:7]
	s_mov_b32 s49, 0x3f317217
	v_mov_b32_e32 v114, 0x41b17218
	s_mov_b32 s78, 0x7f800000
	v_or_b32_e32 v50, 6, v103
	s_waitcnt vmcnt(0)
	v_lshlrev_b32_e32 v4, 16, v54
	v_mul_f32_e32 v4, 0x3fb8aa3b, v4
	v_exp_f32_e32 v4, v4
	v_lshlrev_b32_e32 v5, 16, v55
	v_mul_f32_e32 v5, 0x3fb8aa3b, v5
	v_exp_f32_e32 v5, v5
	v_add_f32_e32 v4, 1.0, v4
	v_rcp_f32_e32 v4, v4
	v_lshlrev_b32_e32 v6, 16, v56
	v_sub_f32_e32 v56, 1.0, v58
	v_add_f32_e32 v5, 1.0, v5
	v_mul_f32_e32 v4, v56, v4
	v_rcp_f32_e32 v5, v5
	v_min_f32_e32 v59, 0x3f7ff972, v4
	v_sub_f32_e32 v4, 1.0, v59
	v_cmp_gt_f32_e32 vcc, s45, v4
	v_mul_f32_e32 v5, v56, v5
	v_min_f32_e32 v107, 0x3f7ff972, v5
	v_cndmask_b32_e64 v7, 0, 32, vcc
	v_ldexp_f32 v4, v4, v7
	v_log_f32_e32 v4, v4
	v_mul_f32_e32 v6, 0x3fb8aa3b, v6
	v_sub_f32_e32 v5, 1.0, v107
	v_exp_f32_e32 v6, v6
	v_cmp_gt_f32_e64 s[22:23], s45, v5
	v_cndmask_b32_e32 v7, 0, v114, vcc
	v_cmp_lt_f32_e64 vcc, |v4|, s78
	v_cndmask_b32_e64 v38, 0, 32, s[22:23]
	v_ldexp_f32 v5, v5, v38
	v_mul_f32_e32 v38, 0x3f317217, v4
	v_fma_f32 v38, v4, s49, -v38
	v_add_f32_e32 v6, 1.0, v6
	v_log_f32_e32 v5, v5
	v_fmac_f32_e32 v38, 0x3377d1cf, v4
	v_rcp_f32_e32 v6, v6
	v_fmac_f32_e32 v38, 0x3f317217, v4
	v_cndmask_b32_e32 v4, v4, v38, vcc
	v_sub_f32_e32 v4, v4, v7
	v_mul_f32_e32 v39, 0x3f317217, v5
	v_add_f32_e32 v4, 0, v4
	v_fma_f32 v39, v5, s49, -v39
	v_cndmask_b32_e64 v108, 0, v4, s[12:13]
	v_mul_f32_e32 v4, v56, v6
	v_fmac_f32_e32 v39, 0x3377d1cf, v5
	v_min_f32_e32 v109, 0x3f7ff972, v4
	v_fmac_f32_e32 v39, 0x3f317217, v5
	v_cmp_lt_f32_e64 vcc, |v5|, s78
	v_sub_f32_e32 v4, 1.0, v109
	s_nop 0
	v_cndmask_b32_e32 v38, v5, v39, vcc
	v_cmp_gt_f32_e32 vcc, s45, v4
	v_cndmask_b32_e64 v39, 0, v114, s[22:23]
	s_nop 0
	v_cndmask_b32_e64 v5, 0, 32, vcc
	v_ldexp_f32 v42, v4, v5
	v_or_b32_e32 v4, 5, v103
	v_cmp_gt_i32_e64 s[22:23], s29, v4
	v_log_f32_e32 v111, v42
	s_nop 0
	v_cndmask_b32_e64 v4, 0, v4, s[22:23]
	v_add_u32_e32 v51, s60, v4
	v_mad_i64_i32 v[4:5], s[24:25], v51, s44, v[2:3]
	v_lshl_add_u64 v[6:7], v[4:5], 0, v[0:1]
	global_load_ushort v110, v[6:7], off
	v_cmp_gt_i32_e64 s[24:25], s29, v50
	v_sub_f32_e32 v6, v38, v39
	v_cndmask_b32_e64 v6, 0, v6, s[16:17]
	v_cndmask_b32_e64 v38, 0, v50, s[24:25]
	v_add_u32_e32 v38, s60, v38
	v_mad_i64_i32 v[38:39], s[26:27], v38, s44, v[2:3]
	v_add_f32_e32 v112, v108, v6
	v_mul_f32_e32 v6, 0x3f317217, v111
	v_lshl_add_u64 v[42:43], v[38:39], 0, v[0:1]
	v_fma_f32 v113, v111, s49, -v6
	v_lshl_add_u64 v[6:7], v[44:45], 0, v[96:97]
	global_load_ushort v45, v[42:43], off
	v_or_b32_e32 v44, 7, v103
	v_cmp_gt_i32_e64 s[26:27], s29, v44
	v_lshl_add_u64 v[4:5], v[4:5], 0, v[96:97]
	v_lshl_add_u64 v[38:39], v[38:39], 0, v[96:97]
	v_cndmask_b32_e64 v42, 0, v44, s[26:27]
	v_add_u32_e32 v52, s60, v42
	v_mad_i64_i32 v[2:3], s[30:31], v52, s44, v[2:3]
	v_lshl_add_u64 v[42:43], v[2:3], 0, v[96:97]
	v_lshl_add_u64 v[0:1], v[2:3], 0, v[0:1]
	global_load_ushort v53, v[42:43], off
	global_load_ushort v54, v[38:39], off
	global_load_ushort v55, v[4:5], off
	global_load_ushort v58, v[6:7], off
	v_lshlrev_b32_e32 v4, 16, v61
	global_load_ushort v0, v[0:1], off
	v_mul_f32_e32 v4, 0x3fb8aa3b, v4
	v_exp_f32_e32 v4, v4
	v_cndmask_b32_e32 v6, 0, v114, vcc
	v_fmac_f32_e32 v113, 0x3377d1cf, v111
	v_fmac_f32_e32 v113, 0x3f317217, v111
	v_add_f32_e32 v4, 1.0, v4
	v_rcp_f32_e32 v4, v4
	v_cmp_lt_f32_e64 s[30:31], |v111|, s78
	v_cndmask_b32_e64 v38, 0, v59, s[12:13]
	v_mul_f32_e32 v2, v56, v4
	v_min_f32_e32 v2, 0x3f7ff972, v2
	v_sub_f32_e32 v3, 1.0, v2
	v_cmp_gt_f32_e32 vcc, s45, v3
	v_cndmask_b32_e64 v5, v111, v113, s[30:31]
	v_sub_f32_e32 v1, v5, v6
	v_cndmask_b32_e64 v4, 0, 32, vcc
	v_ldexp_f32 v3, v3, v4
	v_log_f32_e32 v3, v3
	v_lshlrev_b32_e32 v4, 16, v106
	v_cndmask_b32_e64 v1, 0, v1, s[14:15]
	v_mul_f32_e32 v4, 0x3fb8aa3b, v4
	v_add_f32_e32 v59, v112, v1
	v_mul_f32_e32 v1, 0x3f317217, v3
	v_exp_f32_e32 v4, v4
	v_fma_f32 v1, v3, s49, -v1
	v_fmac_f32_e32 v1, 0x3377d1cf, v3
	v_fmac_f32_e32 v1, 0x3f317217, v3
	v_cmp_lt_f32_e64 s[30:31], |v3|, s78
	v_cndmask_b32_e64 v7, 0, v2, s[20:21]
	s_barrier
	v_cndmask_b32_e64 v1, v3, v1, s[30:31]
	v_add_f32_e32 v3, 1.0, v4
	v_rcp_f32_e32 v3, v3
	v_cndmask_b32_e32 v4, 0, v114, vcc
	v_sub_f32_e32 v1, v1, v4
	v_cndmask_b32_e64 v1, 0, v1, s[20:21]
	v_mul_f32_e32 v3, v56, v3
	v_min_f32_e32 v4, 0x3f7ff972, v3
	v_sub_f32_e32 v3, 1.0, v4
	v_cmp_gt_f32_e32 vcc, s45, v3
	v_add_f32_e32 v61, v59, v1
	s_nop 0
	v_cndmask_b32_e64 v5, 0, 32, vcc
	v_ldexp_f32 v3, v3, v5
	v_log_f32_e32 v3, v3
	v_cndmask_b32_e64 v39, 0, v109, s[14:15]
	v_cndmask_b32_e64 v6, 0, v107, s[16:17]
	v_cndmask_b32_e64 v4, 0, v4, s[18:19]
	v_mul_f32_e32 v1, 0x3f317217, v3
	v_fma_f32 v1, v3, s49, -v1
	v_fmac_f32_e32 v1, 0x3377d1cf, v3
	v_fmac_f32_e32 v1, 0x3f317217, v3
	s_waitcnt vmcnt(6)
	v_lshlrev_b32_e32 v2, 16, v110
	v_mul_f32_e32 v2, 0x3fb8aa3b, v2
	v_exp_f32_e32 v2, v2
	v_cmp_lt_f32_e64 s[30:31], |v3|, s78
	v_add_f32_e32 v2, 1.0, v2
	v_rcp_f32_e32 v2, v2
	v_cndmask_b32_e64 v1, v3, v1, s[30:31]
	v_cndmask_b32_e32 v3, 0, v114, vcc
	v_sub_f32_e32 v1, v1, v3
	v_mul_f32_e32 v2, v56, v2
	v_min_f32_e32 v42, 0x3f7ff972, v2
	v_sub_f32_e32 v2, 1.0, v42
	v_cmp_gt_f32_e32 vcc, s45, v2
	v_cndmask_b32_e64 v1, 0, v1, s[18:19]
	s_waitcnt vmcnt(0)
	v_lshlrev_b32_e32 v0, 16, v0
	v_cndmask_b32_e64 v3, 0, 32, vcc
	v_ldexp_f32 v2, v2, v3
	v_lshlrev_b32_e32 v3, 16, v45
	v_mul_f32_e32 v3, 0x3fb8aa3b, v3
	v_exp_f32_e32 v3, v3
	v_log_f32_e32 v2, v2
	v_mul_f32_e32 v0, 0x3fb8aa3b, v0
	v_exp_f32_e32 v0, v0
	v_add_f32_e32 v3, 1.0, v3
	v_rcp_f32_e32 v3, v3
	v_mul_f32_e32 v5, 0x3f317217, v2
	v_fma_f32 v5, v2, s49, -v5
	v_fmac_f32_e32 v5, 0x3377d1cf, v2
	v_mul_f32_e32 v3, v56, v3
	v_fmac_f32_e32 v5, 0x3f317217, v2
	v_cmp_lt_f32_e64 s[30:31], |v2|, s78
	v_min_f32_e32 v3, 0x3f7ff972, v3
	v_add_f32_e32 v0, 1.0, v0
	v_cndmask_b32_e64 v2, v2, v5, s[30:31]
	v_sub_f32_e32 v5, 1.0, v3
	v_cmp_gt_f32_e64 s[30:31], s45, v5
	v_rcp_f32_e32 v0, v0
	s_nop 0
	v_cndmask_b32_e64 v43, 0, 32, s[30:31]
	v_ldexp_f32 v5, v5, v43
	v_log_f32_e32 v5, v5
	v_cndmask_b32_e32 v43, 0, v114, vcc
	v_sub_f32_e32 v2, v2, v43
	v_mul_f32_e32 v0, v56, v0
	v_mul_f32_e32 v43, 0x3f317217, v5
	v_fma_f32 v43, v5, s49, -v43
	v_fmac_f32_e32 v43, 0x3377d1cf, v5
	v_min_f32_e32 v0, 0x3f7ff972, v0
	v_fmac_f32_e32 v43, 0x3f317217, v5
	v_cmp_lt_f32_e64 vcc, |v5|, s78
	v_sub_f32_e32 v44, 1.0, v0
	v_cndmask_b32_e64 v2, 0, v2, s[22:23]
	v_cndmask_b32_e32 v5, v5, v43, vcc
	v_cmp_gt_f32_e32 vcc, s45, v44
	v_cndmask_b32_e64 v43, 0, v114, s[30:31]
	v_sub_f32_e32 v5, v5, v43
	v_cndmask_b32_e64 v45, 0, 32, vcc
	v_ldexp_f32 v44, v44, v45
	v_log_f32_e32 v44, v44
	v_cndmask_b32_e64 v43, 0, v5, s[24:25]
	v_cndmask_b32_e64 v5, 0, v3, s[24:25]
	v_add_f32_e32 v56, v61, v1
	v_mul_f32_e32 v3, 0x3f317217, v44
	v_fma_f32 v3, v44, s49, -v3
	v_fmac_f32_e32 v3, 0x3377d1cf, v44
	v_fmac_f32_e32 v3, 0x3f317217, v44
	v_cmp_lt_f32_e64 s[30:31], |v44|, s78
	v_cndmask_b32_e64 v1, 0, v0, s[26:27]
	v_cndmask_b32_e64 v0, 0, v42, s[22:23]
	v_cndmask_b32_e64 v3, v44, v3, s[30:31]
	v_cndmask_b32_e32 v44, 0, v114, vcc
	v_sub_f32_e32 v3, v3, v44
	v_add_f32_e32 v114, v56, v2
	v_cndmask_b32_e64 v3, 0, v3, s[26:27]
	v_add_f32_e32 v115, v114, v43
	v_add_f32_e32 v43, v115, v3
	ds_write_b32 v68, v43
	s_waitcnt lgkmcnt(0)
	s_barrier
	ds_read2st64_b32 v[44:45], v69 offset1:2
	ds_read2st64_b32 v[2:3], v69 offset0:4 offset1:6
	s_waitcnt lgkmcnt(1)
	v_add_f32_e32 v45, v44, v45
	s_waitcnt lgkmcnt(0)
	v_add_f32_e32 v42, v45, v2
	v_cndmask_b32_e64 v2, v42, v45, s[4:5]
	v_cndmask_b32_e64 v2, v2, v44, s[2:3]
	v_cndmask_b32_e64 v109, v2, 0, s[0:1]
	v_add_f32_e32 v107, v108, v109
	v_mov_b32_e32 v108, v3
	v_pk_add_f32 v[2:3], v[42:43], v[108:109]
	v_add_f32_e32 v106, v112, v109
	v_sub_f32_e32 v43, v2, v107
	v_mul_f32_e32 v43, 0x3fb8aa3b, v43
	v_exp_f32_e32 v110, v43
	v_sub_f32_e32 v43, v2, v106
	v_mul_f32_e32 v43, 0x3fb8aa3b, v43
	v_add_f32_e32 v96, v59, v109
	v_exp_f32_e32 v112, v43
	v_sub_f32_e32 v43, v2, v96
	v_add_f32_e32 v61, v61, v109
	v_mul_f32_e32 v43, 0x3fb8aa3b, v43
	v_exp_f32_e32 v111, v43
	v_sub_f32_e32 v43, v2, v61
	v_mul_f32_e32 v43, 0x3fb8aa3b, v43
	v_add_f32_e32 v59, v56, v109
	v_exp_f32_e32 v113, v43
	v_sub_f32_e32 v43, v2, v59
	v_add_f32_e32 v56, v114, v109
	v_mul_f32_e32 v43, 0x3fb8aa3b, v43
	v_exp_f32_e32 v108, v43
	v_sub_f32_e32 v43, v2, v56
	v_mul_f32_e32 v43, 0x3fb8aa3b, v43
	v_exp_f32_e32 v114, v43
	v_add_f32_e32 v43, v115, v109
	v_sub_f32_e32 v115, v2, v3
	v_sub_f32_e32 v109, v2, v43
	v_mul_f32_e32 v115, 0x3fb8aa3b, v115
	v_mul_f32_e32 v109, 0x3fb8aa3b, v109
	v_exp_f32_e32 v115, v115
	v_exp_f32_e32 v109, v109
	v_pk_mul_f32 v[112:113], v[6:7], v[112:113]
	v_pk_mul_f32 v[110:111], v[38:39], v[110:111]
	v_pk_mul_f32 v[114:115], v[0:1], v[114:115]
	v_pk_mul_f32 v[108:109], v[4:5], v[108:109]
	v_cvt_pk_bf16_f32 v114, v114, v114
	v_cvt_pk_bf16_f32 v115, v115, v115
	v_cvt_pk_bf16_f32 v112, v112, v112
	v_cvt_pk_bf16_f32 v113, v113, v113
	v_cvt_pk_bf16_f32 v109, v109, v109
	v_cvt_pk_bf16_f32 v108, v108, v108
	v_cvt_pk_bf16_f32 v111, v111, v111
	v_cvt_pk_bf16_f32 v110, v110, v110
	v_lshrrev_b32_e32 v108, 16, v108
	v_lshrrev_b32_e32 v109, 16, v109
	v_lshrrev_b32_e32 v116, 16, v110
	v_lshrrev_b32_e32 v117, 16, v111
	v_and_or_b32 v111, v115, s36, v109
	v_and_or_b32 v110, v114, s36, v108
	v_and_or_b32 v109, v113, s36, v117
	v_and_or_b32 v108, v112, s36, v116
	v_lshl_add_u64 v[112:113], v[40:41], 0, v[14:15]
	v_add_co_u32_e32 v112, vcc, 0x1000, v112
	s_nop 1
	v_addc_co_u32_e32 v113, vcc, 0, v113, vcc
	global_store_dwordx4 v[112:113], v[108:111], off
	s_and_saveexec_b64 s[30:31], s[8:9]
	s_cbranch_execz .LBB0_513
	v_mul_f32_e32 v2, 0x3fb8aa3b, v2
	v_exp_f32_e32 v2, v2
	v_lshl_add_u64 v[40:41], v[40:41], 0, v[36:37]
	v_add_co_u32_e32 v40, vcc, 0x2000, v40
	s_nop 1
	v_addc_co_u32_e32 v41, vcc, 0, v41, vcc
	global_store_dword v[40:41], v2, off offset:2048
.LBB0_513:
	s_or_b64 exec, exec, s[30:31]
	v_lshlrev_b32_e32 v2, 16, v105
	v_mul_f32_e32 v40, 0xbfb8aa3b, v2
	v_exp_f32_e32 v40, v40
	v_mul_f32_e32 v41, 0x3fb8aa3b, v107
	v_exp_f32_e32 v41, v41
	v_add_f32_e32 v40, 1.0, v40
	v_rcp_f32_e32 v40, v40
	s_nop 0
	v_mul_f32_e32 v2, v40, v2
	v_cndmask_b32_e64 v40, 0, v2, s[12:13]
	v_mul_f32_e32 v41, v40, v41
	v_cndmask_b32_e64 v2, v42, v44, s[6:7]
	v_cvt_pk_bf16_f32 v41, v41, v41
	v_add_u32_e32 v42, v71, v72
	ds_write_b16_d16_hi v42, v41 offset:2048
	v_sub_f32_e32 v41, v107, v2
	v_mul_f32_e32 v41, 0x3fb8aa3b, v41
	v_exp_f32_e32 v41, v41
	s_nop 0
	v_mul_f32_e32 v41, v40, v41
	v_cvt_pk_bf16_f32 v41, v41, v41
	ds_write_b16_d16_hi v73, v41 offset:10240
	v_sub_f32_e32 v41, v2, v107
	v_mul_f32_e32 v41, 0x3fb8aa3b, v41
	v_exp_f32_e32 v41, v41
	s_nop 0
	v_mul_f32_e32 v41, v38, v41
	v_cvt_pk_bf16_f32 v41, v41, v41
	ds_write_b16_d16_hi v73, v41 offset:18944
	s_and_saveexec_b64 s[30:31], s[6:7]
	s_xor_b64 s[30:31], exec, s[30:31]
	s_cbranch_execz .LBB0_515
	v_sub_f32_e32 v40, v45, v107
	v_mul_f32_e32 v40, 0x3fb8aa3b, v40
	v_exp_f32_e32 v40, v40
	s_nop 0
	v_mul_f32_e32 v38, v38, v40
	v_cvt_pk_bf16_f32 v38, v38, v38
	ds_write_b16_d16_hi v73, v38 offset:32000
.LBB0_515:
	s_andn2_saveexec_b64 s[30:31], s[30:31]
	s_cbranch_execz .LBB0_517
	v_sub_f32_e32 v38, v107, v45
	v_mul_f32_e32 v38, 0x3fb8aa3b, v38
	v_exp_f32_e32 v38, v38
	s_nop 0
	v_mul_f32_e32 v38, v40, v38
	v_cvt_pk_bf16_f32 v38, v38, v38
	ds_write_b16_d16_hi v74, v38 offset:23296
.LBB0_517:
	s_or_b64 exec, exec, s[30:31]
	v_lshlrev_b32_e32 v38, 16, v104
	v_mul_f32_e32 v40, 0xbfb8aa3b, v38
	v_exp_f32_e32 v40, v40
	s_nop 0
	v_add_f32_e32 v40, 1.0, v40
	v_rcp_f32_e32 v40, v40
	s_nop 0
	v_mul_f32_e32 v38, v40, v38
	v_mul_f32_e32 v40, 0x3fb8aa3b, v106
	v_exp_f32_e32 v40, v40
	v_cndmask_b32_e64 v38, 0, v38, s[16:17]
	v_mul_f32_e32 v40, v38, v40
	v_cvt_pk_bf16_f32 v40, v40, v40
	v_add_u32_e32 v41, v71, v75
	ds_write_b16_d16_hi v41, v40 offset:2048
	v_sub_f32_e32 v40, v106, v2
	v_mul_f32_e32 v40, 0x3fb8aa3b, v40
	v_exp_f32_e32 v40, v40
	s_nop 0
	v_mul_f32_e32 v40, v38, v40
	v_cvt_pk_bf16_f32 v40, v40, v40
	ds_write_b16_d16_hi v76, v40 offset:10240
	v_sub_f32_e32 v40, v2, v106
	v_mul_f32_e32 v40, 0x3fb8aa3b, v40
	v_exp_f32_e32 v40, v40
	s_nop 0
	v_mul_f32_e32 v40, v6, v40
	v_cvt_pk_bf16_f32 v40, v40, v40
	ds_write_b16_d16_hi v76, v40 offset:18944
	s_and_saveexec_b64 s[30:31], s[6:7]
	s_xor_b64 s[30:31], exec, s[30:31]
	s_cbranch_execz .LBB0_519
	v_sub_f32_e32 v38, v45, v106
	v_mul_f32_e32 v38, 0x3fb8aa3b, v38
	v_exp_f32_e32 v38, v38
	s_nop 0
	v_mul_f32_e32 v6, v6, v38
	v_cvt_pk_bf16_f32 v6, v6, v6
	ds_write_b16_d16_hi v76, v6 offset:32000
.LBB0_519:
	s_andn2_saveexec_b64 s[30:31], s[30:31]
	s_cbranch_execz .LBB0_521
	v_sub_f32_e32 v6, v106, v45
	v_mul_f32_e32 v6, 0x3fb8aa3b, v6
	v_exp_f32_e32 v6, v6
	s_nop 0
	v_mul_f32_e32 v6, v38, v6
	v_cvt_pk_bf16_f32 v6, v6, v6
	ds_write_b16_d16_hi v77, v6 offset:23296
.LBB0_521:
	s_or_b64 exec, exec, s[30:31]
	v_lshlrev_b32_e32 v6, 16, v60
	v_mul_f32_e32 v38, 0xbfb8aa3b, v6
	v_exp_f32_e32 v38, v38
	s_nop 0
	v_add_f32_e32 v38, 1.0, v38
	v_rcp_f32_e32 v38, v38
	s_nop 0
	v_mul_f32_e32 v6, v38, v6
	v_mul_f32_e32 v38, 0x3fb8aa3b, v96
	v_exp_f32_e32 v38, v38
	v_cndmask_b32_e64 v6, 0, v6, s[14:15]
	v_mul_f32_e32 v38, v6, v38
	v_cvt_pk_bf16_f32 v38, v38, v38
	v_add_u32_e32 v40, v71, v78
	ds_write_b16_d16_hi v40, v38 offset:2048
	v_sub_f32_e32 v38, v96, v2
	v_mul_f32_e32 v38, 0x3fb8aa3b, v38
	v_exp_f32_e32 v38, v38
	s_nop 0
	v_mul_f32_e32 v38, v6, v38
	v_cvt_pk_bf16_f32 v38, v38, v38
	ds_write_b16_d16_hi v79, v38 offset:10240
	v_sub_f32_e32 v38, v2, v96
	v_mul_f32_e32 v38, 0x3fb8aa3b, v38
	v_exp_f32_e32 v38, v38
	s_nop 0
	v_mul_f32_e32 v38, v39, v38
	v_cvt_pk_bf16_f32 v38, v38, v38
	ds_write_b16_d16_hi v79, v38 offset:18944
	s_and_saveexec_b64 s[30:31], s[6:7]
	s_xor_b64 s[30:31], exec, s[30:31]
	s_cbranch_execz .LBB0_523
	v_sub_f32_e32 v6, v45, v96
	v_mul_f32_e32 v6, 0x3fb8aa3b, v6
	v_exp_f32_e32 v6, v6
	s_nop 0
	v_mul_f32_e32 v6, v39, v6
	v_bfe_u32 v38, v6, 16, 1
	v_add3_u32 v6, v6, v38, s48
	ds_write_b16_d16_hi v79, v6 offset:32000
.LBB0_523:
	s_andn2_saveexec_b64 s[30:31], s[30:31]
	s_cbranch_execz .LBB0_525
	v_sub_f32_e32 v38, v96, v45
	v_mul_f32_e32 v38, 0x3fb8aa3b, v38
	v_exp_f32_e32 v38, v38
	s_nop 0
	v_mul_f32_e32 v6, v6, v38
	v_cvt_pk_bf16_f32 v6, v6, v6
	ds_write_b16_d16_hi v80, v6 offset:23296
.LBB0_525:
	s_or_b64 exec, exec, s[30:31]
	v_lshlrev_b32_e32 v6, 16, v57
	v_mul_f32_e32 v38, 0xbfb8aa3b, v6
	v_exp_f32_e32 v38, v38
	s_nop 0
	v_add_f32_e32 v38, 1.0, v38
	v_rcp_f32_e32 v38, v38
	s_nop 0
	v_mul_f32_e32 v6, v38, v6
	v_mul_f32_e32 v38, 0x3fb8aa3b, v61
	v_exp_f32_e32 v38, v38
	v_cndmask_b32_e64 v6, 0, v6, s[20:21]
	v_mul_f32_e32 v38, v6, v38
	v_cvt_pk_bf16_f32 v38, v38, v38
	v_add_u32_e32 v39, v71, v81
	ds_write_b16_d16_hi v39, v38 offset:2048
	v_sub_f32_e32 v38, v61, v2
	v_mul_f32_e32 v38, 0x3fb8aa3b, v38
	v_exp_f32_e32 v38, v38
	s_nop 0
	v_mul_f32_e32 v38, v6, v38
	v_cvt_pk_bf16_f32 v38, v38, v38
	ds_write_b16_d16_hi v82, v38 offset:10240
	v_sub_f32_e32 v38, v2, v61
	v_mul_f32_e32 v38, 0x3fb8aa3b, v38
	v_exp_f32_e32 v38, v38
	s_nop 0
	v_mul_f32_e32 v38, v7, v38
	v_cvt_pk_bf16_f32 v38, v38, v38
	ds_write_b16_d16_hi v82, v38 offset:18944
	s_and_saveexec_b64 s[30:31], s[6:7]
	s_xor_b64 s[30:31], exec, s[30:31]
	s_cbranch_execz .LBB0_527
	v_sub_f32_e32 v6, v45, v61
	v_mul_f32_e32 v6, 0x3fb8aa3b, v6
	v_exp_f32_e32 v6, v6
	s_nop 0
	v_mul_f32_e32 v6, v7, v6
	v_bfe_u32 v7, v6, 16, 1
	v_add3_u32 v6, v6, v7, s48
	ds_write_b16_d16_hi v82, v6 offset:32000
.LBB0_527:
	s_andn2_saveexec_b64 s[30:31], s[30:31]
	s_cbranch_execz .LBB0_529
	v_sub_f32_e32 v7, v61, v45
	v_mul_f32_e32 v7, 0x3fb8aa3b, v7
	v_exp_f32_e32 v7, v7
	s_nop 0
	v_mul_f32_e32 v6, v6, v7
	v_cvt_pk_bf16_f32 v6, v6, v6
	ds_write_b16_d16_hi v83, v6 offset:23296
.LBB0_529:
	s_or_b64 exec, exec, s[30:31]
	v_lshlrev_b32_e32 v6, 16, v58
	v_mul_f32_e32 v7, 0xbfb8aa3b, v6
	v_exp_f32_e32 v7, v7
	s_nop 0
	v_add_f32_e32 v7, 1.0, v7
	v_rcp_f32_e32 v7, v7
	s_nop 0
	v_mul_f32_e32 v6, v7, v6
	v_mul_f32_e32 v7, 0x3fb8aa3b, v59
	v_exp_f32_e32 v7, v7
	v_cndmask_b32_e64 v6, 0, v6, s[18:19]
	v_mul_f32_e32 v7, v6, v7
	v_cvt_pk_bf16_f32 v7, v7, v7
	v_add_u32_e32 v38, v71, v84
	ds_write_b16_d16_hi v38, v7 offset:2048
	v_sub_f32_e32 v7, v59, v2
	v_mul_f32_e32 v7, 0x3fb8aa3b, v7
	v_exp_f32_e32 v7, v7
	s_nop 0
	v_mul_f32_e32 v7, v6, v7
	v_cvt_pk_bf16_f32 v7, v7, v7
	ds_write_b16_d16_hi v85, v7 offset:10240
	v_sub_f32_e32 v7, v2, v59
	v_mul_f32_e32 v7, 0x3fb8aa3b, v7
	v_exp_f32_e32 v7, v7
	s_nop 0
	v_mul_f32_e32 v7, v4, v7
	v_cvt_pk_bf16_f32 v7, v7, v7
	ds_write_b16_d16_hi v85, v7 offset:18944
	s_and_saveexec_b64 s[30:31], s[6:7]
	s_xor_b64 s[30:31], exec, s[30:31]
	s_cbranch_execz .LBB0_531
	v_sub_f32_e32 v6, v45, v59
	v_mul_f32_e32 v6, 0x3fb8aa3b, v6
	v_exp_f32_e32 v6, v6
	s_nop 0
	v_mul_f32_e32 v4, v4, v6
	v_cvt_pk_bf16_f32 v4, v4, v4
	ds_write_b16_d16_hi v85, v4 offset:32000
.LBB0_531:
	s_andn2_saveexec_b64 s[30:31], s[30:31]
	s_cbranch_execz .LBB0_533
	v_sub_f32_e32 v4, v59, v45
	v_mul_f32_e32 v4, 0x3fb8aa3b, v4
	v_exp_f32_e32 v4, v4
	s_nop 0
	v_mul_f32_e32 v4, v6, v4
	v_cvt_pk_bf16_f32 v4, v4, v4
	ds_write_b16_d16_hi v86, v4 offset:23296
.LBB0_533:
	s_or_b64 exec, exec, s[30:31]
	v_lshlrev_b32_e32 v4, 16, v55
	v_mul_f32_e32 v6, 0xbfb8aa3b, v4
	v_exp_f32_e32 v6, v6
	s_nop 0
	v_add_f32_e32 v6, 1.0, v6
	v_rcp_f32_e32 v6, v6
	s_nop 0
	v_mul_f32_e32 v4, v6, v4
	v_mul_f32_e32 v6, 0x3fb8aa3b, v56
	v_exp_f32_e32 v6, v6
	v_cndmask_b32_e64 v4, 0, v4, s[22:23]
	v_mul_f32_e32 v6, v4, v6
	v_cvt_pk_bf16_f32 v6, v6, v6
	v_add_u32_e32 v7, v71, v87
	ds_write_b16_d16_hi v7, v6 offset:2048
	v_sub_f32_e32 v6, v56, v2
	v_mul_f32_e32 v6, 0x3fb8aa3b, v6
	v_exp_f32_e32 v6, v6
	s_nop 0
	v_mul_f32_e32 v6, v4, v6
	v_cvt_pk_bf16_f32 v6, v6, v6
	ds_write_b16_d16_hi v88, v6 offset:10240
	v_sub_f32_e32 v6, v2, v56
	v_mul_f32_e32 v6, 0x3fb8aa3b, v6
	v_exp_f32_e32 v6, v6
	s_nop 0
	v_mul_f32_e32 v6, v0, v6
	v_cvt_pk_bf16_f32 v6, v6, v6
	ds_write_b16_d16_hi v88, v6 offset:18944
	s_and_saveexec_b64 s[30:31], s[6:7]
	s_xor_b64 s[30:31], exec, s[30:31]
	s_cbranch_execz .LBB0_535
	v_sub_f32_e32 v4, v45, v56
	v_mul_f32_e32 v4, 0x3fb8aa3b, v4
	v_exp_f32_e32 v4, v4
	s_nop 0
	v_mul_f32_e32 v0, v0, v4
	v_cvt_pk_bf16_f32 v0, v0, v0
	ds_write_b16_d16_hi v88, v0 offset:32000
.LBB0_535:
	s_andn2_saveexec_b64 s[30:31], s[30:31]
	s_cbranch_execz .LBB0_537
	v_sub_f32_e32 v0, v56, v45
	v_mul_f32_e32 v0, 0x3fb8aa3b, v0
	v_exp_f32_e32 v0, v0
	s_nop 0
	v_mul_f32_e32 v0, v4, v0
	v_cvt_pk_bf16_f32 v0, v0, v0
	ds_write_b16_d16_hi v89, v0 offset:23296
.LBB0_537:
	s_or_b64 exec, exec, s[30:31]
	v_lshlrev_b32_e32 v0, 16, v54
	v_mul_f32_e32 v4, 0xbfb8aa3b, v0
	v_exp_f32_e32 v4, v4
	s_nop 0
	v_add_f32_e32 v4, 1.0, v4
	v_rcp_f32_e32 v4, v4
	s_nop 0
	v_mul_f32_e32 v0, v4, v0
	v_mul_f32_e32 v4, 0x3fb8aa3b, v43
	v_exp_f32_e32 v4, v4
	v_cndmask_b32_e64 v0, 0, v0, s[24:25]
	v_mul_f32_e32 v4, v0, v4
	v_cvt_pk_bf16_f32 v4, v4, v4
	v_add_u32_e32 v6, v71, v90
	ds_write_b16_d16_hi v6, v4 offset:2048
	v_sub_f32_e32 v4, v43, v2
	v_mul_f32_e32 v4, 0x3fb8aa3b, v4
	v_exp_f32_e32 v4, v4
	s_nop 0
	v_mul_f32_e32 v4, v0, v4
	v_cvt_pk_bf16_f32 v4, v4, v4
	ds_write_b16_d16_hi v91, v4 offset:10240
	v_sub_f32_e32 v4, v2, v43
	v_mul_f32_e32 v4, 0x3fb8aa3b, v4
	v_exp_f32_e32 v4, v4
	s_nop 0
	v_mul_f32_e32 v4, v5, v4
	v_cvt_pk_bf16_f32 v4, v4, v4
	ds_write_b16_d16_hi v91, v4 offset:18944
	s_and_saveexec_b64 s[30:31], s[6:7]
	s_xor_b64 s[30:31], exec, s[30:31]
	s_cbranch_execz .LBB0_539
	v_sub_f32_e32 v0, v45, v43
	v_mul_f32_e32 v0, 0x3fb8aa3b, v0
	v_exp_f32_e32 v0, v0
	s_nop 0
	v_mul_f32_e32 v0, v5, v0
	v_bfe_u32 v4, v0, 16, 1
	v_add3_u32 v0, v0, v4, s48
	ds_write_b16_d16_hi v91, v0 offset:32000
.LBB0_539:
	s_andn2_saveexec_b64 s[30:31], s[30:31]
	s_cbranch_execz .LBB0_541
	v_sub_f32_e32 v4, v43, v45
	v_mul_f32_e32 v4, 0x3fb8aa3b, v4
	v_exp_f32_e32 v4, v4
	s_nop 0
	v_mul_f32_e32 v0, v0, v4
	v_cvt_pk_bf16_f32 v0, v0, v0
	ds_write_b16_d16_hi v92, v0 offset:23296
.LBB0_541:
	s_or_b64 exec, exec, s[30:31]
	v_lshlrev_b32_e32 v0, 16, v53
	v_mul_f32_e32 v4, 0xbfb8aa3b, v0
	v_exp_f32_e32 v4, v4
	s_nop 0
	v_add_f32_e32 v4, 1.0, v4
	v_rcp_f32_e32 v4, v4
	s_nop 0
	v_mul_f32_e32 v0, v4, v0
	v_mul_f32_e32 v4, 0x3fb8aa3b, v3
	v_exp_f32_e32 v4, v4
	v_cndmask_b32_e64 v0, 0, v0, s[26:27]
	v_mul_f32_e32 v4, v0, v4
	v_cvt_pk_bf16_f32 v4, v4, v4
	v_add_u32_e32 v5, v71, v93
	ds_write_b16_d16_hi v5, v4 offset:2048
	v_sub_f32_e32 v4, v3, v2
	v_mul_f32_e32 v4, 0x3fb8aa3b, v4
	v_exp_f32_e32 v4, v4
	v_sub_f32_e32 v2, v2, v3
	v_mul_f32_e32 v2, 0x3fb8aa3b, v2
	v_exp_f32_e32 v2, v2
	v_mul_f32_e32 v4, v0, v4
	v_cvt_pk_bf16_f32 v4, v4, v4
	v_mul_f32_e32 v2, v1, v2
	ds_write_b16_d16_hi v94, v4 offset:10240
	v_cvt_pk_bf16_f32 v2, v2, v2
	ds_write_b16_d16_hi v94, v2 offset:18944
	s_and_saveexec_b64 s[30:31], s[6:7]
	s_xor_b64 s[30:31], exec, s[30:31]
	s_cbranch_execz .LBB0_543
	v_sub_f32_e32 v0, v45, v3
	v_mul_f32_e32 v0, 0x3fb8aa3b, v0
	v_exp_f32_e32 v0, v0
	s_nop 0
	v_mul_f32_e32 v0, v1, v0
	v_bfe_u32 v1, v0, 16, 1
	v_add3_u32 v0, v0, v1, s48
	ds_write_b16_d16_hi v94, v0 offset:32000
.LBB0_543:
	s_andn2_saveexec_b64 s[30:31], s[30:31]
	s_cbranch_execz .LBB0_545
	v_sub_f32_e32 v1, v3, v45
	v_mul_f32_e32 v1, 0x3fb8aa3b, v1
	v_exp_f32_e32 v1, v1
	s_nop 0
	v_mul_f32_e32 v0, v0, v1
	v_cvt_pk_bf16_f32 v0, v0, v0
	ds_write_b16_d16_hi v95, v0 offset:23296

.LBB0_561:
	s_or_b64 exec, exec, s[12:13]
	s_ashr_i32 s12, s33, 31
	s_or_b32 s13, s76, s28
	s_mul_hi_u32 s14, s13, 0x41
	s_mulk_i32 s12, 0x41
	s_ashr_i32 s83, s82, 31
	s_add_i32 s14, s14, s12
	s_mulk_i32 s13, 0x41
	s_add_u32 s12, s13, s82
	s_addc_u32 s13, s14, s83
	s_lshl_b64 s[12:13], s[12:13], 13
	s_waitcnt vmcnt(0)
	v_or_b32_e32 v0, v3, v2
	v_or_b32_e32 v1, v5, v4
	v_or_b32_e32 v2, v7, v6
	v_or_b32_e32 v3, v39, v38
	v_lshl_add_u64 v[4:5], v[16:17], 0, s[12:13]
	global_store_dwordx4 v[4:5], v[0:3], off
	v_add_u32_e32 v4, s38, v70
	s_waitcnt lgkmcnt(0)
	v_add_u32_e32 v0, v99, v18
	s_barrier
	ds_read_b128 v[0:3], v0 offset:2048
	v_lshl_add_u32 v4, v4, 6, v4
	v_ashrrev_i32_e32 v5, 31, v4
	v_lshl_add_u64 v[4:5], v[4:5], 0, s[82:83]
	v_mad_u64_u32 v[6:7], s[12:13], v4, s44, v[20:21]
	v_mad_i32_i24 v7, v5, s44, v7
	s_andn2_b64 vcc, exec, s[70:71]
	s_waitcnt lgkmcnt(0)
	global_store_dwordx4 v[6:7], v[0:3], off
	s_cbranch_vccnz .LBB0_435
	s_mul_i32 s12, s38, 0x41
	s_add_i32 s12, s12, s82
	s_mul_hi_i32 s13, s12, 0x3000
	s_mulk_i32 s12, 0x3000
	s_add_u32 s12, s34, s12
	s_addc_u32 s13, s35, s13
	s_add_u32 s12, s12, 0x2e894000
	s_addc_u32 s13, s13, 0
	s_andn2_b64 vcc, exec, s[58:59]
	s_mov_b64 s[14:15], -1
	s_cbranch_vccnz .LBB0_564
	ds_read_b128 v[0:3], v19
	ds_read_b128 v[4:7], v101
	s_mov_b64 s[14:15], 0
	s_waitcnt lgkmcnt(0)
	v_mfma_f32_16x16x32_bf16 v[0:3], v[0:3], v[4:7], 0
	ds_read_b128 v[4:7], v19 offset:64
	ds_read_b128 v[38:41], v101 offset:64
	s_waitcnt lgkmcnt(0)
	v_mfma_f32_16x16x32_bf16 v[0:3], v[4:7], v[38:41], v[0:3]
	ds_read_b128 v[4:7], v19 offset:128
	ds_read_b128 v[38:41], v101 offset:128
	s_waitcnt lgkmcnt(0)
	v_mfma_f32_16x16x32_bf16 v[0:3], v[4:7], v[38:41], v[0:3]
	ds_read_b128 v[4:7], v19 offset:192
	ds_read_b128 v[38:41], v101 offset:192
	s_waitcnt lgkmcnt(0)
	v_mfma_f32_16x16x32_bf16 v[0:3], v[4:7], v[38:41], v[0:3]
	v_lshl_add_u64 v[4:5], s[12:13], 0, v[22:23]
	s_nop 6
	v_cndmask_b32_e64 v0, v0, 0, s[80:81]
	s_nop 0
	v_cvt_pk_bf16_f32 v0, v0, v0
	v_lshl_add_u64 v[6:7], v[4:5], 0, v[24:25]
	global_store_short_d16_hi v[6:7], v0, off
	v_cndmask_b32_e64 v0, v1, 0, s[62:63]
	v_bfe_u32 v1, v0, 16, 1
	v_add3_u32 v6, v0, v1, s48
	v_lshl_add_u64 v[0:1], v[4:5], 0, v[26:27]
	global_store_short_d16_hi v[0:1], v6, off
	v_cndmask_b32_e64 v0, v2, 0, s[64:65]
	v_cvt_pk_bf16_f32 v2, v0, v0
	v_lshl_add_u64 v[0:1], v[4:5], 0, v[28:29]
	global_store_short_d16_hi v[0:1], v2, off
	v_cndmask_b32_e64 v0, v3, 0, s[66:67]
	v_bfe_u32 v1, v0, 16, 1
	v_add3_u32 v2, v0, v1, s48
	v_lshl_add_u64 v[0:1], v[4:5], 0, v[30:31]
	global_store_short_d16_hi v[0:1], v2, off

.LBB0_665:
	s_mul_hi_i32 s12, s64, 0x2aaaaaab
	s_lshr_b32 s13, s12, 31
	s_ashr_i32 s12, s12, 2
	s_add_i32 s82, s12, s13
	s_mul_i32 s12, s82, 0xffffffe8
	s_add_i32 s92, s64, s12
	s_mov_b64 s[12:13], -1
	s_cmp_gt_i32 s92, 15
	v_lshl_add_u32 v103, s82, 5, v66
	s_cbranch_scc0 .LBB0_739
	v_mov_b32_e32 v155, v97
	s_add_i32 s12, s92, -16
	s_lshr_b32 s38, s12, 1
	s_and_b32 s28, s90, 2
	v_or_b32_e32 v146, s28, v62
	s_movk_i32 s26, 0x810
	v_cmp_gt_i32_e64 s[14:15], s26, v103
	s_mul_i32 s33, s38, 0x810
	s_nop 1
	v_cndmask_b32_e64 v140, 0, v103, s[14:15]
	v_add_u32_e32 v140, s33, v140
	v_mov_b64_e32 v[142:143], s[34:35]
	v_mad_i64_i32 v[144:145], s[16:17], v140, s44, v[142:143]
	v_lshl_or_b32 v140, v146, 7, v102
	v_or_b32_e32 v154, 0x2200, v140
	v_lshl_add_u64 v[146:147], v[144:145], 0, v[154:155]
	v_mov_b32_e32 v141, v155
	s_mov_b64 s[86:87], 0x2a00
	global_load_ushort v158, v[146:147], off
	v_lshl_add_u64 v[146:147], v[144:145], 0, v[140:141]
	v_lshl_add_u64 v[152:153], v[144:145], 0, s[86:87]
	v_add_co_u32_e32 v144, vcc, s74, v144
	s_nop 1
	v_addc_co_u32_e32 v145, vcc, 0, v145, vcc
	global_load_dwordx4 v[160:163], v[144:145], off offset:2560
	global_load_dwordx4 v[164:167], v[152:153], off offset:16
	v_or_b32_e32 v156, 2, v103
	v_cmp_gt_i32_e64 s[12:13], s26, v156
	v_or_b32_e32 v150, 3, v103
	v_or_b32_e32 v144, 1, v103
	v_cmp_gt_i32_e64 s[18:19], s26, v144
	v_cmp_gt_i32_e64 s[16:17], s26, v150
	s_nop 1
	v_cndmask_b32_e64 v144, 0, v144, s[18:19]
	v_add_u32_e32 v157, s33, v144
	v_mad_i64_i32 v[148:149], s[20:21], v157, s44, v[142:143]
	v_lshl_add_u64 v[144:145], v[148:149], 0, v[154:155]
	global_load_ushort v159, v[144:145], off
	v_lshl_add_u64 v[144:145], v[148:149], 0, v[140:141]
	v_lshl_add_u64 v[152:153], v[148:149], 0, s[86:87]
	v_add_co_u32_e32 v148, vcc, s74, v148
	s_nop 1
	v_addc_co_u32_e32 v149, vcc, 0, v149, vcc
	global_load_dwordx4 v[168:171], v[148:149], off offset:2560
	global_load_dwordx4 v[172:175], v[152:153], off offset:16
	v_cndmask_b32_e64 v148, 0, v156, s[12:13]
	v_add_u32_e32 v148, s33, v148
	v_mad_i64_i32 v[148:149], s[20:21], v148, s44, v[142:143]
	v_add_co_u32_e32 v146, vcc, s74, v146
	v_lshl_add_u64 v[152:153], v[148:149], 0, v[154:155]
	s_nop 1
	v_addc_co_u32_e32 v147, vcc, 0, v147, vcc
	global_load_ushort v176, v[152:153], off
	global_load_ushort v177, v[146:147], off offset:1024
	v_lshl_add_u64 v[152:153], v[148:149], 0, v[140:141]
	v_add_co_u32_e32 v146, vcc, s74, v152
	s_nop 1
	v_addc_co_u32_e32 v147, vcc, 0, v153, vcc
	global_load_ushort v178, v[146:147], off offset:1024
	v_lshl_add_u64 v[146:147], v[148:149], 0, s[86:87]
	v_add_co_u32_e32 v148, vcc, s74, v148
	s_nop 1
	v_addc_co_u32_e32 v149, vcc, 0, v149, vcc
	global_load_dwordx4 v[180:183], v[148:149], off offset:2560
	global_load_dwordx4 v[184:187], v[146:147], off offset:16
	v_cndmask_b32_e64 v146, 0, v150, s[16:17]
	v_add_u32_e32 v139, s33, v146
	v_mad_i64_i32 v[146:147], s[20:21], v139, s44, v[142:143]
	v_lshl_add_u64 v[150:151], v[146:147], 0, v[154:155]
	global_load_ushort v179, v[150:151], off
	v_lshl_add_u64 v[150:151], v[146:147], 0, v[140:141]
	v_add_co_u32_e32 v150, vcc, s74, v150
	s_nop 1
	v_addc_co_u32_e32 v151, vcc, 0, v151, vcc
	v_add_co_u32_e32 v144, vcc, s74, v144
	global_load_ushort v188, v[150:151], off offset:1024
	s_nop 1
	v_addc_co_u32_e32 v145, vcc, 0, v145, vcc
	global_load_ushort v189, v[144:145], off offset:1024
	v_lshl_add_u64 v[150:151], v[146:147], 0, s[86:87]
	v_add_co_u32_e32 v144, vcc, s74, v146
	s_nop 1
	v_addc_co_u32_e32 v145, vcc, 0, v147, vcc
	global_load_dwordx4 v[190:193], v[144:145], off offset:2560
	global_load_dwordx4 v[194:197], v[150:151], off offset:16
	s_add_i32 s12, s92, -16
	s_lshr_b32 s38, s12, 1
	s_and_b32 s28, s90, 2
	s_lshl_b32 s93, s38, 2
	v_or_b32_e32 v6, s28, v62
	s_add_i32 s93, s93, 32
	s_ashr_i32 s83, s82, 31
	v_or_b32_e32 v2, s93, v6
	v_mov_b64_e32 v[0:1], s[82:83]
	v_mad_u64_u32 v[0:1], s[12:13], v2, s79, v[0:1]
	v_mov_b64_e32 v[2:3], s[56:57]
	v_mad_u64_u32 v[38:39], s[12:13], v0, s44, v[2:3]
	v_lshlrev_b32_e32 v96, 8, v6
	v_mad_i32_i24 v39, v1, s44, v39
	v_lshl_add_u64 v[0:1], v[10:11], 0, v[96:97]
	global_load_dword v108, v[0:1], off
	v_lshl_add_u64 v[0:1], v[12:13], 0, v[96:97]
	s_movk_i32 s12, 0x1000
	v_add_co_u32_e32 v2, vcc, s12, v0
	global_load_dword v44, v[0:1], off
	global_load_dword v48, v[0:1], off offset:1024
	global_load_dword v42, v[0:1], off offset:2048
	global_load_dword v40, v[0:1], off offset:3072
	v_addc_co_u32_e32 v3, vcc, 0, v1, vcc
	v_add_co_u32_e32 v4, vcc, s74, v0
	s_movk_i32 s26, 0x810
	s_nop 0
	v_addc_co_u32_e32 v5, vcc, 0, v1, vcc
	v_add_co_u32_e32 v0, vcc, s44, v0
	v_cmp_gt_i32_e64 s[14:15], s26, v103
	s_nop 0
	v_addc_co_u32_e32 v1, vcc, 0, v1, vcc
	global_load_dword v54, v[4:5], off offset:-4096
	global_load_dword v52, v[2:3], off offset:1024
	global_load_dword v50, v[2:3], off offset:2048
	global_load_dword v46, v[2:3], off offset:3072
	global_load_dword v45, v[4:5], off
	global_load_dword v49, v[4:5], off offset:1024
	global_load_dword v43, v[4:5], off offset:2048
	global_load_dword v41, v[4:5], off offset:3072
	global_load_dword v55, v[0:1], off
	global_load_dword v53, v[0:1], off offset:1024
	global_load_dword v51, v[0:1], off offset:2048
	global_load_dword v47, v[0:1], off offset:3072
	s_mul_i32 s33, s38, 0x810
	v_cndmask_b32_e64 v0, 0, v103, s[14:15]
	v_add_u32_e32 v0, s33, v0
	v_mov_b64_e32 v[2:3], s[34:35]
	v_mad_i64_i32 v[4:5], s[16:17], v0, s44, v[2:3]
	v_lshl_or_b32 v0, v6, 7, v102
	v_or_b32_e32 v96, 0x2200, v0
	v_lshl_add_u64 v[6:7], v[4:5], 0, v[96:97]
	v_mov_b32_e32 v1, v97
	s_mov_b64 s[86:87], 0x2a00
	s_waitcnt vmcnt(0)
	v_mov_b32_e32 v107, v158
	v_lshl_add_u64 v[6:7], v[4:5], 0, v[0:1]
	v_lshl_add_u64 v[60:61], v[4:5], 0, s[86:87]
	v_add_co_u32_e32 v4, vcc, s74, v4
	s_mov_b32 s29, 0x3f317217
	s_nop 0
	v_addc_co_u32_e32 v5, vcc, 0, v5, vcc
	v_mov_b64_e32 v[56:57], v[160:161]
	v_mov_b64_e32 v[58:59], v[162:163]
	v_mov_b64_e32 v[110:111], v[164:165]
	v_mov_b64_e32 v[112:113], v[166:167]
	v_mov_b32_e32 v138, 0x41b17218
	v_or_b32_e32 v104, 2, v103
	v_cmp_gt_i32_e64 s[12:13], s26, v104
	s_waitcnt vmcnt(0)
	v_and_b32_e32 v60, 0xffff0000, v56
	v_and_b32_e32 v61, 0xffff0000, v110
	v_lshlrev_b32_e32 v4, 16, v56
	v_lshlrev_b32_e32 v5, 16, v110
	v_pk_mul_f32 v[60:61], v[48:49], v[60:61]
	v_lshlrev_b32_e32 v56, 16, v58
	v_pk_fma_f32 v[4:5], v[44:45], v[4:5], v[60:61]
	v_lshlrev_b32_e32 v60, 16, v57
	v_lshlrev_b32_e32 v61, 16, v111
	v_pk_fma_f32 v[4:5], v[42:43], v[60:61], v[4:5]
	v_and_b32_e32 v61, 0xffff0000, v111
	v_and_b32_e32 v60, 0xffff0000, v57
	v_pk_fma_f32 v[4:5], v[40:41], v[60:61], v[4:5]
	v_lshlrev_b32_e32 v57, 16, v112
	v_pk_fma_f32 v[4:5], v[54:55], v[56:57], v[4:5]
	v_and_b32_e32 v57, 0xffff0000, v112
	v_and_b32_e32 v56, 0xffff0000, v58
	v_pk_fma_f32 v[4:5], v[52:53], v[56:57], v[4:5]
	v_lshlrev_b32_e32 v56, 16, v59
	v_lshlrev_b32_e32 v57, 16, v113
	v_pk_fma_f32 v[4:5], v[50:51], v[56:57], v[4:5]
	v_and_b32_e32 v57, 0xffff0000, v113
	v_and_b32_e32 v56, 0xffff0000, v59
	v_pk_fma_f32 v[4:5], v[46:47], v[56:57], v[4:5]
	v_or_b32_e32 v58, 3, v103
	v_add_f32_e32 v4, v108, v4
	v_add_f32_e32 v4, v4, v5
	v_min_f32_e32 v5, 0, v4
	v_mul_f32_e64 v4, |v4|, s94
	v_exp_f32_e32 v4, v4
	s_nop 0
	v_add_f32_e32 v4, 1.0, v4
	v_cmp_gt_f32_e32 vcc, s45, v4
	s_nop 1
	v_cndmask_b32_e64 v56, 0, 32, vcc
	v_ldexp_f32 v4, v4, v56
	v_log_f32_e32 v4, v4
	s_nop 0
	v_mul_f32_e32 v56, 0x3f317217, v4
	v_fma_f32 v56, v4, s29, -v56
	v_fmac_f32_e32 v56, 0x3377d1cf, v4
	v_fmac_f32_e32 v56, 0x3f317217, v4
	v_cmp_lt_f32_e64 s[16:17], |v4|, s95
	s_nop 1
	v_cndmask_b32_e64 v4, v4, v56, s[16:17]
	v_cndmask_b32_e32 v56, 0, v138, vcc
	v_sub_f32_e32 v4, v4, v56
	v_sub_f32_e32 v4, v5, v4
	s_mov_b32 s16, 0x3d800000
	v_fma_f32 v4, v4, s16, 0
	v_cndmask_b32_e64 v109, 0, v4, s[14:15]
	v_or_b32_e32 v4, 1, v103
	v_cmp_gt_i32_e64 s[18:19], s26, v4
	v_cmp_gt_i32_e64 s[16:17], s26, v58
	s_nop 0
	v_cndmask_b32_e64 v4, 0, v4, s[18:19]
	v_add_u32_e32 v105, s33, v4
	v_mad_i64_i32 v[56:57], s[20:21], v105, s44, v[2:3]
	v_lshl_add_u64 v[4:5], v[56:57], 0, v[96:97]
	v_mov_b32_e32 v110, v159
	v_lshl_add_u64 v[4:5], v[56:57], 0, v[0:1]
	v_lshl_add_u64 v[60:61], v[56:57], 0, s[86:87]
	v_add_co_u32_e32 v56, vcc, s74, v56
	s_nop 1
	v_addc_co_u32_e32 v57, vcc, 0, v57, vcc
	v_mov_b64_e32 v[112:113], v[168:169]
	v_mov_b64_e32 v[114:115], v[170:171]
	v_mov_b64_e32 v[116:117], v[172:173]
	v_mov_b64_e32 v[118:119], v[174:175]
	s_waitcnt vmcnt(0)
	v_and_b32_e32 v60, 0xffff0000, v112
	s_waitcnt vmcnt(0)
	v_and_b32_e32 v61, 0xffff0000, v116
	v_lshlrev_b32_e32 v56, 16, v112
	v_lshlrev_b32_e32 v57, 16, v116
	v_pk_mul_f32 v[60:61], v[48:49], v[60:61]
	s_nop 0
	v_pk_fma_f32 v[56:57], v[44:45], v[56:57], v[60:61]
	v_lshlrev_b32_e32 v60, 16, v113
	v_lshlrev_b32_e32 v61, 16, v117
	v_pk_fma_f32 v[56:57], v[42:43], v[60:61], v[56:57]
	v_and_b32_e32 v61, 0xffff0000, v117
	v_and_b32_e32 v60, 0xffff0000, v113
	v_pk_fma_f32 v[56:57], v[40:41], v[60:61], v[56:57]
	v_lshlrev_b32_e32 v60, 16, v114
	v_lshlrev_b32_e32 v61, 16, v118
	v_pk_fma_f32 v[56:57], v[54:55], v[60:61], v[56:57]
	v_and_b32_e32 v61, 0xffff0000, v118
	v_and_b32_e32 v60, 0xffff0000, v114
	v_pk_fma_f32 v[56:57], v[52:53], v[60:61], v[56:57]
	v_lshlrev_b32_e32 v60, 16, v115
	v_lshlrev_b32_e32 v61, 16, v119
	v_pk_fma_f32 v[56:57], v[50:51], v[60:61], v[56:57]
	v_and_b32_e32 v61, 0xffff0000, v119
	v_and_b32_e32 v60, 0xffff0000, v115
	v_pk_fma_f32 v[56:57], v[46:47], v[60:61], v[56:57]
	s_nop 0
	v_add_f32_e32 v56, v108, v56
	v_add_f32_e32 v56, v56, v57
	v_min_f32_e32 v57, 0, v56
	v_mul_f32_e64 v56, |v56|, s94
	v_exp_f32_e32 v56, v56
	s_nop 0
	v_add_f32_e32 v56, 1.0, v56
	v_cmp_gt_f32_e32 vcc, s45, v56
	s_nop 1
	v_cndmask_b32_e64 v59, 0, 32, vcc
	v_ldexp_f32 v56, v56, v59
	v_log_f32_e32 v56, v56
	s_nop 0
	v_mul_f32_e32 v59, 0x3f317217, v56
	v_fma_f32 v59, v56, s29, -v59
	v_fmac_f32_e32 v59, 0x3377d1cf, v56
	v_fmac_f32_e32 v59, 0x3f317217, v56
	v_cmp_lt_f32_e64 s[20:21], |v56|, s95
	s_nop 1
	v_cndmask_b32_e64 v56, v56, v59, s[20:21]
	v_cndmask_b32_e32 v59, 0, v138, vcc
	v_sub_f32_e32 v56, v56, v59
	v_sub_f32_e32 v56, v57, v56
	v_mul_f32_e32 v56, 0x3d800000, v56
	v_cndmask_b32_e64 v56, 0, v56, s[18:19]
	v_add_f32_e32 v113, v109, v56
	v_cndmask_b32_e64 v56, 0, v104, s[12:13]
	v_add_u32_e32 v56, s33, v56
	v_mad_i64_i32 v[56:57], s[20:21], v56, s44, v[2:3]
	v_add_co_u32_e32 v6, vcc, s74, v6
	v_lshl_add_u64 v[60:61], v[56:57], 0, v[96:97]
	s_nop 0
	v_addc_co_u32_e32 v7, vcc, 0, v7, vcc
	v_mov_b32_e32 v114, v176
	v_mov_b32_e32 v59, v177
	v_lshl_add_u64 v[60:61], v[56:57], 0, v[0:1]
	v_add_co_u32_e32 v6, vcc, s74, v60
	s_waitcnt vmcnt(0)
	v_lshlrev_b32_e32 v59, 16, v59
	v_addc_co_u32_e32 v7, vcc, 0, v61, vcc
	v_mov_b32_e32 v6, v178
	s_waitcnt vmcnt(0)
	v_lshlrev_b32_e32 v60, 16, v6
	v_lshl_add_u64 v[6:7], v[56:57], 0, s[86:87]
	v_add_co_u32_e32 v56, vcc, s74, v56
	s_nop 1
	v_addc_co_u32_e32 v57, vcc, 0, v57, vcc
	v_mov_b64_e32 v[116:117], v[180:181]
	v_mov_b64_e32 v[118:119], v[182:183]
	v_mov_b64_e32 v[120:121], v[184:185]
	v_mov_b64_e32 v[122:123], v[186:187]
	s_waitcnt vmcnt(0)
	v_and_b32_e32 v56, 0xffff0000, v116
	s_waitcnt vmcnt(0)
	v_and_b32_e32 v57, 0xffff0000, v120
	v_lshlrev_b32_e32 v6, 16, v116
	v_lshlrev_b32_e32 v7, 16, v120
	v_pk_mul_f32 v[56:57], v[48:49], v[56:57]
	s_nop 0
	v_pk_fma_f32 v[6:7], v[44:45], v[6:7], v[56:57]
	v_lshlrev_b32_e32 v56, 16, v117
	v_lshlrev_b32_e32 v57, 16, v121
	v_pk_fma_f32 v[6:7], v[42:43], v[56:57], v[6:7]
	v_and_b32_e32 v57, 0xffff0000, v121
	v_and_b32_e32 v56, 0xffff0000, v117
	v_pk_fma_f32 v[6:7], v[40:41], v[56:57], v[6:7]
	v_lshlrev_b32_e32 v56, 16, v118
	v_lshlrev_b32_e32 v57, 16, v122
	v_pk_fma_f32 v[6:7], v[54:55], v[56:57], v[6:7]
	v_and_b32_e32 v57, 0xffff0000, v122
	v_and_b32_e32 v56, 0xffff0000, v118
	v_pk_fma_f32 v[6:7], v[52:53], v[56:57], v[6:7]
	v_lshlrev_b32_e32 v56, 16, v119
	v_lshlrev_b32_e32 v57, 16, v123
	v_pk_fma_f32 v[6:7], v[50:51], v[56:57], v[6:7]
	v_and_b32_e32 v57, 0xffff0000, v123
	v_and_b32_e32 v56, 0xffff0000, v119
	v_pk_fma_f32 v[6:7], v[46:47], v[56:57], v[6:7]
	v_cndmask_b32_e64 v57, 0, v60, s[12:13]
	v_add_f32_e32 v6, v108, v6
	v_add_f32_e32 v6, v6, v7
	v_min_f32_e32 v7, 0, v6
	v_mul_f32_e64 v6, |v6|, s94
	v_exp_f32_e32 v6, v6
	s_nop 0
	v_add_f32_e32 v6, 1.0, v6
	v_cmp_gt_f32_e32 vcc, s45, v6
	s_nop 1
	v_cndmask_b32_e64 v56, 0, 32, vcc
	v_ldexp_f32 v6, v6, v56
	v_log_f32_e32 v6, v6
	s_nop 0
	v_mul_f32_e32 v56, 0x3f317217, v6
	v_fma_f32 v56, v6, s29, -v56
	v_fmac_f32_e32 v56, 0x3377d1cf, v6
	v_fmac_f32_e32 v56, 0x3f317217, v6
	v_cmp_lt_f32_e64 s[20:21], |v6|, s95
	s_nop 1
	v_cndmask_b32_e64 v6, v6, v56, s[20:21]
	v_cndmask_b32_e32 v56, 0, v138, vcc
	v_sub_f32_e32 v6, v6, v56
	v_sub_f32_e32 v6, v7, v6
	v_mul_f32_e32 v6, 0x3d800000, v6
	v_cndmask_b32_e64 v6, 0, v6, s[12:13]
	v_add_f32_e32 v117, v113, v6
	v_cndmask_b32_e64 v6, 0, v58, s[16:17]
	v_add_u32_e32 v111, s33, v6
	v_mad_i64_i32 v[6:7], s[20:21], v111, s44, v[2:3]
	v_cndmask_b32_e64 v56, 0, v59, s[14:15]
	v_lshl_add_u64 v[58:59], v[6:7], 0, v[96:97]
	v_mov_b32_e32 v116, v179
	v_lshl_add_u64 v[58:59], v[6:7], 0, v[0:1]
	v_add_co_u32_e32 v58, vcc, s74, v58
	s_nop 1
	v_addc_co_u32_e32 v59, vcc, 0, v59, vcc
	v_add_co_u32_e32 v4, vcc, s74, v4
	v_mov_b32_e32 v58, v188
	s_nop 0
	v_addc_co_u32_e32 v5, vcc, 0, v5, vcc
	v_mov_b32_e32 v4, v189
	s_waitcnt vmcnt(0)
	v_lshlrev_b32_e32 v115, 16, v58
	v_lshl_add_u64 v[58:59], v[6:7], 0, s[86:87]
	s_waitcnt vmcnt(0)
	v_lshlrev_b32_e32 v112, 16, v4
	v_add_co_u32_e32 v4, vcc, s74, v6
	s_nop 1
	v_addc_co_u32_e32 v5, vcc, 0, v7, vcc
	v_mov_b64_e32 v[4:5], v[190:191]
	v_mov_b64_e32 v[6:7], v[192:193]
	s_nop 0
	v_mov_b64_e32 v[58:59], v[194:195]
	v_mov_b64_e32 v[60:61], v[196:197]
	v_mov_b32_e32 v142, v2
	v_mov_b32_e32 v143, v3
	v_mov_b32_e32 v140, v0
	v_mov_b32_e32 v141, v1
	v_or_b32_e32 v139, 4, v103
	v_cmp_gt_i32_e64 s[22:23], s26, v139
	v_or_b32_e32 v150, 6, v103
	s_nop 1
	v_cndmask_b32_e64 v144, 0, v139, s[22:23]
	v_add_u32_e32 v144, s33, v144
	v_mad_i64_i32 v[146:147], s[24:25], v144, s44, v[142:143]
	v_lshl_add_u64 v[144:145], v[146:147], 0, v[96:97]
	global_load_ushort v151, v[144:145], off
	v_lshl_add_u64 v[144:145], v[146:147], 0, v[140:141]
	v_lshl_add_u64 v[148:149], v[146:147], 0, s[86:87]
	v_add_co_u32_e32 v146, vcc, s74, v146
	v_cmp_gt_i32_e64 s[20:21], s26, v150
	s_nop 1
	v_addc_co_u32_e32 v147, vcc, 0, v147, vcc
	global_load_dwordx4 v[160:163], v[146:147], off offset:2560
	global_load_dwordx4 v[164:167], v[148:149], off offset:16
	v_or_b32_e32 v154, 7, v103
	v_or_b32_e32 v146, 5, v103
	v_cmp_gt_i32_e64 s[24:25], s26, v154
	v_cmp_gt_i32_e64 s[98:99], s26, v146
	s_nop 1
	v_cndmask_b32_e64 v146, 0, v146, s[98:99]
	v_add_u32_e32 v152, s33, v146
	v_mad_i64_i32 v[148:149], s[30:31], v152, s44, v[142:143]
	v_lshl_add_u64 v[146:147], v[148:149], 0, v[96:97]
	global_load_ushort v153, v[146:147], off
	v_lshl_add_u64 v[146:147], v[148:149], 0, v[140:141]
	v_lshl_add_u64 v[158:159], v[148:149], 0, s[86:87]
	v_add_co_u32_e32 v148, vcc, s74, v148
	s_nop 1
	v_addc_co_u32_e32 v149, vcc, 0, v149, vcc
	global_load_dwordx4 v[168:171], v[148:149], off offset:2560
	global_load_dwordx4 v[172:175], v[158:159], off offset:16
	v_cndmask_b32_e64 v148, 0, v150, s[20:21]
	v_add_u32_e32 v148, s33, v148
	v_mad_i64_i32 v[148:149], s[30:31], v148, s44, v[142:143]
	v_lshl_add_u64 v[156:157], v[148:149], 0, v[96:97]
	global_load_ushort v155, v[156:157], off
	v_lshl_add_u64 v[156:157], v[148:149], 0, v[140:141]
	v_add_co_u32_e32 v156, vcc, s74, v156
	s_nop 1
	v_addc_co_u32_e32 v157, vcc, 0, v157, vcc
	v_add_co_u32_e32 v144, vcc, s74, v144
	global_load_ushort v176, v[156:157], off offset:1024
	s_nop 1
	v_addc_co_u32_e32 v145, vcc, 0, v145, vcc
	global_load_ushort v177, v[144:145], off offset:1024
	v_lshl_add_u64 v[144:145], v[148:149], 0, s[86:87]
	v_add_co_u32_e32 v148, vcc, s74, v148
	s_nop 1
	v_addc_co_u32_e32 v149, vcc, 0, v149, vcc
	global_load_dwordx4 v[178:181], v[148:149], off offset:2560
	global_load_dwordx4 v[182:185], v[144:145], off offset:16
	v_cndmask_b32_e64 v144, 0, v154, s[24:25]
	v_add_u32_e32 v154, s33, v144
	v_mad_i64_i32 v[142:143], s[30:31], v154, s44, v[142:143]
	v_lshl_add_u64 v[140:141], v[142:143], 0, v[140:141]
	v_add_co_u32_e32 v140, vcc, s74, v140
	v_lshl_add_u64 v[144:145], v[142:143], 0, v[96:97]
	s_nop 1
	v_addc_co_u32_e32 v141, vcc, 0, v141, vcc
	global_load_ushort v186, v[144:145], off
	global_load_ushort v187, v[140:141], off offset:1024
	v_add_co_u32_e32 v140, vcc, s74, v146
	s_nop 1
	v_addc_co_u32_e32 v141, vcc, 0, v147, vcc
	global_load_ushort v188, v[140:141], off offset:1024
	v_lshl_add_u64 v[144:145], v[142:143], 0, s[86:87]
	v_add_co_u32_e32 v140, vcc, s74, v142
	s_nop 1
	v_addc_co_u32_e32 v141, vcc, 0, v143, vcc
	global_load_dwordx4 v[190:193], v[140:141], off offset:2560
	global_load_dwordx4 v[194:197], v[144:145], off offset:16
	s_waitcnt vmcnt(0)
	v_and_b32_e32 v120, 0xffff0000, v4
	s_waitcnt vmcnt(0)
	v_and_b32_e32 v121, 0xffff0000, v58
	v_lshlrev_b32_e32 v118, 16, v4
	v_lshlrev_b32_e32 v119, 16, v58
	v_pk_mul_f32 v[120:121], v[48:49], v[120:121]
	v_and_b32_e32 v58, 0xffff0000, v5
	v_pk_fma_f32 v[118:119], v[44:45], v[118:119], v[120:121]
	v_lshlrev_b32_e32 v120, 16, v5
	v_lshlrev_b32_e32 v121, 16, v59
	v_pk_fma_f32 v[118:119], v[42:43], v[120:121], v[118:119]
	v_and_b32_e32 v59, 0xffff0000, v59
	v_pk_fma_f32 v[4:5], v[40:41], v[58:59], v[118:119]
	v_lshlrev_b32_e32 v58, 16, v6
	v_lshlrev_b32_e32 v59, 16, v60
	v_pk_fma_f32 v[4:5], v[54:55], v[58:59], v[4:5]
	v_and_b32_e32 v59, 0xffff0000, v60
	v_and_b32_e32 v58, 0xffff0000, v6
	v_pk_fma_f32 v[4:5], v[52:53], v[58:59], v[4:5]
	v_lshlrev_b32_e32 v58, 16, v7
	v_lshlrev_b32_e32 v59, 16, v61
	v_pk_fma_f32 v[4:5], v[50:51], v[58:59], v[4:5]
	v_and_b32_e32 v59, 0xffff0000, v61
	v_and_b32_e32 v58, 0xffff0000, v7
	v_pk_fma_f32 v[4:5], v[46:47], v[58:59], v[4:5]
	v_cndmask_b32_e64 v59, 0, v115, s[16:17]
	v_add_f32_e32 v4, v108, v4
	v_add_f32_e32 v4, v4, v5
	v_min_f32_e32 v5, 0, v4
	v_mul_f32_e64 v4, |v4|, s94
	v_exp_f32_e32 v4, v4
	v_or_b32_e32 v115, 4, v103
	v_cmp_gt_i32_e64 s[22:23], s26, v115
	v_cndmask_b32_e64 v58, 0, v112, s[18:19]
	v_add_f32_e32 v4, 1.0, v4
	v_cmp_gt_f32_e32 vcc, s45, v4
	v_or_b32_e32 v112, 6, v103
	s_nop 0
	v_cndmask_b32_e64 v6, 0, 32, vcc
	v_ldexp_f32 v4, v4, v6
	v_log_f32_e32 v4, v4
	s_nop 0
	v_mul_f32_e32 v6, 0x3f317217, v4
	v_fma_f32 v6, v4, s29, -v6
	v_fmac_f32_e32 v6, 0x3377d1cf, v4
	v_fmac_f32_e32 v6, 0x3f317217, v4
	v_cmp_lt_f32_e64 s[20:21], |v4|, s95
	s_nop 1
	v_cndmask_b32_e64 v4, v4, v6, s[20:21]
	v_cndmask_b32_e32 v6, 0, v138, vcc
	v_sub_f32_e32 v4, v4, v6
	v_sub_f32_e32 v4, v5, v4
	v_mul_f32_e32 v4, 0x3d800000, v4
	v_cndmask_b32_e64 v4, 0, v4, s[16:17]
	v_add_f32_e32 v120, v117, v4
	v_cndmask_b32_e64 v4, 0, v115, s[22:23]
	v_add_u32_e32 v4, s33, v4
	v_mad_i64_i32 v[6:7], s[24:25], v4, s44, v[2:3]
	v_lshl_add_u64 v[4:5], v[6:7], 0, v[96:97]
	s_waitcnt vmcnt(0)
	v_mov_b32_e32 v119, v151
	v_lshl_add_u64 v[4:5], v[6:7], 0, v[0:1]
	v_lshl_add_u64 v[60:61], v[6:7], 0, s[86:87]
	v_add_co_u32_e32 v6, vcc, s74, v6
	v_cmp_gt_i32_e64 s[20:21], s26, v112
	s_nop 0
	v_addc_co_u32_e32 v7, vcc, 0, v7, vcc
	v_mov_b64_e32 v[122:123], v[160:161]
	v_mov_b64_e32 v[124:125], v[162:163]
	v_mov_b64_e32 v[126:127], v[164:165]
	v_mov_b64_e32 v[128:129], v[166:167]
	s_waitcnt vmcnt(0)
	v_and_b32_e32 v60, 0xffff0000, v122
	s_waitcnt vmcnt(0)
	v_and_b32_e32 v61, 0xffff0000, v126
	v_lshlrev_b32_e32 v6, 16, v122
	v_lshlrev_b32_e32 v7, 16, v126
	v_pk_mul_f32 v[60:61], v[48:49], v[60:61]
	s_nop 0
	v_pk_fma_f32 v[6:7], v[44:45], v[6:7], v[60:61]
	v_lshlrev_b32_e32 v60, 16, v123
	v_lshlrev_b32_e32 v61, 16, v127
	v_pk_fma_f32 v[6:7], v[42:43], v[60:61], v[6:7]
	v_and_b32_e32 v61, 0xffff0000, v127
	v_and_b32_e32 v60, 0xffff0000, v123
	v_pk_fma_f32 v[6:7], v[40:41], v[60:61], v[6:7]
	v_lshlrev_b32_e32 v60, 16, v124
	v_lshlrev_b32_e32 v61, 16, v128
	v_pk_fma_f32 v[6:7], v[54:55], v[60:61], v[6:7]
	v_and_b32_e32 v61, 0xffff0000, v128
	v_and_b32_e32 v60, 0xffff0000, v124
	v_pk_fma_f32 v[6:7], v[52:53], v[60:61], v[6:7]
	v_lshlrev_b32_e32 v60, 16, v125
	v_lshlrev_b32_e32 v61, 16, v129
	v_pk_fma_f32 v[6:7], v[50:51], v[60:61], v[6:7]
	v_and_b32_e32 v61, 0xffff0000, v129
	v_and_b32_e32 v60, 0xffff0000, v125
	v_pk_fma_f32 v[6:7], v[46:47], v[60:61], v[6:7]
	v_or_b32_e32 v124, 7, v103
	v_add_f32_e32 v6, v108, v6
	v_add_f32_e32 v6, v6, v7
	v_min_f32_e32 v7, 0, v6
	v_mul_f32_e64 v6, |v6|, s94
	v_exp_f32_e32 v6, v6
	s_nop 0
	v_add_f32_e32 v6, 1.0, v6
	v_cmp_gt_f32_e32 vcc, s45, v6
	s_nop 1
	v_cndmask_b32_e64 v60, 0, 32, vcc
	v_ldexp_f32 v6, v6, v60
	v_log_f32_e32 v6, v6
	s_nop 0
	v_mul_f32_e32 v60, 0x3f317217, v6
	v_fma_f32 v60, v6, s29, -v60
	v_fmac_f32_e32 v60, 0x3377d1cf, v6
	v_fmac_f32_e32 v60, 0x3f317217, v6
	v_cmp_lt_f32_e64 s[24:25], |v6|, s95
	s_nop 1
	v_cndmask_b32_e64 v6, v6, v60, s[24:25]
	v_cndmask_b32_e32 v60, 0, v138, vcc
	v_sub_f32_e32 v6, v6, v60
	v_sub_f32_e32 v6, v7, v6
	v_mul_f32_e32 v6, 0x3d800000, v6
	v_cndmask_b32_e64 v123, 0, v6, s[22:23]
	v_or_b32_e32 v6, 5, v103
	v_cmp_gt_i32_e64 s[24:25], s26, v124
	v_cmp_gt_i32_e64 s[26:27], s26, v6
	s_nop 1
	v_cndmask_b32_e64 v6, 0, v6, s[26:27]
	v_add_u32_e32 v118, s33, v6
	v_mad_i64_i32 v[60:61], s[30:31], v118, s44, v[2:3]
	v_lshl_add_u64 v[6:7], v[60:61], 0, v[96:97]
	v_mov_b32_e32 v121, v153
	v_lshl_add_u64 v[6:7], v[60:61], 0, v[0:1]
	v_lshl_add_u64 v[130:131], v[60:61], 0, s[86:87]
	v_add_co_u32_e32 v60, vcc, s74, v60
	s_nop 1
	v_addc_co_u32_e32 v61, vcc, 0, v61, vcc
	v_mov_b64_e32 v[126:127], v[168:169]
	v_mov_b64_e32 v[128:129], v[170:171]
	s_nop 0
	v_mov_b64_e32 v[130:131], v[172:173]
	v_mov_b64_e32 v[132:133], v[174:175]
	s_waitcnt vmcnt(0)
	v_and_b32_e32 v134, 0xffff0000, v126
	s_waitcnt vmcnt(0)
	v_and_b32_e32 v135, 0xffff0000, v130
	v_lshlrev_b32_e32 v60, 16, v126
	v_lshlrev_b32_e32 v61, 16, v130
	v_pk_mul_f32 v[134:135], v[48:49], v[134:135]
	v_and_b32_e32 v130, 0xffff0000, v127
	v_pk_fma_f32 v[60:61], v[44:45], v[60:61], v[134:135]
	v_lshlrev_b32_e32 v134, 16, v127
	v_lshlrev_b32_e32 v135, 16, v131
	v_pk_fma_f32 v[60:61], v[42:43], v[134:135], v[60:61]
	v_and_b32_e32 v131, 0xffff0000, v131
	v_pk_fma_f32 v[60:61], v[40:41], v[130:131], v[60:61]
	v_lshlrev_b32_e32 v126, 16, v128
	v_lshlrev_b32_e32 v127, 16, v132
	v_pk_fma_f32 v[60:61], v[54:55], v[126:127], v[60:61]
	v_and_b32_e32 v127, 0xffff0000, v132
	v_and_b32_e32 v126, 0xffff0000, v128
	v_pk_fma_f32 v[60:61], v[52:53], v[126:127], v[60:61]
	v_lshlrev_b32_e32 v126, 16, v129
	v_lshlrev_b32_e32 v127, 16, v133
	v_pk_fma_f32 v[60:61], v[50:51], v[126:127], v[60:61]
	v_and_b32_e32 v127, 0xffff0000, v133
	v_and_b32_e32 v126, 0xffff0000, v129
	v_pk_fma_f32 v[60:61], v[46:47], v[126:127], v[60:61]
	s_nop 0
	v_add_f32_e32 v60, v108, v60
	v_add_f32_e32 v60, v60, v61
	v_min_f32_e32 v61, 0, v60
	v_mul_f32_e64 v60, |v60|, s94
	v_exp_f32_e32 v60, v60
	s_nop 0
	v_add_f32_e32 v60, 1.0, v60
	v_cmp_gt_f32_e32 vcc, s45, v60
	s_nop 1
	v_cndmask_b32_e64 v122, 0, 32, vcc
	v_ldexp_f32 v60, v60, v122
	v_log_f32_e32 v60, v60
	s_nop 0
	v_mul_f32_e32 v122, 0x3f317217, v60
	v_fma_f32 v122, v60, s29, -v122
	v_fmac_f32_e32 v122, 0x3377d1cf, v60
	v_fmac_f32_e32 v122, 0x3f317217, v60
	v_cmp_lt_f32_e64 s[30:31], |v60|, s95
	s_nop 1
	v_cndmask_b32_e64 v60, v60, v122, s[30:31]
	v_cndmask_b32_e32 v122, 0, v138, vcc
	v_sub_f32_e32 v60, v60, v122
	v_sub_f32_e32 v60, v61, v60
	v_mul_f32_e32 v60, 0x3d800000, v60
	v_cndmask_b32_e64 v125, 0, v60, s[26:27]
	v_cndmask_b32_e64 v60, 0, v112, s[20:21]
	v_add_u32_e32 v60, s33, v60
	v_mad_i64_i32 v[60:61], s[30:31], v60, s44, v[2:3]
	v_lshl_add_u64 v[126:127], v[60:61], 0, v[96:97]
	v_mov_b32_e32 v122, v155
	v_lshl_add_u64 v[126:127], v[60:61], 0, v[0:1]
	v_add_co_u32_e32 v126, vcc, s74, v126
	s_nop 1
	v_addc_co_u32_e32 v127, vcc, 0, v127, vcc
	v_add_co_u32_e32 v4, vcc, s74, v4
	v_mov_b32_e32 v126, v176
	s_nop 0
	v_addc_co_u32_e32 v5, vcc, 0, v5, vcc
	v_mov_b32_e32 v4, v177
	s_waitcnt vmcnt(0)
	v_lshlrev_b32_e32 v135, 16, v126
	s_waitcnt vmcnt(0)
	v_lshlrev_b32_e32 v134, 16, v4
	v_lshl_add_u64 v[4:5], v[60:61], 0, s[86:87]
	v_add_co_u32_e32 v60, vcc, s74, v60
	s_nop 1
	v_addc_co_u32_e32 v61, vcc, 0, v61, vcc
	v_mov_b64_e32 v[126:127], v[178:179]
	v_mov_b64_e32 v[128:129], v[180:181]
	v_mov_b64_e32 v[130:131], v[182:183]
	v_mov_b64_e32 v[132:133], v[184:185]
	s_waitcnt vmcnt(0)
	v_and_b32_e32 v60, 0xffff0000, v126
	s_waitcnt vmcnt(0)
	v_and_b32_e32 v61, 0xffff0000, v130
	v_lshlrev_b32_e32 v4, 16, v126
	v_lshlrev_b32_e32 v5, 16, v130
	v_pk_mul_f32 v[60:61], v[48:49], v[60:61]
	s_nop 0
	v_pk_fma_f32 v[4:5], v[44:45], v[4:5], v[60:61]
	v_lshlrev_b32_e32 v60, 16, v127
	v_lshlrev_b32_e32 v61, 16, v131
	v_pk_fma_f32 v[4:5], v[42:43], v[60:61], v[4:5]
	v_and_b32_e32 v61, 0xffff0000, v131
	v_and_b32_e32 v60, 0xffff0000, v127
	v_pk_fma_f32 v[4:5], v[40:41], v[60:61], v[4:5]
	v_lshlrev_b32_e32 v60, 16, v128
	v_lshlrev_b32_e32 v61, 16, v132
	v_pk_fma_f32 v[4:5], v[54:55], v[60:61], v[4:5]
	v_and_b32_e32 v61, 0xffff0000, v132
	v_and_b32_e32 v60, 0xffff0000, v128
	v_pk_fma_f32 v[4:5], v[52:53], v[60:61], v[4:5]
	v_lshlrev_b32_e32 v60, 16, v129
	v_lshlrev_b32_e32 v61, 16, v133
	v_pk_fma_f32 v[4:5], v[50:51], v[60:61], v[4:5]
	v_and_b32_e32 v61, 0xffff0000, v133
	v_and_b32_e32 v60, 0xffff0000, v129
	v_pk_fma_f32 v[4:5], v[46:47], v[60:61], v[4:5]
	v_cndmask_b32_e64 v61, 0, v135, s[20:21]
	v_add_f32_e32 v4, v108, v4
	v_add_f32_e32 v4, v4, v5
	v_min_f32_e32 v5, 0, v4
	v_mul_f32_e64 v4, |v4|, s94
	v_exp_f32_e32 v4, v4
	s_nop 0
	v_add_f32_e32 v4, 1.0, v4
	v_cmp_gt_f32_e32 vcc, s45, v4
	s_nop 1
	v_cndmask_b32_e64 v60, 0, 32, vcc
	v_ldexp_f32 v4, v4, v60
	v_log_f32_e32 v4, v4
	s_nop 0
	v_mul_f32_e32 v60, 0x3f317217, v4
	v_fma_f32 v60, v4, s29, -v60
	v_fmac_f32_e32 v60, 0x3377d1cf, v4
	v_fmac_f32_e32 v60, 0x3f317217, v4
	v_cmp_lt_f32_e64 s[30:31], |v4|, s95
	s_nop 1
	v_cndmask_b32_e64 v4, v4, v60, s[30:31]
	v_cndmask_b32_e32 v60, 0, v138, vcc
	v_sub_f32_e32 v4, v4, v60
	v_sub_f32_e32 v4, v5, v4
	v_mul_f32_e32 v4, 0x3d800000, v4
	v_cndmask_b32_e64 v126, 0, v4, s[20:21]
	v_cndmask_b32_e64 v4, 0, v124, s[24:25]
	v_add_u32_e32 v124, s33, v4
	v_mad_i64_i32 v[2:3], s[30:31], v124, s44, v[2:3]
	v_lshl_add_u64 v[0:1], v[2:3], 0, v[0:1]
	v_add_co_u32_e32 v0, vcc, s74, v0
	v_lshl_add_u64 v[4:5], v[2:3], 0, v[96:97]
	s_nop 0
	v_addc_co_u32_e32 v1, vcc, 0, v1, vcc
	v_mov_b32_e32 v96, v186
	v_cndmask_b32_e64 v60, 0, v134, s[22:23]
	v_mov_b32_e32 v4, v187
	v_add_co_u32_e32 v0, vcc, s74, v6
	s_waitcnt vmcnt(0)
	v_lshlrev_b32_e32 v132, 16, v4
	v_addc_co_u32_e32 v1, vcc, 0, v7, vcc
	v_mov_b32_e32 v0, v188
	v_lshl_add_u64 v[4:5], v[2:3], 0, s[86:87]
	s_waitcnt vmcnt(0)
	v_lshlrev_b32_e32 v127, 16, v0
	v_add_co_u32_e32 v0, vcc, s74, v2
	s_nop 1
	v_addc_co_u32_e32 v1, vcc, 0, v3, vcc
	v_mov_b64_e32 v[0:1], v[190:191]
	v_mov_b64_e32 v[2:3], v[192:193]
	s_nop 0
	v_mov_b64_e32 v[4:5], v[194:195]
	v_mov_b64_e32 v[6:7], v[196:197]
	s_barrier
	s_waitcnt vmcnt(1)
	v_and_b32_e32 v130, 0xffff0000, v0
	s_waitcnt vmcnt(0)
	v_and_b32_e32 v131, 0xffff0000, v4
	v_lshlrev_b32_e32 v128, 16, v0
	v_lshlrev_b32_e32 v129, 16, v4
	v_pk_mul_f32 v[48:49], v[48:49], v[130:131]
	v_and_b32_e32 v4, 0xffff0000, v1
	v_pk_fma_f32 v[44:45], v[44:45], v[128:129], v[48:49]
	v_lshlrev_b32_e32 v48, 16, v1
	v_lshlrev_b32_e32 v49, 16, v5
	v_pk_fma_f32 v[42:43], v[42:43], v[48:49], v[44:45]
	v_and_b32_e32 v5, 0xffff0000, v5
	v_pk_fma_f32 v[0:1], v[40:41], v[4:5], v[42:43]
	v_lshlrev_b32_e32 v4, 16, v2
	v_lshlrev_b32_e32 v5, 16, v6
	v_pk_fma_f32 v[0:1], v[54:55], v[4:5], v[0:1]
	v_and_b32_e32 v5, 0xffff0000, v6
	v_and_b32_e32 v4, 0xffff0000, v2
	v_pk_fma_f32 v[0:1], v[52:53], v[4:5], v[0:1]
	v_lshlrev_b32_e32 v4, 16, v3
	v_lshlrev_b32_e32 v5, 16, v7
	v_pk_fma_f32 v[0:1], v[50:51], v[4:5], v[0:1]
	v_and_b32_e32 v5, 0xffff0000, v7
	v_and_b32_e32 v4, 0xffff0000, v3
	v_pk_fma_f32 v[0:1], v[46:47], v[4:5], v[0:1]
	v_add_f32_e32 v52, v120, v123
	v_add_f32_e32 v0, v108, v0
	v_add_f32_e32 v0, v0, v1
	v_min_f32_e32 v1, 0, v0
	v_mul_f32_e64 v0, |v0|, s94
	v_exp_f32_e32 v0, v0
	v_add_f32_e32 v53, v52, v125
	v_add_f32_e32 v54, v53, v126
	v_add_f32_e32 v0, 1.0, v0
	v_cmp_gt_f32_e32 vcc, s45, v0
	s_nop 1
	v_cndmask_b32_e64 v2, 0, 32, vcc
	v_ldexp_f32 v0, v0, v2
	v_log_f32_e32 v0, v0
	s_nop 0
	v_mul_f32_e32 v2, 0x3f317217, v0
	v_fma_f32 v2, v0, s29, -v2
	v_fmac_f32_e32 v2, 0x3377d1cf, v0
	v_fmac_f32_e32 v2, 0x3f317217, v0
	v_cmp_lt_f32_e64 s[30:31], |v0|, s95
	s_nop 1
	v_cndmask_b32_e64 v0, v0, v2, s[30:31]
	v_cndmask_b32_e32 v2, 0, v138, vcc
	v_sub_f32_e32 v0, v0, v2
	v_sub_f32_e32 v0, v1, v0
	v_mul_f32_e32 v0, 0x3d800000, v0
	v_cndmask_b32_e64 v2, 0, v0, s[24:25]
	v_add_f32_e32 v5, v54, v2
	ds_write_b32 v67, v5
	s_waitcnt lgkmcnt(0)
	s_barrier
	ds_read2st64_b32 v[6:7], v68 offset1:2
	ds_read2st64_b32 v[2:3], v68 offset0:4 offset1:6
	v_cndmask_b32_e64 v1, 0, v132, s[24:25]
	v_cndmask_b32_e64 v0, 0, v127, s[26:27]
	s_waitcnt lgkmcnt(1)
	v_add_f32_e32 v7, v6, v7
	s_waitcnt lgkmcnt(0)
	v_add_f32_e32 v4, v7, v2
	v_cndmask_b32_e64 v2, v4, v7, s[4:5]
	v_cndmask_b32_e64 v2, v2, v6, s[2:3]
	v_cndmask_b32_e64 v47, v2, 0, s[0:1]
	v_mov_b32_e32 v46, v3
	v_add_f32_e32 v45, v109, v47
	v_pk_add_f32 v[2:3], v[4:5], v[46:47]
	v_add_f32_e32 v44, v113, v47
	v_sub_f32_e32 v5, v2, v45
	v_mul_f32_e32 v5, 0x3fb8aa3b, v5
	v_exp_f32_e32 v40, v5
	v_sub_f32_e32 v5, v2, v44
	v_mul_f32_e32 v5, 0x3fb8aa3b, v5
	v_add_f32_e32 v43, v117, v47
	v_exp_f32_e32 v48, v5
	v_sub_f32_e32 v5, v2, v43
	v_mul_f32_e32 v5, 0x3fb8aa3b, v5
	v_exp_f32_e32 v41, v5
	v_add_f32_e32 v42, v120, v47
	v_sub_f32_e32 v5, v2, v42
	v_mul_f32_e32 v5, 0x3fb8aa3b, v5
	v_pk_mul_f32 v[50:51], v[56:57], v[40:41]
	v_add_f32_e32 v41, v52, v47
	v_exp_f32_e32 v49, v5
	v_sub_f32_e32 v5, v2, v41
	v_add_f32_e32 v40, v53, v47
	v_mul_f32_e32 v5, 0x3fb8aa3b, v5
	v_exp_f32_e32 v46, v5
	v_sub_f32_e32 v5, v2, v40
	v_mul_f32_e32 v5, 0x3fb8aa3b, v5
	v_exp_f32_e32 v52, v5
	v_add_f32_e32 v5, v47, v54
	v_sub_f32_e32 v53, v2, v3
	v_sub_f32_e32 v47, v2, v5
	v_mul_f32_e32 v53, 0x3fb8aa3b, v53
	v_mul_f32_e32 v47, 0x3fb8aa3b, v47
	v_exp_f32_e32 v53, v53
	v_exp_f32_e32 v47, v47
	v_pk_mul_f32 v[48:49], v[58:59], v[48:49]
	v_pk_mul_f32 v[52:53], v[0:1], v[52:53]
	v_pk_mul_f32 v[46:47], v[60:61], v[46:47]
	v_cvt_pk_bf16_f32 v52, v52, v52
	v_cvt_pk_bf16_f32 v53, v53, v53
	v_cvt_pk_bf16_f32 v54, v48, v48
	v_cvt_pk_bf16_f32 v55, v49, v49
	v_cvt_pk_bf16_f32 v47, v47, v47
	v_cvt_pk_bf16_f32 v46, v46, v46
	v_cvt_pk_bf16_f32 v48, v51, v51
	v_cvt_pk_bf16_f32 v49, v50, v50
	v_lshrrev_b32_e32 v46, 16, v46
	v_lshrrev_b32_e32 v47, 16, v47
	v_lshrrev_b32_e32 v50, 16, v49
	v_lshrrev_b32_e32 v51, 16, v48
	v_and_or_b32 v49, v53, s36, v47
	v_and_or_b32 v48, v52, s36, v46
	v_and_or_b32 v47, v55, s36, v51
	v_and_or_b32 v46, v54, s36, v50
	v_lshl_add_u64 v[50:51], v[38:39], 0, v[14:15]
	v_add_co_u32_e32 v50, vcc, 0x1000, v50
	s_nop 1
	v_addc_co_u32_e32 v51, vcc, 0, v51, vcc
	global_store_dwordx4 v[50:51], v[46:49], off
	s_and_saveexec_b64 s[30:31], s[8:9]
	s_cbranch_execz .LBB0_668
	v_mul_f32_e32 v2, 0x3fb8aa3b, v2
	v_exp_f32_e32 v2, v2
	v_lshl_add_u64 v[38:39], v[38:39], 0, v[8:9]
	v_add_co_u32_e32 v38, vcc, 0x2000, v38
	s_nop 1
	v_addc_co_u32_e32 v39, vcc, 0, v39, vcc
	global_store_dword v[38:39], v2, off offset:2048
.LBB0_668:
	s_or_b64 exec, exec, s[30:31]
	v_lshlrev_b32_e32 v2, 16, v107
	v_mul_f32_e32 v2, 0x3e000000, v2
	v_cndmask_b32_e64 v38, 0, v2, s[14:15]
	v_cndmask_b32_e64 v2, v4, v6, s[6:7]
	v_mul_f32_e32 v4, 0x3fb8aa3b, v45
	v_exp_f32_e32 v4, v4
	s_nop 0
	v_mul_f32_e32 v4, v38, v4
	v_cvt_pk_bf16_f32 v4, v4, v4
	v_add_u32_e32 v6, v70, v71
	ds_write_b16_d16_hi v6, v4 offset:2048
	v_sub_f32_e32 v4, v45, v2
	v_mul_f32_e32 v4, 0x3fb8aa3b, v4
	v_exp_f32_e32 v4, v4
	s_nop 0
	v_mul_f32_e32 v4, v38, v4
	v_cvt_pk_bf16_f32 v4, v4, v4
	ds_write_b16_d16_hi v72, v4 offset:10240
	v_sub_f32_e32 v4, v2, v45
	v_mul_f32_e32 v4, 0x3fb8aa3b, v4
	v_exp_f32_e32 v4, v4
	s_nop 0
	v_mul_f32_e32 v4, v56, v4
	v_cvt_pk_bf16_f32 v4, v4, v4
	ds_write_b16_d16_hi v72, v4 offset:18944
	s_and_saveexec_b64 s[30:31], s[6:7]
	s_xor_b64 s[30:31], exec, s[30:31]
	s_cbranch_execz .LBB0_670
	v_sub_f32_e32 v4, v7, v45
	v_mul_f32_e32 v4, 0x3fb8aa3b, v4
	v_exp_f32_e32 v4, v4
	s_nop 0
	v_mul_f32_e32 v4, v56, v4
	v_cvt_pk_bf16_f32 v4, v4, v4
	ds_write_b16_d16_hi v72, v4 offset:32000
.LBB0_670:
	s_andn2_saveexec_b64 s[30:31], s[30:31]
	s_cbranch_execz .LBB0_672
	v_sub_f32_e32 v4, v45, v7
	v_mul_f32_e32 v4, 0x3fb8aa3b, v4
	v_exp_f32_e32 v4, v4
	s_nop 0
	v_mul_f32_e32 v4, v38, v4
	v_cvt_pk_bf16_f32 v4, v4, v4
	ds_write_b16_d16_hi v73, v4 offset:23296
.LBB0_672:
	s_or_b64 exec, exec, s[30:31]
	v_mul_f32_e32 v6, 0x3fb8aa3b, v44
	v_exp_f32_e32 v6, v6
	v_lshlrev_b32_e32 v4, 16, v110
	v_mul_f32_e32 v4, 0x3e000000, v4
	v_cndmask_b32_e64 v4, 0, v4, s[18:19]
	v_mul_f32_e32 v6, v4, v6
	v_cvt_pk_bf16_f32 v6, v6, v6
	v_add_u32_e32 v38, v70, v74
	ds_write_b16_d16_hi v38, v6 offset:2048
	v_sub_f32_e32 v6, v44, v2
	v_mul_f32_e32 v6, 0x3fb8aa3b, v6
	v_exp_f32_e32 v6, v6
	s_nop 0
	v_mul_f32_e32 v6, v4, v6
	v_cvt_pk_bf16_f32 v6, v6, v6
	ds_write_b16_d16_hi v75, v6 offset:10240
	v_sub_f32_e32 v6, v2, v44
	v_mul_f32_e32 v6, 0x3fb8aa3b, v6
	v_exp_f32_e32 v6, v6
	s_nop 0
	v_mul_f32_e32 v6, v58, v6
	v_cvt_pk_bf16_f32 v6, v6, v6
	ds_write_b16_d16_hi v75, v6 offset:18944
	s_and_saveexec_b64 s[30:31], s[6:7]
	s_xor_b64 s[30:31], exec, s[30:31]
	s_cbranch_execz .LBB0_674
	v_sub_f32_e32 v4, v7, v44
	v_mul_f32_e32 v4, 0x3fb8aa3b, v4
	v_exp_f32_e32 v4, v4
	s_nop 0
	v_mul_f32_e32 v4, v58, v4
	v_bfe_u32 v6, v4, 16, 1
	v_add3_u32 v4, v4, v6, s48
	ds_write_b16_d16_hi v75, v4 offset:32000
.LBB0_674:
	s_andn2_saveexec_b64 s[30:31], s[30:31]
	s_cbranch_execz .LBB0_676
	v_sub_f32_e32 v6, v44, v7
	v_mul_f32_e32 v6, 0x3fb8aa3b, v6
	v_exp_f32_e32 v6, v6
	s_nop 0
	v_mul_f32_e32 v4, v4, v6
	v_cvt_pk_bf16_f32 v4, v4, v4
	ds_write_b16_d16_hi v76, v4 offset:23296
.LBB0_676:
	s_or_b64 exec, exec, s[30:31]
	v_mul_f32_e32 v6, 0x3fb8aa3b, v43
	v_exp_f32_e32 v6, v6
	v_lshlrev_b32_e32 v4, 16, v114
	v_mul_f32_e32 v4, 0x3e000000, v4
	v_cndmask_b32_e64 v4, 0, v4, s[12:13]
	v_mul_f32_e32 v6, v4, v6
	v_cvt_pk_bf16_f32 v6, v6, v6
	v_add_u32_e32 v38, v70, v77
	ds_write_b16_d16_hi v38, v6 offset:2048
	v_sub_f32_e32 v6, v43, v2
	v_mul_f32_e32 v6, 0x3fb8aa3b, v6
	v_exp_f32_e32 v6, v6
	s_nop 0
	v_mul_f32_e32 v6, v4, v6
	v_cvt_pk_bf16_f32 v6, v6, v6
	ds_write_b16_d16_hi v78, v6 offset:10240
	v_sub_f32_e32 v6, v2, v43
	v_mul_f32_e32 v6, 0x3fb8aa3b, v6
	v_exp_f32_e32 v6, v6
	s_nop 0
	v_mul_f32_e32 v6, v57, v6
	v_cvt_pk_bf16_f32 v6, v6, v6
	ds_write_b16_d16_hi v78, v6 offset:18944
	s_and_saveexec_b64 s[30:31], s[6:7]
	s_xor_b64 s[30:31], exec, s[30:31]
	s_cbranch_execz .LBB0_678
	v_sub_f32_e32 v4, v7, v43
	v_mul_f32_e32 v4, 0x3fb8aa3b, v4
	v_exp_f32_e32 v4, v4
	s_nop 0
	v_mul_f32_e32 v4, v57, v4
	v_bfe_u32 v6, v4, 16, 1
	v_add3_u32 v4, v4, v6, s48
	ds_write_b16_d16_hi v78, v4 offset:32000
.LBB0_678:
	s_andn2_saveexec_b64 s[30:31], s[30:31]
	s_cbranch_execz .LBB0_680
	v_sub_f32_e32 v6, v43, v7
	v_mul_f32_e32 v6, 0x3fb8aa3b, v6
	v_exp_f32_e32 v6, v6
	s_nop 0
	v_mul_f32_e32 v4, v4, v6
	v_cvt_pk_bf16_f32 v4, v4, v4
	ds_write_b16_d16_hi v79, v4 offset:23296
.LBB0_680:
	s_or_b64 exec, exec, s[30:31]
	v_mul_f32_e32 v6, 0x3fb8aa3b, v42
	v_exp_f32_e32 v6, v6
	v_lshlrev_b32_e32 v4, 16, v116
	v_mul_f32_e32 v4, 0x3e000000, v4
	v_cndmask_b32_e64 v4, 0, v4, s[16:17]
	v_mul_f32_e32 v6, v4, v6
	v_cvt_pk_bf16_f32 v6, v6, v6
	v_add_u32_e32 v38, v70, v80
	ds_write_b16_d16_hi v38, v6 offset:2048
	v_sub_f32_e32 v6, v42, v2
	v_mul_f32_e32 v6, 0x3fb8aa3b, v6
	v_exp_f32_e32 v6, v6
	s_nop 0
	v_mul_f32_e32 v6, v4, v6
	v_cvt_pk_bf16_f32 v6, v6, v6
	ds_write_b16_d16_hi v81, v6 offset:10240
	v_sub_f32_e32 v6, v2, v42
	v_mul_f32_e32 v6, 0x3fb8aa3b, v6
	v_exp_f32_e32 v6, v6
	s_nop 0
	v_mul_f32_e32 v6, v59, v6
	v_cvt_pk_bf16_f32 v6, v6, v6
	ds_write_b16_d16_hi v81, v6 offset:18944
	s_and_saveexec_b64 s[30:31], s[6:7]
	s_xor_b64 s[30:31], exec, s[30:31]
	s_cbranch_execz .LBB0_682
	v_sub_f32_e32 v4, v7, v42
	v_mul_f32_e32 v4, 0x3fb8aa3b, v4
	v_exp_f32_e32 v4, v4
	s_nop 0
	v_mul_f32_e32 v4, v59, v4
	v_bfe_u32 v6, v4, 16, 1
	v_add3_u32 v4, v4, v6, s48
	ds_write_b16_d16_hi v81, v4 offset:32000
.LBB0_682:
	s_andn2_saveexec_b64 s[30:31], s[30:31]
	s_cbranch_execz .LBB0_684
	v_sub_f32_e32 v6, v42, v7
	v_mul_f32_e32 v6, 0x3fb8aa3b, v6
	v_exp_f32_e32 v6, v6
	s_nop 0
	v_mul_f32_e32 v4, v4, v6
	v_cvt_pk_bf16_f32 v4, v4, v4
	ds_write_b16_d16_hi v82, v4 offset:23296
.LBB0_684:
	s_or_b64 exec, exec, s[30:31]
	v_mul_f32_e32 v6, 0x3fb8aa3b, v41
	v_exp_f32_e32 v6, v6
	v_lshlrev_b32_e32 v4, 16, v119
	v_mul_f32_e32 v4, 0x3e000000, v4
	v_cndmask_b32_e64 v4, 0, v4, s[22:23]
	v_mul_f32_e32 v6, v4, v6
	v_cvt_pk_bf16_f32 v6, v6, v6
	v_add_u32_e32 v38, v70, v83
	ds_write_b16_d16_hi v38, v6 offset:2048
	v_sub_f32_e32 v6, v41, v2
	v_mul_f32_e32 v6, 0x3fb8aa3b, v6
	v_exp_f32_e32 v6, v6
	s_nop 0
	v_mul_f32_e32 v6, v4, v6
	v_cvt_pk_bf16_f32 v6, v6, v6
	ds_write_b16_d16_hi v84, v6 offset:10240
	v_sub_f32_e32 v6, v2, v41
	v_mul_f32_e32 v6, 0x3fb8aa3b, v6
	v_exp_f32_e32 v6, v6
	s_nop 0
	v_mul_f32_e32 v6, v60, v6
	v_cvt_pk_bf16_f32 v6, v6, v6
	ds_write_b16_d16_hi v84, v6 offset:18944
	s_and_saveexec_b64 s[30:31], s[6:7]
	s_xor_b64 s[30:31], exec, s[30:31]
	s_cbranch_execz .LBB0_686
	v_sub_f32_e32 v4, v7, v41
	v_mul_f32_e32 v4, 0x3fb8aa3b, v4
	v_exp_f32_e32 v4, v4
	s_nop 0
	v_mul_f32_e32 v4, v60, v4
	v_bfe_u32 v6, v4, 16, 1
	v_add3_u32 v4, v4, v6, s48
	ds_write_b16_d16_hi v84, v4 offset:32000
.LBB0_686:
	s_andn2_saveexec_b64 s[30:31], s[30:31]
	s_cbranch_execz .LBB0_688
	v_sub_f32_e32 v6, v41, v7
	v_mul_f32_e32 v6, 0x3fb8aa3b, v6
	v_exp_f32_e32 v6, v6
	s_nop 0
	v_mul_f32_e32 v4, v4, v6
	v_cvt_pk_bf16_f32 v4, v4, v4
	ds_write_b16_d16_hi v85, v4 offset:23296
.LBB0_688:
	s_or_b64 exec, exec, s[30:31]
	v_mul_f32_e32 v6, 0x3fb8aa3b, v40
	v_exp_f32_e32 v6, v6
	v_lshlrev_b32_e32 v4, 16, v121
	v_mul_f32_e32 v4, 0x3e000000, v4
	v_cndmask_b32_e64 v4, 0, v4, s[26:27]
	v_mul_f32_e32 v6, v4, v6
	v_cvt_pk_bf16_f32 v6, v6, v6
	v_add_u32_e32 v38, v70, v86
	ds_write_b16_d16_hi v38, v6 offset:2048
	v_sub_f32_e32 v6, v40, v2
	v_mul_f32_e32 v6, 0x3fb8aa3b, v6
	v_exp_f32_e32 v6, v6
	s_nop 0
	v_mul_f32_e32 v6, v4, v6
	v_cvt_pk_bf16_f32 v6, v6, v6
	ds_write_b16_d16_hi v87, v6 offset:10240
	v_sub_f32_e32 v6, v2, v40
	v_mul_f32_e32 v6, 0x3fb8aa3b, v6
	v_exp_f32_e32 v6, v6
	s_nop 0
	v_mul_f32_e32 v6, v0, v6
	v_cvt_pk_bf16_f32 v6, v6, v6
	ds_write_b16_d16_hi v87, v6 offset:18944
	s_and_saveexec_b64 s[30:31], s[6:7]
	s_xor_b64 s[30:31], exec, s[30:31]
	s_cbranch_execz .LBB0_690
	v_sub_f32_e32 v4, v7, v40
	v_mul_f32_e32 v4, 0x3fb8aa3b, v4
	v_exp_f32_e32 v4, v4
	s_nop 0
	v_mul_f32_e32 v0, v0, v4
	v_cvt_pk_bf16_f32 v0, v0, v0
	ds_write_b16_d16_hi v87, v0 offset:32000
.LBB0_690:
	s_andn2_saveexec_b64 s[30:31], s[30:31]
	s_cbranch_execz .LBB0_692
	v_sub_f32_e32 v0, v40, v7
	v_mul_f32_e32 v0, 0x3fb8aa3b, v0
	v_exp_f32_e32 v0, v0
	s_nop 0
	v_mul_f32_e32 v0, v4, v0
	v_cvt_pk_bf16_f32 v0, v0, v0
	ds_write_b16_d16_hi v88, v0 offset:23296
.LBB0_692:
	s_or_b64 exec, exec, s[30:31]
	v_mul_f32_e32 v4, 0x3fb8aa3b, v5
	v_exp_f32_e32 v4, v4
	v_lshlrev_b32_e32 v0, 16, v122
	v_mul_f32_e32 v0, 0x3e000000, v0
	v_cndmask_b32_e64 v0, 0, v0, s[20:21]
	v_mul_f32_e32 v4, v0, v4
	v_cvt_pk_bf16_f32 v4, v4, v4
	v_add_u32_e32 v6, v70, v89
	ds_write_b16_d16_hi v6, v4 offset:2048
	v_sub_f32_e32 v4, v5, v2
	v_mul_f32_e32 v4, 0x3fb8aa3b, v4
	v_exp_f32_e32 v4, v4
	s_nop 0
	v_mul_f32_e32 v4, v0, v4
	v_cvt_pk_bf16_f32 v4, v4, v4
	ds_write_b16_d16_hi v90, v4 offset:10240
	v_sub_f32_e32 v4, v2, v5
	v_mul_f32_e32 v4, 0x3fb8aa3b, v4
	v_exp_f32_e32 v4, v4
	s_nop 0
	v_mul_f32_e32 v4, v61, v4
	v_cvt_pk_bf16_f32 v4, v4, v4
	ds_write_b16_d16_hi v90, v4 offset:18944
	s_and_saveexec_b64 s[30:31], s[6:7]
	s_xor_b64 s[30:31], exec, s[30:31]
	s_cbranch_execz .LBB0_694
	v_sub_f32_e32 v0, v7, v5
	v_mul_f32_e32 v0, 0x3fb8aa3b, v0
	v_exp_f32_e32 v0, v0
	s_nop 0
	v_mul_f32_e32 v0, v61, v0
	v_bfe_u32 v4, v0, 16, 1
	v_add3_u32 v0, v0, v4, s48
	ds_write_b16_d16_hi v90, v0 offset:32000
.LBB0_694:
	s_andn2_saveexec_b64 s[30:31], s[30:31]
	s_cbranch_execz .LBB0_696
	v_sub_f32_e32 v4, v5, v7
	v_mul_f32_e32 v4, 0x3fb8aa3b, v4
	v_exp_f32_e32 v4, v4
	s_nop 0
	v_mul_f32_e32 v0, v0, v4
	v_cvt_pk_bf16_f32 v0, v0, v0
	ds_write_b16_d16_hi v91, v0 offset:23296
.LBB0_696:
	s_or_b64 exec, exec, s[30:31]
	v_mul_f32_e32 v4, 0x3fb8aa3b, v3
	v_exp_f32_e32 v4, v4
	v_lshlrev_b32_e32 v0, 16, v96
	v_mul_f32_e32 v0, 0x3e000000, v0
	v_cndmask_b32_e64 v0, 0, v0, s[24:25]
	v_mul_f32_e32 v4, v0, v4
	v_cvt_pk_bf16_f32 v4, v4, v4
	v_add_u32_e32 v5, v70, v92
	ds_write_b16_d16_hi v5, v4 offset:2048
	v_sub_f32_e32 v4, v3, v2
	v_mul_f32_e32 v4, 0x3fb8aa3b, v4
	v_exp_f32_e32 v4, v4
	v_sub_f32_e32 v2, v2, v3
	v_mul_f32_e32 v2, 0x3fb8aa3b, v2
	v_exp_f32_e32 v2, v2
	v_mul_f32_e32 v4, v0, v4
	v_cvt_pk_bf16_f32 v4, v4, v4
	v_mul_f32_e32 v2, v1, v2
	ds_write_b16_d16_hi v93, v4 offset:10240
	v_cvt_pk_bf16_f32 v2, v2, v2
	ds_write_b16_d16_hi v93, v2 offset:18944
	s_and_saveexec_b64 s[30:31], s[6:7]
	s_xor_b64 s[30:31], exec, s[30:31]
	s_cbranch_execz .LBB0_698
	v_sub_f32_e32 v0, v7, v3
	v_mul_f32_e32 v0, 0x3fb8aa3b, v0
	v_exp_f32_e32 v0, v0
	s_nop 0
	v_mul_f32_e32 v0, v1, v0
	v_bfe_u32 v1, v0, 16, 1
	v_add3_u32 v0, v0, v1, s48
	ds_write_b16_d16_hi v93, v0 offset:32000
.LBB0_698:
	s_andn2_saveexec_b64 s[30:31], s[30:31]
	s_cbranch_execz .LBB0_700
	v_sub_f32_e32 v1, v3, v7
	v_mul_f32_e32 v1, 0x3fb8aa3b, v1
	v_exp_f32_e32 v1, v1
	s_nop 0
	v_mul_f32_e32 v0, v0, v1
	v_cvt_pk_bf16_f32 v0, v0, v0
	ds_write_b16_d16_hi v94, v0 offset:23296

.LBB0_732:
	s_or_b64 exec, exec, s[12:13]
	s_or_b32 s12, s30, s49
	s_mul_hi_u32 s13, s12, 0x41
	s_add_i32 s13, s13, s31
	s_mulk_i32 s12, 0x41
	s_add_u32 s12, s12, s33
	s_addc_u32 s13, s13, s38
	s_or_b32 s14, s93, s28
	s_waitcnt vmcnt(0)
	v_or_b32_e32 v41, v5, v4
	s_lshl_b64 s[12:13], s[12:13], 13
	v_add_u32_e32 v6, s14, v69
	v_mov_b64_e32 v[4:5], s[82:83]
	v_or_b32_e32 v39, v1, v0
	v_lshl_add_u64 v[0:1], v[16:17], 0, s[12:13]
	v_mad_i64_i32 v[4:5], s[12:13], v6, s79, v[4:5]
	v_mad_u64_u32 v[6:7], s[12:13], v4, s44, v[20:21]
	s_add_i32 s12, s14, s76
	s_mul_hi_i32 s13, s12, 0x41
	s_mulk_i32 s12, 0x41
	s_add_u32 s12, s12, s82
	v_or_b32_e32 v38, v49, v48
	v_or_b32_e32 v40, v3, v2
	s_addc_u32 s13, s13, s83
	global_store_dwordx4 v[0:1], v[38:41], off
	v_add_u32_e32 v0, v98, v18
	s_mulk_i32 s13, 0x3000
	s_mul_hi_u32 s14, s12, 0x3000
	s_waitcnt lgkmcnt(0)
	s_barrier
	ds_read_b128 v[0:3], v0 offset:2048
	s_add_i32 s14, s14, s13
	s_mulk_i32 s12, 0x3000
	s_add_u32 s12, s54, s12
	s_addc_u32 s13, s55, s14
	s_add_u32 s12, s12, 0x2e894000
	v_mad_i32_i24 v7, v5, s44, v7
	s_addc_u32 s13, s13, 0
	s_andn2_b64 vcc, exec, s[58:59]
	s_mov_b64 s[14:15], -1
	s_waitcnt lgkmcnt(0)
	global_store_dwordx4 v[6:7], v[0:3], off
	s_cbranch_vccnz .LBB0_734
	ds_read_b128 v[0:3], v99
	ds_read_b128 v[4:7], v101
	s_mov_b64 s[14:15], 0
	s_waitcnt lgkmcnt(0)
	v_mfma_f32_16x16x32_bf16 v[0:3], v[0:3], v[4:7], 0
	ds_read_b128 v[4:7], v99 offset:64
	ds_read_b128 v[38:41], v101 offset:64
	s_waitcnt lgkmcnt(0)
	v_mfma_f32_16x16x32_bf16 v[0:3], v[4:7], v[38:41], v[0:3]
	v_lshl_add_u64 v[4:5], s[12:13], 0, v[22:23]
	s_nop 6
	v_cndmask_b32_e64 v0, v0, 0, s[60:61]
	s_nop 0
	v_cvt_pk_bf16_f32 v0, v0, v0
	v_lshl_add_u64 v[6:7], v[4:5], 0, v[24:25]
	global_store_short_d16_hi v[6:7], v0, off
	v_cndmask_b32_e64 v0, v1, 0, s[62:63]
	v_bfe_u32 v1, v0, 16, 1
	v_add3_u32 v6, v0, v1, s48
	v_lshl_add_u64 v[0:1], v[4:5], 0, v[26:27]
	global_store_short_d16_hi v[0:1], v6, off
	v_cndmask_b32_e64 v0, v2, 0, s[88:89]
	v_cvt_pk_bf16_f32 v2, v0, v0
	v_lshl_add_u64 v[0:1], v[4:5], 0, v[28:29]
	global_store_short_d16_hi v[0:1], v2, off
	v_cndmask_b32_e64 v0, v3, 0, s[66:67]
	v_bfe_u32 v1, v0, 16, 1
	v_add3_u32 v2, v0, v1, s48
	v_lshl_add_u64 v[0:1], v[4:5], 0, v[30:31]
	global_store_short_d16_hi v[0:1], v2, off

.LBB0_739:
	s_and_b64 vcc, exec, s[12:13]
	s_cbranch_vccz .LBB0_664
	s_movk_i32 s29, 0x810
	v_or_b32_e32 v38, 1, v103
	s_ashr_i32 s33, s92, 2
	v_cmp_gt_i32_e64 s[12:13], s29, v103
	v_cmp_gt_i32_e64 s[16:17], s29, v38
	s_mul_i32 s83, s33, 0x810
	v_cndmask_b32_e64 v0, 0, v103, s[12:13]
	v_cndmask_b32_e64 v38, 0, v38, s[16:17]
	v_add_u32_e32 v0, s83, v0
	v_mov_b64_e32 v[2:3], s[34:35]
	v_add_u32_e32 v47, s83, v38
	v_or_b32_e32 v46, 2, v103
	v_mad_i64_i32 v[4:5], s[14:15], v0, s44, v[2:3]
	v_mad_i64_i32 v[38:39], s[14:15], v47, s44, v[2:3]
	s_and_b32 s28, s92, 3
	v_cmp_gt_i32_e64 s[14:15], s29, v46
	s_lshl_b32 s86, s28, 7
	v_add_lshl_u32 v0, s86, v64, 1
	v_cndmask_b32_e64 v42, 0, v46, s[14:15]
	v_mov_b32_e32 v1, v97
	v_add_u32_e32 v42, s83, v42
	v_lshl_add_u64 v[6:7], v[4:5], 0, v[0:1]
	v_mad_i64_i32 v[42:43], s[18:19], v42, s44, v[2:3]
	v_lshl_add_u64 v[40:41], v[38:39], 0, v[0:1]
	v_lshl_add_u64 v[44:45], v[42:43], 0, v[0:1]
	global_load_ushort v54, v[6:7], off
	global_load_ushort v55, v[40:41], off
	global_load_ushort v56, v[44:45], off
	s_lshl_b32 s38, s28, 9
	v_lshl_add_u64 v[6:7], v[34:35], 0, s[38:39]
	global_load_dword v58, v[6:7], off
	v_or_b32_e32 v40, 3, v103
	v_or_b32_e32 v48, 4, v103
	v_cmp_gt_i32_e64 s[20:21], s29, v40
	s_lshl_b32 s22, s28, 1
	s_lshl_b32 s87, s33, 3
	v_cndmask_b32_e64 v40, 0, v40, s[20:21]
	v_cmp_gt_i32_e64 s[18:19], s29, v48
	s_or_b32 s38, s22, s87
	v_add_u32_e32 v49, s83, v40
	v_cndmask_b32_e64 v41, 0, v48, s[18:19]
	v_add_lshl_u32 v96, s86, v63, 1
	v_add_u32_e32 v44, s83, v41
	v_or_b32_e32 v50, s38, v62
	v_mad_i64_i32 v[40:41], s[22:23], v49, s44, v[2:3]
	v_mad_i64_i32 v[44:45], s[22:23], v44, s44, v[2:3]
	v_lshl_add_u32 v57, v50, 6, v50
	v_lshl_add_u64 v[4:5], v[4:5], 0, v[96:97]
	v_lshl_add_u64 v[50:51], v[40:41], 0, v[96:97]
	v_lshl_add_u64 v[38:39], v[38:39], 0, v[96:97]
	v_lshl_add_u64 v[42:43], v[42:43], 0, v[96:97]
	v_lshl_add_u64 v[40:41], v[40:41], 0, v[0:1]
	v_lshl_add_u64 v[52:53], v[44:45], 0, v[0:1]
	v_add_u32_e32 v59, s82, v57
	global_load_ushort v57, v[50:51], off
	global_load_ushort v60, v[42:43], off
	global_load_ushort v104, v[38:39], off
	global_load_ushort v105, v[4:5], off
	global_load_ushort v61, v[40:41], off
	global_load_ushort v107, v[52:53], off
	v_mov_b64_e32 v[6:7], s[56:57]
	v_mad_i64_i32 v[40:41], s[22:23], v59, s44, v[6:7]
	s_mov_b32 s49, 0x3f317217
	v_mov_b32_e32 v115, 0x41b17218
	v_or_b32_e32 v50, 6, v103
	s_waitcnt vmcnt(0)
	v_lshlrev_b32_e32 v4, 16, v54
	v_mul_f32_e32 v4, 0x3fb8aa3b, v4
	v_exp_f32_e32 v4, v4
	v_lshlrev_b32_e32 v5, 16, v55
	v_mul_f32_e32 v5, 0x3fb8aa3b, v5
	v_exp_f32_e32 v5, v5
	v_add_f32_e32 v4, 1.0, v4
	v_rcp_f32_e32 v4, v4
	v_lshlrev_b32_e32 v6, 16, v56
	v_sub_f32_e32 v56, 1.0, v58
	v_add_f32_e32 v5, 1.0, v5
	v_mul_f32_e32 v4, v56, v4
	v_rcp_f32_e32 v5, v5
	v_min_f32_e32 v59, 0x3f7ff972, v4
	v_sub_f32_e32 v4, 1.0, v59
	v_cmp_gt_f32_e32 vcc, s45, v4
	v_mul_f32_e32 v5, v56, v5
	v_min_f32_e32 v108, 0x3f7ff972, v5
	v_cndmask_b32_e64 v7, 0, 32, vcc
	v_ldexp_f32 v4, v4, v7
	v_log_f32_e32 v4, v4
	v_mul_f32_e32 v6, 0x3fb8aa3b, v6
	v_sub_f32_e32 v5, 1.0, v108
	v_exp_f32_e32 v6, v6
	v_cmp_gt_f32_e64 s[22:23], s45, v5
	v_cndmask_b32_e32 v7, 0, v115, vcc
	v_cmp_lt_f32_e64 vcc, |v4|, s95
	v_cndmask_b32_e64 v38, 0, 32, s[22:23]
	v_ldexp_f32 v5, v5, v38
	v_mul_f32_e32 v38, 0x3f317217, v4
	v_fma_f32 v38, v4, s49, -v38
	v_add_f32_e32 v6, 1.0, v6
	v_log_f32_e32 v5, v5
	v_fmac_f32_e32 v38, 0x3377d1cf, v4
	v_rcp_f32_e32 v6, v6
	v_fmac_f32_e32 v38, 0x3f317217, v4
	v_cndmask_b32_e32 v4, v4, v38, vcc
	v_sub_f32_e32 v4, v4, v7
	v_mul_f32_e32 v39, 0x3f317217, v5
	v_add_f32_e32 v4, 0, v4
	v_fma_f32 v39, v5, s49, -v39
	v_cndmask_b32_e64 v109, 0, v4, s[12:13]
	v_mul_f32_e32 v4, v56, v6
	v_fmac_f32_e32 v39, 0x3377d1cf, v5
	v_min_f32_e32 v110, 0x3f7ff972, v4
	v_fmac_f32_e32 v39, 0x3f317217, v5
	v_cmp_lt_f32_e64 vcc, |v5|, s95
	v_sub_f32_e32 v4, 1.0, v110
	s_nop 0
	v_cndmask_b32_e32 v38, v5, v39, vcc
	v_cmp_gt_f32_e32 vcc, s45, v4
	v_cndmask_b32_e64 v39, 0, v115, s[22:23]
	s_nop 0
	v_cndmask_b32_e64 v5, 0, 32, vcc
	v_ldexp_f32 v42, v4, v5
	v_or_b32_e32 v4, 5, v103
	v_cmp_gt_i32_e64 s[22:23], s29, v4
	v_log_f32_e32 v112, v42
	s_nop 0
	v_cndmask_b32_e64 v4, 0, v4, s[22:23]
	v_add_u32_e32 v51, s83, v4
	v_mad_i64_i32 v[4:5], s[24:25], v51, s44, v[2:3]
	v_lshl_add_u64 v[6:7], v[4:5], 0, v[0:1]
	global_load_ushort v111, v[6:7], off
	v_cmp_gt_i32_e64 s[24:25], s29, v50
	v_sub_f32_e32 v6, v38, v39
	v_cndmask_b32_e64 v6, 0, v6, s[16:17]
	v_cndmask_b32_e64 v38, 0, v50, s[24:25]
	v_add_u32_e32 v38, s83, v38
	v_mad_i64_i32 v[38:39], s[26:27], v38, s44, v[2:3]
	v_add_f32_e32 v113, v109, v6
	v_mul_f32_e32 v6, 0x3f317217, v112
	v_lshl_add_u64 v[42:43], v[38:39], 0, v[0:1]
	v_fma_f32 v114, v112, s49, -v6
	v_lshl_add_u64 v[6:7], v[44:45], 0, v[96:97]
	global_load_ushort v45, v[42:43], off
	v_or_b32_e32 v44, 7, v103
	v_cmp_gt_i32_e64 s[26:27], s29, v44
	v_lshl_add_u64 v[4:5], v[4:5], 0, v[96:97]
	v_lshl_add_u64 v[38:39], v[38:39], 0, v[96:97]
	v_cndmask_b32_e64 v42, 0, v44, s[26:27]
	v_add_u32_e32 v52, s83, v42
	v_mad_i64_i32 v[2:3], s[30:31], v52, s44, v[2:3]
	v_lshl_add_u64 v[42:43], v[2:3], 0, v[96:97]
	v_lshl_add_u64 v[0:1], v[2:3], 0, v[0:1]
	global_load_ushort v53, v[42:43], off
	global_load_ushort v54, v[38:39], off
	global_load_ushort v55, v[4:5], off
	global_load_ushort v58, v[6:7], off
	v_lshlrev_b32_e32 v4, 16, v61
	global_load_ushort v0, v[0:1], off
	v_mul_f32_e32 v4, 0x3fb8aa3b, v4
	v_exp_f32_e32 v4, v4
	v_cndmask_b32_e32 v6, 0, v115, vcc
	v_fmac_f32_e32 v114, 0x3377d1cf, v112
	v_fmac_f32_e32 v114, 0x3f317217, v112
	v_add_f32_e32 v4, 1.0, v4
	v_rcp_f32_e32 v4, v4
	v_cmp_lt_f32_e64 s[30:31], |v112|, s95
	v_cndmask_b32_e64 v38, 0, v59, s[12:13]
	v_mul_f32_e32 v2, v56, v4
	v_min_f32_e32 v2, 0x3f7ff972, v2
	v_sub_f32_e32 v3, 1.0, v2
	v_cmp_gt_f32_e32 vcc, s45, v3
	v_cndmask_b32_e64 v5, v112, v114, s[30:31]
	v_sub_f32_e32 v1, v5, v6
	v_cndmask_b32_e64 v4, 0, 32, vcc
	v_ldexp_f32 v3, v3, v4
	v_log_f32_e32 v3, v3
	v_lshlrev_b32_e32 v4, 16, v107
	v_cndmask_b32_e64 v1, 0, v1, s[14:15]
	v_mul_f32_e32 v4, 0x3fb8aa3b, v4
	v_add_f32_e32 v59, v113, v1
	v_mul_f32_e32 v1, 0x3f317217, v3
	v_exp_f32_e32 v4, v4
	v_fma_f32 v1, v3, s49, -v1
	v_fmac_f32_e32 v1, 0x3377d1cf, v3
	v_fmac_f32_e32 v1, 0x3f317217, v3
	v_cmp_lt_f32_e64 s[30:31], |v3|, s95
	v_cndmask_b32_e64 v7, 0, v2, s[20:21]
	s_barrier
	v_cndmask_b32_e64 v1, v3, v1, s[30:31]
	v_add_f32_e32 v3, 1.0, v4
	v_rcp_f32_e32 v3, v3
	v_cndmask_b32_e32 v4, 0, v115, vcc
	v_sub_f32_e32 v1, v1, v4
	v_cndmask_b32_e64 v1, 0, v1, s[20:21]
	v_mul_f32_e32 v3, v56, v3
	v_min_f32_e32 v4, 0x3f7ff972, v3
	v_sub_f32_e32 v3, 1.0, v4
	v_cmp_gt_f32_e32 vcc, s45, v3
	v_add_f32_e32 v61, v59, v1
	s_nop 0
	v_cndmask_b32_e64 v5, 0, 32, vcc
	v_ldexp_f32 v3, v3, v5
	v_log_f32_e32 v3, v3
	v_cndmask_b32_e64 v39, 0, v110, s[14:15]
	v_cndmask_b32_e64 v6, 0, v108, s[16:17]
	v_cndmask_b32_e64 v4, 0, v4, s[18:19]
	v_mul_f32_e32 v1, 0x3f317217, v3
	v_fma_f32 v1, v3, s49, -v1
	v_fmac_f32_e32 v1, 0x3377d1cf, v3
	v_fmac_f32_e32 v1, 0x3f317217, v3
	s_waitcnt vmcnt(6)
	v_lshlrev_b32_e32 v2, 16, v111
	v_mul_f32_e32 v2, 0x3fb8aa3b, v2
	v_exp_f32_e32 v2, v2
	v_cmp_lt_f32_e64 s[30:31], |v3|, s95
	v_add_f32_e32 v2, 1.0, v2
	v_rcp_f32_e32 v2, v2
	v_cndmask_b32_e64 v1, v3, v1, s[30:31]
	v_cndmask_b32_e32 v3, 0, v115, vcc
	v_sub_f32_e32 v1, v1, v3
	v_mul_f32_e32 v2, v56, v2
	v_min_f32_e32 v42, 0x3f7ff972, v2
	v_sub_f32_e32 v2, 1.0, v42
	v_cmp_gt_f32_e32 vcc, s45, v2
	v_cndmask_b32_e64 v1, 0, v1, s[18:19]
	s_waitcnt vmcnt(0)
	v_lshlrev_b32_e32 v0, 16, v0
	v_cndmask_b32_e64 v3, 0, 32, vcc
	v_ldexp_f32 v2, v2, v3
	v_lshlrev_b32_e32 v3, 16, v45
	v_mul_f32_e32 v3, 0x3fb8aa3b, v3
	v_exp_f32_e32 v3, v3
	v_log_f32_e32 v2, v2
	v_mul_f32_e32 v0, 0x3fb8aa3b, v0
	v_exp_f32_e32 v0, v0
	v_add_f32_e32 v3, 1.0, v3
	v_rcp_f32_e32 v3, v3
	v_mul_f32_e32 v5, 0x3f317217, v2
	v_fma_f32 v5, v2, s49, -v5
	v_fmac_f32_e32 v5, 0x3377d1cf, v2
	v_mul_f32_e32 v3, v56, v3
	v_fmac_f32_e32 v5, 0x3f317217, v2
	v_cmp_lt_f32_e64 s[30:31], |v2|, s95
	v_min_f32_e32 v3, 0x3f7ff972, v3
	v_add_f32_e32 v0, 1.0, v0
	v_cndmask_b32_e64 v2, v2, v5, s[30:31]
	v_sub_f32_e32 v5, 1.0, v3
	v_cmp_gt_f32_e64 s[30:31], s45, v5
	v_rcp_f32_e32 v0, v0
	s_nop 0
	v_cndmask_b32_e64 v43, 0, 32, s[30:31]
	v_ldexp_f32 v5, v5, v43
	v_log_f32_e32 v5, v5
	v_cndmask_b32_e32 v43, 0, v115, vcc
	v_sub_f32_e32 v2, v2, v43
	v_mul_f32_e32 v0, v56, v0
	v_mul_f32_e32 v43, 0x3f317217, v5
	v_fma_f32 v43, v5, s49, -v43
	v_fmac_f32_e32 v43, 0x3377d1cf, v5
	v_min_f32_e32 v0, 0x3f7ff972, v0
	v_fmac_f32_e32 v43, 0x3f317217, v5
	v_cmp_lt_f32_e64 vcc, |v5|, s95
	v_sub_f32_e32 v44, 1.0, v0
	v_cndmask_b32_e64 v2, 0, v2, s[22:23]
	v_cndmask_b32_e32 v5, v5, v43, vcc
	v_cmp_gt_f32_e32 vcc, s45, v44
	v_cndmask_b32_e64 v43, 0, v115, s[30:31]
	v_sub_f32_e32 v5, v5, v43
	v_cndmask_b32_e64 v45, 0, 32, vcc
	v_ldexp_f32 v44, v44, v45
	v_log_f32_e32 v44, v44
	v_cndmask_b32_e64 v43, 0, v5, s[24:25]
	v_cndmask_b32_e64 v5, 0, v3, s[24:25]
	v_add_f32_e32 v56, v61, v1
	v_mul_f32_e32 v3, 0x3f317217, v44
	v_fma_f32 v3, v44, s49, -v3
	v_fmac_f32_e32 v3, 0x3377d1cf, v44
	v_fmac_f32_e32 v3, 0x3f317217, v44
	v_cmp_lt_f32_e64 s[30:31], |v44|, s95
	v_add_f32_e32 v116, v56, v2
	v_add_f32_e32 v117, v116, v43
	v_cndmask_b32_e64 v3, v44, v3, s[30:31]
	v_cndmask_b32_e32 v44, 0, v115, vcc
	v_sub_f32_e32 v3, v3, v44
	v_cndmask_b32_e64 v3, 0, v3, s[26:27]
	v_add_f32_e32 v43, v117, v3
	ds_write_b32 v67, v43
	s_waitcnt lgkmcnt(0)
	s_barrier
	ds_read2st64_b32 v[44:45], v68 offset1:2
	ds_read2st64_b32 v[2:3], v68 offset0:4 offset1:6
	v_cndmask_b32_e64 v1, 0, v0, s[26:27]
	v_cndmask_b32_e64 v0, 0, v42, s[22:23]
	s_waitcnt lgkmcnt(1)
	v_add_f32_e32 v45, v44, v45
	s_waitcnt lgkmcnt(0)
	v_add_f32_e32 v42, v45, v2
	v_cndmask_b32_e64 v2, v42, v45, s[4:5]
	v_cndmask_b32_e64 v2, v2, v44, s[2:3]
	v_cndmask_b32_e64 v111, v2, 0, s[0:1]
	v_mov_b32_e32 v110, v3
	v_add_f32_e32 v108, v109, v111
	v_pk_add_f32 v[2:3], v[42:43], v[110:111]
	v_add_f32_e32 v107, v113, v111
	v_sub_f32_e32 v43, v2, v108
	v_mul_f32_e32 v43, 0x3fb8aa3b, v43
	v_exp_f32_e32 v112, v43
	v_sub_f32_e32 v43, v2, v107
	v_mul_f32_e32 v43, 0x3fb8aa3b, v43
	v_add_f32_e32 v96, v59, v111
	v_exp_f32_e32 v114, v43
	v_sub_f32_e32 v43, v2, v96
	v_add_f32_e32 v61, v61, v111
	v_mul_f32_e32 v43, 0x3fb8aa3b, v43
	v_exp_f32_e32 v113, v43
	v_sub_f32_e32 v43, v2, v61
	v_mul_f32_e32 v43, 0x3fb8aa3b, v43
	v_add_f32_e32 v59, v56, v111
	v_exp_f32_e32 v115, v43
	v_sub_f32_e32 v43, v2, v59
	v_add_f32_e32 v56, v116, v111
	v_mul_f32_e32 v43, 0x3fb8aa3b, v43
	v_exp_f32_e32 v110, v43
	v_sub_f32_e32 v43, v2, v56
	v_mul_f32_e32 v43, 0x3fb8aa3b, v43
	v_exp_f32_e32 v116, v43
	v_add_f32_e32 v43, v117, v111
	v_sub_f32_e32 v109, v2, v43
	v_mul_f32_e32 v109, 0x3fb8aa3b, v109
	v_exp_f32_e32 v111, v109
	v_sub_f32_e32 v109, v2, v3
	v_mul_f32_e32 v109, 0x3fb8aa3b, v109
	v_exp_f32_e32 v117, v109
	v_pk_mul_f32 v[114:115], v[6:7], v[114:115]
	v_pk_mul_f32 v[112:113], v[38:39], v[112:113]
	v_pk_mul_f32 v[110:111], v[4:5], v[110:111]
	v_pk_mul_f32 v[116:117], v[0:1], v[116:117]
	v_cvt_pk_bf16_f32 v116, v116, v116
	v_cvt_pk_bf16_f32 v109, v117, v117
	v_cvt_pk_bf16_f32 v114, v114, v114
	v_cvt_pk_bf16_f32 v115, v115, v115
	v_cvt_pk_bf16_f32 v111, v111, v111
	v_cvt_pk_bf16_f32 v110, v110, v110
	v_cvt_pk_bf16_f32 v113, v113, v113
	v_cvt_pk_bf16_f32 v112, v112, v112
	v_lshrrev_b32_e32 v110, 16, v110
	v_lshrrev_b32_e32 v111, 16, v111
	v_lshrrev_b32_e32 v117, 16, v112
	v_lshrrev_b32_e32 v118, 16, v113
	v_and_or_b32 v113, v109, s36, v111
	v_and_or_b32 v112, v116, s36, v110
	v_and_or_b32 v111, v115, s36, v118
	v_and_or_b32 v110, v114, s36, v117
	v_lshl_add_u64 v[114:115], v[40:41], 0, v[14:15]
	v_add_co_u32_e32 v114, vcc, 0x1000, v114
	s_nop 1
	v_addc_co_u32_e32 v115, vcc, 0, v115, vcc
	global_store_dwordx4 v[114:115], v[110:113], off
	s_and_saveexec_b64 s[30:31], s[8:9]
	s_cbranch_execz .LBB0_742
	v_mul_f32_e32 v2, 0x3fb8aa3b, v2
	v_exp_f32_e32 v2, v2
	v_lshl_add_u64 v[40:41], v[40:41], 0, v[36:37]
	v_add_co_u32_e32 v40, vcc, 0x2000, v40
	s_nop 1
	v_addc_co_u32_e32 v41, vcc, 0, v41, vcc
	global_store_dword v[40:41], v2, off offset:2048
.LBB0_742:
	s_or_b64 exec, exec, s[30:31]
	v_lshlrev_b32_e32 v2, 16, v105
	v_mul_f32_e32 v40, 0xbfb8aa3b, v2
	v_exp_f32_e32 v40, v40
	v_mul_f32_e32 v41, 0x3fb8aa3b, v108
	v_exp_f32_e32 v41, v41
	v_add_f32_e32 v40, 1.0, v40
	v_rcp_f32_e32 v40, v40
	s_nop 0
	v_mul_f32_e32 v2, v40, v2
	v_cndmask_b32_e64 v40, 0, v2, s[12:13]
	v_mul_f32_e32 v41, v40, v41
	v_cndmask_b32_e64 v2, v42, v44, s[6:7]
	v_cvt_pk_bf16_f32 v41, v41, v41
	v_add_u32_e32 v42, v70, v71
	ds_write_b16_d16_hi v42, v41 offset:2048
	v_sub_f32_e32 v41, v108, v2
	v_mul_f32_e32 v41, 0x3fb8aa3b, v41
	v_exp_f32_e32 v41, v41
	s_nop 0
	v_mul_f32_e32 v41, v40, v41
	v_cvt_pk_bf16_f32 v41, v41, v41
	ds_write_b16_d16_hi v72, v41 offset:10240
	v_sub_f32_e32 v41, v2, v108
	v_mul_f32_e32 v41, 0x3fb8aa3b, v41
	v_exp_f32_e32 v41, v41
	s_nop 0
	v_mul_f32_e32 v41, v38, v41
	v_cvt_pk_bf16_f32 v41, v41, v41
	ds_write_b16_d16_hi v72, v41 offset:18944
	s_and_saveexec_b64 s[30:31], s[6:7]
	s_xor_b64 s[30:31], exec, s[30:31]
	s_cbranch_execz .LBB0_744
	v_sub_f32_e32 v40, v45, v108
	v_mul_f32_e32 v40, 0x3fb8aa3b, v40
	v_exp_f32_e32 v40, v40
	s_nop 0
	v_mul_f32_e32 v38, v38, v40
	v_cvt_pk_bf16_f32 v38, v38, v38
	ds_write_b16_d16_hi v72, v38 offset:32000
.LBB0_744:
	s_andn2_saveexec_b64 s[30:31], s[30:31]
	s_cbranch_execz .LBB0_746
	v_sub_f32_e32 v38, v108, v45
	v_mul_f32_e32 v38, 0x3fb8aa3b, v38
	v_exp_f32_e32 v38, v38
	s_nop 0
	v_mul_f32_e32 v38, v40, v38
	v_cvt_pk_bf16_f32 v38, v38, v38
	ds_write_b16_d16_hi v73, v38 offset:23296
.LBB0_746:
	s_or_b64 exec, exec, s[30:31]
	v_lshlrev_b32_e32 v38, 16, v104
	v_mul_f32_e32 v40, 0xbfb8aa3b, v38
	v_exp_f32_e32 v40, v40
	s_nop 0
	v_add_f32_e32 v40, 1.0, v40
	v_rcp_f32_e32 v40, v40
	s_nop 0
	v_mul_f32_e32 v38, v40, v38
	v_mul_f32_e32 v40, 0x3fb8aa3b, v107
	v_exp_f32_e32 v40, v40
	v_cndmask_b32_e64 v38, 0, v38, s[16:17]
	v_mul_f32_e32 v40, v38, v40
	v_cvt_pk_bf16_f32 v40, v40, v40
	v_add_u32_e32 v41, v70, v74
	ds_write_b16_d16_hi v41, v40 offset:2048
	v_sub_f32_e32 v40, v107, v2
	v_mul_f32_e32 v40, 0x3fb8aa3b, v40
	v_exp_f32_e32 v40, v40
	s_nop 0
	v_mul_f32_e32 v40, v38, v40
	v_cvt_pk_bf16_f32 v40, v40, v40
	ds_write_b16_d16_hi v75, v40 offset:10240
	v_sub_f32_e32 v40, v2, v107
	v_mul_f32_e32 v40, 0x3fb8aa3b, v40
	v_exp_f32_e32 v40, v40
	s_nop 0
	v_mul_f32_e32 v40, v6, v40
	v_cvt_pk_bf16_f32 v40, v40, v40
	ds_write_b16_d16_hi v75, v40 offset:18944
	s_and_saveexec_b64 s[30:31], s[6:7]
	s_xor_b64 s[30:31], exec, s[30:31]
	s_cbranch_execz .LBB0_748
	v_sub_f32_e32 v38, v45, v107
	v_mul_f32_e32 v38, 0x3fb8aa3b, v38
	v_exp_f32_e32 v38, v38
	s_nop 0
	v_mul_f32_e32 v6, v6, v38
	v_cvt_pk_bf16_f32 v6, v6, v6
	ds_write_b16_d16_hi v75, v6 offset:32000
.LBB0_748:
	s_andn2_saveexec_b64 s[30:31], s[30:31]
	s_cbranch_execz .LBB0_750
	v_sub_f32_e32 v6, v107, v45
	v_mul_f32_e32 v6, 0x3fb8aa3b, v6
	v_exp_f32_e32 v6, v6
	s_nop 0
	v_mul_f32_e32 v6, v38, v6
	v_cvt_pk_bf16_f32 v6, v6, v6
	ds_write_b16_d16_hi v76, v6 offset:23296
.LBB0_750:
	s_or_b64 exec, exec, s[30:31]
	v_lshlrev_b32_e32 v6, 16, v60
	v_mul_f32_e32 v38, 0xbfb8aa3b, v6
	v_exp_f32_e32 v38, v38
	s_nop 0
	v_add_f32_e32 v38, 1.0, v38
	v_rcp_f32_e32 v38, v38
	s_nop 0
	v_mul_f32_e32 v6, v38, v6
	v_mul_f32_e32 v38, 0x3fb8aa3b, v96
	v_exp_f32_e32 v38, v38
	v_cndmask_b32_e64 v6, 0, v6, s[14:15]
	v_mul_f32_e32 v38, v6, v38
	v_cvt_pk_bf16_f32 v38, v38, v38
	v_add_u32_e32 v40, v70, v77
	ds_write_b16_d16_hi v40, v38 offset:2048
	v_sub_f32_e32 v38, v96, v2
	v_mul_f32_e32 v38, 0x3fb8aa3b, v38
	v_exp_f32_e32 v38, v38
	s_nop 0
	v_mul_f32_e32 v38, v6, v38
	v_cvt_pk_bf16_f32 v38, v38, v38
	ds_write_b16_d16_hi v78, v38 offset:10240
	v_sub_f32_e32 v38, v2, v96
	v_mul_f32_e32 v38, 0x3fb8aa3b, v38
	v_exp_f32_e32 v38, v38
	s_nop 0
	v_mul_f32_e32 v38, v39, v38
	v_cvt_pk_bf16_f32 v38, v38, v38
	ds_write_b16_d16_hi v78, v38 offset:18944
	s_and_saveexec_b64 s[30:31], s[6:7]
	s_xor_b64 s[30:31], exec, s[30:31]
	s_cbranch_execz .LBB0_752
	v_sub_f32_e32 v6, v45, v96
	v_mul_f32_e32 v6, 0x3fb8aa3b, v6
	v_exp_f32_e32 v6, v6
	s_nop 0
	v_mul_f32_e32 v6, v39, v6
	v_bfe_u32 v38, v6, 16, 1
	v_add3_u32 v6, v6, v38, s48
	ds_write_b16_d16_hi v78, v6 offset:32000
.LBB0_752:
	s_andn2_saveexec_b64 s[30:31], s[30:31]
	s_cbranch_execz .LBB0_754
	v_sub_f32_e32 v38, v96, v45
	v_mul_f32_e32 v38, 0x3fb8aa3b, v38
	v_exp_f32_e32 v38, v38
	s_nop 0
	v_mul_f32_e32 v6, v6, v38
	v_cvt_pk_bf16_f32 v6, v6, v6
	ds_write_b16_d16_hi v79, v6 offset:23296
.LBB0_754:
	s_or_b64 exec, exec, s[30:31]
	v_lshlrev_b32_e32 v6, 16, v57
	v_mul_f32_e32 v38, 0xbfb8aa3b, v6
	v_exp_f32_e32 v38, v38
	s_nop 0
	v_add_f32_e32 v38, 1.0, v38
	v_rcp_f32_e32 v38, v38
	s_nop 0
	v_mul_f32_e32 v6, v38, v6
	v_mul_f32_e32 v38, 0x3fb8aa3b, v61
	v_exp_f32_e32 v38, v38
	v_cndmask_b32_e64 v6, 0, v6, s[20:21]
	v_mul_f32_e32 v38, v6, v38
	v_cvt_pk_bf16_f32 v38, v38, v38
	v_add_u32_e32 v39, v70, v80
	ds_write_b16_d16_hi v39, v38 offset:2048
	v_sub_f32_e32 v38, v61, v2
	v_mul_f32_e32 v38, 0x3fb8aa3b, v38
	v_exp_f32_e32 v38, v38
	s_nop 0
	v_mul_f32_e32 v38, v6, v38
	v_cvt_pk_bf16_f32 v38, v38, v38
	ds_write_b16_d16_hi v81, v38 offset:10240
	v_sub_f32_e32 v38, v2, v61
	v_mul_f32_e32 v38, 0x3fb8aa3b, v38
	v_exp_f32_e32 v38, v38
	s_nop 0
	v_mul_f32_e32 v38, v7, v38
	v_cvt_pk_bf16_f32 v38, v38, v38
	ds_write_b16_d16_hi v81, v38 offset:18944
	s_and_saveexec_b64 s[30:31], s[6:7]
	s_xor_b64 s[30:31], exec, s[30:31]
	s_cbranch_execz .LBB0_756
	v_sub_f32_e32 v6, v45, v61
	v_mul_f32_e32 v6, 0x3fb8aa3b, v6
	v_exp_f32_e32 v6, v6
	s_nop 0
	v_mul_f32_e32 v6, v7, v6
	v_bfe_u32 v7, v6, 16, 1
	v_add3_u32 v6, v6, v7, s48
	ds_write_b16_d16_hi v81, v6 offset:32000
.LBB0_756:
	s_andn2_saveexec_b64 s[30:31], s[30:31]
	s_cbranch_execz .LBB0_758
	v_sub_f32_e32 v7, v61, v45
	v_mul_f32_e32 v7, 0x3fb8aa3b, v7
	v_exp_f32_e32 v7, v7
	s_nop 0
	v_mul_f32_e32 v6, v6, v7
	v_cvt_pk_bf16_f32 v6, v6, v6
	ds_write_b16_d16_hi v82, v6 offset:23296
.LBB0_758:
	s_or_b64 exec, exec, s[30:31]
	v_lshlrev_b32_e32 v6, 16, v58
	v_mul_f32_e32 v7, 0xbfb8aa3b, v6
	v_exp_f32_e32 v7, v7
	s_nop 0
	v_add_f32_e32 v7, 1.0, v7
	v_rcp_f32_e32 v7, v7
	s_nop 0
	v_mul_f32_e32 v6, v7, v6
	v_mul_f32_e32 v7, 0x3fb8aa3b, v59
	v_exp_f32_e32 v7, v7
	v_cndmask_b32_e64 v6, 0, v6, s[18:19]
	v_mul_f32_e32 v7, v6, v7
	v_cvt_pk_bf16_f32 v7, v7, v7
	v_add_u32_e32 v38, v70, v83
	ds_write_b16_d16_hi v38, v7 offset:2048
	v_sub_f32_e32 v7, v59, v2
	v_mul_f32_e32 v7, 0x3fb8aa3b, v7
	v_exp_f32_e32 v7, v7
	s_nop 0
	v_mul_f32_e32 v7, v6, v7
	v_cvt_pk_bf16_f32 v7, v7, v7
	ds_write_b16_d16_hi v84, v7 offset:10240
	v_sub_f32_e32 v7, v2, v59
	v_mul_f32_e32 v7, 0x3fb8aa3b, v7
	v_exp_f32_e32 v7, v7
	s_nop 0
	v_mul_f32_e32 v7, v4, v7
	v_cvt_pk_bf16_f32 v7, v7, v7
	ds_write_b16_d16_hi v84, v7 offset:18944
	s_and_saveexec_b64 s[30:31], s[6:7]
	s_xor_b64 s[30:31], exec, s[30:31]
	s_cbranch_execz .LBB0_760
	v_sub_f32_e32 v6, v45, v59
	v_mul_f32_e32 v6, 0x3fb8aa3b, v6
	v_exp_f32_e32 v6, v6
	s_nop 0
	v_mul_f32_e32 v4, v4, v6
	v_cvt_pk_bf16_f32 v4, v4, v4
	ds_write_b16_d16_hi v84, v4 offset:32000
.LBB0_760:
	s_andn2_saveexec_b64 s[30:31], s[30:31]
	s_cbranch_execz .LBB0_762
	v_sub_f32_e32 v4, v59, v45
	v_mul_f32_e32 v4, 0x3fb8aa3b, v4
	v_exp_f32_e32 v4, v4
	s_nop 0
	v_mul_f32_e32 v4, v6, v4
	v_cvt_pk_bf16_f32 v4, v4, v4
	ds_write_b16_d16_hi v85, v4 offset:23296
.LBB0_762:
	s_or_b64 exec, exec, s[30:31]
	v_lshlrev_b32_e32 v4, 16, v55
	v_mul_f32_e32 v6, 0xbfb8aa3b, v4
	v_exp_f32_e32 v6, v6
	s_nop 0
	v_add_f32_e32 v6, 1.0, v6
	v_rcp_f32_e32 v6, v6
	s_nop 0
	v_mul_f32_e32 v4, v6, v4
	v_mul_f32_e32 v6, 0x3fb8aa3b, v56
	v_exp_f32_e32 v6, v6
	v_cndmask_b32_e64 v4, 0, v4, s[22:23]
	v_mul_f32_e32 v6, v4, v6
	v_cvt_pk_bf16_f32 v6, v6, v6
	v_add_u32_e32 v7, v70, v86
	ds_write_b16_d16_hi v7, v6 offset:2048
	v_sub_f32_e32 v6, v56, v2
	v_mul_f32_e32 v6, 0x3fb8aa3b, v6
	v_exp_f32_e32 v6, v6
	s_nop 0
	v_mul_f32_e32 v6, v4, v6
	v_cvt_pk_bf16_f32 v6, v6, v6
	ds_write_b16_d16_hi v87, v6 offset:10240
	v_sub_f32_e32 v6, v2, v56
	v_mul_f32_e32 v6, 0x3fb8aa3b, v6
	v_exp_f32_e32 v6, v6
	s_nop 0
	v_mul_f32_e32 v6, v0, v6
	v_cvt_pk_bf16_f32 v6, v6, v6
	ds_write_b16_d16_hi v87, v6 offset:18944
	s_and_saveexec_b64 s[30:31], s[6:7]
	s_xor_b64 s[30:31], exec, s[30:31]
	s_cbranch_execz .LBB0_764
	v_sub_f32_e32 v4, v45, v56
	v_mul_f32_e32 v4, 0x3fb8aa3b, v4
	v_exp_f32_e32 v4, v4
	s_nop 0
	v_mul_f32_e32 v0, v0, v4
	v_cvt_pk_bf16_f32 v0, v0, v0
	ds_write_b16_d16_hi v87, v0 offset:32000
.LBB0_764:
	s_andn2_saveexec_b64 s[30:31], s[30:31]
	s_cbranch_execz .LBB0_766
	v_sub_f32_e32 v0, v56, v45
	v_mul_f32_e32 v0, 0x3fb8aa3b, v0
	v_exp_f32_e32 v0, v0
	s_nop 0
	v_mul_f32_e32 v0, v4, v0
	v_cvt_pk_bf16_f32 v0, v0, v0
	ds_write_b16_d16_hi v88, v0 offset:23296
.LBB0_766:
	s_or_b64 exec, exec, s[30:31]
	v_lshlrev_b32_e32 v0, 16, v54
	v_mul_f32_e32 v4, 0xbfb8aa3b, v0
	v_exp_f32_e32 v4, v4
	s_nop 0
	v_add_f32_e32 v4, 1.0, v4
	v_rcp_f32_e32 v4, v4
	s_nop 0
	v_mul_f32_e32 v0, v4, v0
	v_mul_f32_e32 v4, 0x3fb8aa3b, v43
	v_exp_f32_e32 v4, v4
	v_cndmask_b32_e64 v0, 0, v0, s[24:25]
	v_mul_f32_e32 v4, v0, v4
	v_cvt_pk_bf16_f32 v4, v4, v4
	v_add_u32_e32 v6, v70, v89
	ds_write_b16_d16_hi v6, v4 offset:2048
	v_sub_f32_e32 v4, v43, v2
	v_mul_f32_e32 v4, 0x3fb8aa3b, v4
	v_exp_f32_e32 v4, v4
	s_nop 0
	v_mul_f32_e32 v4, v0, v4
	v_cvt_pk_bf16_f32 v4, v4, v4
	ds_write_b16_d16_hi v90, v4 offset:10240
	v_sub_f32_e32 v4, v2, v43
	v_mul_f32_e32 v4, 0x3fb8aa3b, v4
	v_exp_f32_e32 v4, v4
	s_nop 0
	v_mul_f32_e32 v4, v5, v4
	v_cvt_pk_bf16_f32 v4, v4, v4
	ds_write_b16_d16_hi v90, v4 offset:18944
	s_and_saveexec_b64 s[30:31], s[6:7]
	s_xor_b64 s[30:31], exec, s[30:31]
	s_cbranch_execz .LBB0_768
	v_sub_f32_e32 v0, v45, v43
	v_mul_f32_e32 v0, 0x3fb8aa3b, v0
	v_exp_f32_e32 v0, v0
	s_nop 0
	v_mul_f32_e32 v0, v5, v0
	v_bfe_u32 v4, v0, 16, 1
	v_add3_u32 v0, v0, v4, s48
	ds_write_b16_d16_hi v90, v0 offset:32000
.LBB0_768:
	s_andn2_saveexec_b64 s[30:31], s[30:31]
	s_cbranch_execz .LBB0_770
	v_sub_f32_e32 v4, v43, v45
	v_mul_f32_e32 v4, 0x3fb8aa3b, v4
	v_exp_f32_e32 v4, v4
	s_nop 0
	v_mul_f32_e32 v0, v0, v4
	v_cvt_pk_bf16_f32 v0, v0, v0
	ds_write_b16_d16_hi v91, v0 offset:23296
.LBB0_770:
	s_or_b64 exec, exec, s[30:31]
	v_lshlrev_b32_e32 v0, 16, v53
	v_mul_f32_e32 v4, 0xbfb8aa3b, v0
	v_exp_f32_e32 v4, v4
	s_nop 0
	v_add_f32_e32 v4, 1.0, v4
	v_rcp_f32_e32 v4, v4
	s_nop 0
	v_mul_f32_e32 v0, v4, v0
	v_mul_f32_e32 v4, 0x3fb8aa3b, v3
	v_exp_f32_e32 v4, v4
	v_cndmask_b32_e64 v0, 0, v0, s[26:27]
	v_mul_f32_e32 v4, v0, v4
	v_cvt_pk_bf16_f32 v4, v4, v4
	v_add_u32_e32 v5, v70, v92
	ds_write_b16_d16_hi v5, v4 offset:2048
	v_sub_f32_e32 v4, v3, v2
	v_mul_f32_e32 v4, 0x3fb8aa3b, v4
	v_exp_f32_e32 v4, v4
	v_sub_f32_e32 v2, v2, v3
	v_mul_f32_e32 v2, 0x3fb8aa3b, v2
	v_exp_f32_e32 v2, v2
	v_mul_f32_e32 v4, v0, v4
	v_cvt_pk_bf16_f32 v4, v4, v4
	v_mul_f32_e32 v2, v1, v2
	ds_write_b16_d16_hi v93, v4 offset:10240
	v_cvt_pk_bf16_f32 v2, v2, v2
	ds_write_b16_d16_hi v93, v2 offset:18944
	s_and_saveexec_b64 s[30:31], s[6:7]
	s_xor_b64 s[30:31], exec, s[30:31]
	s_cbranch_execz .LBB0_772
	v_sub_f32_e32 v0, v45, v3
	v_mul_f32_e32 v0, 0x3fb8aa3b, v0
	v_exp_f32_e32 v0, v0
	s_nop 0
	v_mul_f32_e32 v0, v1, v0
	v_bfe_u32 v1, v0, 16, 1
	v_add3_u32 v0, v0, v1, s48
	ds_write_b16_d16_hi v93, v0 offset:32000
.LBB0_772:
	s_andn2_saveexec_b64 s[30:31], s[30:31]
	s_cbranch_execz .LBB0_774
	v_sub_f32_e32 v1, v3, v45
	v_mul_f32_e32 v1, 0x3fb8aa3b, v1
	v_exp_f32_e32 v1, v1
	s_nop 0
	v_mul_f32_e32 v0, v0, v1
	v_cvt_pk_bf16_f32 v0, v0, v0
	ds_write_b16_d16_hi v94, v0 offset:23296

.LBB0_790:
	s_or_b64 exec, exec, s[12:13]
	s_ashr_i32 s12, s33, 31
	s_or_b32 s13, s87, s28
	s_mul_hi_u32 s14, s13, 0x41
	s_mulk_i32 s12, 0x41
	s_ashr_i32 s83, s82, 31
	s_add_i32 s14, s14, s12
	s_mulk_i32 s13, 0x41
	s_add_u32 s12, s13, s82
	s_addc_u32 s13, s14, s83
	s_lshl_b64 s[12:13], s[12:13], 13
	s_waitcnt vmcnt(0)
	v_or_b32_e32 v0, v3, v2
	v_or_b32_e32 v1, v5, v4
	v_or_b32_e32 v2, v7, v6
	v_or_b32_e32 v3, v39, v38
	v_lshl_add_u64 v[4:5], v[16:17], 0, s[12:13]
	global_store_dwordx4 v[4:5], v[0:3], off
	v_add_u32_e32 v4, s38, v69
	s_waitcnt lgkmcnt(0)
	v_add_u32_e32 v0, v98, v18
	s_barrier
	ds_read_b128 v[0:3], v0 offset:2048
	v_lshl_add_u32 v4, v4, 6, v4
	v_ashrrev_i32_e32 v5, 31, v4
	v_lshl_add_u64 v[4:5], v[4:5], 0, s[82:83]
	v_mad_u64_u32 v[6:7], s[12:13], v4, s44, v[20:21]
	v_mad_i32_i24 v7, v5, s44, v7
	s_andn2_b64 vcc, exec, s[70:71]
	s_waitcnt lgkmcnt(0)
	global_store_dwordx4 v[6:7], v[0:3], off
	s_cbranch_vccnz .LBB0_664
	s_mul_i32 s12, s38, 0x41
	s_add_i32 s12, s12, s82
	s_mul_hi_i32 s13, s12, 0x3000
	s_mulk_i32 s12, 0x3000
	s_add_u32 s12, s54, s12
	s_addc_u32 s13, s55, s13
	s_add_u32 s12, s12, 0x2e894000
	s_addc_u32 s13, s13, 0
	s_andn2_b64 vcc, exec, s[58:59]
	s_mov_b64 s[14:15], -1
	s_cbranch_vccnz .LBB0_793
	ds_read_b128 v[0:3], v19
	ds_read_b128 v[4:7], v100
	s_mov_b64 s[14:15], 0
	s_waitcnt lgkmcnt(0)
	v_mfma_f32_16x16x32_bf16 v[0:3], v[0:3], v[4:7], 0
	ds_read_b128 v[4:7], v19 offset:64
	ds_read_b128 v[38:41], v100 offset:64
	s_waitcnt lgkmcnt(0)
	v_mfma_f32_16x16x32_bf16 v[0:3], v[4:7], v[38:41], v[0:3]
	ds_read_b128 v[4:7], v19 offset:128
	ds_read_b128 v[38:41], v100 offset:128
	s_waitcnt lgkmcnt(0)
	v_mfma_f32_16x16x32_bf16 v[0:3], v[4:7], v[38:41], v[0:3]
	ds_read_b128 v[4:7], v19 offset:192
	ds_read_b128 v[38:41], v100 offset:192
	s_waitcnt lgkmcnt(0)
	v_mfma_f32_16x16x32_bf16 v[0:3], v[4:7], v[38:41], v[0:3]
	v_lshl_add_u64 v[4:5], s[12:13], 0, v[22:23]
	s_nop 6
	v_cndmask_b32_e64 v0, v0, 0, s[60:61]
	s_nop 0
	v_cvt_pk_bf16_f32 v0, v0, v0
	v_lshl_add_u64 v[6:7], v[4:5], 0, v[24:25]
	global_store_short_d16_hi v[6:7], v0, off
	v_cndmask_b32_e64 v0, v1, 0, s[62:63]
	v_bfe_u32 v1, v0, 16, 1
	v_add3_u32 v6, v0, v1, s48
	v_lshl_add_u64 v[0:1], v[4:5], 0, v[26:27]
	global_store_short_d16_hi v[0:1], v6, off
	v_cndmask_b32_e64 v0, v2, 0, s[88:89]
	v_cvt_pk_bf16_f32 v2, v0, v0
	v_lshl_add_u64 v[0:1], v[4:5], 0, v[28:29]
	global_store_short_d16_hi v[0:1], v2, off
	v_cndmask_b32_e64 v0, v3, 0, s[66:67]
	v_bfe_u32 v1, v0, 16, 1
	v_add3_u32 v2, v0, v1, s48
	v_lshl_add_u64 v[0:1], v[4:5], 0, v[30:31]
	global_store_short_d16_hi v[0:1], v2, off

.LBB0_800:
	s_mul_hi_i32 s0, s66, 0x7e07e07f
	s_lshr_b32 s1, s0, 31
	s_ashr_i32 s8, s0, 5
	s_add_i32 s8, s8, s1
	s_mul_i32 s0, s8, 0x41
	s_sub_i32 s12, s66, s0
	s_ashr_i32 s13, s8, 3
	s_lshl_b32 s10, s12, 5
	s_cmp_lg_u32 s12, 64
	v_and_b32_e32 v107, 31, v136
	s_cselect_b64 s[0:1], -1, 0
	v_or_b32_e32 v4, s10, v107
	v_cmp_gt_u32_e32 vcc, 16, v107
	v_ashrrev_i32_e32 v0, 31, v4
	s_or_b64 s[2:3], s[0:1], vcc
	v_cndmask_b32_e64 v1, 0, v0, s[2:3]
	v_cndmask_b32_e64 v0, 0, v4, s[2:3]
	v_mov_b32_e32 v2, 0x810
	v_ashrrev_i32_e32 v138, 5, v136
	v_mad_i64_i32 v[0:1], s[4:5], s13, v2, v[0:1]
	v_mov_b64_e32 v[2:3], s[56:57]
	v_mad_u64_u32 v[2:3], s[4:5], v0, s44, v[2:3]
	v_lshlrev_b32_e32 v68, 3, v138
	v_mad_i32_i24 v3, v1, s44, v3
	v_ashrrev_i32_e32 v69, 31, v68
	v_lshl_add_u64 v[102:103], v[68:69], 1, v[2:3]
	v_cmp_lt_i32_e64 s[4:5], 0, v4
	s_and_b32 s14, s8, 7
	s_lshl_b32 s11, s14, 6
	s_mul_hi_i32 s7, s13, 0x810
	s_mul_i32 s6, s13, 0x810
	v_or_b32_e32 v134, s34, v107
	v_or_b32_e32 v134, s11, v134
	v_mov_b32_e32 v135, s35
	v_lshlrev_b64 v[110:111], 7, v[134:135]
	v_lshlrev_b64 v[114:115], 8, v[134:135]
	v_lshl_add_u64 v[110:111], s[92:93], 0, v[110:111]
	v_lshl_add_u64 v[114:115], s[92:93], 0, v[114:115]
	v_lshl_add_u64 v[110:111], v[68:69], 1, v[110:111]
	v_lshl_add_u64 v[114:115], v[68:69], 1, v[114:115]
	s_mov_b64 s[100:101], 0x800
	v_lshl_add_u64 v[110:111], v[110:111], 0, s[100:101]
	s_mov_b64 s[100:101], 0x40000
	v_lshl_add_u64 v[112:113], v[110:111], 0, s[100:101]
	s_mov_b64 s[100:101], 0x80000
	v_lshl_add_u64 v[114:115], v[114:115], 0, s[100:101]
	s_mov_b64 s[100:101], 0x2000
	v_lshl_add_u64 v[116:117], v[114:115], 0, s[100:101]
	v_lshl_add_u64 v[108:109], v[68:69], 2, s[60:61]
	s_mov_b64 s[100:101], 0x1800
	v_lshl_add_u64 v[108:109], v[108:109], 0, s[100:101]
	s_mov_b32 s100, 0xffffdc00
	s_mov_b32 s101, -1
	v_lshl_add_u64 v[104:105], v[102:103], 0, s[100:101]
	s_mov_b64 s[100:101], 0xc00
	v_lshl_add_u64 v[134:135], v[102:103], 0, s[100:101]
	v_cndmask_b32_e64 v104, v134, v104, s[4:5]
	v_cndmask_b32_e64 v105, v135, v105, s[4:5]
	global_load_dwordx4 v[192:195], v[110:111], off offset:-2048
	global_load_dwordx4 v[196:199], v[110:111], off offset:2048
	global_load_dwordx4 v[144:147], v[102:103], off offset:3072
	global_load_dwordx4 v[148:151], v[104:105], off
	global_load_dwordx4 v[152:155], v[108:109], off
	global_load_dwordx4 v[156:159], v[108:109], off offset:16
	global_load_dword v212, v[102:103], off offset:3200
	global_load_dword v213, v[102:103], off offset:3328
	global_load_dword v214, v[102:103], off offset:3456
	global_load_dword v139, v[104:105], off offset:128
	global_load_dword v244, v[104:105], off offset:256
	global_load_dword v245, v[104:105], off offset:384
	global_load_dwordx4 v[200:203], v[110:111], off offset:-2016
	global_load_dwordx4 v[204:207], v[110:111], off offset:2080
	global_load_dwordx4 v[160:163], v[102:103], off offset:3104
	global_load_dwordx4 v[164:167], v[104:105], off offset:32
	global_load_dwordx4 v[168:171], v[108:109], off offset:64
	global_load_dwordx4 v[172:175], v[108:109], off offset:80
	global_load_dwordx4 v[208:211], v[110:111], off offset:-1984
	global_load_dwordx4 v[222:225], v[110:111], off offset:2112
	global_load_dwordx4 v[176:179], v[102:103], off offset:3136
	global_load_dwordx4 v[180:183], v[104:105], off offset:64
	global_load_dwordx4 v[184:187], v[108:109], off offset:128
	global_load_dwordx4 v[188:191], v[108:109], off offset:144
	global_load_dwordx4 v[226:229], v[110:111], off offset:-1952
	global_load_dwordx4 v[238:241], v[110:111], off offset:2144
	s_waitcnt vmcnt(20)
	v_lshlrev_b32_e32 v118, 16, v144
	v_and_b32_e32 v119, 0xffff0000, v144
	v_lshlrev_b32_e32 v120, 16, v145
	v_and_b32_e32 v121, 0xffff0000, v145
	v_lshlrev_b32_e32 v122, 16, v146
	v_and_b32_e32 v123, 0xffff0000, v146
	v_lshlrev_b32_e32 v124, 16, v147
	v_and_b32_e32 v125, 0xffff0000, v147
	v_cndmask_b32_e64 v148, 0, v148, s[4:5]
	v_cndmask_b32_e64 v149, 0, v149, s[4:5]
	v_cndmask_b32_e64 v150, 0, v150, s[4:5]
	v_cndmask_b32_e64 v151, 0, v151, s[4:5]
	v_lshlrev_b32_e32 v126, 16, v148
	v_and_b32_e32 v127, 0xffff0000, v148
	v_lshlrev_b32_e32 v128, 16, v149
	v_and_b32_e32 v129, 0xffff0000, v149
	v_lshlrev_b32_e32 v130, 16, v150
	v_and_b32_e32 v131, 0xffff0000, v150
	v_lshlrev_b32_e32 v132, 16, v151
	v_and_b32_e32 v133, 0xffff0000, v151
	global_load_dwordx4 v[144:147], v[102:103], off offset:3168
	global_load_dwordx4 v[148:151], v[104:105], off offset:96
	v_sub_f32_e32 v126, v126, v118
	v_sub_f32_e32 v127, v127, v119
	v_sub_f32_e32 v128, v128, v120
	v_sub_f32_e32 v129, v129, v121
	v_sub_f32_e32 v130, v130, v122
	v_sub_f32_e32 v131, v131, v123
	v_sub_f32_e32 v132, v132, v124
	v_sub_f32_e32 v133, v133, v125
	v_fmac_f32_e32 v118, v126, v152
	v_fmac_f32_e32 v119, v127, v153
	v_fmac_f32_e32 v120, v128, v154
	v_fmac_f32_e32 v121, v129, v155
	v_fmac_f32_e32 v122, v130, v156
	v_fmac_f32_e32 v123, v131, v157
	v_fmac_f32_e32 v124, v132, v158
	v_fmac_f32_e32 v125, v133, v159
	global_load_dwordx4 v[152:155], v[108:109], off offset:192
	global_load_dwordx4 v[156:159], v[108:109], off offset:208
	v_add_f32_e32 v126, v118, v118
	v_add_f32_e32 v127, v119, v119
	v_add_f32_e32 v128, v120, v120
	v_add_f32_e32 v129, v121, v121
	v_add_f32_e32 v130, v122, v122
	v_add_f32_e32 v131, v123, v123
	v_add_f32_e32 v132, v124, v124
	v_add_f32_e32 v133, v125, v125
	v_mul_f32_e32 v126, 0x3fb8aa3b, v126
	v_mul_f32_e32 v127, 0x3fb8aa3b, v127
	v_mul_f32_e32 v128, 0x3fb8aa3b, v128
	v_mul_f32_e32 v129, 0x3fb8aa3b, v129
	v_mul_f32_e32 v130, 0x3fb8aa3b, v130
	v_mul_f32_e32 v131, 0x3fb8aa3b, v131
	v_mul_f32_e32 v132, 0x3fb8aa3b, v132
	v_mul_f32_e32 v133, 0x3fb8aa3b, v133
	v_exp_f32_e32 v126, v126
	v_exp_f32_e32 v127, v127
	v_exp_f32_e32 v128, v128
	v_exp_f32_e32 v129, v129
	v_exp_f32_e32 v130, v130
	v_exp_f32_e32 v131, v131
	v_exp_f32_e32 v132, v132
	v_exp_f32_e32 v133, v133
	v_add_f32_e32 v126, 1.0, v126
	v_add_f32_e32 v127, 1.0, v127
	v_add_f32_e32 v128, 1.0, v128
	v_add_f32_e32 v129, 1.0, v129
	v_add_f32_e32 v130, 1.0, v130
	v_add_f32_e32 v131, 1.0, v131
	v_add_f32_e32 v132, 1.0, v132
	v_add_f32_e32 v133, 1.0, v133
	v_rcp_f32_e32 v126, v126
	v_rcp_f32_e32 v127, v127
	v_rcp_f32_e32 v128, v128
	v_rcp_f32_e32 v129, v129
	v_rcp_f32_e32 v130, v130
	v_rcp_f32_e32 v131, v131
	v_rcp_f32_e32 v132, v132
	v_rcp_f32_e32 v133, v133
	v_fma_f32 v118, v126, -2.0, 1.0
	v_fma_f32 v119, v127, -2.0, 1.0
	v_fma_f32 v120, v128, -2.0, 1.0
	v_fma_f32 v121, v129, -2.0, 1.0
	v_fma_f32 v122, v130, -2.0, 1.0
	v_fma_f32 v123, v131, -2.0, 1.0
	v_fma_f32 v124, v132, -2.0, 1.0
	v_fma_f32 v125, v133, -2.0, 1.0
	s_nop 0
	v_cvt_pk_bf16_f32 v98, v118, v119
	v_cvt_pk_bf16_f32 v99, v120, v121
	v_cvt_pk_bf16_f32 v100, v122, v123
	v_cvt_pk_bf16_f32 v101, v124, v125
	v_cndmask_b32_e64 v98, 0, v98, s[2:3]
	v_cndmask_b32_e64 v99, 0, v99, s[2:3]
	v_cndmask_b32_e64 v100, 0, v100, s[2:3]
	v_cndmask_b32_e64 v101, 0, v101, s[2:3]
	s_nop 1
	v_mfma_f32_32x32x16_bf16 v[32:47], v[98:101], v[192:195], 0
	v_mfma_f32_32x32x16_bf16 v[48:63], v[98:101], v[196:199], 0
	global_load_dwordx4 v[192:195], v[112:113], off offset:-2048
	global_load_dwordx4 v[196:199], v[112:113], off offset:2048
	s_waitcnt vmcnt(14)
	v_lshlrev_b32_e32 v118, 16, v160
	v_and_b32_e32 v119, 0xffff0000, v160
	v_lshlrev_b32_e32 v120, 16, v161
	v_and_b32_e32 v121, 0xffff0000, v161
	v_lshlrev_b32_e32 v122, 16, v162
	v_and_b32_e32 v123, 0xffff0000, v162
	v_lshlrev_b32_e32 v124, 16, v163
	v_and_b32_e32 v125, 0xffff0000, v163
	v_cndmask_b32_e64 v164, 0, v164, s[4:5]
	v_cndmask_b32_e64 v165, 0, v165, s[4:5]
	v_cndmask_b32_e64 v166, 0, v166, s[4:5]
	v_cndmask_b32_e64 v167, 0, v167, s[4:5]
	v_lshlrev_b32_e32 v126, 16, v164
	v_and_b32_e32 v127, 0xffff0000, v164
	v_lshlrev_b32_e32 v128, 16, v165
	v_and_b32_e32 v129, 0xffff0000, v165
	v_lshlrev_b32_e32 v130, 16, v166
	v_and_b32_e32 v131, 0xffff0000, v166
	v_lshlrev_b32_e32 v132, 16, v167
	v_and_b32_e32 v133, 0xffff0000, v167
	global_load_dwordx4 v[160:163], v[102:103], off offset:3200
	global_load_dwordx4 v[164:167], v[104:105], off offset:128
	v_sub_f32_e32 v126, v126, v118
	v_sub_f32_e32 v127, v127, v119
	v_sub_f32_e32 v128, v128, v120
	v_sub_f32_e32 v129, v129, v121
	v_sub_f32_e32 v130, v130, v122
	v_sub_f32_e32 v131, v131, v123
	v_sub_f32_e32 v132, v132, v124
	v_sub_f32_e32 v133, v133, v125
	v_fmac_f32_e32 v118, v126, v168
	v_fmac_f32_e32 v119, v127, v169
	v_fmac_f32_e32 v120, v128, v170
	v_fmac_f32_e32 v121, v129, v171
	v_fmac_f32_e32 v122, v130, v172
	v_fmac_f32_e32 v123, v131, v173
	v_fmac_f32_e32 v124, v132, v174
	v_fmac_f32_e32 v125, v133, v175
	global_load_dwordx4 v[168:171], v[108:109], off offset:256
	global_load_dwordx4 v[172:175], v[108:109], off offset:272
	v_add_f32_e32 v126, v118, v118
	v_add_f32_e32 v127, v119, v119
	v_add_f32_e32 v128, v120, v120
	v_add_f32_e32 v129, v121, v121
	v_add_f32_e32 v130, v122, v122
	v_add_f32_e32 v131, v123, v123
	v_add_f32_e32 v132, v124, v124
	v_add_f32_e32 v133, v125, v125
	v_mul_f32_e32 v126, 0x3fb8aa3b, v126
	v_mul_f32_e32 v127, 0x3fb8aa3b, v127
	v_mul_f32_e32 v128, 0x3fb8aa3b, v128
	v_mul_f32_e32 v129, 0x3fb8aa3b, v129
	v_mul_f32_e32 v130, 0x3fb8aa3b, v130
	v_mul_f32_e32 v131, 0x3fb8aa3b, v131
	v_mul_f32_e32 v132, 0x3fb8aa3b, v132
	v_mul_f32_e32 v133, 0x3fb8aa3b, v133
	v_exp_f32_e32 v126, v126
	v_exp_f32_e32 v127, v127
	v_exp_f32_e32 v128, v128
	v_exp_f32_e32 v129, v129
	v_exp_f32_e32 v130, v130
	v_exp_f32_e32 v131, v131
	v_exp_f32_e32 v132, v132
	v_exp_f32_e32 v133, v133
	v_add_f32_e32 v126, 1.0, v126
	v_add_f32_e32 v127, 1.0, v127
	v_add_f32_e32 v128, 1.0, v128
	v_add_f32_e32 v129, 1.0, v129
	v_add_f32_e32 v130, 1.0, v130
	v_add_f32_e32 v131, 1.0, v131
	v_add_f32_e32 v132, 1.0, v132
	v_add_f32_e32 v133, 1.0, v133
	v_rcp_f32_e32 v126, v126
	v_rcp_f32_e32 v127, v127
	v_rcp_f32_e32 v128, v128
	v_rcp_f32_e32 v129, v129
	v_rcp_f32_e32 v130, v130
	v_rcp_f32_e32 v131, v131
	v_rcp_f32_e32 v132, v132
	v_rcp_f32_e32 v133, v133
	v_fma_f32 v118, v126, -2.0, 1.0
	v_fma_f32 v119, v127, -2.0, 1.0
	v_fma_f32 v120, v128, -2.0, 1.0
	v_fma_f32 v121, v129, -2.0, 1.0
	v_fma_f32 v122, v130, -2.0, 1.0
	v_fma_f32 v123, v131, -2.0, 1.0
	v_fma_f32 v124, v132, -2.0, 1.0
	v_fma_f32 v125, v133, -2.0, 1.0
	s_nop 0
	v_cvt_pk_bf16_f32 v98, v118, v119
	v_cvt_pk_bf16_f32 v99, v120, v121
	v_cvt_pk_bf16_f32 v100, v122, v123
	v_cvt_pk_bf16_f32 v101, v124, v125
	v_cndmask_b32_e64 v98, 0, v98, s[2:3]
	v_cndmask_b32_e64 v99, 0, v99, s[2:3]
	v_cndmask_b32_e64 v100, 0, v100, s[2:3]
	v_cndmask_b32_e64 v101, 0, v101, s[2:3]
	s_nop 1
	v_mfma_f32_32x32x16_bf16 v[32:47], v[98:101], v[200:203], v[32:47]
	v_mfma_f32_32x32x16_bf16 v[48:63], v[98:101], v[204:207], v[48:63]
	global_load_dwordx4 v[200:203], v[112:113], off offset:-2016
	global_load_dwordx4 v[204:207], v[112:113], off offset:2080
	s_waitcnt vmcnt(14)
	v_lshlrev_b32_e32 v118, 16, v176
	v_and_b32_e32 v119, 0xffff0000, v176
	v_lshlrev_b32_e32 v120, 16, v177
	v_and_b32_e32 v121, 0xffff0000, v177
	v_lshlrev_b32_e32 v122, 16, v178
	v_and_b32_e32 v123, 0xffff0000, v178
	v_lshlrev_b32_e32 v124, 16, v179
	v_and_b32_e32 v125, 0xffff0000, v179
	v_cndmask_b32_e64 v180, 0, v180, s[4:5]
	v_cndmask_b32_e64 v181, 0, v181, s[4:5]
	v_cndmask_b32_e64 v182, 0, v182, s[4:5]
	v_cndmask_b32_e64 v183, 0, v183, s[4:5]
	v_lshlrev_b32_e32 v126, 16, v180
	v_and_b32_e32 v127, 0xffff0000, v180
	v_lshlrev_b32_e32 v128, 16, v181
	v_and_b32_e32 v129, 0xffff0000, v181
	v_lshlrev_b32_e32 v130, 16, v182
	v_and_b32_e32 v131, 0xffff0000, v182
	v_lshlrev_b32_e32 v132, 16, v183
	v_and_b32_e32 v133, 0xffff0000, v183
	global_load_dwordx4 v[176:179], v[102:103], off offset:3232
	global_load_dwordx4 v[180:183], v[104:105], off offset:160
	v_sub_f32_e32 v126, v126, v118
	v_sub_f32_e32 v127, v127, v119
	v_sub_f32_e32 v128, v128, v120
	v_sub_f32_e32 v129, v129, v121
	v_sub_f32_e32 v130, v130, v122
	v_sub_f32_e32 v131, v131, v123
	v_sub_f32_e32 v132, v132, v124
	v_sub_f32_e32 v133, v133, v125
	v_fmac_f32_e32 v118, v126, v184
	v_fmac_f32_e32 v119, v127, v185
	v_fmac_f32_e32 v120, v128, v186
	v_fmac_f32_e32 v121, v129, v187
	v_fmac_f32_e32 v122, v130, v188
	v_fmac_f32_e32 v123, v131, v189
	v_fmac_f32_e32 v124, v132, v190
	v_fmac_f32_e32 v125, v133, v191
	global_load_dwordx4 v[184:187], v[108:109], off offset:320
	global_load_dwordx4 v[188:191], v[108:109], off offset:336
	v_add_f32_e32 v126, v118, v118
	v_add_f32_e32 v127, v119, v119
	v_add_f32_e32 v128, v120, v120
	v_add_f32_e32 v129, v121, v121
	v_add_f32_e32 v130, v122, v122
	v_add_f32_e32 v131, v123, v123
	v_add_f32_e32 v132, v124, v124
	v_add_f32_e32 v133, v125, v125
	v_mul_f32_e32 v126, 0x3fb8aa3b, v126
	v_mul_f32_e32 v127, 0x3fb8aa3b, v127
	v_mul_f32_e32 v128, 0x3fb8aa3b, v128
	v_mul_f32_e32 v129, 0x3fb8aa3b, v129
	v_mul_f32_e32 v130, 0x3fb8aa3b, v130
	v_mul_f32_e32 v131, 0x3fb8aa3b, v131
	v_mul_f32_e32 v132, 0x3fb8aa3b, v132
	v_mul_f32_e32 v133, 0x3fb8aa3b, v133
	v_exp_f32_e32 v126, v126
	v_exp_f32_e32 v127, v127
	v_exp_f32_e32 v128, v128
	v_exp_f32_e32 v129, v129
	v_exp_f32_e32 v130, v130
	v_exp_f32_e32 v131, v131
	v_exp_f32_e32 v132, v132
	v_exp_f32_e32 v133, v133
	v_add_f32_e32 v126, 1.0, v126
	v_add_f32_e32 v127, 1.0, v127
	v_add_f32_e32 v128, 1.0, v128
	v_add_f32_e32 v129, 1.0, v129
	v_add_f32_e32 v130, 1.0, v130
	v_add_f32_e32 v131, 1.0, v131
	v_add_f32_e32 v132, 1.0, v132
	v_add_f32_e32 v133, 1.0, v133
	v_rcp_f32_e32 v126, v126
	v_rcp_f32_e32 v127, v127
	v_rcp_f32_e32 v128, v128
	v_rcp_f32_e32 v129, v129
	v_rcp_f32_e32 v130, v130
	v_rcp_f32_e32 v131, v131
	v_rcp_f32_e32 v132, v132
	v_rcp_f32_e32 v133, v133
	v_fma_f32 v118, v126, -2.0, 1.0
	v_fma_f32 v119, v127, -2.0, 1.0
	v_fma_f32 v120, v128, -2.0, 1.0
	v_fma_f32 v121, v129, -2.0, 1.0
	v_fma_f32 v122, v130, -2.0, 1.0
	v_fma_f32 v123, v131, -2.0, 1.0
	v_fma_f32 v124, v132, -2.0, 1.0
	v_fma_f32 v125, v133, -2.0, 1.0
	s_nop 0
	v_cvt_pk_bf16_f32 v98, v118, v119
	v_cvt_pk_bf16_f32 v99, v120, v121
	v_cvt_pk_bf16_f32 v100, v122, v123
	v_cvt_pk_bf16_f32 v101, v124, v125
	v_cndmask_b32_e64 v98, 0, v98, s[2:3]
	v_cndmask_b32_e64 v99, 0, v99, s[2:3]
	v_cndmask_b32_e64 v100, 0, v100, s[2:3]
	v_cndmask_b32_e64 v101, 0, v101, s[2:3]
	s_nop 1
	v_mfma_f32_32x32x16_bf16 v[32:47], v[98:101], v[208:211], v[32:47]
	v_mfma_f32_32x32x16_bf16 v[48:63], v[98:101], v[222:225], v[48:63]
	global_load_dwordx4 v[208:211], v[112:113], off offset:-1984
	global_load_dwordx4 v[222:225], v[112:113], off offset:2112
	s_waitcnt vmcnt(14)
	v_lshlrev_b32_e32 v118, 16, v144
	v_and_b32_e32 v119, 0xffff0000, v144
	v_lshlrev_b32_e32 v120, 16, v145
	v_and_b32_e32 v121, 0xffff0000, v145
	v_lshlrev_b32_e32 v122, 16, v146
	v_and_b32_e32 v123, 0xffff0000, v146
	v_lshlrev_b32_e32 v124, 16, v147
	v_and_b32_e32 v125, 0xffff0000, v147
	v_cndmask_b32_e64 v148, 0, v148, s[4:5]
	v_cndmask_b32_e64 v149, 0, v149, s[4:5]
	v_cndmask_b32_e64 v150, 0, v150, s[4:5]
	v_cndmask_b32_e64 v151, 0, v151, s[4:5]
	v_lshlrev_b32_e32 v126, 16, v148
	v_and_b32_e32 v127, 0xffff0000, v148
	v_lshlrev_b32_e32 v128, 16, v149
	v_and_b32_e32 v129, 0xffff0000, v149
	v_lshlrev_b32_e32 v130, 16, v150
	v_and_b32_e32 v131, 0xffff0000, v150
	v_lshlrev_b32_e32 v132, 16, v151
	v_and_b32_e32 v133, 0xffff0000, v151
	global_load_dwordx4 v[144:147], v[102:103], off offset:3264
	global_load_dwordx4 v[148:151], v[104:105], off offset:192
	v_sub_f32_e32 v126, v126, v118
	v_sub_f32_e32 v127, v127, v119
	v_sub_f32_e32 v128, v128, v120
	v_sub_f32_e32 v129, v129, v121
	v_sub_f32_e32 v130, v130, v122
	v_sub_f32_e32 v131, v131, v123
	v_sub_f32_e32 v132, v132, v124
	v_sub_f32_e32 v133, v133, v125
	v_fmac_f32_e32 v118, v126, v152
	v_fmac_f32_e32 v119, v127, v153
	v_fmac_f32_e32 v120, v128, v154
	v_fmac_f32_e32 v121, v129, v155
	v_fmac_f32_e32 v122, v130, v156
	v_fmac_f32_e32 v123, v131, v157
	v_fmac_f32_e32 v124, v132, v158
	v_fmac_f32_e32 v125, v133, v159
	global_load_dwordx4 v[152:155], v[108:109], off offset:384
	global_load_dwordx4 v[156:159], v[108:109], off offset:400
	v_add_f32_e32 v126, v118, v118
	v_add_f32_e32 v127, v119, v119
	v_add_f32_e32 v128, v120, v120
	v_add_f32_e32 v129, v121, v121
	v_add_f32_e32 v130, v122, v122
	v_add_f32_e32 v131, v123, v123
	v_add_f32_e32 v132, v124, v124
	v_add_f32_e32 v133, v125, v125
	v_mul_f32_e32 v126, 0x3fb8aa3b, v126
	v_mul_f32_e32 v127, 0x3fb8aa3b, v127
	v_mul_f32_e32 v128, 0x3fb8aa3b, v128
	v_mul_f32_e32 v129, 0x3fb8aa3b, v129
	v_mul_f32_e32 v130, 0x3fb8aa3b, v130
	v_mul_f32_e32 v131, 0x3fb8aa3b, v131
	v_mul_f32_e32 v132, 0x3fb8aa3b, v132
	v_mul_f32_e32 v133, 0x3fb8aa3b, v133
	v_exp_f32_e32 v126, v126
	v_exp_f32_e32 v127, v127
	v_exp_f32_e32 v128, v128
	v_exp_f32_e32 v129, v129
	v_exp_f32_e32 v130, v130
	v_exp_f32_e32 v131, v131
	v_exp_f32_e32 v132, v132
	v_exp_f32_e32 v133, v133
	v_add_f32_e32 v126, 1.0, v126
	v_add_f32_e32 v127, 1.0, v127
	v_add_f32_e32 v128, 1.0, v128
	v_add_f32_e32 v129, 1.0, v129
	v_add_f32_e32 v130, 1.0, v130
	v_add_f32_e32 v131, 1.0, v131
	v_add_f32_e32 v132, 1.0, v132
	v_add_f32_e32 v133, 1.0, v133
	v_rcp_f32_e32 v126, v126
	v_rcp_f32_e32 v127, v127
	v_rcp_f32_e32 v128, v128
	v_rcp_f32_e32 v129, v129
	v_rcp_f32_e32 v130, v130
	v_rcp_f32_e32 v131, v131
	v_rcp_f32_e32 v132, v132
	v_rcp_f32_e32 v133, v133
	v_fma_f32 v118, v126, -2.0, 1.0
	v_fma_f32 v119, v127, -2.0, 1.0
	v_fma_f32 v120, v128, -2.0, 1.0
	v_fma_f32 v121, v129, -2.0, 1.0
	v_fma_f32 v122, v130, -2.0, 1.0
	v_fma_f32 v123, v131, -2.0, 1.0
	v_fma_f32 v124, v132, -2.0, 1.0
	v_fma_f32 v125, v133, -2.0, 1.0
	s_nop 0
	v_cvt_pk_bf16_f32 v98, v118, v119
	v_cvt_pk_bf16_f32 v99, v120, v121
	v_cvt_pk_bf16_f32 v100, v122, v123
	v_cvt_pk_bf16_f32 v101, v124, v125
	v_cndmask_b32_e64 v98, 0, v98, s[2:3]
	v_cndmask_b32_e64 v99, 0, v99, s[2:3]
	v_cndmask_b32_e64 v100, 0, v100, s[2:3]
	v_cndmask_b32_e64 v101, 0, v101, s[2:3]
	s_nop 1
	v_mfma_f32_32x32x16_bf16 v[32:47], v[98:101], v[226:229], v[32:47]
	v_mfma_f32_32x32x16_bf16 v[48:63], v[98:101], v[238:241], v[48:63]
	global_load_dwordx4 v[226:229], v[112:113], off offset:-1952
	global_load_dwordx4 v[238:241], v[112:113], off offset:2144
	s_waitcnt vmcnt(14)
	v_lshlrev_b32_e32 v118, 16, v160
	v_and_b32_e32 v119, 0xffff0000, v160
	v_lshlrev_b32_e32 v120, 16, v161
	v_and_b32_e32 v121, 0xffff0000, v161
	v_lshlrev_b32_e32 v122, 16, v162
	v_and_b32_e32 v123, 0xffff0000, v162
	v_lshlrev_b32_e32 v124, 16, v163
	v_and_b32_e32 v125, 0xffff0000, v163
	v_cndmask_b32_e64 v164, 0, v164, s[4:5]
	v_cndmask_b32_e64 v165, 0, v165, s[4:5]
	v_cndmask_b32_e64 v166, 0, v166, s[4:5]
	v_cndmask_b32_e64 v167, 0, v167, s[4:5]
	v_lshlrev_b32_e32 v126, 16, v164
	v_and_b32_e32 v127, 0xffff0000, v164
	v_lshlrev_b32_e32 v128, 16, v165
	v_and_b32_e32 v129, 0xffff0000, v165
	v_lshlrev_b32_e32 v130, 16, v166
	v_and_b32_e32 v131, 0xffff0000, v166
	v_lshlrev_b32_e32 v132, 16, v167
	v_and_b32_e32 v133, 0xffff0000, v167
	global_load_dwordx4 v[160:163], v[102:103], off offset:3296
	global_load_dwordx4 v[164:167], v[104:105], off offset:224
	v_sub_f32_e32 v126, v126, v118
	v_sub_f32_e32 v127, v127, v119
	v_sub_f32_e32 v128, v128, v120
	v_sub_f32_e32 v129, v129, v121
	v_sub_f32_e32 v130, v130, v122
	v_sub_f32_e32 v131, v131, v123
	v_sub_f32_e32 v132, v132, v124
	v_sub_f32_e32 v133, v133, v125
	v_fmac_f32_e32 v118, v126, v168
	v_fmac_f32_e32 v119, v127, v169
	v_fmac_f32_e32 v120, v128, v170
	v_fmac_f32_e32 v121, v129, v171
	v_fmac_f32_e32 v122, v130, v172
	v_fmac_f32_e32 v123, v131, v173
	v_fmac_f32_e32 v124, v132, v174
	v_fmac_f32_e32 v125, v133, v175
	global_load_dwordx4 v[168:171], v[108:109], off offset:448
	global_load_dwordx4 v[172:175], v[108:109], off offset:464
	v_cvt_pk_bf16_f32 v98, v118, v119
	v_cvt_pk_bf16_f32 v99, v120, v121
	v_cvt_pk_bf16_f32 v100, v122, v123
	v_cvt_pk_bf16_f32 v101, v124, v125
	v_cndmask_b32_e64 v98, 0, v98, s[2:3]
	v_cndmask_b32_e64 v99, 0, v99, s[2:3]
	v_cndmask_b32_e64 v100, 0, v100, s[2:3]
	v_cndmask_b32_e64 v101, 0, v101, s[2:3]
	s_nop 1
	v_mfma_f32_32x32x16_bf16 v[0:15], v[98:101], v[192:195], 0
	v_mfma_f32_32x32x16_bf16 v[16:31], v[98:101], v[196:199], 0
	global_load_dwordx4 v[192:195], v[114:115], off
	global_load_dwordx4 v[196:199], v[116:117], off
	s_waitcnt vmcnt(14)
	v_lshlrev_b32_e32 v118, 16, v176
	v_and_b32_e32 v119, 0xffff0000, v176
	v_lshlrev_b32_e32 v120, 16, v177
	v_and_b32_e32 v121, 0xffff0000, v177
	v_lshlrev_b32_e32 v122, 16, v178
	v_and_b32_e32 v123, 0xffff0000, v178
	v_lshlrev_b32_e32 v124, 16, v179
	v_and_b32_e32 v125, 0xffff0000, v179
	v_cndmask_b32_e64 v180, 0, v180, s[4:5]
	v_cndmask_b32_e64 v181, 0, v181, s[4:5]
	v_cndmask_b32_e64 v182, 0, v182, s[4:5]
	v_cndmask_b32_e64 v183, 0, v183, s[4:5]
	v_lshlrev_b32_e32 v126, 16, v180
	v_and_b32_e32 v127, 0xffff0000, v180
	v_lshlrev_b32_e32 v128, 16, v181
	v_and_b32_e32 v129, 0xffff0000, v181
	v_lshlrev_b32_e32 v130, 16, v182
	v_and_b32_e32 v131, 0xffff0000, v182
	v_lshlrev_b32_e32 v132, 16, v183
	v_and_b32_e32 v133, 0xffff0000, v183
	global_load_dwordx4 v[176:179], v[102:103], off offset:3328
	global_load_dwordx4 v[180:183], v[104:105], off offset:256
	v_sub_f32_e32 v126, v126, v118
	v_sub_f32_e32 v127, v127, v119
	v_sub_f32_e32 v128, v128, v120
	v_sub_f32_e32 v129, v129, v121
	v_sub_f32_e32 v130, v130, v122
	v_sub_f32_e32 v131, v131, v123
	v_sub_f32_e32 v132, v132, v124
	v_sub_f32_e32 v133, v133, v125
	v_fmac_f32_e32 v118, v126, v184
	v_fmac_f32_e32 v119, v127, v185
	v_fmac_f32_e32 v120, v128, v186
	v_fmac_f32_e32 v121, v129, v187
	v_fmac_f32_e32 v122, v130, v188
	v_fmac_f32_e32 v123, v131, v189
	v_fmac_f32_e32 v124, v132, v190
	v_fmac_f32_e32 v125, v133, v191
	global_load_dwordx4 v[184:187], v[108:109], off offset:512
	global_load_dwordx4 v[188:191], v[108:109], off offset:528
	v_cvt_pk_bf16_f32 v98, v118, v119
	v_cvt_pk_bf16_f32 v99, v120, v121
	v_cvt_pk_bf16_f32 v100, v122, v123
	v_cvt_pk_bf16_f32 v101, v124, v125
	v_cndmask_b32_e64 v98, 0, v98, s[2:3]
	v_cndmask_b32_e64 v99, 0, v99, s[2:3]
	v_cndmask_b32_e64 v100, 0, v100, s[2:3]
	v_cndmask_b32_e64 v101, 0, v101, s[2:3]
	s_nop 1
	v_mfma_f32_32x32x16_bf16 v[0:15], v[98:101], v[200:203], v[0:15]
	v_mfma_f32_32x32x16_bf16 v[16:31], v[98:101], v[204:207], v[16:31]
	global_load_dwordx4 v[200:203], v[114:115], off offset:32
	global_load_dwordx4 v[204:207], v[116:117], off offset:32
	s_waitcnt vmcnt(14)
	v_lshlrev_b32_e32 v118, 16, v144
	v_and_b32_e32 v119, 0xffff0000, v144
	v_lshlrev_b32_e32 v120, 16, v145
	v_and_b32_e32 v121, 0xffff0000, v145
	v_lshlrev_b32_e32 v122, 16, v146
	v_and_b32_e32 v123, 0xffff0000, v146
	v_lshlrev_b32_e32 v124, 16, v147
	v_and_b32_e32 v125, 0xffff0000, v147
	v_cndmask_b32_e64 v148, 0, v148, s[4:5]
	v_cndmask_b32_e64 v149, 0, v149, s[4:5]
	v_cndmask_b32_e64 v150, 0, v150, s[4:5]
	v_cndmask_b32_e64 v151, 0, v151, s[4:5]
	v_lshlrev_b32_e32 v126, 16, v148
	v_and_b32_e32 v127, 0xffff0000, v148
	v_lshlrev_b32_e32 v128, 16, v149
	v_and_b32_e32 v129, 0xffff0000, v149
	v_lshlrev_b32_e32 v130, 16, v150
	v_and_b32_e32 v131, 0xffff0000, v150
	v_lshlrev_b32_e32 v132, 16, v151
	v_and_b32_e32 v133, 0xffff0000, v151
	global_load_dwordx4 v[144:147], v[102:103], off offset:3360
	global_load_dwordx4 v[148:151], v[104:105], off offset:288
	v_sub_f32_e32 v126, v126, v118
	v_sub_f32_e32 v127, v127, v119
	v_sub_f32_e32 v128, v128, v120
	v_sub_f32_e32 v129, v129, v121
	v_sub_f32_e32 v130, v130, v122
	v_sub_f32_e32 v131, v131, v123
	v_sub_f32_e32 v132, v132, v124
	v_sub_f32_e32 v133, v133, v125
	v_fmac_f32_e32 v118, v126, v152
	v_fmac_f32_e32 v119, v127, v153
	v_fmac_f32_e32 v120, v128, v154
	v_fmac_f32_e32 v121, v129, v155
	v_fmac_f32_e32 v122, v130, v156
	v_fmac_f32_e32 v123, v131, v157
	v_fmac_f32_e32 v124, v132, v158
	v_fmac_f32_e32 v125, v133, v159
	global_load_dwordx4 v[152:155], v[108:109], off offset:576
	global_load_dwordx4 v[156:159], v[108:109], off offset:592
	v_cvt_pk_bf16_f32 v98, v118, v119
	v_cvt_pk_bf16_f32 v99, v120, v121
	v_cvt_pk_bf16_f32 v100, v122, v123
	v_cvt_pk_bf16_f32 v101, v124, v125
	v_cndmask_b32_e64 v98, 0, v98, s[2:3]
	v_cndmask_b32_e64 v99, 0, v99, s[2:3]
	v_cndmask_b32_e64 v100, 0, v100, s[2:3]
	v_cndmask_b32_e64 v101, 0, v101, s[2:3]
	s_nop 1
	v_mfma_f32_32x32x16_bf16 v[0:15], v[98:101], v[208:211], v[0:15]
	v_mfma_f32_32x32x16_bf16 v[16:31], v[98:101], v[222:225], v[16:31]
	global_load_dwordx4 v[208:211], v[114:115], off offset:64
	global_load_dwordx4 v[222:225], v[116:117], off offset:64
	s_waitcnt vmcnt(14)
	v_lshlrev_b32_e32 v118, 16, v160
	v_and_b32_e32 v119, 0xffff0000, v160
	v_lshlrev_b32_e32 v120, 16, v161
	v_and_b32_e32 v121, 0xffff0000, v161
	v_lshlrev_b32_e32 v122, 16, v162
	v_and_b32_e32 v123, 0xffff0000, v162
	v_lshlrev_b32_e32 v124, 16, v163
	v_and_b32_e32 v125, 0xffff0000, v163
	v_cndmask_b32_e64 v164, 0, v164, s[4:5]
	v_cndmask_b32_e64 v165, 0, v165, s[4:5]
	v_cndmask_b32_e64 v166, 0, v166, s[4:5]
	v_cndmask_b32_e64 v167, 0, v167, s[4:5]
	v_lshlrev_b32_e32 v126, 16, v164
	v_and_b32_e32 v127, 0xffff0000, v164
	v_lshlrev_b32_e32 v128, 16, v165
	v_and_b32_e32 v129, 0xffff0000, v165
	v_lshlrev_b32_e32 v130, 16, v166
	v_and_b32_e32 v131, 0xffff0000, v166
	v_lshlrev_b32_e32 v132, 16, v167
	v_and_b32_e32 v133, 0xffff0000, v167
	global_load_dwordx4 v[160:163], v[102:103], off offset:3392
	global_load_dwordx4 v[164:167], v[104:105], off offset:320
	v_sub_f32_e32 v126, v126, v118
	v_sub_f32_e32 v127, v127, v119
	v_sub_f32_e32 v128, v128, v120
	v_sub_f32_e32 v129, v129, v121
	v_sub_f32_e32 v130, v130, v122
	v_sub_f32_e32 v131, v131, v123
	v_sub_f32_e32 v132, v132, v124
	v_sub_f32_e32 v133, v133, v125
	v_fmac_f32_e32 v118, v126, v168
	v_fmac_f32_e32 v119, v127, v169
	v_fmac_f32_e32 v120, v128, v170
	v_fmac_f32_e32 v121, v129, v171
	v_fmac_f32_e32 v122, v130, v172
	v_fmac_f32_e32 v123, v131, v173
	v_fmac_f32_e32 v124, v132, v174
	v_fmac_f32_e32 v125, v133, v175
	global_load_dwordx4 v[168:171], v[108:109], off offset:640
	global_load_dwordx4 v[172:175], v[108:109], off offset:656
	v_cvt_pk_bf16_f32 v98, v118, v119
	v_cvt_pk_bf16_f32 v99, v120, v121
	v_cvt_pk_bf16_f32 v100, v122, v123
	v_cvt_pk_bf16_f32 v101, v124, v125
	v_cndmask_b32_e64 v98, 0, v98, s[2:3]
	v_cndmask_b32_e64 v99, 0, v99, s[2:3]
	v_cndmask_b32_e64 v100, 0, v100, s[2:3]
	v_cndmask_b32_e64 v101, 0, v101, s[2:3]
	s_nop 1
	v_mfma_f32_32x32x16_bf16 v[0:15], v[98:101], v[226:229], v[0:15]
	v_mfma_f32_32x32x16_bf16 v[16:31], v[98:101], v[238:241], v[16:31]
	global_load_dwordx4 v[226:229], v[114:115], off offset:96
	global_load_dwordx4 v[238:241], v[116:117], off offset:96
	s_waitcnt vmcnt(14)
	v_lshlrev_b32_e32 v118, 16, v176
	v_and_b32_e32 v119, 0xffff0000, v176
	v_lshlrev_b32_e32 v120, 16, v177
	v_and_b32_e32 v121, 0xffff0000, v177
	v_lshlrev_b32_e32 v122, 16, v178
	v_and_b32_e32 v123, 0xffff0000, v178
	v_lshlrev_b32_e32 v124, 16, v179
	v_and_b32_e32 v125, 0xffff0000, v179
	v_cndmask_b32_e64 v180, 0, v180, s[4:5]
	v_cndmask_b32_e64 v181, 0, v181, s[4:5]
	v_cndmask_b32_e64 v182, 0, v182, s[4:5]
	v_cndmask_b32_e64 v183, 0, v183, s[4:5]
	v_lshlrev_b32_e32 v126, 16, v180
	v_and_b32_e32 v127, 0xffff0000, v180
	v_lshlrev_b32_e32 v128, 16, v181
	v_and_b32_e32 v129, 0xffff0000, v181
	v_lshlrev_b32_e32 v130, 16, v182
	v_and_b32_e32 v131, 0xffff0000, v182
	v_lshlrev_b32_e32 v132, 16, v183
	v_and_b32_e32 v133, 0xffff0000, v183
	global_load_dwordx4 v[176:179], v[102:103], off offset:3424
	global_load_dwordx4 v[180:183], v[104:105], off offset:352
	v_sub_f32_e32 v126, v126, v118
	v_sub_f32_e32 v127, v127, v119
	v_sub_f32_e32 v128, v128, v120
	v_sub_f32_e32 v129, v129, v121
	v_sub_f32_e32 v130, v130, v122
	v_sub_f32_e32 v131, v131, v123
	v_sub_f32_e32 v132, v132, v124
	v_sub_f32_e32 v133, v133, v125
	v_fmac_f32_e32 v118, v126, v184
	v_fmac_f32_e32 v119, v127, v185
	v_fmac_f32_e32 v120, v128, v186
	v_fmac_f32_e32 v121, v129, v187
	v_fmac_f32_e32 v122, v130, v188
	v_fmac_f32_e32 v123, v131, v189
	v_fmac_f32_e32 v124, v132, v190
	v_fmac_f32_e32 v125, v133, v191
	global_load_dwordx4 v[184:187], v[108:109], off offset:704
	global_load_dwordx4 v[188:191], v[108:109], off offset:720
	v_mul_f32_e32 v126, 0xbfb8aa3b, v118
	v_mul_f32_e32 v127, 0xbfb8aa3b, v119
	v_mul_f32_e32 v128, 0xbfb8aa3b, v120
	v_mul_f32_e32 v129, 0xbfb8aa3b, v121
	v_mul_f32_e32 v130, 0xbfb8aa3b, v122
	v_mul_f32_e32 v131, 0xbfb8aa3b, v123
	v_mul_f32_e32 v132, 0xbfb8aa3b, v124
	v_mul_f32_e32 v133, 0xbfb8aa3b, v125
	v_exp_f32_e32 v126, v126
	v_exp_f32_e32 v127, v127
	v_exp_f32_e32 v128, v128
	v_exp_f32_e32 v129, v129
	v_exp_f32_e32 v130, v130
	v_exp_f32_e32 v131, v131
	v_exp_f32_e32 v132, v132
	v_exp_f32_e32 v133, v133
	v_add_f32_e32 v126, 1.0, v126
	v_add_f32_e32 v127, 1.0, v127
	v_add_f32_e32 v128, 1.0, v128
	v_add_f32_e32 v129, 1.0, v129
	v_add_f32_e32 v130, 1.0, v130
	v_add_f32_e32 v131, 1.0, v131
	v_add_f32_e32 v132, 1.0, v132
	v_add_f32_e32 v133, 1.0, v133
	v_rcp_f32_e32 v126, v126
	v_rcp_f32_e32 v127, v127
	v_rcp_f32_e32 v128, v128
	v_rcp_f32_e32 v129, v129
	v_rcp_f32_e32 v130, v130
	v_rcp_f32_e32 v131, v131
	v_rcp_f32_e32 v132, v132
	v_rcp_f32_e32 v133, v133
	s_nop 0
	v_cvt_pk_bf16_f32 v98, v126, v127
	v_cvt_pk_bf16_f32 v99, v128, v129
	v_cvt_pk_bf16_f32 v100, v130, v131
	v_cvt_pk_bf16_f32 v101, v132, v133
	v_cndmask_b32_e64 v98, 0, v98, s[2:3]
	v_cndmask_b32_e64 v99, 0, v99, s[2:3]
	v_cndmask_b32_e64 v100, 0, v100, s[2:3]
	v_cndmask_b32_e64 v101, 0, v101, s[2:3]
	s_nop 1
	v_mfma_f32_32x32x16_bf16 v[80:95], v[98:101], v[192:195], 0
	v_mfma_f32_32x32x16_bf16 v[64:79], v[98:101], v[196:199], 0
	global_load_dwordx4 v[192:195], v[114:115], off offset:128
	global_load_dwordx4 v[196:199], v[116:117], off offset:128
	s_waitcnt vmcnt(14)
	v_lshlrev_b32_e32 v118, 16, v144
	v_and_b32_e32 v119, 0xffff0000, v144
	v_lshlrev_b32_e32 v120, 16, v145
	v_and_b32_e32 v121, 0xffff0000, v145
	v_lshlrev_b32_e32 v122, 16, v146
	v_and_b32_e32 v123, 0xffff0000, v146
	v_lshlrev_b32_e32 v124, 16, v147
	v_and_b32_e32 v125, 0xffff0000, v147
	v_cndmask_b32_e64 v148, 0, v148, s[4:5]
	v_cndmask_b32_e64 v149, 0, v149, s[4:5]
	v_cndmask_b32_e64 v150, 0, v150, s[4:5]
	v_cndmask_b32_e64 v151, 0, v151, s[4:5]
	v_lshlrev_b32_e32 v126, 16, v148
	v_and_b32_e32 v127, 0xffff0000, v148
	v_lshlrev_b32_e32 v128, 16, v149
	v_and_b32_e32 v129, 0xffff0000, v149
	v_lshlrev_b32_e32 v130, 16, v150
	v_and_b32_e32 v131, 0xffff0000, v150
	v_lshlrev_b32_e32 v132, 16, v151
	v_and_b32_e32 v133, 0xffff0000, v151
	global_load_dwordx4 v[144:147], v[102:103], off offset:3456
	global_load_dwordx4 v[148:151], v[104:105], off offset:384
	v_sub_f32_e32 v126, v126, v118
	v_sub_f32_e32 v127, v127, v119
	v_sub_f32_e32 v128, v128, v120
	v_sub_f32_e32 v129, v129, v121
	v_sub_f32_e32 v130, v130, v122
	v_sub_f32_e32 v131, v131, v123
	v_sub_f32_e32 v132, v132, v124
	v_sub_f32_e32 v133, v133, v125
	v_fmac_f32_e32 v118, v126, v152
	v_fmac_f32_e32 v119, v127, v153
	v_fmac_f32_e32 v120, v128, v154
	v_fmac_f32_e32 v121, v129, v155
	v_fmac_f32_e32 v122, v130, v156
	v_fmac_f32_e32 v123, v131, v157
	v_fmac_f32_e32 v124, v132, v158
	v_fmac_f32_e32 v125, v133, v159
	global_load_dwordx4 v[152:155], v[108:109], off offset:768
	global_load_dwordx4 v[156:159], v[108:109], off offset:784
	v_mul_f32_e32 v126, 0xbfb8aa3b, v118
	v_mul_f32_e32 v127, 0xbfb8aa3b, v119
	v_mul_f32_e32 v128, 0xbfb8aa3b, v120
	v_mul_f32_e32 v129, 0xbfb8aa3b, v121
	v_mul_f32_e32 v130, 0xbfb8aa3b, v122
	v_mul_f32_e32 v131, 0xbfb8aa3b, v123
	v_mul_f32_e32 v132, 0xbfb8aa3b, v124
	v_mul_f32_e32 v133, 0xbfb8aa3b, v125
	v_exp_f32_e32 v126, v126
	v_exp_f32_e32 v127, v127
	v_exp_f32_e32 v128, v128
	v_exp_f32_e32 v129, v129
	v_exp_f32_e32 v130, v130
	v_exp_f32_e32 v131, v131
	v_exp_f32_e32 v132, v132
	v_exp_f32_e32 v133, v133
	v_add_f32_e32 v126, 1.0, v126
	v_add_f32_e32 v127, 1.0, v127
	v_add_f32_e32 v128, 1.0, v128
	v_add_f32_e32 v129, 1.0, v129
	v_add_f32_e32 v130, 1.0, v130
	v_add_f32_e32 v131, 1.0, v131
	v_add_f32_e32 v132, 1.0, v132
	v_add_f32_e32 v133, 1.0, v133
	v_rcp_f32_e32 v126, v126
	v_rcp_f32_e32 v127, v127
	v_rcp_f32_e32 v128, v128
	v_rcp_f32_e32 v129, v129
	v_rcp_f32_e32 v130, v130
	v_rcp_f32_e32 v131, v131
	v_rcp_f32_e32 v132, v132
	v_rcp_f32_e32 v133, v133
	s_nop 0
	v_cvt_pk_bf16_f32 v98, v126, v127
	v_cvt_pk_bf16_f32 v99, v128, v129
	v_cvt_pk_bf16_f32 v100, v130, v131
	v_cvt_pk_bf16_f32 v101, v132, v133
	v_cndmask_b32_e64 v98, 0, v98, s[2:3]
	v_cndmask_b32_e64 v99, 0, v99, s[2:3]
	v_cndmask_b32_e64 v100, 0, v100, s[2:3]
	v_cndmask_b32_e64 v101, 0, v101, s[2:3]
	s_nop 1
	v_mfma_f32_32x32x16_bf16 v[80:95], v[98:101], v[200:203], v[80:95]
	v_mfma_f32_32x32x16_bf16 v[64:79], v[98:101], v[204:207], v[64:79]
	global_load_dwordx4 v[200:203], v[114:115], off offset:160
	global_load_dwordx4 v[204:207], v[116:117], off offset:160
	s_waitcnt vmcnt(14)
	v_lshlrev_b32_e32 v118, 16, v160
	v_and_b32_e32 v119, 0xffff0000, v160
	v_lshlrev_b32_e32 v120, 16, v161
	v_and_b32_e32 v121, 0xffff0000, v161
	v_lshlrev_b32_e32 v122, 16, v162
	v_and_b32_e32 v123, 0xffff0000, v162
	v_lshlrev_b32_e32 v124, 16, v163
	v_and_b32_e32 v125, 0xffff0000, v163
	v_cndmask_b32_e64 v164, 0, v164, s[4:5]
	v_cndmask_b32_e64 v165, 0, v165, s[4:5]
	v_cndmask_b32_e64 v166, 0, v166, s[4:5]
	v_cndmask_b32_e64 v167, 0, v167, s[4:5]
	v_lshlrev_b32_e32 v126, 16, v164
	v_and_b32_e32 v127, 0xffff0000, v164
	v_lshlrev_b32_e32 v128, 16, v165
	v_and_b32_e32 v129, 0xffff0000, v165
	v_lshlrev_b32_e32 v130, 16, v166
	v_and_b32_e32 v131, 0xffff0000, v166
	v_lshlrev_b32_e32 v132, 16, v167
	v_and_b32_e32 v133, 0xffff0000, v167
	global_load_dwordx4 v[160:163], v[102:103], off offset:3488
	global_load_dwordx4 v[164:167], v[104:105], off offset:416
	v_sub_f32_e32 v126, v126, v118
	v_sub_f32_e32 v127, v127, v119
	v_sub_f32_e32 v128, v128, v120
	v_sub_f32_e32 v129, v129, v121
	v_sub_f32_e32 v130, v130, v122
	v_sub_f32_e32 v131, v131, v123
	v_sub_f32_e32 v132, v132, v124
	v_sub_f32_e32 v133, v133, v125
	v_fmac_f32_e32 v118, v126, v168
	v_fmac_f32_e32 v119, v127, v169
	v_fmac_f32_e32 v120, v128, v170
	v_fmac_f32_e32 v121, v129, v171
	v_fmac_f32_e32 v122, v130, v172
	v_fmac_f32_e32 v123, v131, v173
	v_fmac_f32_e32 v124, v132, v174
	v_fmac_f32_e32 v125, v133, v175
	global_load_dwordx4 v[168:171], v[108:109], off offset:832
	global_load_dwordx4 v[172:175], v[108:109], off offset:848
	v_mul_f32_e32 v126, 0xbfb8aa3b, v118
	v_mul_f32_e32 v127, 0xbfb8aa3b, v119
	v_mul_f32_e32 v128, 0xbfb8aa3b, v120
	v_mul_f32_e32 v129, 0xbfb8aa3b, v121
	v_mul_f32_e32 v130, 0xbfb8aa3b, v122
	v_mul_f32_e32 v131, 0xbfb8aa3b, v123
	v_mul_f32_e32 v132, 0xbfb8aa3b, v124
	v_mul_f32_e32 v133, 0xbfb8aa3b, v125
	v_exp_f32_e32 v126, v126
	v_exp_f32_e32 v127, v127
	v_exp_f32_e32 v128, v128
	v_exp_f32_e32 v129, v129
	v_exp_f32_e32 v130, v130
	v_exp_f32_e32 v131, v131
	v_exp_f32_e32 v132, v132
	v_exp_f32_e32 v133, v133
	v_add_f32_e32 v126, 1.0, v126
	v_add_f32_e32 v127, 1.0, v127
	v_add_f32_e32 v128, 1.0, v128
	v_add_f32_e32 v129, 1.0, v129
	v_add_f32_e32 v130, 1.0, v130
	v_add_f32_e32 v131, 1.0, v131
	v_add_f32_e32 v132, 1.0, v132
	v_add_f32_e32 v133, 1.0, v133
	v_rcp_f32_e32 v126, v126
	v_rcp_f32_e32 v127, v127
	v_rcp_f32_e32 v128, v128
	v_rcp_f32_e32 v129, v129
	v_rcp_f32_e32 v130, v130
	v_rcp_f32_e32 v131, v131
	v_rcp_f32_e32 v132, v132
	v_rcp_f32_e32 v133, v133
	s_nop 0
	v_cvt_pk_bf16_f32 v98, v126, v127
	v_cvt_pk_bf16_f32 v99, v128, v129
	v_cvt_pk_bf16_f32 v100, v130, v131
	v_cvt_pk_bf16_f32 v101, v132, v133
	v_cndmask_b32_e64 v98, 0, v98, s[2:3]
	v_cndmask_b32_e64 v99, 0, v99, s[2:3]
	v_cndmask_b32_e64 v100, 0, v100, s[2:3]
	v_cndmask_b32_e64 v101, 0, v101, s[2:3]
	s_nop 1
	v_mfma_f32_32x32x16_bf16 v[80:95], v[98:101], v[208:211], v[80:95]
	v_mfma_f32_32x32x16_bf16 v[64:79], v[98:101], v[222:225], v[64:79]
	global_load_dwordx4 v[208:211], v[114:115], off offset:192
	global_load_dwordx4 v[222:225], v[116:117], off offset:192
	s_waitcnt vmcnt(14)
	v_lshlrev_b32_e32 v118, 16, v176
	v_and_b32_e32 v119, 0xffff0000, v176
	v_lshlrev_b32_e32 v120, 16, v177
	v_and_b32_e32 v121, 0xffff0000, v177
	v_lshlrev_b32_e32 v122, 16, v178
	v_and_b32_e32 v123, 0xffff0000, v178
	v_lshlrev_b32_e32 v124, 16, v179
	v_and_b32_e32 v125, 0xffff0000, v179
	v_cndmask_b32_e64 v180, 0, v180, s[4:5]
	v_cndmask_b32_e64 v181, 0, v181, s[4:5]
	v_cndmask_b32_e64 v182, 0, v182, s[4:5]
	v_cndmask_b32_e64 v183, 0, v183, s[4:5]
	v_lshlrev_b32_e32 v126, 16, v180
	v_and_b32_e32 v127, 0xffff0000, v180
	v_lshlrev_b32_e32 v128, 16, v181
	v_and_b32_e32 v129, 0xffff0000, v181
	v_lshlrev_b32_e32 v130, 16, v182
	v_and_b32_e32 v131, 0xffff0000, v182
	v_lshlrev_b32_e32 v132, 16, v183
	v_and_b32_e32 v133, 0xffff0000, v183
	global_load_dwordx4 v[176:179], v[102:103], off offset:3520
	global_load_dwordx4 v[180:183], v[104:105], off offset:448
	v_sub_f32_e32 v126, v126, v118
	v_sub_f32_e32 v127, v127, v119
	v_sub_f32_e32 v128, v128, v120
	v_sub_f32_e32 v129, v129, v121
	v_sub_f32_e32 v130, v130, v122
	v_sub_f32_e32 v131, v131, v123
	v_sub_f32_e32 v132, v132, v124
	v_sub_f32_e32 v133, v133, v125
	v_fmac_f32_e32 v118, v126, v184
	v_fmac_f32_e32 v119, v127, v185
	v_fmac_f32_e32 v120, v128, v186
	v_fmac_f32_e32 v121, v129, v187
	v_fmac_f32_e32 v122, v130, v188
	v_fmac_f32_e32 v123, v131, v189
	v_fmac_f32_e32 v124, v132, v190
	v_fmac_f32_e32 v125, v133, v191
	global_load_dwordx4 v[184:187], v[108:109], off offset:896
	global_load_dwordx4 v[188:191], v[108:109], off offset:912
	v_mul_f32_e32 v126, 0xbfb8aa3b, v118
	v_mul_f32_e32 v127, 0xbfb8aa3b, v119
	v_mul_f32_e32 v128, 0xbfb8aa3b, v120
	v_mul_f32_e32 v129, 0xbfb8aa3b, v121
	v_mul_f32_e32 v130, 0xbfb8aa3b, v122
	v_mul_f32_e32 v131, 0xbfb8aa3b, v123
	v_mul_f32_e32 v132, 0xbfb8aa3b, v124
	v_mul_f32_e32 v133, 0xbfb8aa3b, v125
	v_exp_f32_e32 v126, v126
	v_exp_f32_e32 v127, v127
	v_exp_f32_e32 v128, v128
	v_exp_f32_e32 v129, v129
	v_exp_f32_e32 v130, v130
	v_exp_f32_e32 v131, v131
	v_exp_f32_e32 v132, v132
	v_exp_f32_e32 v133, v133
	v_add_f32_e32 v126, 1.0, v126
	v_add_f32_e32 v127, 1.0, v127
	v_add_f32_e32 v128, 1.0, v128
	v_add_f32_e32 v129, 1.0, v129
	v_add_f32_e32 v130, 1.0, v130
	v_add_f32_e32 v131, 1.0, v131
	v_add_f32_e32 v132, 1.0, v132
	v_add_f32_e32 v133, 1.0, v133
	v_rcp_f32_e32 v126, v126
	v_rcp_f32_e32 v127, v127
	v_rcp_f32_e32 v128, v128
	v_rcp_f32_e32 v129, v129
	v_rcp_f32_e32 v130, v130
	v_rcp_f32_e32 v131, v131
	v_rcp_f32_e32 v132, v132
	v_rcp_f32_e32 v133, v133
	s_nop 0
	v_cvt_pk_bf16_f32 v98, v126, v127
	v_cvt_pk_bf16_f32 v99, v128, v129
	v_cvt_pk_bf16_f32 v100, v130, v131
	v_cvt_pk_bf16_f32 v101, v132, v133
	v_cndmask_b32_e64 v98, 0, v98, s[2:3]
	v_cndmask_b32_e64 v99, 0, v99, s[2:3]
	v_cndmask_b32_e64 v100, 0, v100, s[2:3]
	v_cndmask_b32_e64 v101, 0, v101, s[2:3]
	s_nop 1
	v_mfma_f32_32x32x16_bf16 v[80:95], v[98:101], v[226:229], v[80:95]
	v_mfma_f32_32x32x16_bf16 v[64:79], v[98:101], v[238:241], v[64:79]
	global_load_dwordx4 v[226:229], v[114:115], off offset:224
	global_load_dwordx4 v[238:241], v[116:117], off offset:224
	s_waitcnt vmcnt(14)
	v_lshlrev_b32_e32 v118, 16, v144
	v_and_b32_e32 v119, 0xffff0000, v144
	v_lshlrev_b32_e32 v120, 16, v145
	v_and_b32_e32 v121, 0xffff0000, v145
	v_lshlrev_b32_e32 v122, 16, v146
	v_and_b32_e32 v123, 0xffff0000, v146
	v_lshlrev_b32_e32 v124, 16, v147
	v_and_b32_e32 v125, 0xffff0000, v147
	v_cndmask_b32_e64 v148, 0, v148, s[4:5]
	v_cndmask_b32_e64 v149, 0, v149, s[4:5]
	v_cndmask_b32_e64 v150, 0, v150, s[4:5]
	v_cndmask_b32_e64 v151, 0, v151, s[4:5]
	v_lshlrev_b32_e32 v126, 16, v148
	v_and_b32_e32 v127, 0xffff0000, v148
	v_lshlrev_b32_e32 v128, 16, v149
	v_and_b32_e32 v129, 0xffff0000, v149
	v_lshlrev_b32_e32 v130, 16, v150
	v_and_b32_e32 v131, 0xffff0000, v150
	v_lshlrev_b32_e32 v132, 16, v151
	v_and_b32_e32 v133, 0xffff0000, v151
	global_load_dwordx4 v[144:147], v[102:103], off offset:3552
	global_load_dwordx4 v[148:151], v[104:105], off offset:480
	v_sub_f32_e32 v126, v126, v118
	v_sub_f32_e32 v127, v127, v119
	v_sub_f32_e32 v128, v128, v120
	v_sub_f32_e32 v129, v129, v121
	v_sub_f32_e32 v130, v130, v122
	v_sub_f32_e32 v131, v131, v123
	v_sub_f32_e32 v132, v132, v124
	v_sub_f32_e32 v133, v133, v125
	v_fmac_f32_e32 v118, v126, v152
	v_fmac_f32_e32 v119, v127, v153
	v_fmac_f32_e32 v120, v128, v154
	v_fmac_f32_e32 v121, v129, v155
	v_fmac_f32_e32 v122, v130, v156
	v_fmac_f32_e32 v123, v131, v157
	v_fmac_f32_e32 v124, v132, v158
	v_fmac_f32_e32 v125, v133, v159
	global_load_dwordx4 v[152:155], v[108:109], off offset:960
	global_load_dwordx4 v[156:159], v[108:109], off offset:976
	v_mul_f32_e32 v126, 0xbfb8aa3b, v118
	v_mul_f32_e32 v127, 0xbfb8aa3b, v119
	v_mul_f32_e32 v128, 0xbfb8aa3b, v120
	v_mul_f32_e32 v129, 0xbfb8aa3b, v121
	v_mul_f32_e32 v130, 0xbfb8aa3b, v122
	v_mul_f32_e32 v131, 0xbfb8aa3b, v123
	v_mul_f32_e32 v132, 0xbfb8aa3b, v124
	v_mul_f32_e32 v133, 0xbfb8aa3b, v125
	v_exp_f32_e32 v126, v126
	v_exp_f32_e32 v127, v127
	v_exp_f32_e32 v128, v128
	v_exp_f32_e32 v129, v129
	v_exp_f32_e32 v130, v130
	v_exp_f32_e32 v131, v131
	v_exp_f32_e32 v132, v132
	v_exp_f32_e32 v133, v133
	v_add_f32_e32 v126, 1.0, v126
	v_add_f32_e32 v127, 1.0, v127
	v_add_f32_e32 v128, 1.0, v128
	v_add_f32_e32 v129, 1.0, v129
	v_add_f32_e32 v130, 1.0, v130
	v_add_f32_e32 v131, 1.0, v131
	v_add_f32_e32 v132, 1.0, v132
	v_add_f32_e32 v133, 1.0, v133
	v_rcp_f32_e32 v126, v126
	v_rcp_f32_e32 v127, v127
	v_rcp_f32_e32 v128, v128
	v_rcp_f32_e32 v129, v129
	v_rcp_f32_e32 v130, v130
	v_rcp_f32_e32 v131, v131
	v_rcp_f32_e32 v132, v132
	v_rcp_f32_e32 v133, v133
	s_nop 0
	v_cvt_pk_bf16_f32 v98, v126, v127
	v_cvt_pk_bf16_f32 v99, v128, v129
	v_cvt_pk_bf16_f32 v100, v130, v131
	v_cvt_pk_bf16_f32 v101, v132, v133
	v_cndmask_b32_e64 v98, 0, v98, s[2:3]
	v_cndmask_b32_e64 v99, 0, v99, s[2:3]
	v_cndmask_b32_e64 v100, 0, v100, s[2:3]
	v_cndmask_b32_e64 v101, 0, v101, s[2:3]
	s_nop 1
	v_mfma_f32_32x32x16_bf16 v[80:95], v[98:101], v[192:195], v[80:95]
	v_mfma_f32_32x32x16_bf16 v[64:79], v[98:101], v[196:199], v[64:79]
	s_waitcnt vmcnt(12)
	v_lshlrev_b32_e32 v118, 16, v160
	v_and_b32_e32 v119, 0xffff0000, v160
	v_lshlrev_b32_e32 v120, 16, v161
	v_and_b32_e32 v121, 0xffff0000, v161
	v_lshlrev_b32_e32 v122, 16, v162
	v_and_b32_e32 v123, 0xffff0000, v162
	v_lshlrev_b32_e32 v124, 16, v163
	v_and_b32_e32 v125, 0xffff0000, v163
	v_cndmask_b32_e64 v164, 0, v164, s[4:5]
	v_cndmask_b32_e64 v165, 0, v165, s[4:5]
	v_cndmask_b32_e64 v166, 0, v166, s[4:5]
	v_cndmask_b32_e64 v167, 0, v167, s[4:5]
	v_lshlrev_b32_e32 v126, 16, v164
	v_and_b32_e32 v127, 0xffff0000, v164
	v_lshlrev_b32_e32 v128, 16, v165
	v_and_b32_e32 v129, 0xffff0000, v165
	v_lshlrev_b32_e32 v130, 16, v166
	v_and_b32_e32 v131, 0xffff0000, v166
	v_lshlrev_b32_e32 v132, 16, v167
	v_and_b32_e32 v133, 0xffff0000, v167
	v_sub_f32_e32 v126, v126, v118
	v_sub_f32_e32 v127, v127, v119
	v_sub_f32_e32 v128, v128, v120
	v_sub_f32_e32 v129, v129, v121
	v_sub_f32_e32 v130, v130, v122
	v_sub_f32_e32 v131, v131, v123
	v_sub_f32_e32 v132, v132, v124
	v_sub_f32_e32 v133, v133, v125
	v_fmac_f32_e32 v118, v126, v168
	v_fmac_f32_e32 v119, v127, v169
	v_fmac_f32_e32 v120, v128, v170
	v_fmac_f32_e32 v121, v129, v171
	v_fmac_f32_e32 v122, v130, v172
	v_fmac_f32_e32 v123, v131, v173
	v_fmac_f32_e32 v124, v132, v174
	v_fmac_f32_e32 v125, v133, v175
	v_mul_f32_e32 v126, 0xbfb8aa3b, v118
	v_mul_f32_e32 v127, 0xbfb8aa3b, v119
	v_mul_f32_e32 v128, 0xbfb8aa3b, v120
	v_mul_f32_e32 v129, 0xbfb8aa3b, v121
	v_mul_f32_e32 v130, 0xbfb8aa3b, v122
	v_mul_f32_e32 v131, 0xbfb8aa3b, v123
	v_mul_f32_e32 v132, 0xbfb8aa3b, v124
	v_mul_f32_e32 v133, 0xbfb8aa3b, v125
	v_exp_f32_e32 v126, v126
	v_exp_f32_e32 v127, v127
	v_exp_f32_e32 v128, v128
	v_exp_f32_e32 v129, v129
	v_exp_f32_e32 v130, v130
	v_exp_f32_e32 v131, v131
	v_exp_f32_e32 v132, v132
	v_exp_f32_e32 v133, v133
	v_add_f32_e32 v126, 1.0, v126
	v_add_f32_e32 v127, 1.0, v127
	v_add_f32_e32 v128, 1.0, v128
	v_add_f32_e32 v129, 1.0, v129
	v_add_f32_e32 v130, 1.0, v130
	v_add_f32_e32 v131, 1.0, v131
	v_add_f32_e32 v132, 1.0, v132
	v_add_f32_e32 v133, 1.0, v133
	v_rcp_f32_e32 v126, v126
	v_rcp_f32_e32 v127, v127
	v_rcp_f32_e32 v128, v128
	v_rcp_f32_e32 v129, v129
	v_rcp_f32_e32 v130, v130
	v_rcp_f32_e32 v131, v131
	v_rcp_f32_e32 v132, v132
	v_rcp_f32_e32 v133, v133
	s_nop 0
	v_cvt_pk_bf16_f32 v98, v126, v127
	v_cvt_pk_bf16_f32 v99, v128, v129
	v_cvt_pk_bf16_f32 v100, v130, v131
	v_cvt_pk_bf16_f32 v101, v132, v133
	v_cndmask_b32_e64 v98, 0, v98, s[2:3]
	v_cndmask_b32_e64 v99, 0, v99, s[2:3]
	v_cndmask_b32_e64 v100, 0, v100, s[2:3]
	v_cndmask_b32_e64 v101, 0, v101, s[2:3]
	s_nop 1
	v_mfma_f32_32x32x16_bf16 v[80:95], v[98:101], v[200:203], v[80:95]
	v_mfma_f32_32x32x16_bf16 v[64:79], v[98:101], v[204:207], v[64:79]
	s_waitcnt vmcnt(6)
	v_lshlrev_b32_e32 v118, 16, v176
	v_and_b32_e32 v119, 0xffff0000, v176
	v_lshlrev_b32_e32 v120, 16, v177
	v_and_b32_e32 v121, 0xffff0000, v177
	v_lshlrev_b32_e32 v122, 16, v178
	v_and_b32_e32 v123, 0xffff0000, v178
	v_lshlrev_b32_e32 v124, 16, v179
	v_and_b32_e32 v125, 0xffff0000, v179
	v_cndmask_b32_e64 v180, 0, v180, s[4:5]
	v_cndmask_b32_e64 v181, 0, v181, s[4:5]
	v_cndmask_b32_e64 v182, 0, v182, s[4:5]
	v_cndmask_b32_e64 v183, 0, v183, s[4:5]
	v_lshlrev_b32_e32 v126, 16, v180
	v_and_b32_e32 v127, 0xffff0000, v180
	v_lshlrev_b32_e32 v128, 16, v181
	v_and_b32_e32 v129, 0xffff0000, v181
	v_lshlrev_b32_e32 v130, 16, v182
	v_and_b32_e32 v131, 0xffff0000, v182
	v_lshlrev_b32_e32 v132, 16, v183
	v_and_b32_e32 v133, 0xffff0000, v183
	v_sub_f32_e32 v126, v126, v118
	v_sub_f32_e32 v127, v127, v119
	v_sub_f32_e32 v128, v128, v120
	v_sub_f32_e32 v129, v129, v121
	v_sub_f32_e32 v130, v130, v122
	v_sub_f32_e32 v131, v131, v123
	v_sub_f32_e32 v132, v132, v124
	v_sub_f32_e32 v133, v133, v125
	v_fmac_f32_e32 v118, v126, v184
	v_fmac_f32_e32 v119, v127, v185
	v_fmac_f32_e32 v120, v128, v186
	v_fmac_f32_e32 v121, v129, v187
	v_fmac_f32_e32 v122, v130, v188
	v_fmac_f32_e32 v123, v131, v189
	v_fmac_f32_e32 v124, v132, v190
	v_fmac_f32_e32 v125, v133, v191
	v_mul_f32_e32 v126, 0xbfb8aa3b, v118
	v_mul_f32_e32 v127, 0xbfb8aa3b, v119
	v_mul_f32_e32 v128, 0xbfb8aa3b, v120
	v_mul_f32_e32 v129, 0xbfb8aa3b, v121
	v_mul_f32_e32 v130, 0xbfb8aa3b, v122
	v_mul_f32_e32 v131, 0xbfb8aa3b, v123
	v_mul_f32_e32 v132, 0xbfb8aa3b, v124
	v_mul_f32_e32 v133, 0xbfb8aa3b, v125
	v_exp_f32_e32 v126, v126
	v_exp_f32_e32 v127, v127
	v_exp_f32_e32 v128, v128
	v_exp_f32_e32 v129, v129
	v_exp_f32_e32 v130, v130
	v_exp_f32_e32 v131, v131
	v_exp_f32_e32 v132, v132
	v_exp_f32_e32 v133, v133
	v_add_f32_e32 v126, 1.0, v126
	v_add_f32_e32 v127, 1.0, v127
	v_add_f32_e32 v128, 1.0, v128
	v_add_f32_e32 v129, 1.0, v129
	v_add_f32_e32 v130, 1.0, v130
	v_add_f32_e32 v131, 1.0, v131
	v_add_f32_e32 v132, 1.0, v132
	v_add_f32_e32 v133, 1.0, v133
	v_rcp_f32_e32 v126, v126
	v_rcp_f32_e32 v127, v127
	v_rcp_f32_e32 v128, v128
	v_rcp_f32_e32 v129, v129
	v_rcp_f32_e32 v130, v130
	v_rcp_f32_e32 v131, v131
	v_rcp_f32_e32 v132, v132
	v_rcp_f32_e32 v133, v133
	s_nop 0
	v_cvt_pk_bf16_f32 v98, v126, v127
	v_cvt_pk_bf16_f32 v99, v128, v129
	v_cvt_pk_bf16_f32 v100, v130, v131
	v_cvt_pk_bf16_f32 v101, v132, v133
	v_cndmask_b32_e64 v98, 0, v98, s[2:3]
	v_cndmask_b32_e64 v99, 0, v99, s[2:3]
	v_cndmask_b32_e64 v100, 0, v100, s[2:3]
	v_cndmask_b32_e64 v101, 0, v101, s[2:3]
	s_nop 1
	v_mfma_f32_32x32x16_bf16 v[80:95], v[98:101], v[208:211], v[80:95]
	v_mfma_f32_32x32x16_bf16 v[64:79], v[98:101], v[222:225], v[64:79]
	s_waitcnt vmcnt(0)
	v_lshlrev_b32_e32 v118, 16, v144
	v_and_b32_e32 v119, 0xffff0000, v144
	v_lshlrev_b32_e32 v120, 16, v145
	v_and_b32_e32 v121, 0xffff0000, v145
	v_lshlrev_b32_e32 v122, 16, v146
	v_and_b32_e32 v123, 0xffff0000, v146
	v_lshlrev_b32_e32 v124, 16, v147
	v_and_b32_e32 v125, 0xffff0000, v147
	v_cndmask_b32_e64 v148, 0, v148, s[4:5]
	v_cndmask_b32_e64 v149, 0, v149, s[4:5]
	v_cndmask_b32_e64 v150, 0, v150, s[4:5]
	v_cndmask_b32_e64 v151, 0, v151, s[4:5]
	v_lshlrev_b32_e32 v126, 16, v148
	v_and_b32_e32 v127, 0xffff0000, v148
	v_lshlrev_b32_e32 v128, 16, v149
	v_and_b32_e32 v129, 0xffff0000, v149
	v_lshlrev_b32_e32 v130, 16, v150
	v_and_b32_e32 v131, 0xffff0000, v150
	v_lshlrev_b32_e32 v132, 16, v151
	v_and_b32_e32 v133, 0xffff0000, v151
	v_sub_f32_e32 v126, v126, v118
	v_sub_f32_e32 v127, v127, v119
	v_sub_f32_e32 v128, v128, v120
	v_sub_f32_e32 v129, v129, v121
	v_sub_f32_e32 v130, v130, v122
	v_sub_f32_e32 v131, v131, v123
	v_sub_f32_e32 v132, v132, v124
	v_sub_f32_e32 v133, v133, v125
	v_fmac_f32_e32 v118, v126, v152
	v_fmac_f32_e32 v119, v127, v153
	v_fmac_f32_e32 v120, v128, v154
	v_fmac_f32_e32 v121, v129, v155
	v_fmac_f32_e32 v122, v130, v156
	v_fmac_f32_e32 v123, v131, v157
	v_fmac_f32_e32 v124, v132, v158
	v_fmac_f32_e32 v125, v133, v159
	v_mul_f32_e32 v126, 0xbfb8aa3b, v118
	v_mul_f32_e32 v127, 0xbfb8aa3b, v119
	v_mul_f32_e32 v128, 0xbfb8aa3b, v120
	v_mul_f32_e32 v129, 0xbfb8aa3b, v121
	v_mul_f32_e32 v130, 0xbfb8aa3b, v122
	v_mul_f32_e32 v131, 0xbfb8aa3b, v123
	v_mul_f32_e32 v132, 0xbfb8aa3b, v124
	v_mul_f32_e32 v133, 0xbfb8aa3b, v125
	v_exp_f32_e32 v126, v126
	v_exp_f32_e32 v127, v127
	v_exp_f32_e32 v128, v128
	v_exp_f32_e32 v129, v129
	v_exp_f32_e32 v130, v130
	v_exp_f32_e32 v131, v131
	v_exp_f32_e32 v132, v132
	v_exp_f32_e32 v133, v133
	v_add_f32_e32 v126, 1.0, v126
	v_add_f32_e32 v127, 1.0, v127
	v_add_f32_e32 v128, 1.0, v128
	v_add_f32_e32 v129, 1.0, v129
	v_add_f32_e32 v130, 1.0, v130
	v_add_f32_e32 v131, 1.0, v131
	v_add_f32_e32 v132, 1.0, v132
	v_add_f32_e32 v133, 1.0, v133
	v_rcp_f32_e32 v126, v126
	v_rcp_f32_e32 v127, v127
	v_rcp_f32_e32 v128, v128
	v_rcp_f32_e32 v129, v129
	v_rcp_f32_e32 v130, v130
	v_rcp_f32_e32 v131, v131
	v_rcp_f32_e32 v132, v132
	v_rcp_f32_e32 v133, v133
	s_nop 0
	v_cvt_pk_bf16_f32 v98, v126, v127
	v_cvt_pk_bf16_f32 v99, v128, v129
	v_cvt_pk_bf16_f32 v100, v130, v131
	v_cvt_pk_bf16_f32 v101, v132, v133
	v_cndmask_b32_e64 v98, 0, v98, s[2:3]
	v_cndmask_b32_e64 v99, 0, v99, s[2:3]
	v_cndmask_b32_e64 v100, 0, v100, s[2:3]
	v_cndmask_b32_e64 v101, 0, v101, s[2:3]
	s_nop 1
	v_mfma_f32_32x32x16_bf16 v[80:95], v[98:101], v[226:229], v[80:95]
	v_mfma_f32_32x32x16_bf16 v[64:79], v[98:101], v[238:241], v[64:79]
	s_ashr_i32 s3, s10, 31
	s_add_u32 s2, s6, s10
	v_lshlrev_b32_e32 v108, 2, v138
	s_addc_u32 s3, s7, s3
	v_ashrrev_i32_e32 v109, 31, v108
	v_lshl_add_u64 v[102:103], s[2:3], 0, v[108:109]
	v_lshlrev_b64 v[98:99], 10, v[102:103]
	v_lshl_add_u64 v[98:99], s[86:87], 0, v[98:99]
	s_lshl_b32 s38, s11, 1
	v_lshl_add_u64 v[100:101], v[98:99], 0, s[38:39]
	v_lshlrev_b32_e32 v98, 1, v107
	v_mov_b32_e32 v99, v97
	v_or_b32_e32 v104, s11, v107
	v_lshl_add_u64 v[110:111], v[100:101], 0, v[98:99]
	v_or_b32_e32 v100, s34, v104
	v_mov_b32_e32 v101, s35
	v_readlane_b32 s16, v254, 50
	v_lshlrev_b64 v[100:101], 2, v[100:101]
	v_readlane_b32 s17, v254, 51
	v_readlane_b32 s18, v254, 52
	v_readlane_b32 s19, v254, 53
	v_readlane_b32 s20, v254, 54
	v_readlane_b32 s21, v254, 55
	v_readlane_b32 s22, v254, 56
	v_readlane_b32 s23, v254, 57
	v_readlane_b32 s24, v254, 58
	v_readlane_b32 s25, v254, 59
	v_readlane_b32 s26, v254, 60
	v_readlane_b32 s27, v254, 61
	v_readlane_b32 s28, v254, 62
	v_readlane_b32 s29, v254, 63
	v_readlane_b32 s30, v255, 0
	v_readlane_b32 s31, v255, 1
	v_lshl_add_u64 v[112:113], s[28:29], 0, v[100:101]
	v_readlane_b32 s16, v253, 34
	v_readlane_b32 s17, v253, 35
	global_load_dword v96, v[112:113], off
	s_nop 0
	v_lshl_add_u64 v[112:113], s[16:17], 0, v[100:101]
	global_load_dword v112, v[112:113], off
	v_cvt_pk_bf16_f32 v80, v80, v80
	global_store_short_d16_hi v[110:111], v80, off
	v_cvt_pk_bf16_f32 v80, v81, v81
	global_store_short_d16_hi v[110:111], v80, off offset:1024
	v_cvt_pk_bf16_f32 v80, v82, v82
	global_store_short_d16_hi v[110:111], v80, off offset:2048
	v_cvt_pk_bf16_f32 v80, v83, v83
	global_store_short_d16_hi v[110:111], v80, off offset:3072
	v_cvt_pk_bf16_f32 v82, v84, v84
	v_add_co_u32_e32 v80, vcc, s74, v110
	v_readlane_b32 s18, v253, 36
	s_nop 0
	v_addc_co_u32_e32 v81, vcc, 0, v111, vcc
	global_store_short_d16_hi v[80:81], v82, off
	v_cvt_pk_bf16_f32 v82, v85, v85
	global_store_short_d16_hi v[80:81], v82, off offset:1024
	v_cvt_pk_bf16_f32 v82, v86, v86
	global_store_short_d16_hi v[80:81], v82, off offset:2048
	v_cvt_pk_bf16_f32 v82, v87, v87
	global_store_short_d16_hi v[80:81], v82, off offset:3072
	v_cndmask_b32_e64 v82, 0, 1, s[0:1]
	v_cmp_ne_u32_e64 s[2:3], 1, v82
	s_andn2_b64 vcc, exec, s[0:1]
	v_readlane_b32 s19, v253, 37
	v_readlane_b32 s20, v253, 38
	v_readlane_b32 s21, v253, 39
	v_readlane_b32 s22, v253, 40
	v_readlane_b32 s23, v253, 41
	v_readlane_b32 s24, v253, 42
	v_readlane_b32 s25, v253, 43
	v_readlane_b32 s26, v253, 44
	v_readlane_b32 s27, v253, 45
	v_readlane_b32 s28, v253, 46
	v_readlane_b32 s29, v253, 47
	v_readlane_b32 s30, v253, 48
	v_readlane_b32 s31, v253, 49
	s_cbranch_vccnz .LBB0_904
	v_cvt_pk_bf16_f32 v84, v88, v88
	v_add_co_u32_e32 v82, vcc, 0x4000, v110
	s_nop 1
	v_addc_co_u32_e32 v83, vcc, 0, v111, vcc
	global_store_short_d16_hi v[82:83], v84, off
	s_and_b64 vcc, exec, s[2:3]
	s_cbranch_vccz .LBB0_905

.LBB0_899:
	v_cvt_pk_bf16_f32 v84, v90, v90
	v_add_co_u32_e32 v82, vcc, 0x4000, v110
	s_nop 1
	v_addc_co_u32_e32 v83, vcc, 0, v111, vcc
	global_store_short_d16_hi v[82:83], v84, off offset:2048
	s_and_b64 vcc, exec, s[2:3]
	s_cbranch_vccz .LBB0_907

.LBB0_901:
	v_cvt_pk_bf16_f32 v84, v92, v92
	v_add_co_u32_e32 v82, vcc, 0x6000, v110
	s_nop 1
	v_addc_co_u32_e32 v83, vcc, 0, v111, vcc
	global_store_short_d16_hi v[82:83], v84, off
	s_and_b64 vcc, exec, s[2:3]
	s_cbranch_vccz .LBB0_909

.LBB0_903:
	v_cvt_pk_bf16_f32 v84, v94, v94
	v_add_co_u32_e32 v82, vcc, 0x6000, v110
	s_nop 1
	v_addc_co_u32_e32 v83, vcc, 0, v111, vcc
	global_store_short_d16_hi v[82:83], v84, off offset:2048
	s_and_b64 vcc, exec, s[2:3]
	s_cbranch_vccz .LBB0_911
	s_branch .LBB0_912

.LBB0_905:
	v_cvt_pk_bf16_f32 v84, v89, v89
	v_add_co_u32_e32 v82, vcc, 0x4000, v110
	s_nop 1
	v_addc_co_u32_e32 v83, vcc, 0, v111, vcc
	global_store_short_d16_hi v[82:83], v84, off offset:1024
	s_and_b64 vcc, exec, s[2:3]
	s_cbranch_vccz .LBB0_899

.LBB0_907:
	v_cvt_pk_bf16_f32 v84, v91, v91
	v_add_co_u32_e32 v82, vcc, 0x4000, v110
	s_nop 1
	v_addc_co_u32_e32 v83, vcc, 0, v111, vcc
	global_store_short_d16_hi v[82:83], v84, off offset:3072
	s_and_b64 vcc, exec, s[2:3]
	s_cbranch_vccz .LBB0_901

.LBB0_909:
	v_cvt_pk_bf16_f32 v84, v93, v93
	v_add_co_u32_e32 v82, vcc, 0x6000, v110
	s_nop 1
	v_addc_co_u32_e32 v83, vcc, 0, v111, vcc
	global_store_short_d16_hi v[82:83], v84, off offset:1024
	s_and_b64 vcc, exec, s[2:3]
	s_cbranch_vccz .LBB0_903

.LBB0_911:
	v_cvt_pk_bf16_f32 v84, v95, v95
	v_add_co_u32_e32 v82, vcc, 0x6000, v110
	s_nop 1
	v_addc_co_u32_e32 v83, vcc, 0, v111, vcc
	global_store_short_d16_hi v[82:83], v84, off offset:3072
.LBB0_912:
	v_lshlrev_b32_e32 v82, 2, v104
	global_load_dword v83, v82, s[94:95] offset:128
	global_load_dword v84, v82, s[58:59] offset:128
	v_cvt_pk_bf16_f32 v64, v64, v64
	global_store_short_d16_hi v[110:111], v64, off offset:64
	v_cvt_pk_bf16_f32 v64, v65, v65
	global_store_short_d16_hi v[110:111], v64, off offset:1088
	v_cvt_pk_bf16_f32 v64, v66, v66
	global_store_short_d16_hi v[110:111], v64, off offset:2112
	v_cvt_pk_bf16_f32 v64, v67, v67
	global_store_short_d16_hi v[110:111], v64, off offset:3136
	v_cvt_pk_bf16_f32 v64, v68, v68
	global_store_short_d16_hi v[80:81], v64, off offset:64
	v_cvt_pk_bf16_f32 v64, v69, v69
	global_store_short_d16_hi v[80:81], v64, off offset:1088
	v_cvt_pk_bf16_f32 v64, v70, v70
	global_store_short_d16_hi v[80:81], v64, off offset:2112
	v_mov_b32_e32 v105, v97
	v_cvt_pk_bf16_f32 v64, v71, v71
	s_and_b64 vcc, exec, s[2:3]
	global_store_short_d16_hi v[80:81], v64, off offset:3136
	s_cbranch_vccnz .LBB0_920
	v_cvt_pk_bf16_f32 v66, v72, v72
	v_add_co_u32_e32 v64, vcc, 0x4000, v110
	s_nop 1
	v_addc_co_u32_e32 v65, vcc, 0, v111, vcc
	global_store_short_d16_hi v[64:65], v66, off offset:64
	s_and_b64 vcc, exec, s[2:3]
	s_cbranch_vccz .LBB0_921

.LBB0_915:
	v_cvt_pk_bf16_f32 v66, v74, v74
	v_add_co_u32_e32 v64, vcc, 0x4000, v110
	s_nop 1
	v_addc_co_u32_e32 v65, vcc, 0, v111, vcc
	global_store_short_d16_hi v[64:65], v66, off offset:2112
	s_and_b64 vcc, exec, s[2:3]
	s_cbranch_vccz .LBB0_923

.LBB0_917:
	v_cvt_pk_bf16_f32 v66, v76, v76
	v_add_co_u32_e32 v64, vcc, 0x6000, v110
	s_nop 1
	v_addc_co_u32_e32 v65, vcc, 0, v111, vcc
	global_store_short_d16_hi v[64:65], v66, off offset:64
	s_and_b64 vcc, exec, s[2:3]
	s_cbranch_vccz .LBB0_925

.LBB0_919:
	v_cvt_pk_bf16_f32 v66, v78, v78
	v_add_co_u32_e32 v64, vcc, 0x6000, v110
	s_nop 1
	v_addc_co_u32_e32 v65, vcc, 0, v111, vcc
	global_store_short_d16_hi v[64:65], v66, off offset:2112
	s_and_b64 vcc, exec, s[2:3]
	s_cbranch_vccz .LBB0_927
	s_branch .LBB0_928

.LBB0_921:
	v_cvt_pk_bf16_f32 v66, v73, v73
	v_add_co_u32_e32 v64, vcc, 0x4000, v110
	s_nop 1
	v_addc_co_u32_e32 v65, vcc, 0, v111, vcc
	global_store_short_d16_hi v[64:65], v66, off offset:1088
	s_and_b64 vcc, exec, s[2:3]
	s_cbranch_vccz .LBB0_915

.LBB0_923:
	v_cvt_pk_bf16_f32 v66, v75, v75
	v_add_co_u32_e32 v64, vcc, 0x4000, v110
	s_nop 1
	v_addc_co_u32_e32 v65, vcc, 0, v111, vcc
	global_store_short_d16_hi v[64:65], v66, off offset:3136
	s_and_b64 vcc, exec, s[2:3]
	s_cbranch_vccz .LBB0_917

.LBB0_925:
	v_cvt_pk_bf16_f32 v66, v77, v77
	v_add_co_u32_e32 v64, vcc, 0x6000, v110
	s_nop 1
	v_addc_co_u32_e32 v65, vcc, 0, v111, vcc
	global_store_short_d16_hi v[64:65], v66, off offset:1088
	s_and_b64 vcc, exec, s[2:3]
	s_cbranch_vccz .LBB0_919

.LBB0_927:
	v_cvt_pk_bf16_f32 v66, v79, v79
	v_add_co_u32_e32 v64, vcc, 0x6000, v110
	s_nop 1
	v_addc_co_u32_e32 v65, vcc, 0, v111, vcc
	global_store_short_d16_hi v[64:65], v66, off offset:3136

.LBB0_935:
	s_or_b64 exec, exec, s[4:5]
	s_waitcnt vmcnt(8)
	v_add_f32_e32 v16, v16, v84
	v_mul_f32_e32 v16, 0xbfb8aa3b, v16
	v_add_f32_e32 v17, v17, v84
	v_exp_f32_e32 v16, v16
	v_mul_f32_e32 v17, 0xbfb8aa3b, v17
	v_add_f32_e32 v18, v18, v84
	v_exp_f32_e32 v17, v17
	v_mul_f32_e32 v18, 0xbfb8aa3b, v18
	v_exp_f32_e32 v18, v18
	v_add_f32_e32 v16, 1.0, v16
	v_cndmask_b32_e64 v126, v79, v52, s[0:1]
	v_rcp_f32_e32 v52, v16
	v_add_f32_e32 v16, 1.0, v17
	v_add_f32_e32 v17, v19, v84
	v_cndmask_b32_e64 v124, v85, v65, s[0:1]
	v_cndmask_b32_e64 v85, v70, v53, s[0:1]
	v_rcp_f32_e32 v53, v16
	v_add_f32_e32 v16, 1.0, v18
	v_mul_f32_e32 v17, 0xbfb8aa3b, v17
	v_add_f32_e32 v18, v20, v84
	v_exp_f32_e32 v17, v17
	v_mul_f32_e32 v18, 0xbfb8aa3b, v18
	v_exp_f32_e32 v18, v18
	v_cndmask_b32_e64 v118, v73, v46, s[0:1]
	v_rcp_f32_e32 v46, v16
	v_add_f32_e32 v16, 1.0, v17
	v_add_f32_e32 v17, v21, v84
	v_add_f32_e32 v2, v2, v112
	v_cndmask_b32_e64 v127, v78, v47, s[0:1]
	v_rcp_f32_e32 v47, v16
	v_add_f32_e32 v16, 1.0, v18
	v_mul_f32_e32 v17, 0xbfb8aa3b, v17
	v_add_f32_e32 v18, v22, v84
	v_mul_f32_e32 v2, 0xbfb8aa3b, v2
	v_add_f32_e32 v3, v3, v112
	v_exp_f32_e32 v17, v17
	v_mul_f32_e32 v18, 0xbfb8aa3b, v18
	v_exp_f32_e32 v2, v2
	v_mul_f32_e32 v3, 0xbfb8aa3b, v3
	v_exp_f32_e32 v18, v18
	v_exp_f32_e32 v3, v3
	v_add_f32_e32 v4, v4, v112
	v_mul_f32_e32 v4, 0xbfb8aa3b, v4
	v_cndmask_b32_e64 v116, v77, v44, s[0:1]
	v_rcp_f32_e32 v44, v16
	v_add_f32_e32 v16, 1.0, v17
	v_add_f32_e32 v2, 1.0, v2
	v_exp_f32_e32 v4, v4
	v_readlane_b32 s16, v253, 34
	v_cndmask_b32_e64 v117, v76, v45, s[0:1]
	v_rcp_f32_e32 v45, v16
	v_add_f32_e32 v16, 1.0, v18
	v_rcp_f32_e32 v18, v2
	v_add_f32_e32 v2, 1.0, v3
	s_waitcnt lgkmcnt(0)
	v_readlane_b32 s22, v253, 40
	v_readlane_b32 s23, v253, 41
	v_rcp_f32_e32 v19, v2
	v_cndmask_b32_e64 v125, v83, v66, s[0:1]
	v_lshl_add_u64 v[2:3], s[22:23], 0, v[100:101]
	v_cndmask_b32_e64 v119, v72, v42, s[0:1]
	global_load_dword v66, v82, s[60:61] offset:2048
	global_load_dword v72, v82, s[60:61]
	global_load_dword v214, v[2:3], off
	v_add_f32_e32 v2, v5, v112
	v_add_f32_e32 v4, 1.0, v4
	v_mul_f32_e32 v2, 0xbfb8aa3b, v2
	v_exp_f32_e32 v3, v2
	global_load_dword v38, v82, s[60:61] offset:2176
	global_load_dword v42, v82, s[60:61] offset:128
	v_rcp_f32_e32 v2, v4
	v_add_f32_e32 v4, v6, v112
	v_readlane_b32 s24, v253, 42
	v_readlane_b32 s25, v253, 43
	v_mul_f32_e32 v4, 0xbfb8aa3b, v4
	v_exp_f32_e32 v6, v4
	v_lshl_add_u64 v[4:5], s[24:25], 0, v[100:101]
	v_cndmask_b32_e64 v65, v68, v62, s[0:1]
	global_load_dword v32, v82, s[82:83] offset:128
	global_load_dword v62, v[4:5], off
	v_readlane_b32 s26, v253, 44
	v_readlane_b32 s27, v253, 45
	v_cndmask_b32_e64 v35, v89, v63, s[0:1]
	v_cndmask_b32_e64 v67, v67, v57, s[0:1]
	v_lshl_add_u64 v[4:5], s[26:27], 0, v[100:101]
	global_load_dword v22, v[4:5], off
	global_load_dword v34, v82, s[70:71] offset:128
	v_cndmask_b32_e64 v89, v69, v56, s[0:1]
	v_lshl_add_u64 v[56:57], s[34:35], 0, v[104:105]
	v_lshl_add_u64 v[4:5], v[56:57], 2, s[26:27]
	global_load_dword v20, v[4:5], off offset:128
	v_add_f32_e32 v7, v7, v112
	v_mul_f32_e32 v7, 0xbfb8aa3b, v7
	v_exp_f32_e32 v7, v7
	v_add_f32_e32 v4, 1.0, v6
	v_rcp_f32_e32 v78, v4
	v_mov_b32_e32 v83, v97
	v_add_f32_e32 v4, 1.0, v7
	v_rcp_f32_e32 v79, v4
	v_add_f32_e32 v4, v8, v112
	v_mul_f32_e32 v4, 0xbfb8aa3b, v4
	v_exp_f32_e32 v6, v4
	v_lshl_add_u64 v[4:5], s[60:61], 0, v[82:83]
	s_movk_i32 s5, 0x1000
	v_add_co_u32_e32 v4, vcc, s5, v4
	v_cndmask_b32_e64 v63, v88, v64, s[0:1]
	s_nop 0
	v_addc_co_u32_e32 v5, vcc, 0, v5, vcc
	global_load_dword v64, v[4:5], off
	global_load_dword v36, v[4:5], off offset:128
	v_add_f32_e32 v17, v23, v84
	v_mul_f32_e32 v17, 0xbfb8aa3b, v17
	v_exp_f32_e32 v17, v17
	v_lshlrev_b64 v[54:55], 9, v[102:103]
	v_lshl_add_u64 v[4:5], v[54:55], 1, s[88:89]
	v_rcp_f32_e32 v40, v16
	v_add_f32_e32 v16, 1.0, v17
	v_lshl_add_u64 v[4:5], v[4:5], 0, s[38:39]
	v_mov_b32_e32 v99, v97
	v_cmp_lt_i32_e32 vcc, v246, v252
	v_rcp_f32_e32 v41, v16
	v_lshl_add_u64 v[16:17], v[4:5], 0, v[98:99]
	v_cndmask_b32_e32 v4, v217, v246, vcc
	v_cmp_lt_i32_e32 vcc, v247, v252
	v_lshlrev_b32_e32 v94, 2, v4
	s_movk_i32 s5, 0x640
	v_cndmask_b32_e32 v4, v217, v247, vcc
	v_cmp_lt_i32_e32 vcc, v248, v252
	v_lshlrev_b32_e32 v90, 2, v4
	v_add_f32_e32 v0, v0, v112
	v_cndmask_b32_e32 v4, v217, v248, vcc
	v_cmp_lt_i32_e32 vcc, v221, v252
	v_lshlrev_b32_e32 v88, 2, v4
	v_add_f32_e32 v1, v1, v112
	v_cndmask_b32_e32 v4, v217, v221, vcc
	v_lshlrev_b32_e32 v82, 2, v4
	v_mul_lo_u32 v4, v138, s5
	v_mul_f32_e32 v0, 0xbfb8aa3b, v0
	v_mul_f32_e32 v1, 0xbfb8aa3b, v1
	v_add_f32_e32 v6, 1.0, v6
	v_add3_u32 v33, s76, v4, v98
	v_cndmask_b32_e64 v140, v71, v43, s[0:1]
	v_exp_f32_e32 v0, v0
	v_exp_f32_e32 v1, v1
	v_rcp_f32_e32 v83, v6
	ds_read_u16 v21, v33 offset:256
	ds_read_u16 v4, v33 offset:128
	ds_read_u16 v5, v33
	ds_read_u16 v6, v33 offset:400
	ds_read_u16 v7, v33 offset:464
	ds_read_u16 v23, v33 offset:320
	ds_read_u16 v43, v33 offset:192
	ds_read_u16 v54, v33 offset:64
	ds_read_u16 v55, v33 offset:528
	ds_read_u16 v57, v33 offset:656
	ds_read_u16 v68, v33 offset:720
	ds_read_u16 v69, v33 offset:592
	s_waitcnt lgkmcnt(9)
	v_lshlrev_b32_e32 v56, 16, v5
	s_waitcnt lgkmcnt(8)
	v_lshlrev_b32_e32 v70, 16, v6
	v_add_f32_e32 v0, 1.0, v0
	v_add_f32_e32 v1, 1.0, v1
	v_sub_f32_e32 v6, v56, v70
	v_rcp_f32_e32 v0, v0
	v_rcp_f32_e32 v1, v1
	s_waitcnt vmcnt(10)
	v_fmac_f32_e32 v70, v72, v6
	s_waitcnt lgkmcnt(4)
	v_lshlrev_b32_e32 v6, 16, v54
	v_lshlrev_b32_e32 v56, 16, v7
	v_sub_f32_e32 v6, v6, v56
	v_lshlrev_b32_e32 v4, 16, v4
	s_waitcnt lgkmcnt(3)
	v_lshlrev_b32_e32 v55, 16, v55
	s_waitcnt vmcnt(7)
	v_fmac_f32_e32 v56, v42, v6
	v_lshlrev_b32_e32 v6, 16, v43
	s_waitcnt lgkmcnt(0)
	v_lshlrev_b32_e32 v43, 16, v69
	v_sub_f32_e32 v4, v4, v55
	v_sub_f32_e32 v6, v6, v43
	v_fmac_f32_e32 v55, v66, v4
	v_pk_add_f32 v[4:5], v[0:1], -1.0 op_sel_hi:[1,0]
	v_fmac_f32_e32 v43, v38, v6
	s_waitcnt vmcnt(6)
	v_mul_f32_e32 v54, v32, v43
	s_waitcnt vmcnt(5)
	v_pk_fma_f32 v[4:5], v[4:5], v[62:63], 1.0 op_sel_hi:[1,0,0]
	v_mul_f32_e32 v69, v54, v54
	v_mul_f32_e32 v54, v4, v55
	v_pk_add_f32 v[6:7], v[52:53], -1.0 op_sel_hi:[1,0]
	v_mul_f32_e32 v54, v70, v54
	v_mul_f32_e32 v71, v214, v55
	s_waitcnt vmcnt(4)
	v_fma_f32 v70, v22, v54, 0
	s_waitcnt vmcnt(3)
	v_pk_fma_f32 v[54:55], v[6:7], v[34:35], 1.0 op_sel_hi:[1,0,0]
	v_fmac_f32_e32 v69, v71, v71
	v_mul_f32_e32 v6, v54, v43
	v_mul_f32_e32 v6, v56, v6
	s_waitcnt vmcnt(2)
	v_fmac_f32_e32 v70, v20, v6
	ds_bpermute_b32 v6, v94, v70
	ds_bpermute_b32 v71, v94, v69
	v_cmp_lt_i32_e32 vcc, v216, v252
	v_lshlrev_b32_e32 v7, 16, v57
	v_lshlrev_b32_e32 v21, 16, v21
	s_waitcnt lgkmcnt(1)
	v_add_f32_e32 v6, v70, v6
	ds_bpermute_b32 v56, v90, v6
	v_cndmask_b32_e32 v8, v217, v216, vcc
	v_lshlrev_b32_e32 v101, 2, v8
	s_waitcnt lgkmcnt(1)
	v_add_f32_e32 v8, v69, v71
	ds_bpermute_b32 v43, v90, v8
	s_waitcnt lgkmcnt(1)
	v_add_f32_e32 v6, v6, v56
	ds_bpermute_b32 v56, v88, v6
	v_sub_f32_e32 v21, v21, v7
	s_waitcnt vmcnt(1)
	v_fmac_f32_e32 v7, v64, v21
	s_waitcnt lgkmcnt(1)
	v_add_f32_e32 v8, v8, v43
	ds_bpermute_b32 v43, v88, v8
	s_waitcnt lgkmcnt(1)
	v_add_f32_e32 v6, v6, v56
	ds_bpermute_b32 v56, v82, v6
	v_lshlrev_b32_e32 v21, 16, v68
	v_lshlrev_b32_e32 v23, 16, v23
	s_waitcnt lgkmcnt(1)
	v_add_f32_e32 v8, v8, v43
	v_sub_f32_e32 v23, v23, v21
	s_waitcnt lgkmcnt(0)
	v_add_f32_e32 v6, v6, v56
	ds_bpermute_b32 v43, v82, v8
	s_waitcnt vmcnt(0)
	v_fmac_f32_e32 v21, v36, v23
	ds_bpermute_b32 v23, v101, v6
	v_add_f32_e32 v3, 1.0, v3
	v_rcp_f32_e32 v3, v3
	s_waitcnt lgkmcnt(1)
	v_add_f32_e32 v99, v8, v43
	ds_bpermute_b32 v100, v101, v99
	s_waitcnt lgkmcnt(1)
	v_add_f32_e32 v6, v6, v23
	v_mul_f32_e32 v7, v7, v6
	v_or_b32_e32 v109, 1, v108
	s_movk_i32 s5, 0x190
	v_cvt_pk_bf16_f32 v7, v7, v7
	v_mul_f32_e32 v6, v21, v6
	v_mul_lo_u32 v8, v109, s5
	global_store_short_d16_hi v[16:17], v7, off
	s_ashr_i32 s4, s13, 31
	v_add3_u32 v135, s76, v8, v98
	v_cvt_pk_bf16_f32 v6, v6, v6
	v_readlane_b32 s17, v253, 35
	v_readlane_b32 s18, v253, 36
	v_readlane_b32 s19, v253, 37
	v_readlane_b32 s20, v253, 38
	v_readlane_b32 s21, v253, 39
	v_readlane_b32 s28, v253, 46
	v_readlane_b32 s29, v253, 47
	v_readlane_b32 s30, v253, 48
	v_readlane_b32 s31, v253, 49
	global_store_short_d16_hi v[16:17], v6, off offset:64
	ds_read_u16 v6, v135 offset:656
	ds_read_u16 v7, v135 offset:256
	ds_read_u16 v23, v135 offset:528
	ds_read_u16 v43, v135 offset:400
	ds_read_u16 v21, v135
	s_waitcnt lgkmcnt(4)
	v_lshlrev_b32_e32 v6, 16, v6
	s_waitcnt lgkmcnt(3)
	v_lshlrev_b32_e32 v7, 16, v7
	v_sub_f32_e32 v7, v7, v6
	v_fmac_f32_e32 v6, v64, v7
	ds_read_u16 v7, v135 offset:128
	s_waitcnt lgkmcnt(3)
	v_lshlrev_b32_e32 v23, 16, v23
	s_waitcnt lgkmcnt(1)
	v_lshlrev_b32_e32 v21, 16, v21
	v_lshlrev_b32_e32 v43, 16, v43
	v_sub_f32_e32 v21, v21, v43
	s_waitcnt lgkmcnt(0)
	v_lshlrev_b32_e32 v7, 16, v7
	v_sub_f32_e32 v7, v7, v23
	v_fmac_f32_e32 v23, v66, v7
	v_mul_f32_e32 v7, v5, v23
	v_fmac_f32_e32 v43, v72, v21
	v_mul_f32_e32 v7, v43, v7
	ds_read_u16 v21, v135 offset:720
	ds_read_u16 v43, v135 offset:320
	v_fma_f32 v7, v22, v7, 0
	ds_read_u16 v56, v135 offset:464
	v_mul_f32_e32 v23, v214, v23
	s_waitcnt lgkmcnt(2)
	v_lshlrev_b32_e32 v21, 16, v21
	s_waitcnt lgkmcnt(1)
	v_lshlrev_b32_e32 v43, 16, v43
	v_sub_f32_e32 v43, v43, v21
	v_fmac_f32_e32 v21, v36, v43
	ds_read_u16 v43, v135 offset:64
	s_waitcnt lgkmcnt(1)
	v_lshlrev_b32_e32 v56, 16, v56
	ds_read_u16 v57, v135 offset:592
	s_waitcnt lgkmcnt(1)
	v_lshlrev_b32_e32 v43, 16, v43
	v_sub_f32_e32 v43, v43, v56
	v_fmac_f32_e32 v56, v42, v43
	ds_read_u16 v43, v135 offset:192
	s_waitcnt lgkmcnt(1)
	v_lshlrev_b32_e32 v57, 16, v57
	s_waitcnt lgkmcnt(0)
	v_lshlrev_b32_e32 v43, 16, v43
	v_sub_f32_e32 v43, v43, v57
	v_fmac_f32_e32 v57, v38, v43
	v_mul_f32_e32 v43, v55, v57
	v_mul_f32_e32 v43, v56, v43
	v_fmac_f32_e32 v7, v20, v43
	v_mul_f32_e32 v43, v32, v57
	v_mul_f32_e32 v43, v43, v43
	v_fmac_f32_e32 v43, v23, v23
	ds_bpermute_b32 v23, v94, v43
	s_waitcnt lgkmcnt(0)
	v_add_f32_e32 v23, v43, v23
	ds_bpermute_b32 v43, v90, v23
	s_waitcnt lgkmcnt(0)
	v_add_f32_e32 v23, v23, v43
	ds_bpermute_b32 v43, v88, v23
	s_waitcnt lgkmcnt(0)
	v_add_f32_e32 v23, v23, v43
	ds_bpermute_b32 v43, v82, v23
	s_waitcnt lgkmcnt(0)
	v_add_f32_e32 v102, v23, v43
	ds_bpermute_b32 v23, v94, v7
	ds_bpermute_b32 v103, v101, v102
	s_waitcnt lgkmcnt(1)
	v_add_f32_e32 v7, v7, v23
	ds_bpermute_b32 v23, v90, v7
	s_waitcnt lgkmcnt(0)
	v_add_f32_e32 v7, v7, v23
	ds_bpermute_b32 v23, v88, v7
	s_waitcnt lgkmcnt(0)
	v_add_f32_e32 v7, v7, v23
	ds_bpermute_b32 v23, v82, v7
	s_waitcnt lgkmcnt(0)
	v_add_f32_e32 v7, v7, v23
	ds_bpermute_b32 v23, v101, v7
	s_waitcnt lgkmcnt(0)
	v_add_f32_e32 v7, v7, v23
	v_mul_f32_e32 v6, v6, v7
	v_cvt_pk_bf16_f32 v6, v6, v6
	global_store_short_d16_hi v[16:17], v6, off offset:1024
	v_mul_f32_e32 v6, v21, v7
	v_cvt_pk_bf16_f32 v6, v6, v6
	global_store_short_d16_hi v[16:17], v6, off offset:1088
	ds_read_u16 v6, v135 offset:1056
	ds_read_u16 v7, v135 offset:656
	ds_read_u16 v21, v135 offset:528
	ds_read_u16 v23, v135 offset:400
	ds_read_u16 v43, v135 offset:928
	s_waitcnt lgkmcnt(4)
	v_lshlrev_b32_e32 v68, 16, v6
	ds_read_u16 v6, v135 offset:800
	ds_read_u16 v57, v135 offset:864
	ds_read_u16 v56, v135 offset:464
	s_waitcnt lgkmcnt(6)
	v_lshlrev_b32_e32 v69, 16, v7
	s_waitcnt lgkmcnt(5)
	v_lshlrev_b32_e32 v7, 16, v21
	s_waitcnt lgkmcnt(4)
	v_lshlrev_b32_e32 v21, 16, v23
	s_waitcnt lgkmcnt(3)
	v_lshlrev_b32_e32 v23, 16, v43
	s_waitcnt lgkmcnt(2)
	v_lshlrev_b32_e32 v43, 16, v6
	v_sub_f32_e32 v21, v21, v43
	v_fmac_f32_e32 v43, v72, v21
	s_waitcnt lgkmcnt(0)
	v_lshlrev_b32_e32 v21, 16, v56
	ds_read_u16 v56, v135 offset:592
	ds_read_u16 v71, v135 offset:992
	v_lshlrev_b32_e32 v73, 16, v57
	v_sub_f32_e32 v6, v7, v23
	v_sub_f32_e32 v21, v21, v73
	v_fmac_f32_e32 v23, v66, v6
	v_pk_add_f32 v[6:7], v[18:19], -1.0 op_sel_hi:[1,0]
	v_fmac_f32_e32 v73, v42, v21
	s_waitcnt lgkmcnt(1)
	v_lshlrev_b32_e32 v21, 16, v56
	s_waitcnt lgkmcnt(0)
	v_lshlrev_b32_e32 v71, 16, v71
	v_sub_f32_e32 v21, v21, v71
	v_pk_add_f32 v[56:57], v[46:47], -1.0 op_sel_hi:[1,0]
	v_pk_fma_f32 v[6:7], v[6:7], v[62:63], 1.0 op_sel_hi:[1,0,0]
	v_fmac_f32_e32 v71, v38, v21
	v_mul_f32_e32 v21, v6, v23
	v_pk_fma_f32 v[56:57], v[56:57], v[34:35], 1.0 op_sel_hi:[1,0,0]
	v_mul_f32_e32 v70, v214, v23
	v_mul_f32_e32 v21, v43, v21
	v_mul_f32_e32 v23, v56, v71
	v_fma_f32 v21, v22, v21, 0
	v_mul_f32_e32 v23, v73, v23
	v_fmac_f32_e32 v21, v20, v23
	ds_bpermute_b32 v23, v94, v21
	v_mul_f32_e32 v43, v32, v71
	v_mul_f32_e32 v43, v43, v43
	v_fmac_f32_e32 v43, v70, v70
	ds_bpermute_b32 v70, v94, v43
	s_waitcnt lgkmcnt(1)
	v_add_f32_e32 v21, v21, v23
	ds_bpermute_b32 v23, v90, v21
	v_sub_f32_e32 v69, v69, v68
	v_fmac_f32_e32 v68, v64, v69
	s_waitcnt lgkmcnt(1)
	v_add_f32_e32 v43, v43, v70
	ds_bpermute_b32 v69, v90, v43
	s_waitcnt lgkmcnt(1)
	v_add_f32_e32 v21, v21, v23
	ds_bpermute_b32 v23, v88, v21
	ds_read_u16 v70, v135 offset:1120
	ds_read_u16 v71, v135 offset:720
	s_waitcnt lgkmcnt(3)
	v_add_f32_e32 v43, v43, v69
	ds_bpermute_b32 v69, v88, v43
	s_waitcnt lgkmcnt(3)
	v_add_f32_e32 v21, v21, v23
	ds_bpermute_b32 v23, v82, v21
	s_waitcnt lgkmcnt(3)
	v_lshlrev_b32_e32 v70, 16, v70
	s_waitcnt lgkmcnt(2)
	v_lshlrev_b32_e32 v71, 16, v71
	s_waitcnt lgkmcnt(1)
	v_add_f32_e32 v43, v43, v69
	ds_bpermute_b32 v69, v82, v43
	s_waitcnt lgkmcnt(1)
	v_add_f32_e32 v21, v21, v23
	ds_bpermute_b32 v23, v101, v21
	v_sub_f32_e32 v71, v71, v70
	v_fmac_f32_e32 v70, v36, v71
	s_waitcnt lgkmcnt(1)
	v_add_f32_e32 v120, v43, v69
	ds_bpermute_b32 v121, v101, v120
	s_waitcnt lgkmcnt(1)
	v_add_f32_e32 v21, v21, v23
	v_mul_f32_e32 v23, v68, v21
	v_cvt_pk_bf16_f32 v23, v23, v23
	v_mul_f32_e32 v21, v70, v21
	global_store_short_d16_hi v[16:17], v23, off offset:2048
	v_cvt_pk_bf16_f32 v21, v21, v21
	global_store_short_d16_hi v[16:17], v21, off offset:2112
	ds_read_u16 v21, v135 offset:1456
	ds_read_u16 v23, v135 offset:1056
	ds_read_u16 v68, v135 offset:1328
	ds_read_u16 v69, v135 offset:1200
	ds_read_u16 v43, v135 offset:800
	s_waitcnt lgkmcnt(4)
	v_lshlrev_b32_e32 v21, 16, v21
	s_waitcnt lgkmcnt(3)
	v_lshlrev_b32_e32 v23, 16, v23
	v_sub_f32_e32 v23, v23, v21
	v_fmac_f32_e32 v21, v64, v23
	ds_read_u16 v23, v135 offset:928
	s_waitcnt lgkmcnt(3)
	v_lshlrev_b32_e32 v68, 16, v68
	s_waitcnt lgkmcnt(1)
	v_lshlrev_b32_e32 v43, 16, v43
	v_lshlrev_b32_e32 v69, 16, v69
	v_sub_f32_e32 v43, v43, v69
	s_waitcnt lgkmcnt(0)
	v_lshlrev_b32_e32 v23, 16, v23
	v_sub_f32_e32 v23, v23, v68
	v_fmac_f32_e32 v68, v66, v23
	v_mul_f32_e32 v23, v7, v68
	v_fmac_f32_e32 v69, v72, v43
	v_mul_f32_e32 v23, v69, v23
	ds_read_u16 v43, v135 offset:1520
	ds_read_u16 v69, v135 offset:1120
	v_fma_f32 v23, v22, v23, 0
	ds_read_u16 v70, v135 offset:1264
	v_mul_f32_e32 v68, v214, v68
	s_waitcnt lgkmcnt(2)
	v_lshlrev_b32_e32 v43, 16, v43
	s_waitcnt lgkmcnt(1)
	v_lshlrev_b32_e32 v69, 16, v69
	v_sub_f32_e32 v69, v69, v43
	v_fmac_f32_e32 v43, v36, v69
	ds_read_u16 v69, v135 offset:864
	s_waitcnt lgkmcnt(1)
	v_lshlrev_b32_e32 v70, 16, v70
	ds_read_u16 v71, v135 offset:1392
	s_waitcnt lgkmcnt(1)
	v_lshlrev_b32_e32 v69, 16, v69
	v_sub_f32_e32 v69, v69, v70
	v_fmac_f32_e32 v70, v42, v69
	ds_read_u16 v69, v135 offset:992
	s_waitcnt lgkmcnt(1)
	v_lshlrev_b32_e32 v71, 16, v71
	s_waitcnt lgkmcnt(0)
	v_lshlrev_b32_e32 v69, 16, v69
	v_sub_f32_e32 v69, v69, v71
	v_fmac_f32_e32 v71, v38, v69
	v_mul_f32_e32 v69, v57, v71
	v_mul_f32_e32 v69, v70, v69
	v_fmac_f32_e32 v23, v20, v69
	v_mul_f32_e32 v69, v32, v71
	v_mul_f32_e32 v69, v69, v69
	v_fmac_f32_e32 v69, v68, v68
	ds_bpermute_b32 v68, v94, v69
	s_waitcnt lgkmcnt(0)
	v_add_f32_e32 v68, v69, v68
	ds_bpermute_b32 v69, v90, v68
	s_waitcnt lgkmcnt(0)
	v_add_f32_e32 v68, v68, v69
	ds_bpermute_b32 v69, v88, v68
	s_waitcnt lgkmcnt(0)
	v_add_f32_e32 v68, v68, v69
	ds_bpermute_b32 v69, v82, v68
	s_waitcnt lgkmcnt(0)
	v_add_f32_e32 v164, v68, v69
	ds_bpermute_b32 v68, v94, v23
	ds_bpermute_b32 v165, v101, v164
	s_waitcnt lgkmcnt(1)
	v_add_f32_e32 v23, v23, v68
	ds_bpermute_b32 v68, v90, v23
	s_waitcnt lgkmcnt(0)
	v_add_f32_e32 v23, v23, v68
	ds_bpermute_b32 v68, v88, v23
	s_waitcnt lgkmcnt(0)
	v_add_f32_e32 v23, v23, v68
	ds_bpermute_b32 v68, v82, v23
	s_waitcnt lgkmcnt(0)
	v_add_f32_e32 v23, v23, v68
	ds_bpermute_b32 v68, v101, v23
	s_waitcnt lgkmcnt(0)
	v_add_f32_e32 v23, v23, v68
	v_mul_f32_e32 v21, v21, v23
	v_cvt_pk_bf16_f32 v21, v21, v21
	global_store_short_d16_hi v[16:17], v21, off offset:3072
	v_mul_f32_e32 v21, v43, v23
	v_cvt_pk_bf16_f32 v21, v21, v21
	global_store_short_d16_hi v[16:17], v21, off offset:3136
	ds_read_u16 v21, v135 offset:3456
	ds_read_u16 v23, v135 offset:3056
	ds_read_u16 v43, v135 offset:2928
	ds_read_u16 v68, v135 offset:2800
	ds_read_u16 v69, v135 offset:3328
	ds_read_u16 v70, v135 offset:3200
	s_waitcnt lgkmcnt(5)
	v_lshlrev_b32_e32 v21, 16, v21
	s_waitcnt lgkmcnt(3)
	v_lshlrev_b32_e32 v43, 16, v43
	s_waitcnt lgkmcnt(2)
	v_lshlrev_b32_e32 v71, 16, v68
	s_waitcnt lgkmcnt(1)
	v_lshlrev_b32_e32 v73, 16, v69
	v_sub_f32_e32 v43, v43, v73
	v_fmac_f32_e32 v73, v66, v43
	ds_read_u16 v43, v135 offset:2864
	s_waitcnt lgkmcnt(1)
	v_lshlrev_b32_e32 v76, 16, v70
	v_sub_f32_e32 v70, v71, v76
	ds_read_u16 v71, v135 offset:3264
	v_fmac_f32_e32 v76, v72, v70
	ds_read_u16 v70, v135 offset:2992
	ds_read_u16 v96, v135 offset:3392
	s_waitcnt lgkmcnt(3)
	v_lshlrev_b32_e32 v43, 16, v43
	v_pk_add_f32 v[68:69], v[2:3], -1.0 op_sel_hi:[1,0]
	s_waitcnt lgkmcnt(2)
	v_lshlrev_b32_e32 v114, 16, v71
	v_sub_f32_e32 v43, v43, v114
	v_fmac_f32_e32 v114, v42, v43
	s_waitcnt lgkmcnt(1)
	v_lshlrev_b32_e32 v43, 16, v70
	s_waitcnt lgkmcnt(0)
	v_lshlrev_b32_e32 v96, 16, v96
	v_sub_f32_e32 v43, v43, v96
	v_pk_add_f32 v[70:71], v[44:45], -1.0 op_sel_hi:[1,0]
	v_pk_fma_f32 v[104:105], v[68:69], v[62:63], 1.0 op_sel_hi:[1,0,0]
	v_fmac_f32_e32 v96, v38, v43
	v_mul_f32_e32 v43, v104, v73
	v_pk_fma_f32 v[68:69], v[70:71], v[34:35], 1.0 op_sel_hi:[1,0,0]
	v_mul_f32_e32 v43, v76, v43
	v_mul_f32_e32 v70, v68, v96
	v_fma_f32 v43, v22, v43, 0
	v_mul_f32_e32 v70, v114, v70
	v_fmac_f32_e32 v43, v20, v70
	ds_bpermute_b32 v70, v94, v43
	v_mul_f32_e32 v71, v32, v96
	v_mul_f32_e32 v77, v214, v73
	v_mul_f32_e32 v71, v71, v71
	v_fmac_f32_e32 v71, v77, v77
	s_waitcnt lgkmcnt(0)
	v_add_f32_e32 v43, v43, v70
	ds_bpermute_b32 v73, v94, v71
	ds_bpermute_b32 v70, v90, v43
	v_lshlrev_b32_e32 v23, 16, v23
	v_sub_f32_e32 v23, v23, v21
	v_fmac_f32_e32 v21, v64, v23
	s_waitcnt lgkmcnt(1)
	v_add_f32_e32 v23, v71, v73
	s_waitcnt lgkmcnt(0)
	v_add_f32_e32 v43, v43, v70
	ds_bpermute_b32 v71, v90, v23
	ds_bpermute_b32 v70, v88, v43
	ds_read_u16 v73, v135 offset:3520
	ds_read_u16 v76, v135 offset:3120
	s_waitcnt lgkmcnt(3)
	v_add_f32_e32 v23, v23, v71
	s_waitcnt lgkmcnt(2)
	v_add_f32_e32 v43, v43, v70
	ds_bpermute_b32 v71, v88, v23
	ds_bpermute_b32 v70, v82, v43
	s_waitcnt lgkmcnt(3)
	v_lshlrev_b32_e32 v73, 16, v73
	s_waitcnt lgkmcnt(2)
	v_lshlrev_b32_e32 v76, 16, v76
	v_sub_f32_e32 v76, v76, v73
	s_waitcnt lgkmcnt(1)
	v_add_f32_e32 v23, v23, v71
	s_waitcnt lgkmcnt(0)
	v_add_f32_e32 v43, v43, v70
	ds_bpermute_b32 v71, v82, v23
	ds_bpermute_b32 v70, v101, v43
	v_fmac_f32_e32 v73, v36, v76
	v_add_co_u32_e32 v76, vcc, s74, v16
	s_waitcnt lgkmcnt(1)
	v_add_f32_e32 v178, v23, v71
	s_waitcnt lgkmcnt(0)
	v_add_f32_e32 v23, v43, v70
	v_mul_f32_e32 v21, v21, v23
	ds_bpermute_b32 v179, v101, v178
	v_cvt_pk_bf16_f32 v21, v21, v21
	v_addc_co_u32_e32 v77, vcc, 0, v17, vcc
	global_store_short_d16_hi v[76:77], v21, off
	v_mul_f32_e32 v21, v73, v23
	v_cvt_pk_bf16_f32 v21, v21, v21
	global_store_short_d16_hi v[76:77], v21, off offset:64
	ds_read_u16 v21, v135 offset:3856
	ds_read_u16 v23, v135 offset:3456
	ds_read_u16 v70, v135 offset:3728
	ds_read_u16 v71, v135 offset:3600
	ds_read_u16 v43, v135 offset:3200
	s_waitcnt lgkmcnt(4)
	v_lshlrev_b32_e32 v21, 16, v21
	s_waitcnt lgkmcnt(3)
	v_lshlrev_b32_e32 v23, 16, v23
	v_sub_f32_e32 v23, v23, v21
	v_fmac_f32_e32 v21, v64, v23
	ds_read_u16 v23, v135 offset:3328
	s_waitcnt lgkmcnt(3)
	v_lshlrev_b32_e32 v70, 16, v70
	s_waitcnt lgkmcnt(1)
	v_lshlrev_b32_e32 v43, 16, v43
	v_lshlrev_b32_e32 v71, 16, v71
	v_sub_f32_e32 v43, v43, v71
	s_waitcnt lgkmcnt(0)
	v_lshlrev_b32_e32 v23, 16, v23
	v_sub_f32_e32 v23, v23, v70
	v_fmac_f32_e32 v70, v66, v23
	v_mul_f32_e32 v23, v105, v70
	v_fmac_f32_e32 v71, v72, v43
	v_mul_f32_e32 v23, v71, v23
	ds_read_u16 v43, v135 offset:3920
	ds_read_u16 v71, v135 offset:3520
	v_fma_f32 v23, v22, v23, 0
	ds_read_u16 v73, v135 offset:3664
	v_mul_f32_e32 v70, v214, v70
	s_waitcnt lgkmcnt(2)
	v_lshlrev_b32_e32 v43, 16, v43
	s_waitcnt lgkmcnt(1)
	v_lshlrev_b32_e32 v71, 16, v71
	v_sub_f32_e32 v71, v71, v43
	v_fmac_f32_e32 v43, v36, v71
	ds_read_u16 v71, v135 offset:3264
	s_waitcnt lgkmcnt(1)
	v_lshlrev_b32_e32 v73, 16, v73
	ds_read_u16 v96, v135 offset:3792
	s_waitcnt lgkmcnt(1)
	v_lshlrev_b32_e32 v71, 16, v71
	v_sub_f32_e32 v71, v71, v73
	v_fmac_f32_e32 v73, v42, v71
	ds_read_u16 v71, v135 offset:3392
	s_waitcnt lgkmcnt(1)
	v_lshlrev_b32_e32 v96, 16, v96
	s_waitcnt lgkmcnt(0)
	v_lshlrev_b32_e32 v71, 16, v71
	v_sub_f32_e32 v71, v71, v96
	v_fmac_f32_e32 v96, v38, v71
	v_mul_f32_e32 v71, v69, v96
	v_mul_f32_e32 v71, v73, v71
	v_fmac_f32_e32 v23, v20, v71
	v_mul_f32_e32 v71, v32, v96
	v_mul_f32_e32 v71, v71, v71
	v_fmac_f32_e32 v71, v70, v70
	ds_bpermute_b32 v70, v94, v71
	s_waitcnt lgkmcnt(0)
	v_add_f32_e32 v70, v71, v70
	ds_bpermute_b32 v71, v90, v70
	s_waitcnt lgkmcnt(0)
	v_add_f32_e32 v70, v70, v71
	ds_bpermute_b32 v71, v88, v70
	s_waitcnt lgkmcnt(0)
	v_add_f32_e32 v70, v70, v71
	ds_bpermute_b32 v71, v82, v70
	s_waitcnt lgkmcnt(0)
	v_add_f32_e32 v180, v70, v71
	ds_bpermute_b32 v70, v94, v23
	ds_bpermute_b32 v181, v101, v180
	s_waitcnt lgkmcnt(1)
	v_add_f32_e32 v23, v23, v70
	ds_bpermute_b32 v70, v90, v23
	s_waitcnt lgkmcnt(0)
	v_add_f32_e32 v23, v23, v70
	ds_bpermute_b32 v70, v88, v23
	s_waitcnt lgkmcnt(0)
	v_add_f32_e32 v23, v23, v70
	ds_bpermute_b32 v70, v82, v23
	s_waitcnt lgkmcnt(0)
	v_add_f32_e32 v23, v23, v70
	ds_bpermute_b32 v70, v101, v23
	s_waitcnt lgkmcnt(0)
	v_add_f32_e32 v23, v23, v70
	v_mul_f32_e32 v21, v21, v23
	v_cvt_pk_bf16_f32 v21, v21, v21
	global_store_short_d16_hi v[76:77], v21, off offset:1024
	v_mul_f32_e32 v21, v43, v23
	v_cvt_pk_bf16_f32 v21, v21, v21
	global_store_short_d16_hi v[76:77], v21, off offset:1088
	ds_read_u16 v21, v135 offset:4256
	ds_read_u16 v23, v135 offset:3856
	ds_read_u16 v43, v135 offset:3728
	ds_read_u16 v70, v135 offset:3600
	ds_read_u16 v71, v135 offset:4128
	ds_read_u16 v73, v135 offset:4000
	ds_read_u16 v114, v135 offset:4064
	s_waitcnt lgkmcnt(4)
	v_lshlrev_b32_e32 v43, 16, v43
	s_waitcnt lgkmcnt(3)
	v_lshlrev_b32_e32 v96, 16, v70
	s_waitcnt lgkmcnt(2)
	v_lshlrev_b32_e32 v139, 16, v71
	v_sub_f32_e32 v43, v43, v139
	v_fmac_f32_e32 v139, v66, v43
	ds_read_u16 v43, v135 offset:3664
	s_waitcnt lgkmcnt(2)
	v_lshlrev_b32_e32 v73, 16, v73
	v_sub_f32_e32 v96, v96, v73
	v_fmac_f32_e32 v73, v72, v96
	ds_read_u16 v96, v135 offset:3792
	ds_read_u16 v115, v135 offset:4192
	s_waitcnt lgkmcnt(2)
	v_lshlrev_b32_e32 v43, 16, v43
	v_lshlrev_b32_e32 v142, 16, v114
	v_sub_f32_e32 v43, v43, v142
	v_pk_add_f32 v[70:71], v[78:79], -1.0 op_sel_hi:[1,0]
	v_fmac_f32_e32 v142, v42, v43
	s_waitcnt lgkmcnt(1)
	v_lshlrev_b32_e32 v43, 16, v96
	s_waitcnt lgkmcnt(0)
	v_lshlrev_b32_e32 v96, 16, v115
	v_sub_f32_e32 v43, v43, v96
	v_pk_add_f32 v[122:123], v[40:41], -1.0 op_sel_hi:[1,0]
	v_pk_fma_f32 v[114:115], v[70:71], v[62:63], 1.0 op_sel_hi:[1,0,0]
	v_fmac_f32_e32 v96, v38, v43
	v_mul_f32_e32 v43, v114, v139
	v_pk_fma_f32 v[70:71], v[122:123], v[34:35], 1.0 op_sel_hi:[1,0,0]
	v_mul_f32_e32 v43, v73, v43
	v_mul_f32_e32 v73, v70, v96
	v_fma_f32 v43, v22, v43, 0
	v_mul_f32_e32 v73, v142, v73
	v_fmac_f32_e32 v43, v20, v73
	ds_bpermute_b32 v73, v94, v43
	v_mul_f32_e32 v96, v32, v96
	v_mul_f32_e32 v141, v214, v139
	v_mul_f32_e32 v96, v96, v96
	v_fmac_f32_e32 v96, v141, v141
	s_waitcnt lgkmcnt(0)
	v_add_f32_e32 v43, v43, v73
	ds_bpermute_b32 v122, v94, v96
	ds_bpermute_b32 v73, v90, v43
	v_lshlrev_b32_e32 v21, 16, v21
	v_lshlrev_b32_e32 v23, 16, v23
	v_sub_f32_e32 v23, v23, v21
	v_fmac_f32_e32 v21, v64, v23
	s_waitcnt lgkmcnt(1)
	v_add_f32_e32 v23, v96, v122
	s_waitcnt lgkmcnt(0)
	v_add_f32_e32 v43, v43, v73
	ds_bpermute_b32 v96, v90, v23
	ds_bpermute_b32 v73, v88, v43
	ds_read_u16 v122, v135 offset:4320
	ds_read_u16 v123, v135 offset:3920
	s_waitcnt lgkmcnt(3)
	v_add_f32_e32 v23, v23, v96
	s_waitcnt lgkmcnt(2)
	v_add_f32_e32 v43, v43, v73
	ds_bpermute_b32 v96, v88, v23
	ds_bpermute_b32 v73, v82, v43
	s_waitcnt lgkmcnt(3)
	v_lshlrev_b32_e32 v122, 16, v122
	s_waitcnt lgkmcnt(2)
	v_lshlrev_b32_e32 v123, 16, v123
	v_sub_f32_e32 v123, v123, v122
	s_waitcnt lgkmcnt(1)
	v_add_f32_e32 v23, v23, v96
	s_waitcnt lgkmcnt(0)
	v_add_f32_e32 v43, v43, v73
	ds_bpermute_b32 v96, v82, v23
	ds_bpermute_b32 v73, v101, v43
	v_fmac_f32_e32 v122, v36, v123
	s_waitcnt lgkmcnt(1)
	v_add_f32_e32 v182, v23, v96
	s_waitcnt lgkmcnt(0)
	v_add_f32_e32 v23, v43, v73
	v_mul_f32_e32 v21, v21, v23
	ds_bpermute_b32 v183, v101, v182
	v_cvt_pk_bf16_f32 v21, v21, v21
	global_store_short_d16_hi v[76:77], v21, off offset:2048
	v_mul_f32_e32 v21, v122, v23
	v_cvt_pk_bf16_f32 v21, v21, v21
	global_store_short_d16_hi v[76:77], v21, off offset:2112
	ds_read_u16 v21, v135 offset:4656
	ds_read_u16 v23, v135 offset:4256
	ds_read_u16 v73, v135 offset:4528
	ds_read_u16 v96, v135 offset:4400
	ds_read_u16 v43, v135 offset:4000
	s_waitcnt lgkmcnt(4)
	v_lshlrev_b32_e32 v21, 16, v21
	s_waitcnt lgkmcnt(3)
	v_lshlrev_b32_e32 v23, 16, v23
	v_sub_f32_e32 v23, v23, v21
	v_fmac_f32_e32 v21, v64, v23
	ds_read_u16 v23, v135 offset:4128
	s_waitcnt lgkmcnt(3)
	v_lshlrev_b32_e32 v73, 16, v73
	s_waitcnt lgkmcnt(1)
	v_lshlrev_b32_e32 v43, 16, v43
	v_lshlrev_b32_e32 v96, 16, v96
	v_sub_f32_e32 v43, v43, v96
	s_waitcnt lgkmcnt(0)
	v_lshlrev_b32_e32 v23, 16, v23
	v_sub_f32_e32 v23, v23, v73
	v_fmac_f32_e32 v73, v66, v23
	v_mul_f32_e32 v23, v115, v73
	v_fmac_f32_e32 v96, v72, v43
	v_mul_f32_e32 v23, v96, v23
	ds_read_u16 v43, v135 offset:4720
	ds_read_u16 v96, v135 offset:4320
	v_fma_f32 v23, v22, v23, 0
	ds_read_u16 v122, v135 offset:4464
	v_mul_f32_e32 v73, v214, v73
	s_waitcnt lgkmcnt(2)
	v_lshlrev_b32_e32 v43, 16, v43
	s_waitcnt lgkmcnt(1)
	v_lshlrev_b32_e32 v96, 16, v96
	v_sub_f32_e32 v96, v96, v43
	v_fmac_f32_e32 v43, v36, v96
	ds_read_u16 v96, v135 offset:4064
	s_waitcnt lgkmcnt(1)
	v_lshlrev_b32_e32 v122, 16, v122
	ds_read_u16 v123, v135 offset:4592
	s_waitcnt lgkmcnt(1)
	v_lshlrev_b32_e32 v96, 16, v96
	v_sub_f32_e32 v96, v96, v122
	v_fmac_f32_e32 v122, v42, v96
	ds_read_u16 v96, v135 offset:4192
	s_waitcnt lgkmcnt(1)
	v_lshlrev_b32_e32 v123, 16, v123
	s_waitcnt lgkmcnt(0)
	v_lshlrev_b32_e32 v96, 16, v96
	v_sub_f32_e32 v96, v96, v123
	v_fmac_f32_e32 v123, v38, v96
	v_mul_f32_e32 v96, v71, v123
	v_mul_f32_e32 v96, v122, v96
	v_fmac_f32_e32 v23, v20, v96
	v_mul_f32_e32 v96, v32, v123
	v_mul_f32_e32 v96, v96, v96
	v_fmac_f32_e32 v96, v73, v73
	ds_bpermute_b32 v73, v94, v96
	s_waitcnt lgkmcnt(0)
	v_add_f32_e32 v73, v96, v73
	ds_bpermute_b32 v96, v90, v73
	s_waitcnt lgkmcnt(0)
	v_add_f32_e32 v73, v73, v96
	ds_bpermute_b32 v96, v88, v73
	s_waitcnt lgkmcnt(0)
	v_add_f32_e32 v73, v73, v96
	ds_bpermute_b32 v96, v82, v73
	s_waitcnt lgkmcnt(0)
	v_add_f32_e32 v184, v73, v96
	ds_bpermute_b32 v73, v94, v23
	ds_bpermute_b32 v185, v101, v184
	s_waitcnt lgkmcnt(1)
	v_add_f32_e32 v23, v23, v73
	ds_bpermute_b32 v73, v90, v23
	s_waitcnt lgkmcnt(0)
	v_add_f32_e32 v23, v23, v73
	ds_bpermute_b32 v73, v88, v23
	s_waitcnt lgkmcnt(0)
	v_add_f32_e32 v23, v23, v73
	ds_bpermute_b32 v73, v82, v23
	s_waitcnt lgkmcnt(0)
	v_add_f32_e32 v23, v23, v73
	ds_bpermute_b32 v73, v101, v23
	s_waitcnt lgkmcnt(0)
	v_add_f32_e32 v23, v23, v73
	v_mul_f32_e32 v21, v21, v23
	v_cvt_pk_bf16_f32 v21, v21, v21
	global_store_short_d16_hi v[76:77], v21, off offset:3072
	v_mul_f32_e32 v21, v43, v23
	v_cvt_pk_bf16_f32 v21, v21, v21
	global_store_short_d16_hi v[76:77], v21, off offset:3136
	v_add_u32_e32 v8, 0x1770, v8
	v_add3_u32 v155, s76, v8, v98
	ds_read_u16 v123, v155 offset:656
	ds_read_u16 v139, v155 offset:256
	s_and_b64 vcc, exec, s[0:1]
	v_add_f32_e32 v168, -1.0, v83
	s_cbranch_vccz .LBB0_937
	ds_read_u16 v21, v155 offset:528
	ds_read_u16 v23, v155 offset:128
	ds_read_u16 v43, v155 offset:400
	ds_read_u16 v73, v155
	s_waitcnt lgkmcnt(3)
	v_lshlrev_b32_e32 v77, 16, v21
	s_waitcnt lgkmcnt(2)
	v_lshlrev_b32_e32 v21, 16, v23
	s_waitcnt lgkmcnt(1)
	v_lshlrev_b32_e32 v143, 16, v43
	s_waitcnt lgkmcnt(0)
	v_lshlrev_b32_e32 v142, 16, v73
	v_mov_b32_e32 v76, v143
	v_pk_add_f32 v[144:145], v[142:143], v[76:77] neg_lo:[0,1] neg_hi:[0,1]
	v_sub_f32_e32 v21, v21, v77
	v_mov_b32_e32 v73, v62
	v_mov_b32_e32 v145, v168
	v_mov_b32_e32 v142, v143
	v_mov_b32_e32 v143, v215
	v_pk_fma_f32 v[142:143], v[72:73], v[144:145], v[142:143]
	v_fmac_f32_e32 v77, v66, v21
	v_mul_f32_e32 v21, v143, v77
	v_mul_f32_e32 v76, v142, v21
	v_mov_b32_e32 v23, v214
	v_pk_mul_f32 v[142:143], v[22:23], v[76:77]
	v_mov_b32_e32 v144, v97
	v_mov_b32_e32 v145, v143
	v_pk_fma_f32 v[76:77], v[22:23], v[76:77], v[144:145]
	v_pk_mul_f32 v[142:143], v[142:143], v[142:143]
	s_nop 0
	v_mov_b32_e32 v77, v143
	s_branch .LBB0_938

.LBB0_940:
	ds_bpermute_b32 v21, v94, v77
	ds_bpermute_b32 v24, v94, v76
	s_and_b64 vcc, exec, s[2:3]
	s_waitcnt lgkmcnt(1)
	v_add_f32_e32 v21, v77, v21
	s_waitcnt lgkmcnt(0)
	v_add_f32_e32 v24, v76, v24
	ds_bpermute_b32 v43, v90, v21
	ds_bpermute_b32 v76, v90, v24
	s_waitcnt lgkmcnt(1)
	v_add_f32_e32 v21, v21, v43
	s_waitcnt lgkmcnt(0)
	v_add_f32_e32 v24, v24, v76
	ds_bpermute_b32 v43, v88, v21
	ds_bpermute_b32 v76, v88, v24
	s_waitcnt lgkmcnt(1)
	v_add_f32_e32 v21, v21, v43
	s_waitcnt lgkmcnt(0)
	v_add_f32_e32 v43, v24, v76
	ds_bpermute_b32 v24, v82, v21
	ds_bpermute_b32 v76, v82, v43
	s_waitcnt lgkmcnt(1)
	v_add_f32_e32 v24, v21, v24
	s_waitcnt lgkmcnt(0)
	v_add_f32_e32 v21, v43, v76
	ds_bpermute_b32 v122, v101, v24
	ds_bpermute_b32 v43, v101, v21
	s_cbranch_vccnz .LBB0_942
	v_lshlrev_b32_e32 v23, 16, v23
	v_lshlrev_b32_e32 v73, 16, v73
	v_sub_f32_e32 v73, v73, v23
	v_fmac_f32_e32 v23, v36, v73
	v_lshlrev_b32_e32 v73, 16, v123
	v_lshlrev_b32_e32 v76, 16, v139
	v_sub_f32_e32 v76, v76, v73
	v_fmac_f32_e32 v73, v64, v76
	s_waitcnt lgkmcnt(0)
	v_add_f32_e32 v21, v21, v43
	v_mul_f32_e32 v43, v73, v21
	v_mul_f32_e32 v21, v23, v21
	v_add_co_u32_e32 v76, vcc, 0x4000, v16
	s_nop 0
	v_cvt_pk_bf16_f32 v43, v43, v43
	v_addc_co_u32_e32 v77, vcc, 0, v17, vcc
	v_cvt_pk_bf16_f32 v21, v21, v21
	global_store_short_d16_hi v[76:77], v43, off
	global_store_short_d16_hi v[76:77], v21, off offset:64

.LBB0_947:
	ds_bpermute_b32 v21, v94, v9
	ds_bpermute_b32 v25, v94, v8
	s_and_b64 vcc, exec, s[2:3]
	s_waitcnt lgkmcnt(1)
	v_add_f32_e32 v9, v9, v21
	s_waitcnt lgkmcnt(0)
	v_add_f32_e32 v8, v8, v25
	ds_bpermute_b32 v21, v90, v9
	ds_bpermute_b32 v25, v90, v8
	s_waitcnt lgkmcnt(1)
	v_add_f32_e32 v9, v9, v21
	s_waitcnt lgkmcnt(0)
	v_add_f32_e32 v8, v8, v25
	ds_bpermute_b32 v21, v88, v9
	ds_bpermute_b32 v25, v88, v8
	s_waitcnt lgkmcnt(1)
	v_add_f32_e32 v9, v9, v21
	s_waitcnt lgkmcnt(0)
	v_add_f32_e32 v8, v8, v25
	ds_bpermute_b32 v21, v82, v9
	ds_bpermute_b32 v43, v82, v8
	s_waitcnt lgkmcnt(1)
	v_add_f32_e32 v25, v9, v21
	s_waitcnt lgkmcnt(0)
	v_add_f32_e32 v8, v8, v43
	ds_bpermute_b32 v123, v101, v25
	ds_bpermute_b32 v9, v101, v8
	s_cbranch_vccnz .LBB0_949
	v_lshlrev_b32_e32 v21, 16, v23
	v_lshlrev_b32_e32 v23, 16, v73
	v_sub_f32_e32 v23, v23, v21
	v_fmac_f32_e32 v21, v36, v23
	v_lshlrev_b32_e32 v23, 16, v77
	v_lshlrev_b32_e32 v43, 16, v139
	v_sub_f32_e32 v43, v43, v23
	v_fmac_f32_e32 v23, v64, v43
	s_waitcnt lgkmcnt(0)
	v_add_f32_e32 v43, v8, v9
	v_mul_f32_e32 v8, v23, v43
	v_cvt_pk_bf16_f32 v23, v8, v8
	v_add_co_u32_e32 v8, vcc, 0x4000, v16
	v_mul_f32_e32 v21, v21, v43
	s_nop 0
	v_addc_co_u32_e32 v9, vcc, 0, v17, vcc
	global_store_short_d16_hi v[8:9], v23, off offset:1024
	v_cvt_pk_bf16_f32 v21, v21, v21
	global_store_short_d16_hi v[8:9], v21, off offset:1088

.LBB0_954:
	ds_bpermute_b32 v10, v94, v9
	ds_bpermute_b32 v21, v94, v8
	s_and_b64 vcc, exec, s[2:3]
	s_waitcnt lgkmcnt(1)
	v_add_f32_e32 v9, v9, v10
	s_waitcnt lgkmcnt(0)
	v_add_f32_e32 v8, v8, v21
	ds_bpermute_b32 v10, v90, v9
	ds_bpermute_b32 v21, v90, v8
	s_waitcnt lgkmcnt(1)
	v_add_f32_e32 v9, v9, v10
	s_waitcnt lgkmcnt(0)
	v_add_f32_e32 v8, v8, v21
	ds_bpermute_b32 v10, v88, v9
	ds_bpermute_b32 v21, v88, v8
	s_waitcnt lgkmcnt(1)
	v_add_f32_e32 v9, v9, v10
	s_waitcnt lgkmcnt(0)
	v_add_f32_e32 v8, v8, v21
	ds_bpermute_b32 v10, v82, v9
	ds_bpermute_b32 v21, v82, v8
	s_waitcnt lgkmcnt(1)
	v_add_f32_e32 v10, v9, v10
	s_waitcnt lgkmcnt(0)
	v_add_f32_e32 v8, v8, v21
	ds_bpermute_b32 v26, v101, v10
	ds_bpermute_b32 v9, v101, v8
	s_cbranch_vccnz .LBB0_956
	v_lshlrev_b32_e32 v21, 16, v23
	v_lshlrev_b32_e32 v23, 16, v73
	v_sub_f32_e32 v23, v23, v21
	v_fmac_f32_e32 v21, v36, v23
	v_lshlrev_b32_e32 v23, 16, v77
	v_lshlrev_b32_e32 v43, 16, v139
	v_sub_f32_e32 v43, v43, v23
	v_fmac_f32_e32 v23, v64, v43
	s_waitcnt lgkmcnt(0)
	v_add_f32_e32 v43, v8, v9
	v_mul_f32_e32 v8, v23, v43
	v_cvt_pk_bf16_f32 v23, v8, v8
	v_add_co_u32_e32 v8, vcc, 0x4000, v16
	v_mul_f32_e32 v21, v21, v43
	s_nop 0
	v_addc_co_u32_e32 v9, vcc, 0, v17, vcc
	global_store_short_d16_hi v[8:9], v23, off offset:2048
	v_cvt_pk_bf16_f32 v21, v21, v21
	global_store_short_d16_hi v[8:9], v21, off offset:2112

.LBB0_961:
	ds_bpermute_b32 v11, v94, v9
	ds_bpermute_b32 v21, v94, v8
	s_and_b64 vcc, exec, s[2:3]
	s_waitcnt lgkmcnt(1)
	v_add_f32_e32 v9, v9, v11
	s_waitcnt lgkmcnt(0)
	v_add_f32_e32 v8, v8, v21
	ds_bpermute_b32 v11, v90, v9
	ds_bpermute_b32 v21, v90, v8
	s_waitcnt lgkmcnt(1)
	v_add_f32_e32 v9, v9, v11
	s_waitcnt lgkmcnt(0)
	v_add_f32_e32 v8, v8, v21
	ds_bpermute_b32 v11, v88, v9
	ds_bpermute_b32 v21, v88, v8
	s_waitcnt lgkmcnt(1)
	v_add_f32_e32 v9, v9, v11
	s_waitcnt lgkmcnt(0)
	v_add_f32_e32 v8, v8, v21
	ds_bpermute_b32 v11, v82, v9
	ds_bpermute_b32 v21, v82, v8
	s_waitcnt lgkmcnt(1)
	v_add_f32_e32 v11, v9, v11
	s_waitcnt lgkmcnt(0)
	v_add_f32_e32 v8, v8, v21
	ds_bpermute_b32 v27, v101, v11
	ds_bpermute_b32 v9, v101, v8
	s_cbranch_vccnz .LBB0_963
	v_lshlrev_b32_e32 v21, 16, v23
	v_lshlrev_b32_e32 v23, 16, v73
	v_sub_f32_e32 v23, v23, v21
	v_fmac_f32_e32 v21, v36, v23
	v_lshlrev_b32_e32 v23, 16, v77
	v_lshlrev_b32_e32 v43, 16, v139
	v_sub_f32_e32 v43, v43, v23
	v_fmac_f32_e32 v23, v64, v43
	s_waitcnt lgkmcnt(0)
	v_add_f32_e32 v43, v8, v9
	v_mul_f32_e32 v8, v23, v43
	v_cvt_pk_bf16_f32 v23, v8, v8
	v_add_co_u32_e32 v8, vcc, 0x4000, v16
	v_mul_f32_e32 v21, v21, v43
	s_nop 0
	v_addc_co_u32_e32 v9, vcc, 0, v17, vcc
	global_store_short_d16_hi v[8:9], v23, off offset:3072
	v_cvt_pk_bf16_f32 v21, v21, v21
	global_store_short_d16_hi v[8:9], v21, off offset:3136

.LBB0_968:
	ds_bpermute_b32 v12, v94, v9
	ds_bpermute_b32 v21, v94, v8
	s_and_b64 vcc, exec, s[2:3]
	s_waitcnt lgkmcnt(1)
	v_add_f32_e32 v9, v9, v12
	s_waitcnt lgkmcnt(0)
	v_add_f32_e32 v8, v8, v21
	ds_bpermute_b32 v12, v90, v9
	ds_bpermute_b32 v21, v90, v8
	s_waitcnt lgkmcnt(1)
	v_add_f32_e32 v9, v9, v12
	s_waitcnt lgkmcnt(0)
	v_add_f32_e32 v8, v8, v21
	ds_bpermute_b32 v12, v88, v9
	ds_bpermute_b32 v21, v88, v8
	s_waitcnt lgkmcnt(1)
	v_add_f32_e32 v9, v9, v12
	s_waitcnt lgkmcnt(0)
	v_add_f32_e32 v8, v8, v21
	ds_bpermute_b32 v12, v82, v9
	ds_bpermute_b32 v21, v82, v8
	s_waitcnt lgkmcnt(1)
	v_add_f32_e32 v12, v9, v12
	s_waitcnt lgkmcnt(0)
	v_add_f32_e32 v8, v8, v21
	ds_bpermute_b32 v186, v101, v12
	ds_bpermute_b32 v9, v101, v8
	s_cbranch_vccnz .LBB0_970
	v_lshlrev_b32_e32 v21, 16, v23
	v_lshlrev_b32_e32 v23, 16, v28
	v_sub_f32_e32 v23, v23, v21
	v_fmac_f32_e32 v21, v36, v23
	v_lshlrev_b32_e32 v23, 16, v77
	v_lshlrev_b32_e32 v28, 16, v141
	v_sub_f32_e32 v28, v28, v23
	v_fmac_f32_e32 v23, v64, v28
	s_waitcnt lgkmcnt(0)
	v_add_f32_e32 v28, v8, v9
	v_mul_f32_e32 v8, v23, v28
	v_cvt_pk_bf16_f32 v23, v8, v8
	v_add_co_u32_e32 v8, vcc, 0x6000, v16
	v_mul_f32_e32 v21, v21, v28
	s_nop 0
	v_addc_co_u32_e32 v9, vcc, 0, v17, vcc
	global_store_short_d16_hi v[8:9], v23, off
	v_cvt_pk_bf16_f32 v21, v21, v21
	global_store_short_d16_hi v[8:9], v21, off offset:64

.LBB0_975:
	ds_bpermute_b32 v13, v94, v9
	ds_bpermute_b32 v21, v94, v8
	s_and_b64 vcc, exec, s[2:3]
	s_waitcnt lgkmcnt(1)
	v_add_f32_e32 v9, v9, v13
	s_waitcnt lgkmcnt(0)
	v_add_f32_e32 v8, v8, v21
	ds_bpermute_b32 v13, v90, v9
	ds_bpermute_b32 v21, v90, v8
	s_waitcnt lgkmcnt(1)
	v_add_f32_e32 v9, v9, v13
	s_waitcnt lgkmcnt(0)
	v_add_f32_e32 v8, v8, v21
	ds_bpermute_b32 v13, v88, v9
	ds_bpermute_b32 v21, v88, v8
	s_waitcnt lgkmcnt(1)
	v_add_f32_e32 v9, v9, v13
	s_waitcnt lgkmcnt(0)
	v_add_f32_e32 v8, v8, v21
	ds_bpermute_b32 v13, v82, v9
	ds_bpermute_b32 v21, v82, v8
	s_waitcnt lgkmcnt(1)
	v_add_f32_e32 v13, v9, v13
	s_waitcnt lgkmcnt(0)
	v_add_f32_e32 v8, v8, v21
	ds_bpermute_b32 v76, v101, v13
	ds_bpermute_b32 v9, v101, v8
	s_cbranch_vccnz .LBB0_977
	v_lshlrev_b32_e32 v21, 16, v23
	v_lshlrev_b32_e32 v23, 16, v29
	v_sub_f32_e32 v23, v23, v21
	v_fmac_f32_e32 v21, v36, v23
	v_lshlrev_b32_e32 v23, 16, v28
	v_lshlrev_b32_e32 v28, 16, v141
	v_sub_f32_e32 v28, v28, v23
	v_fmac_f32_e32 v23, v64, v28
	s_waitcnt lgkmcnt(0)
	v_add_f32_e32 v28, v8, v9
	v_mul_f32_e32 v8, v23, v28
	v_cvt_pk_bf16_f32 v23, v8, v8
	v_add_co_u32_e32 v8, vcc, 0x6000, v16
	v_mul_f32_e32 v21, v21, v28
	s_nop 0
	v_addc_co_u32_e32 v9, vcc, 0, v17, vcc
	global_store_short_d16_hi v[8:9], v23, off offset:1024
	v_cvt_pk_bf16_f32 v21, v21, v21
	global_store_short_d16_hi v[8:9], v21, off offset:1088

.LBB0_982:
	ds_bpermute_b32 v14, v94, v9
	ds_bpermute_b32 v21, v94, v8
	s_and_b64 vcc, exec, s[2:3]
	s_waitcnt lgkmcnt(1)
	v_add_f32_e32 v9, v9, v14
	s_waitcnt lgkmcnt(0)
	v_add_f32_e32 v8, v8, v21
	ds_bpermute_b32 v14, v90, v9
	ds_bpermute_b32 v21, v90, v8
	s_waitcnt lgkmcnt(1)
	v_add_f32_e32 v9, v9, v14
	s_waitcnt lgkmcnt(0)
	v_add_f32_e32 v8, v8, v21
	ds_bpermute_b32 v14, v88, v9
	ds_bpermute_b32 v21, v88, v8
	s_waitcnt lgkmcnt(1)
	v_add_f32_e32 v9, v9, v14
	s_waitcnt lgkmcnt(0)
	v_add_f32_e32 v8, v8, v21
	ds_bpermute_b32 v14, v82, v9
	ds_bpermute_b32 v21, v82, v8
	s_waitcnt lgkmcnt(1)
	v_add_f32_e32 v14, v9, v14
	s_waitcnt lgkmcnt(0)
	v_add_f32_e32 v8, v8, v21
	ds_bpermute_b32 v30, v101, v14
	ds_bpermute_b32 v9, v101, v8
	s_cbranch_vccnz .LBB0_984
	v_lshlrev_b32_e32 v21, 16, v23
	v_lshlrev_b32_e32 v23, 16, v73
	v_sub_f32_e32 v23, v23, v21
	v_fmac_f32_e32 v21, v36, v23
	v_lshlrev_b32_e32 v23, 16, v28
	v_lshlrev_b32_e32 v28, 16, v29
	v_sub_f32_e32 v28, v28, v23
	v_fmac_f32_e32 v23, v64, v28
	s_waitcnt lgkmcnt(0)
	v_add_f32_e32 v28, v8, v9
	v_mul_f32_e32 v8, v23, v28
	v_cvt_pk_bf16_f32 v23, v8, v8
	v_add_co_u32_e32 v8, vcc, 0x6000, v16
	v_mul_f32_e32 v21, v21, v28
	s_nop 0
	v_addc_co_u32_e32 v9, vcc, 0, v17, vcc
	global_store_short_d16_hi v[8:9], v23, off offset:2048
	v_cvt_pk_bf16_f32 v21, v21, v21
	global_store_short_d16_hi v[8:9], v21, off offset:2112

.LBB0_989:
	ds_bpermute_b32 v20, v94, v9
	ds_bpermute_b32 v21, v94, v8
	s_and_b64 vcc, exec, s[2:3]
	s_waitcnt lgkmcnt(1)
	v_add_f32_e32 v9, v9, v20
	s_waitcnt lgkmcnt(0)
	v_add_f32_e32 v8, v8, v21
	ds_bpermute_b32 v20, v90, v9
	ds_bpermute_b32 v21, v90, v8
	s_waitcnt lgkmcnt(1)
	v_add_f32_e32 v9, v9, v20
	s_waitcnt lgkmcnt(0)
	v_add_f32_e32 v8, v8, v21
	ds_bpermute_b32 v20, v88, v9
	ds_bpermute_b32 v21, v88, v8
	s_waitcnt lgkmcnt(1)
	v_add_f32_e32 v9, v9, v20
	s_waitcnt lgkmcnt(0)
	v_add_f32_e32 v20, v8, v21
	ds_bpermute_b32 v8, v82, v9
	ds_bpermute_b32 v21, v82, v20
	s_waitcnt lgkmcnt(1)
	v_add_f32_e32 v8, v9, v8
	s_waitcnt lgkmcnt(0)
	v_add_f32_e32 v20, v20, v21
	ds_bpermute_b32 v9, v101, v8
	ds_bpermute_b32 v21, v101, v20
	s_cbranch_vccnz .LBB0_991
	v_lshlrev_b32_e32 v22, 16, v22
	v_lshlrev_b32_e32 v23, 16, v23
	v_sub_f32_e32 v23, v23, v22
	v_fmac_f32_e32 v22, v36, v23
	v_lshlrev_b32_e32 v15, 16, v15
	v_lshlrev_b32_e32 v23, 16, v28
	v_sub_f32_e32 v23, v23, v15
	v_fmac_f32_e32 v15, v64, v23
	s_waitcnt lgkmcnt(0)
	v_add_f32_e32 v20, v20, v21
	v_mul_f32_e32 v15, v15, v20
	v_add_co_u32_e32 v16, vcc, 0x6000, v16
	v_cvt_pk_bf16_f32 v15, v15, v15
	s_nop 0
	v_addc_co_u32_e32 v17, vcc, 0, v17, vcc
	global_store_short_d16_hi v[16:17], v15, off offset:3072
	v_mul_f32_e32 v15, v22, v20
	v_cvt_pk_bf16_f32 v15, v15, v15
	global_store_short_d16_hi v[16:17], v15, off offset:3136

.LBB0_1136:
	v_readlane_b32 s2, v255, 40
	s_add_i32 s0, s2, 1
	v_readlane_b32 s3, v255, 41
	v_writelane_b32 v255, s0, 42
	s_waitcnt lgkmcnt(0)
	s_barrier
	v_writelane_b32 v255, s1, 43
	s_mov_b32 s0, s1
	s_mov_b32 s1, -1
	v_readlane_b32 s3, v255, 5
	s_mul_i32 s2, s3, s0
	v_mbcnt_lo_u32_b32 v0, s1, 0
	v_readlane_b32 s4, v253, 2
	s_lshl_b32 s0, s0, 14
	v_mbcnt_hi_u32_b32 v0, s1, v0
	s_add_i32 s87, s2, s46
	v_readlane_b32 s5, v253, 3
	v_readlane_b32 s6, v253, 4
	v_readlane_b32 s7, v253, 5
	s_add_i32 s86, s0, 0
	v_and_b32_e32 v224, 63, v0
	s_mov_b64 s[12:13], s[6:7]
	s_mov_b64 s[10:11], s[4:5]
	s_cmpk_gt_i32 s87, 0xff
	s_mov_b64 s[0:1], -1
	s_cbranch_scc0 .LBB0_1315
	s_add_i32 s95, s87, 0xffffff00
	s_cmpk_gt_u32 s87, 0x17f
	s_cbranch_scc1 .LBB0_1147
	s_lshr_b32 s38, s95, 5
	s_and_b32 s0, s87, 31
	v_readlane_b32 s4, v255, 52
	v_readlane_b32 s5, v255, 53
	s_add_u32 s1, s12, s4
	s_addc_u32 s5, s13, s5
	s_lshl_b32 s4, s0, 9
	s_add_u32 s4, s1, s4
	v_lshlrev_b32_e32 v0, 1, v224
	s_addc_u32 s5, s5, 0
	v_ashrrev_i32_e32 v1, 31, v0
	v_lshl_add_u64 v[0:1], v[0:1], 2, s[4:5]
	s_mov_b32 s1, 0x399f2000
	v_add_co_u32_e32 v0, vcc, s1, v0
	s_mul_i32 s4, s38, 0x280000
	s_nop 0
	v_addc_co_u32_e32 v1, vcc, 0, v1, vcc
	global_load_dwordx2 v[0:1], v[0:1], off
	s_mul_i32 s5, s0, 0x14000
	s_mul_hi_u32 s1, s38, 0x280000
	s_add_u32 s4, s4, s5
	s_addc_u32 s1, s1, 0
	s_add_u32 s4, s12, s4
	v_ashrrev_i32_e32 v225, 31, v224
	s_addc_u32 s5, s13, s1
	v_lshl_add_u64 v[4:5], v[224:225], 2, s[4:5]
	s_mov_b64 s[4:5], 0x39a02400
	v_lshl_add_u64 v[4:5], v[4:5], 0, s[4:5]
	s_mul_i32 s4, s38, 0x140000
	s_mul_i32 s5, s0, 0xa000
	s_mul_hi_u32 s1, s38, 0x140000
	s_add_u32 s4, s4, s5
	s_addc_u32 s1, s1, 0
	s_add_u32 s4, s12, s4
	s_addc_u32 s5, s13, s1
	v_lshl_add_u64 v[6:7], v[224:225], 1, s[4:5]
	s_mov_b64 s[4:5], 0x3a402200
	v_lshl_add_u64 v[6:7], v[6:7], 0, s[4:5]
	v_mov_b32_e32 v10, 0
	s_mov_b32 s1, -4
	v_mov_b32_e32 v8, 0
	s_waitcnt vmcnt(0)
	v_pk_mov_b32 v[2:3], v[0:1], v[0:1] op_sel:[1,0]
	v_mov_b32_e32 v9, 0
	s_mov_b64 s[100:101], 0x1000
	v_mov_b64_e32 v[148:149], v[4:5]
	global_load_dword v101, v[148:149], off offset:-1024
	global_load_dword v100, v[148:149], off offset:-768
	global_load_dword v103, v[148:149], off offset:-512
	global_load_dword v102, v[148:149], off offset:-256
	global_load_dword v105, v[148:149], off
	global_load_dword v104, v[148:149], off offset:256
	global_load_dword v107, v[148:149], off offset:512
	global_load_dword v106, v[148:149], off offset:768
	global_load_dword v109, v[148:149], off offset:1024
	global_load_dword v108, v[148:149], off offset:1280
	global_load_dword v111, v[148:149], off offset:1536
	global_load_dword v110, v[148:149], off offset:1792
	global_load_dword v113, v[148:149], off offset:2048
	global_load_dword v112, v[148:149], off offset:2304
	global_load_dword v115, v[148:149], off offset:2560
	global_load_dword v114, v[148:149], off offset:2816
	v_lshl_add_u64 v[148:149], v[148:149], 0, s[100:101]
	global_load_dword v117, v[148:149], off offset:-1024
	global_load_dword v116, v[148:149], off offset:-768
	global_load_dword v119, v[148:149], off offset:-512
	global_load_dword v118, v[148:149], off offset:-256
	global_load_dword v121, v[148:149], off
	global_load_dword v120, v[148:149], off offset:256
	global_load_dword v123, v[148:149], off offset:512
	global_load_dword v122, v[148:149], off offset:768
	global_load_dword v125, v[148:149], off offset:1024
	global_load_dword v124, v[148:149], off offset:1280
	global_load_dword v127, v[148:149], off offset:1536
	global_load_dword v126, v[148:149], off offset:1792
	global_load_dword v129, v[148:149], off offset:2048
	global_load_dword v128, v[148:149], off offset:2304
	global_load_dword v131, v[148:149], off offset:2560
	global_load_dword v130, v[148:149], off offset:2816
	v_lshl_add_u64 v[148:149], v[148:149], 0, s[100:101]
	global_load_dword v133, v[148:149], off offset:-1024
	global_load_dword v132, v[148:149], off offset:-768
	global_load_dword v135, v[148:149], off offset:-512
	global_load_dword v134, v[148:149], off offset:-256
	global_load_dword v137, v[148:149], off
	global_load_dword v136, v[148:149], off offset:256
	global_load_dword v139, v[148:149], off offset:512
	global_load_dword v138, v[148:149], off offset:768
	global_load_dword v141, v[148:149], off offset:1024
	global_load_dword v140, v[148:149], off offset:1280
	global_load_dword v143, v[148:149], off offset:1536
	global_load_dword v142, v[148:149], off offset:1792
	global_load_dword v145, v[148:149], off offset:2048
	global_load_dword v144, v[148:149], off offset:2304
	global_load_dword v147, v[148:149], off offset:2560
	global_load_dword v146, v[148:149], off offset:2816
	v_lshl_add_u64 v[148:149], v[148:149], 0, s[100:101]
	s_waitcnt vmcnt(32)
	v_cvt_pk_bf16_f32 v10, v9, v9
	global_store_short_d16_hi v[6:7], v10, off offset:-512
	v_cvt_pk_bf16_f32 v11, v8, v8
	global_store_short_d16_hi v[6:7], v11, off offset:-384
	v_pk_mul_f32 v[16:17], v[0:1], v[8:9] op_sel_hi:[1,0]
	s_nop 0
	v_pk_fma_f32 v[18:19], v[2:3], v[8:9], v[16:17] op_sel:[0,1,0]
	v_pk_fma_f32 v[8:9], v[2:3], v[8:9], v[16:17] op_sel:[0,1,0] neg_lo:[0,0,1] neg_hi:[0,0,1]
	s_nop 0
	v_mov_b32_e32 v19, v9
	v_pk_add_f32 v[8:9], v[100:101], v[18:19]
	v_cvt_pk_bf16_f32 v10, v9, v9
	global_store_short_d16_hi v[6:7], v10, off offset:-256
	v_cvt_pk_bf16_f32 v11, v8, v8
	global_store_short_d16_hi v[6:7], v11, off offset:-128
	v_pk_mul_f32 v[16:17], v[0:1], v[8:9] op_sel_hi:[1,0]
	s_nop 0
	v_pk_fma_f32 v[18:19], v[2:3], v[8:9], v[16:17] op_sel:[0,1,0]
	v_pk_fma_f32 v[8:9], v[2:3], v[8:9], v[16:17] op_sel:[0,1,0] neg_lo:[0,0,1] neg_hi:[0,0,1]
	s_nop 0
	v_mov_b32_e32 v19, v9
	v_pk_add_f32 v[8:9], v[102:103], v[18:19]
	v_cvt_pk_bf16_f32 v10, v9, v9
	global_store_short_d16_hi v[6:7], v10, off
	v_cvt_pk_bf16_f32 v11, v8, v8
	global_store_short_d16_hi v[6:7], v11, off offset:128
	v_pk_mul_f32 v[16:17], v[0:1], v[8:9] op_sel_hi:[1,0]
	s_nop 0
	v_pk_fma_f32 v[18:19], v[2:3], v[8:9], v[16:17] op_sel:[0,1,0]
	v_pk_fma_f32 v[8:9], v[2:3], v[8:9], v[16:17] op_sel:[0,1,0] neg_lo:[0,0,1] neg_hi:[0,0,1]
	s_nop 0
	v_mov_b32_e32 v19, v9
	v_pk_add_f32 v[8:9], v[104:105], v[18:19]
	v_cvt_pk_bf16_f32 v10, v9, v9
	global_store_short_d16_hi v[6:7], v10, off offset:256
	v_cvt_pk_bf16_f32 v11, v8, v8
	global_store_short_d16_hi v[6:7], v11, off offset:384
	v_pk_mul_f32 v[16:17], v[0:1], v[8:9] op_sel_hi:[1,0]
	s_nop 0
	v_pk_fma_f32 v[18:19], v[2:3], v[8:9], v[16:17] op_sel:[0,1,0]
	v_pk_fma_f32 v[8:9], v[2:3], v[8:9], v[16:17] op_sel:[0,1,0] neg_lo:[0,0,1] neg_hi:[0,0,1]
	s_nop 0
	v_mov_b32_e32 v19, v9
	v_pk_add_f32 v[8:9], v[106:107], v[18:19]
	v_cvt_pk_bf16_f32 v10, v9, v9
	global_store_short_d16_hi v[6:7], v10, off offset:512
	v_cvt_pk_bf16_f32 v11, v8, v8
	global_store_short_d16_hi v[6:7], v11, off offset:640
	v_pk_mul_f32 v[16:17], v[0:1], v[8:9] op_sel_hi:[1,0]
	s_nop 0
	v_pk_fma_f32 v[18:19], v[2:3], v[8:9], v[16:17] op_sel:[0,1,0]
	v_pk_fma_f32 v[8:9], v[2:3], v[8:9], v[16:17] op_sel:[0,1,0] neg_lo:[0,0,1] neg_hi:[0,0,1]
	s_nop 0
	v_mov_b32_e32 v19, v9
	v_pk_add_f32 v[8:9], v[108:109], v[18:19]
	v_cvt_pk_bf16_f32 v10, v9, v9
	global_store_short_d16_hi v[6:7], v10, off offset:768
	v_cvt_pk_bf16_f32 v11, v8, v8
	global_store_short_d16_hi v[6:7], v11, off offset:896
	v_pk_mul_f32 v[16:17], v[0:1], v[8:9] op_sel_hi:[1,0]
	s_nop 0
	v_pk_fma_f32 v[18:19], v[2:3], v[8:9], v[16:17] op_sel:[0,1,0]
	v_pk_fma_f32 v[8:9], v[2:3], v[8:9], v[16:17] op_sel:[0,1,0] neg_lo:[0,0,1] neg_hi:[0,0,1]
	s_nop 0
	v_mov_b32_e32 v19, v9
	v_pk_add_f32 v[8:9], v[110:111], v[18:19]
	v_cvt_pk_bf16_f32 v10, v9, v9
	global_store_short_d16_hi v[6:7], v10, off offset:1024
	v_cvt_pk_bf16_f32 v11, v8, v8
	global_store_short_d16_hi v[6:7], v11, off offset:1152
	v_pk_mul_f32 v[16:17], v[0:1], v[8:9] op_sel_hi:[1,0]
	s_nop 0
	v_pk_fma_f32 v[18:19], v[2:3], v[8:9], v[16:17] op_sel:[0,1,0]
	v_pk_fma_f32 v[8:9], v[2:3], v[8:9], v[16:17] op_sel:[0,1,0] neg_lo:[0,0,1] neg_hi:[0,0,1]
	s_nop 0
	v_mov_b32_e32 v19, v9
	v_pk_add_f32 v[8:9], v[112:113], v[18:19]
	v_cvt_pk_bf16_f32 v10, v9, v9
	global_store_short_d16_hi v[6:7], v10, off offset:1280
	v_cvt_pk_bf16_f32 v11, v8, v8
	global_store_short_d16_hi v[6:7], v11, off offset:1408
	v_pk_mul_f32 v[16:17], v[0:1], v[8:9] op_sel_hi:[1,0]
	s_nop 0
	v_pk_fma_f32 v[18:19], v[2:3], v[8:9], v[16:17] op_sel:[0,1,0]
	v_pk_fma_f32 v[8:9], v[2:3], v[8:9], v[16:17] op_sel:[0,1,0] neg_lo:[0,0,1] neg_hi:[0,0,1]
	s_nop 0
	v_mov_b32_e32 v19, v9
	v_pk_add_f32 v[8:9], v[114:115], v[18:19]
	v_lshl_add_u64 v[6:7], v[6:7], 0, s[84:85]
	s_mov_b32 s1, 0
.Lmy_s5c_loop:
	global_load_dword v101, v[148:149], off offset:-1024
	global_load_dword v100, v[148:149], off offset:-768
	global_load_dword v103, v[148:149], off offset:-512
	global_load_dword v102, v[148:149], off offset:-256
	global_load_dword v105, v[148:149], off
	global_load_dword v104, v[148:149], off offset:256
	global_load_dword v107, v[148:149], off offset:512
	global_load_dword v106, v[148:149], off offset:768
	global_load_dword v109, v[148:149], off offset:1024
	global_load_dword v108, v[148:149], off offset:1280
	global_load_dword v111, v[148:149], off offset:1536
	global_load_dword v110, v[148:149], off offset:1792
	global_load_dword v113, v[148:149], off offset:2048
	global_load_dword v112, v[148:149], off offset:2304
	global_load_dword v115, v[148:149], off offset:2560
	global_load_dword v114, v[148:149], off offset:2816
	v_lshl_add_u64 v[148:149], v[148:149], 0, s[100:101]
	s_waitcnt vmcnt(48)
	v_cvt_pk_bf16_f32 v10, v9, v9
	global_store_short_d16_hi v[6:7], v10, off offset:-512
	v_cvt_pk_bf16_f32 v11, v8, v8
	global_store_short_d16_hi v[6:7], v11, off offset:-384
	v_pk_mul_f32 v[16:17], v[0:1], v[8:9] op_sel_hi:[1,0]
	s_nop 0
	v_pk_fma_f32 v[18:19], v[2:3], v[8:9], v[16:17] op_sel:[0,1,0]
	v_pk_fma_f32 v[8:9], v[2:3], v[8:9], v[16:17] op_sel:[0,1,0] neg_lo:[0,0,1] neg_hi:[0,0,1]
	s_nop 0
	v_mov_b32_e32 v19, v9
	v_pk_add_f32 v[8:9], v[116:117], v[18:19]
	v_cvt_pk_bf16_f32 v10, v9, v9
	global_store_short_d16_hi v[6:7], v10, off offset:-256
	v_cvt_pk_bf16_f32 v11, v8, v8
	global_store_short_d16_hi v[6:7], v11, off offset:-128
	v_pk_mul_f32 v[16:17], v[0:1], v[8:9] op_sel_hi:[1,0]
	s_nop 0
	v_pk_fma_f32 v[18:19], v[2:3], v[8:9], v[16:17] op_sel:[0,1,0]
	v_pk_fma_f32 v[8:9], v[2:3], v[8:9], v[16:17] op_sel:[0,1,0] neg_lo:[0,0,1] neg_hi:[0,0,1]
	s_nop 0
	v_mov_b32_e32 v19, v9
	v_pk_add_f32 v[8:9], v[118:119], v[18:19]
	v_cvt_pk_bf16_f32 v10, v9, v9
	global_store_short_d16_hi v[6:7], v10, off
	v_cvt_pk_bf16_f32 v11, v8, v8
	global_store_short_d16_hi v[6:7], v11, off offset:128
	v_pk_mul_f32 v[16:17], v[0:1], v[8:9] op_sel_hi:[1,0]
	s_nop 0
	v_pk_fma_f32 v[18:19], v[2:3], v[8:9], v[16:17] op_sel:[0,1,0]
	v_pk_fma_f32 v[8:9], v[2:3], v[8:9], v[16:17] op_sel:[0,1,0] neg_lo:[0,0,1] neg_hi:[0,0,1]
	s_nop 0
	v_mov_b32_e32 v19, v9
	v_pk_add_f32 v[8:9], v[120:121], v[18:19]
	v_cvt_pk_bf16_f32 v10, v9, v9
	global_store_short_d16_hi v[6:7], v10, off offset:256
	v_cvt_pk_bf16_f32 v11, v8, v8
	global_store_short_d16_hi v[6:7], v11, off offset:384
	v_pk_mul_f32 v[16:17], v[0:1], v[8:9] op_sel_hi:[1,0]
	s_nop 0
	v_pk_fma_f32 v[18:19], v[2:3], v[8:9], v[16:17] op_sel:[0,1,0]
	v_pk_fma_f32 v[8:9], v[2:3], v[8:9], v[16:17] op_sel:[0,1,0] neg_lo:[0,0,1] neg_hi:[0,0,1]
	s_nop 0
	v_mov_b32_e32 v19, v9
	v_pk_add_f32 v[8:9], v[122:123], v[18:19]
	v_cvt_pk_bf16_f32 v10, v9, v9
	global_store_short_d16_hi v[6:7], v10, off offset:512
	v_cvt_pk_bf16_f32 v11, v8, v8
	global_store_short_d16_hi v[6:7], v11, off offset:640
	v_pk_mul_f32 v[16:17], v[0:1], v[8:9] op_sel_hi:[1,0]
	s_nop 0
	v_pk_fma_f32 v[18:19], v[2:3], v[8:9], v[16:17] op_sel:[0,1,0]
	v_pk_fma_f32 v[8:9], v[2:3], v[8:9], v[16:17] op_sel:[0,1,0] neg_lo:[0,0,1] neg_hi:[0,0,1]
	s_nop 0
	v_mov_b32_e32 v19, v9
	v_pk_add_f32 v[8:9], v[124:125], v[18:19]
	v_cvt_pk_bf16_f32 v10, v9, v9
	global_store_short_d16_hi v[6:7], v10, off offset:768
	v_cvt_pk_bf16_f32 v11, v8, v8
	global_store_short_d16_hi v[6:7], v11, off offset:896
	v_pk_mul_f32 v[16:17], v[0:1], v[8:9] op_sel_hi:[1,0]
	s_nop 0
	v_pk_fma_f32 v[18:19], v[2:3], v[8:9], v[16:17] op_sel:[0,1,0]
	v_pk_fma_f32 v[8:9], v[2:3], v[8:9], v[16:17] op_sel:[0,1,0] neg_lo:[0,0,1] neg_hi:[0,0,1]
	s_nop 0
	v_mov_b32_e32 v19, v9
	v_pk_add_f32 v[8:9], v[126:127], v[18:19]
	v_cvt_pk_bf16_f32 v10, v9, v9
	global_store_short_d16_hi v[6:7], v10, off offset:1024
	v_cvt_pk_bf16_f32 v11, v8, v8
	global_store_short_d16_hi v[6:7], v11, off offset:1152
	v_pk_mul_f32 v[16:17], v[0:1], v[8:9] op_sel_hi:[1,0]
	s_nop 0
	v_pk_fma_f32 v[18:19], v[2:3], v[8:9], v[16:17] op_sel:[0,1,0]
	v_pk_fma_f32 v[8:9], v[2:3], v[8:9], v[16:17] op_sel:[0,1,0] neg_lo:[0,0,1] neg_hi:[0,0,1]
	s_nop 0
	v_mov_b32_e32 v19, v9
	v_pk_add_f32 v[8:9], v[128:129], v[18:19]
	v_cvt_pk_bf16_f32 v10, v9, v9
	global_store_short_d16_hi v[6:7], v10, off offset:1280
	v_cvt_pk_bf16_f32 v11, v8, v8
	global_store_short_d16_hi v[6:7], v11, off offset:1408
	v_pk_mul_f32 v[16:17], v[0:1], v[8:9] op_sel_hi:[1,0]
	s_nop 0
	v_pk_fma_f32 v[18:19], v[2:3], v[8:9], v[16:17] op_sel:[0,1,0]
	v_pk_fma_f32 v[8:9], v[2:3], v[8:9], v[16:17] op_sel:[0,1,0] neg_lo:[0,0,1] neg_hi:[0,0,1]
	s_nop 0
	v_mov_b32_e32 v19, v9
	v_pk_add_f32 v[8:9], v[130:131], v[18:19]
	v_lshl_add_u64 v[6:7], v[6:7], 0, s[84:85]
	global_load_dword v117, v[148:149], off offset:-1024
	global_load_dword v116, v[148:149], off offset:-768
	global_load_dword v119, v[148:149], off offset:-512
	global_load_dword v118, v[148:149], off offset:-256
	global_load_dword v121, v[148:149], off
	global_load_dword v120, v[148:149], off offset:256
	global_load_dword v123, v[148:149], off offset:512
	global_load_dword v122, v[148:149], off offset:768
	global_load_dword v125, v[148:149], off offset:1024
	global_load_dword v124, v[148:149], off offset:1280
	global_load_dword v127, v[148:149], off offset:1536
	global_load_dword v126, v[148:149], off offset:1792
	global_load_dword v129, v[148:149], off offset:2048
	global_load_dword v128, v[148:149], off offset:2304
	global_load_dword v131, v[148:149], off offset:2560
	global_load_dword v130, v[148:149], off offset:2816
	v_lshl_add_u64 v[148:149], v[148:149], 0, s[100:101]
	s_waitcnt vmcnt(48)
	v_cvt_pk_bf16_f32 v10, v9, v9
	global_store_short_d16_hi v[6:7], v10, off offset:-512
	v_cvt_pk_bf16_f32 v11, v8, v8
	global_store_short_d16_hi v[6:7], v11, off offset:-384
	v_pk_mul_f32 v[16:17], v[0:1], v[8:9] op_sel_hi:[1,0]
	s_nop 0
	v_pk_fma_f32 v[18:19], v[2:3], v[8:9], v[16:17] op_sel:[0,1,0]
	v_pk_fma_f32 v[8:9], v[2:3], v[8:9], v[16:17] op_sel:[0,1,0] neg_lo:[0,0,1] neg_hi:[0,0,1]
	s_nop 0
	v_mov_b32_e32 v19, v9
	v_pk_add_f32 v[8:9], v[132:133], v[18:19]
	v_cvt_pk_bf16_f32 v10, v9, v9
	global_store_short_d16_hi v[6:7], v10, off offset:-256
	v_cvt_pk_bf16_f32 v11, v8, v8
	global_store_short_d16_hi v[6:7], v11, off offset:-128
	v_pk_mul_f32 v[16:17], v[0:1], v[8:9] op_sel_hi:[1,0]
	s_nop 0
	v_pk_fma_f32 v[18:19], v[2:3], v[8:9], v[16:17] op_sel:[0,1,0]
	v_pk_fma_f32 v[8:9], v[2:3], v[8:9], v[16:17] op_sel:[0,1,0] neg_lo:[0,0,1] neg_hi:[0,0,1]
	s_nop 0
	v_mov_b32_e32 v19, v9
	v_pk_add_f32 v[8:9], v[134:135], v[18:19]
	v_cvt_pk_bf16_f32 v10, v9, v9
	global_store_short_d16_hi v[6:7], v10, off
	v_cvt_pk_bf16_f32 v11, v8, v8
	global_store_short_d16_hi v[6:7], v11, off offset:128
	v_pk_mul_f32 v[16:17], v[0:1], v[8:9] op_sel_hi:[1,0]
	s_nop 0
	v_pk_fma_f32 v[18:19], v[2:3], v[8:9], v[16:17] op_sel:[0,1,0]
	v_pk_fma_f32 v[8:9], v[2:3], v[8:9], v[16:17] op_sel:[0,1,0] neg_lo:[0,0,1] neg_hi:[0,0,1]
	s_nop 0
	v_mov_b32_e32 v19, v9
	v_pk_add_f32 v[8:9], v[136:137], v[18:19]
	v_cvt_pk_bf16_f32 v10, v9, v9
	global_store_short_d16_hi v[6:7], v10, off offset:256
	v_cvt_pk_bf16_f32 v11, v8, v8
	global_store_short_d16_hi v[6:7], v11, off offset:384
	v_pk_mul_f32 v[16:17], v[0:1], v[8:9] op_sel_hi:[1,0]
	s_nop 0
	v_pk_fma_f32 v[18:19], v[2:3], v[8:9], v[16:17] op_sel:[0,1,0]
	v_pk_fma_f32 v[8:9], v[2:3], v[8:9], v[16:17] op_sel:[0,1,0] neg_lo:[0,0,1] neg_hi:[0,0,1]
	s_nop 0
	v_mov_b32_e32 v19, v9
	v_pk_add_f32 v[8:9], v[138:139], v[18:19]
	v_cvt_pk_bf16_f32 v10, v9, v9
	global_store_short_d16_hi v[6:7], v10, off offset:512
	v_cvt_pk_bf16_f32 v11, v8, v8
	global_store_short_d16_hi v[6:7], v11, off offset:640
	v_pk_mul_f32 v[16:17], v[0:1], v[8:9] op_sel_hi:[1,0]
	s_nop 0
	v_pk_fma_f32 v[18:19], v[2:3], v[8:9], v[16:17] op_sel:[0,1,0]
	v_pk_fma_f32 v[8:9], v[2:3], v[8:9], v[16:17] op_sel:[0,1,0] neg_lo:[0,0,1] neg_hi:[0,0,1]
	s_nop 0
	v_mov_b32_e32 v19, v9
	v_pk_add_f32 v[8:9], v[140:141], v[18:19]
	v_cvt_pk_bf16_f32 v10, v9, v9
	global_store_short_d16_hi v[6:7], v10, off offset:768
	v_cvt_pk_bf16_f32 v11, v8, v8
	global_store_short_d16_hi v[6:7], v11, off offset:896
	v_pk_mul_f32 v[16:17], v[0:1], v[8:9] op_sel_hi:[1,0]
	s_nop 0
	v_pk_fma_f32 v[18:19], v[2:3], v[8:9], v[16:17] op_sel:[0,1,0]
	v_pk_fma_f32 v[8:9], v[2:3], v[8:9], v[16:17] op_sel:[0,1,0] neg_lo:[0,0,1] neg_hi:[0,0,1]
	s_nop 0
	v_mov_b32_e32 v19, v9
	v_pk_add_f32 v[8:9], v[142:143], v[18:19]
	v_cvt_pk_bf16_f32 v10, v9, v9
	global_store_short_d16_hi v[6:7], v10, off offset:1024
	v_cvt_pk_bf16_f32 v11, v8, v8
	global_store_short_d16_hi v[6:7], v11, off offset:1152
	v_pk_mul_f32 v[16:17], v[0:1], v[8:9] op_sel_hi:[1,0]
	s_nop 0
	v_pk_fma_f32 v[18:19], v[2:3], v[8:9], v[16:17] op_sel:[0,1,0]
	v_pk_fma_f32 v[8:9], v[2:3], v[8:9], v[16:17] op_sel:[0,1,0] neg_lo:[0,0,1] neg_hi:[0,0,1]
	s_nop 0
	v_mov_b32_e32 v19, v9
	v_pk_add_f32 v[8:9], v[144:145], v[18:19]
	v_cvt_pk_bf16_f32 v10, v9, v9
	global_store_short_d16_hi v[6:7], v10, off offset:1280
	v_cvt_pk_bf16_f32 v11, v8, v8
	global_store_short_d16_hi v[6:7], v11, off offset:1408
	v_pk_mul_f32 v[16:17], v[0:1], v[8:9] op_sel_hi:[1,0]
	s_nop 0
	v_pk_fma_f32 v[18:19], v[2:3], v[8:9], v[16:17] op_sel:[0,1,0]
	v_pk_fma_f32 v[8:9], v[2:3], v[8:9], v[16:17] op_sel:[0,1,0] neg_lo:[0,0,1] neg_hi:[0,0,1]
	s_nop 0
	v_mov_b32_e32 v19, v9
	v_pk_add_f32 v[8:9], v[146:147], v[18:19]
	v_lshl_add_u64 v[6:7], v[6:7], 0, s[84:85]
	global_load_dword v133, v[148:149], off offset:-1024
	global_load_dword v132, v[148:149], off offset:-768
	global_load_dword v135, v[148:149], off offset:-512
	global_load_dword v134, v[148:149], off offset:-256
	global_load_dword v137, v[148:149], off
	global_load_dword v136, v[148:149], off offset:256
	global_load_dword v139, v[148:149], off offset:512
	global_load_dword v138, v[148:149], off offset:768
	global_load_dword v141, v[148:149], off offset:1024
	global_load_dword v140, v[148:149], off offset:1280
	global_load_dword v143, v[148:149], off offset:1536
	global_load_dword v142, v[148:149], off offset:1792
	global_load_dword v145, v[148:149], off offset:2048
	global_load_dword v144, v[148:149], off offset:2304
	global_load_dword v147, v[148:149], off offset:2560
	global_load_dword v146, v[148:149], off offset:2816
	v_lshl_add_u64 v[148:149], v[148:149], 0, s[100:101]
	s_waitcnt vmcnt(48)
	v_cvt_pk_bf16_f32 v10, v9, v9
	global_store_short_d16_hi v[6:7], v10, off offset:-512
	v_cvt_pk_bf16_f32 v11, v8, v8
	global_store_short_d16_hi v[6:7], v11, off offset:-384
	v_pk_mul_f32 v[16:17], v[0:1], v[8:9] op_sel_hi:[1,0]
	s_nop 0
	v_pk_fma_f32 v[18:19], v[2:3], v[8:9], v[16:17] op_sel:[0,1,0]
	v_pk_fma_f32 v[8:9], v[2:3], v[8:9], v[16:17] op_sel:[0,1,0] neg_lo:[0,0,1] neg_hi:[0,0,1]
	s_nop 0
	v_mov_b32_e32 v19, v9
	v_pk_add_f32 v[8:9], v[100:101], v[18:19]
	v_cvt_pk_bf16_f32 v10, v9, v9
	global_store_short_d16_hi v[6:7], v10, off offset:-256
	v_cvt_pk_bf16_f32 v11, v8, v8
	global_store_short_d16_hi v[6:7], v11, off offset:-128
	v_pk_mul_f32 v[16:17], v[0:1], v[8:9] op_sel_hi:[1,0]
	s_nop 0
	v_pk_fma_f32 v[18:19], v[2:3], v[8:9], v[16:17] op_sel:[0,1,0]
	v_pk_fma_f32 v[8:9], v[2:3], v[8:9], v[16:17] op_sel:[0,1,0] neg_lo:[0,0,1] neg_hi:[0,0,1]
	s_nop 0
	v_mov_b32_e32 v19, v9
	v_pk_add_f32 v[8:9], v[102:103], v[18:19]
	v_cvt_pk_bf16_f32 v10, v9, v9
	global_store_short_d16_hi v[6:7], v10, off
	v_cvt_pk_bf16_f32 v11, v8, v8
	global_store_short_d16_hi v[6:7], v11, off offset:128
	v_pk_mul_f32 v[16:17], v[0:1], v[8:9] op_sel_hi:[1,0]
	s_nop 0
	v_pk_fma_f32 v[18:19], v[2:3], v[8:9], v[16:17] op_sel:[0,1,0]
	v_pk_fma_f32 v[8:9], v[2:3], v[8:9], v[16:17] op_sel:[0,1,0] neg_lo:[0,0,1] neg_hi:[0,0,1]
	s_nop 0
	v_mov_b32_e32 v19, v9
	v_pk_add_f32 v[8:9], v[104:105], v[18:19]
	v_cvt_pk_bf16_f32 v10, v9, v9
	global_store_short_d16_hi v[6:7], v10, off offset:256
	v_cvt_pk_bf16_f32 v11, v8, v8
	global_store_short_d16_hi v[6:7], v11, off offset:384
	v_pk_mul_f32 v[16:17], v[0:1], v[8:9] op_sel_hi:[1,0]
	s_nop 0
	v_pk_fma_f32 v[18:19], v[2:3], v[8:9], v[16:17] op_sel:[0,1,0]
	v_pk_fma_f32 v[8:9], v[2:3], v[8:9], v[16:17] op_sel:[0,1,0] neg_lo:[0,0,1] neg_hi:[0,0,1]
	s_nop 0
	v_mov_b32_e32 v19, v9
	v_pk_add_f32 v[8:9], v[106:107], v[18:19]
	v_cvt_pk_bf16_f32 v10, v9, v9
	global_store_short_d16_hi v[6:7], v10, off offset:512
	v_cvt_pk_bf16_f32 v11, v8, v8
	global_store_short_d16_hi v[6:7], v11, off offset:640
	v_pk_mul_f32 v[16:17], v[0:1], v[8:9] op_sel_hi:[1,0]
	s_nop 0
	v_pk_fma_f32 v[18:19], v[2:3], v[8:9], v[16:17] op_sel:[0,1,0]
	v_pk_fma_f32 v[8:9], v[2:3], v[8:9], v[16:17] op_sel:[0,1,0] neg_lo:[0,0,1] neg_hi:[0,0,1]
	s_nop 0
	v_mov_b32_e32 v19, v9
	v_pk_add_f32 v[8:9], v[108:109], v[18:19]
	v_cvt_pk_bf16_f32 v10, v9, v9
	global_store_short_d16_hi v[6:7], v10, off offset:768
	v_cvt_pk_bf16_f32 v11, v8, v8
	global_store_short_d16_hi v[6:7], v11, off offset:896
	v_pk_mul_f32 v[16:17], v[0:1], v[8:9] op_sel_hi:[1,0]
	s_nop 0
	v_pk_fma_f32 v[18:19], v[2:3], v[8:9], v[16:17] op_sel:[0,1,0]
	v_pk_fma_f32 v[8:9], v[2:3], v[8:9], v[16:17] op_sel:[0,1,0] neg_lo:[0,0,1] neg_hi:[0,0,1]
	s_nop 0
	v_mov_b32_e32 v19, v9
	v_pk_add_f32 v[8:9], v[110:111], v[18:19]
	v_cvt_pk_bf16_f32 v10, v9, v9
	global_store_short_d16_hi v[6:7], v10, off offset:1024
	v_cvt_pk_bf16_f32 v11, v8, v8
	global_store_short_d16_hi v[6:7], v11, off offset:1152
	v_pk_mul_f32 v[16:17], v[0:1], v[8:9] op_sel_hi:[1,0]
	s_nop 0
	v_pk_fma_f32 v[18:19], v[2:3], v[8:9], v[16:17] op_sel:[0,1,0]
	v_pk_fma_f32 v[8:9], v[2:3], v[8:9], v[16:17] op_sel:[0,1,0] neg_lo:[0,0,1] neg_hi:[0,0,1]
	s_nop 0
	v_mov_b32_e32 v19, v9
	v_pk_add_f32 v[8:9], v[112:113], v[18:19]
	v_cvt_pk_bf16_f32 v10, v9, v9
	global_store_short_d16_hi v[6:7], v10, off offset:1280
	v_cvt_pk_bf16_f32 v11, v8, v8
	global_store_short_d16_hi v[6:7], v11, off offset:1408
	v_pk_mul_f32 v[16:17], v[0:1], v[8:9] op_sel_hi:[1,0]
	s_nop 0
	v_pk_fma_f32 v[18:19], v[2:3], v[8:9], v[16:17] op_sel:[0,1,0]
	v_pk_fma_f32 v[8:9], v[2:3], v[8:9], v[16:17] op_sel:[0,1,0] neg_lo:[0,0,1] neg_hi:[0,0,1]
	s_nop 0
	v_mov_b32_e32 v19, v9
	v_pk_add_f32 v[8:9], v[114:115], v[18:19]
	v_lshl_add_u64 v[6:7], v[6:7], 0, s[84:85]
	s_add_i32 s1, s1, 1
	s_cmp_lt_u32 s1, 4
	s_cbranch_scc1 .Lmy_s5c_loop
	global_load_dword v101, v[148:149], off offset:-1024
	global_load_dword v100, v[148:149], off offset:-768
	global_load_dword v103, v[148:149], off offset:-512
	global_load_dword v102, v[148:149], off offset:-256
	global_load_dword v105, v[148:149], off
	global_load_dword v104, v[148:149], off offset:256
	global_load_dword v107, v[148:149], off offset:512
	global_load_dword v106, v[148:149], off offset:768
	global_load_dword v109, v[148:149], off offset:1024
	global_load_dword v108, v[148:149], off offset:1280
	global_load_dword v111, v[148:149], off offset:1536
	global_load_dword v110, v[148:149], off offset:1792
	global_load_dword v113, v[148:149], off offset:2048
	global_load_dword v112, v[148:149], off offset:2304
	global_load_dword v115, v[148:149], off offset:2560
	global_load_dword v114, v[148:149], off offset:2816
	v_lshl_add_u64 v[148:149], v[148:149], 0, s[100:101]
	s_waitcnt vmcnt(63)
	v_cvt_pk_bf16_f32 v10, v9, v9
	global_store_short_d16_hi v[6:7], v10, off offset:-512
	v_cvt_pk_bf16_f32 v11, v8, v8
	global_store_short_d16_hi v[6:7], v11, off offset:-384
	v_pk_mul_f32 v[16:17], v[0:1], v[8:9] op_sel_hi:[1,0]
	s_nop 0
	v_pk_fma_f32 v[18:19], v[2:3], v[8:9], v[16:17] op_sel:[0,1,0]
	v_pk_fma_f32 v[8:9], v[2:3], v[8:9], v[16:17] op_sel:[0,1,0] neg_lo:[0,0,1] neg_hi:[0,0,1]
	s_nop 0
	v_mov_b32_e32 v19, v9
	v_pk_add_f32 v[8:9], v[116:117], v[18:19]
	v_cvt_pk_bf16_f32 v10, v9, v9
	global_store_short_d16_hi v[6:7], v10, off offset:-256
	v_cvt_pk_bf16_f32 v11, v8, v8
	global_store_short_d16_hi v[6:7], v11, off offset:-128
	v_pk_mul_f32 v[16:17], v[0:1], v[8:9] op_sel_hi:[1,0]
	s_nop 0
	v_pk_fma_f32 v[18:19], v[2:3], v[8:9], v[16:17] op_sel:[0,1,0]
	v_pk_fma_f32 v[8:9], v[2:3], v[8:9], v[16:17] op_sel:[0,1,0] neg_lo:[0,0,1] neg_hi:[0,0,1]
	s_nop 0
	v_mov_b32_e32 v19, v9
	v_pk_add_f32 v[8:9], v[118:119], v[18:19]
	v_cvt_pk_bf16_f32 v10, v9, v9
	global_store_short_d16_hi v[6:7], v10, off
	v_cvt_pk_bf16_f32 v11, v8, v8
	global_store_short_d16_hi v[6:7], v11, off offset:128
	v_pk_mul_f32 v[16:17], v[0:1], v[8:9] op_sel_hi:[1,0]
	s_nop 0
	v_pk_fma_f32 v[18:19], v[2:3], v[8:9], v[16:17] op_sel:[0,1,0]
	v_pk_fma_f32 v[8:9], v[2:3], v[8:9], v[16:17] op_sel:[0,1,0] neg_lo:[0,0,1] neg_hi:[0,0,1]
	s_nop 0
	v_mov_b32_e32 v19, v9
	v_pk_add_f32 v[8:9], v[120:121], v[18:19]
	v_cvt_pk_bf16_f32 v10, v9, v9
	global_store_short_d16_hi v[6:7], v10, off offset:256
	v_cvt_pk_bf16_f32 v11, v8, v8
	global_store_short_d16_hi v[6:7], v11, off offset:384
	v_pk_mul_f32 v[16:17], v[0:1], v[8:9] op_sel_hi:[1,0]
	s_nop 0
	v_pk_fma_f32 v[18:19], v[2:3], v[8:9], v[16:17] op_sel:[0,1,0]
	v_pk_fma_f32 v[8:9], v[2:3], v[8:9], v[16:17] op_sel:[0,1,0] neg_lo:[0,0,1] neg_hi:[0,0,1]
	s_nop 0
	v_mov_b32_e32 v19, v9
	v_pk_add_f32 v[8:9], v[122:123], v[18:19]
	v_cvt_pk_bf16_f32 v10, v9, v9
	global_store_short_d16_hi v[6:7], v10, off offset:512
	v_cvt_pk_bf16_f32 v11, v8, v8
	global_store_short_d16_hi v[6:7], v11, off offset:640
	v_pk_mul_f32 v[16:17], v[0:1], v[8:9] op_sel_hi:[1,0]
	s_nop 0
	v_pk_fma_f32 v[18:19], v[2:3], v[8:9], v[16:17] op_sel:[0,1,0]
	v_pk_fma_f32 v[8:9], v[2:3], v[8:9], v[16:17] op_sel:[0,1,0] neg_lo:[0,0,1] neg_hi:[0,0,1]
	s_nop 0
	v_mov_b32_e32 v19, v9
	v_pk_add_f32 v[8:9], v[124:125], v[18:19]
	v_cvt_pk_bf16_f32 v10, v9, v9
	global_store_short_d16_hi v[6:7], v10, off offset:768
	v_cvt_pk_bf16_f32 v11, v8, v8
	global_store_short_d16_hi v[6:7], v11, off offset:896
	v_pk_mul_f32 v[16:17], v[0:1], v[8:9] op_sel_hi:[1,0]
	s_nop 0
	v_pk_fma_f32 v[18:19], v[2:3], v[8:9], v[16:17] op_sel:[0,1,0]
	v_pk_fma_f32 v[8:9], v[2:3], v[8:9], v[16:17] op_sel:[0,1,0] neg_lo:[0,0,1] neg_hi:[0,0,1]
	s_nop 0
	v_mov_b32_e32 v19, v9
	v_pk_add_f32 v[8:9], v[126:127], v[18:19]
	v_cvt_pk_bf16_f32 v10, v9, v9
	global_store_short_d16_hi v[6:7], v10, off offset:1024
	v_cvt_pk_bf16_f32 v11, v8, v8
	global_store_short_d16_hi v[6:7], v11, off offset:1152
	v_pk_mul_f32 v[16:17], v[0:1], v[8:9] op_sel_hi:[1,0]
	s_nop 0
	v_pk_fma_f32 v[18:19], v[2:3], v[8:9], v[16:17] op_sel:[0,1,0]
	v_pk_fma_f32 v[8:9], v[2:3], v[8:9], v[16:17] op_sel:[0,1,0] neg_lo:[0,0,1] neg_hi:[0,0,1]
	s_nop 0
	v_mov_b32_e32 v19, v9
	v_pk_add_f32 v[8:9], v[128:129], v[18:19]
	v_cvt_pk_bf16_f32 v10, v9, v9
	global_store_short_d16_hi v[6:7], v10, off offset:1280
	v_cvt_pk_bf16_f32 v11, v8, v8
	global_store_short_d16_hi v[6:7], v11, off offset:1408
	v_pk_mul_f32 v[16:17], v[0:1], v[8:9] op_sel_hi:[1,0]
	s_nop 0
	v_pk_fma_f32 v[18:19], v[2:3], v[8:9], v[16:17] op_sel:[0,1,0]
	v_pk_fma_f32 v[8:9], v[2:3], v[8:9], v[16:17] op_sel:[0,1,0] neg_lo:[0,0,1] neg_hi:[0,0,1]
	s_nop 0
	v_mov_b32_e32 v19, v9
	v_pk_add_f32 v[8:9], v[130:131], v[18:19]
	v_lshl_add_u64 v[6:7], v[6:7], 0, s[84:85]
	global_load_dword v117, v[148:149], off offset:-1024
	global_load_dword v116, v[148:149], off offset:-768
	v_lshl_add_u64 v[148:149], v[148:149], 0, s[100:101]
	s_waitcnt vmcnt(50)
	v_cvt_pk_bf16_f32 v10, v9, v9
	global_store_short_d16_hi v[6:7], v10, off offset:-512
	v_cvt_pk_bf16_f32 v11, v8, v8
	global_store_short_d16_hi v[6:7], v11, off offset:-384
	v_pk_mul_f32 v[16:17], v[0:1], v[8:9] op_sel_hi:[1,0]
	s_nop 0
	v_pk_fma_f32 v[18:19], v[2:3], v[8:9], v[16:17] op_sel:[0,1,0]
	v_pk_fma_f32 v[8:9], v[2:3], v[8:9], v[16:17] op_sel:[0,1,0] neg_lo:[0,0,1] neg_hi:[0,0,1]
	s_nop 0
	v_mov_b32_e32 v19, v9
	v_pk_add_f32 v[8:9], v[132:133], v[18:19]
	v_cvt_pk_bf16_f32 v10, v9, v9
	global_store_short_d16_hi v[6:7], v10, off offset:-256
	v_cvt_pk_bf16_f32 v11, v8, v8
	global_store_short_d16_hi v[6:7], v11, off offset:-128
	v_pk_mul_f32 v[16:17], v[0:1], v[8:9] op_sel_hi:[1,0]
	s_nop 0
	v_pk_fma_f32 v[18:19], v[2:3], v[8:9], v[16:17] op_sel:[0,1,0]
	v_pk_fma_f32 v[8:9], v[2:3], v[8:9], v[16:17] op_sel:[0,1,0] neg_lo:[0,0,1] neg_hi:[0,0,1]
	s_nop 0
	v_mov_b32_e32 v19, v9
	v_pk_add_f32 v[8:9], v[134:135], v[18:19]
	v_cvt_pk_bf16_f32 v10, v9, v9
	global_store_short_d16_hi v[6:7], v10, off
	v_cvt_pk_bf16_f32 v11, v8, v8
	global_store_short_d16_hi v[6:7], v11, off offset:128
	v_pk_mul_f32 v[16:17], v[0:1], v[8:9] op_sel_hi:[1,0]
	s_nop 0
	v_pk_fma_f32 v[18:19], v[2:3], v[8:9], v[16:17] op_sel:[0,1,0]
	v_pk_fma_f32 v[8:9], v[2:3], v[8:9], v[16:17] op_sel:[0,1,0] neg_lo:[0,0,1] neg_hi:[0,0,1]
	s_nop 0
	v_mov_b32_e32 v19, v9
	v_pk_add_f32 v[8:9], v[136:137], v[18:19]
	v_cvt_pk_bf16_f32 v10, v9, v9
	global_store_short_d16_hi v[6:7], v10, off offset:256
	v_cvt_pk_bf16_f32 v11, v8, v8
	global_store_short_d16_hi v[6:7], v11, off offset:384
	v_pk_mul_f32 v[16:17], v[0:1], v[8:9] op_sel_hi:[1,0]
	s_nop 0
	v_pk_fma_f32 v[18:19], v[2:3], v[8:9], v[16:17] op_sel:[0,1,0]
	v_pk_fma_f32 v[8:9], v[2:3], v[8:9], v[16:17] op_sel:[0,1,0] neg_lo:[0,0,1] neg_hi:[0,0,1]
	s_nop 0
	v_mov_b32_e32 v19, v9
	v_pk_add_f32 v[8:9], v[138:139], v[18:19]
	v_cvt_pk_bf16_f32 v10, v9, v9
	global_store_short_d16_hi v[6:7], v10, off offset:512
	v_cvt_pk_bf16_f32 v11, v8, v8
	global_store_short_d16_hi v[6:7], v11, off offset:640
	v_pk_mul_f32 v[16:17], v[0:1], v[8:9] op_sel_hi:[1,0]
	s_nop 0
	v_pk_fma_f32 v[18:19], v[2:3], v[8:9], v[16:17] op_sel:[0,1,0]
	v_pk_fma_f32 v[8:9], v[2:3], v[8:9], v[16:17] op_sel:[0,1,0] neg_lo:[0,0,1] neg_hi:[0,0,1]
	s_nop 0
	v_mov_b32_e32 v19, v9
	v_pk_add_f32 v[8:9], v[140:141], v[18:19]
	v_cvt_pk_bf16_f32 v10, v9, v9
	global_store_short_d16_hi v[6:7], v10, off offset:768
	v_cvt_pk_bf16_f32 v11, v8, v8
	global_store_short_d16_hi v[6:7], v11, off offset:896
	v_pk_mul_f32 v[16:17], v[0:1], v[8:9] op_sel_hi:[1,0]
	s_nop 0
	v_pk_fma_f32 v[18:19], v[2:3], v[8:9], v[16:17] op_sel:[0,1,0]
	v_pk_fma_f32 v[8:9], v[2:3], v[8:9], v[16:17] op_sel:[0,1,0] neg_lo:[0,0,1] neg_hi:[0,0,1]
	s_nop 0
	v_mov_b32_e32 v19, v9
	v_pk_add_f32 v[8:9], v[142:143], v[18:19]
	v_cvt_pk_bf16_f32 v10, v9, v9
	global_store_short_d16_hi v[6:7], v10, off offset:1024
	v_cvt_pk_bf16_f32 v11, v8, v8
	global_store_short_d16_hi v[6:7], v11, off offset:1152
	v_pk_mul_f32 v[16:17], v[0:1], v[8:9] op_sel_hi:[1,0]
	s_nop 0
	v_pk_fma_f32 v[18:19], v[2:3], v[8:9], v[16:17] op_sel:[0,1,0]
	v_pk_fma_f32 v[8:9], v[2:3], v[8:9], v[16:17] op_sel:[0,1,0] neg_lo:[0,0,1] neg_hi:[0,0,1]
	s_nop 0
	v_mov_b32_e32 v19, v9
	v_pk_add_f32 v[8:9], v[144:145], v[18:19]
	v_cvt_pk_bf16_f32 v10, v9, v9
	global_store_short_d16_hi v[6:7], v10, off offset:1280
	v_cvt_pk_bf16_f32 v11, v8, v8
	global_store_short_d16_hi v[6:7], v11, off offset:1408
	v_pk_mul_f32 v[16:17], v[0:1], v[8:9] op_sel_hi:[1,0]
	s_nop 0
	v_pk_fma_f32 v[18:19], v[2:3], v[8:9], v[16:17] op_sel:[0,1,0]
	v_pk_fma_f32 v[8:9], v[2:3], v[8:9], v[16:17] op_sel:[0,1,0] neg_lo:[0,0,1] neg_hi:[0,0,1]
	s_nop 0
	v_mov_b32_e32 v19, v9
	v_pk_add_f32 v[8:9], v[146:147], v[18:19]
	v_lshl_add_u64 v[6:7], v[6:7], 0, s[84:85]
	s_waitcnt vmcnt(34)
	v_cvt_pk_bf16_f32 v10, v9, v9
	global_store_short_d16_hi v[6:7], v10, off offset:-512
	v_cvt_pk_bf16_f32 v11, v8, v8
	global_store_short_d16_hi v[6:7], v11, off offset:-384
	v_pk_mul_f32 v[16:17], v[0:1], v[8:9] op_sel_hi:[1,0]
	s_nop 0
	v_pk_fma_f32 v[18:19], v[2:3], v[8:9], v[16:17] op_sel:[0,1,0]
	v_pk_fma_f32 v[8:9], v[2:3], v[8:9], v[16:17] op_sel:[0,1,0] neg_lo:[0,0,1] neg_hi:[0,0,1]
	s_nop 0
	v_mov_b32_e32 v19, v9
	v_pk_add_f32 v[8:9], v[100:101], v[18:19]
	v_cvt_pk_bf16_f32 v10, v9, v9
	global_store_short_d16_hi v[6:7], v10, off offset:-256
	v_cvt_pk_bf16_f32 v11, v8, v8
	global_store_short_d16_hi v[6:7], v11, off offset:-128
	v_pk_mul_f32 v[16:17], v[0:1], v[8:9] op_sel_hi:[1,0]
	s_nop 0
	v_pk_fma_f32 v[18:19], v[2:3], v[8:9], v[16:17] op_sel:[0,1,0]
	v_pk_fma_f32 v[8:9], v[2:3], v[8:9], v[16:17] op_sel:[0,1,0] neg_lo:[0,0,1] neg_hi:[0,0,1]
	s_nop 0
	v_mov_b32_e32 v19, v9
	v_pk_add_f32 v[8:9], v[102:103], v[18:19]
	v_cvt_pk_bf16_f32 v10, v9, v9
	global_store_short_d16_hi v[6:7], v10, off
	v_cvt_pk_bf16_f32 v11, v8, v8
	global_store_short_d16_hi v[6:7], v11, off offset:128
	v_pk_mul_f32 v[16:17], v[0:1], v[8:9] op_sel_hi:[1,0]
	s_nop 0
	v_pk_fma_f32 v[18:19], v[2:3], v[8:9], v[16:17] op_sel:[0,1,0]
	v_pk_fma_f32 v[8:9], v[2:3], v[8:9], v[16:17] op_sel:[0,1,0] neg_lo:[0,0,1] neg_hi:[0,0,1]
	s_nop 0
	v_mov_b32_e32 v19, v9
	v_pk_add_f32 v[8:9], v[104:105], v[18:19]
	v_cvt_pk_bf16_f32 v10, v9, v9
	global_store_short_d16_hi v[6:7], v10, off offset:256
	v_cvt_pk_bf16_f32 v11, v8, v8
	global_store_short_d16_hi v[6:7], v11, off offset:384
	v_pk_mul_f32 v[16:17], v[0:1], v[8:9] op_sel_hi:[1,0]
	s_nop 0
	v_pk_fma_f32 v[18:19], v[2:3], v[8:9], v[16:17] op_sel:[0,1,0]
	v_pk_fma_f32 v[8:9], v[2:3], v[8:9], v[16:17] op_sel:[0,1,0] neg_lo:[0,0,1] neg_hi:[0,0,1]
	s_nop 0
	v_mov_b32_e32 v19, v9
	v_pk_add_f32 v[8:9], v[106:107], v[18:19]
	v_cvt_pk_bf16_f32 v10, v9, v9
	global_store_short_d16_hi v[6:7], v10, off offset:512
	v_cvt_pk_bf16_f32 v11, v8, v8
	global_store_short_d16_hi v[6:7], v11, off offset:640
	v_pk_mul_f32 v[16:17], v[0:1], v[8:9] op_sel_hi:[1,0]
	s_nop 0
	v_pk_fma_f32 v[18:19], v[2:3], v[8:9], v[16:17] op_sel:[0,1,0]
	v_pk_fma_f32 v[8:9], v[2:3], v[8:9], v[16:17] op_sel:[0,1,0] neg_lo:[0,0,1] neg_hi:[0,0,1]
	s_nop 0
	v_mov_b32_e32 v19, v9
	v_pk_add_f32 v[8:9], v[108:109], v[18:19]
	v_cvt_pk_bf16_f32 v10, v9, v9
	global_store_short_d16_hi v[6:7], v10, off offset:768
	v_cvt_pk_bf16_f32 v11, v8, v8
	global_store_short_d16_hi v[6:7], v11, off offset:896
	v_pk_mul_f32 v[16:17], v[0:1], v[8:9] op_sel_hi:[1,0]
	s_nop 0
	v_pk_fma_f32 v[18:19], v[2:3], v[8:9], v[16:17] op_sel:[0,1,0]
	v_pk_fma_f32 v[8:9], v[2:3], v[8:9], v[16:17] op_sel:[0,1,0] neg_lo:[0,0,1] neg_hi:[0,0,1]
	s_nop 0
	v_mov_b32_e32 v19, v9
	v_pk_add_f32 v[8:9], v[110:111], v[18:19]
	v_cvt_pk_bf16_f32 v10, v9, v9
	global_store_short_d16_hi v[6:7], v10, off offset:1024
	v_cvt_pk_bf16_f32 v11, v8, v8
	global_store_short_d16_hi v[6:7], v11, off offset:1152
	v_pk_mul_f32 v[16:17], v[0:1], v[8:9] op_sel_hi:[1,0]
	s_nop 0
	v_pk_fma_f32 v[18:19], v[2:3], v[8:9], v[16:17] op_sel:[0,1,0]
	v_pk_fma_f32 v[8:9], v[2:3], v[8:9], v[16:17] op_sel:[0,1,0] neg_lo:[0,0,1] neg_hi:[0,0,1]
	s_nop 0
	v_mov_b32_e32 v19, v9
	v_pk_add_f32 v[8:9], v[112:113], v[18:19]
	v_cvt_pk_bf16_f32 v10, v9, v9
	global_store_short_d16_hi v[6:7], v10, off offset:1280
	v_cvt_pk_bf16_f32 v11, v8, v8
	global_store_short_d16_hi v[6:7], v11, off offset:1408
	v_pk_mul_f32 v[16:17], v[0:1], v[8:9] op_sel_hi:[1,0]
	s_nop 0
	v_pk_fma_f32 v[18:19], v[2:3], v[8:9], v[16:17] op_sel:[0,1,0]
	v_pk_fma_f32 v[8:9], v[2:3], v[8:9], v[16:17] op_sel:[0,1,0] neg_lo:[0,0,1] neg_hi:[0,0,1]
	s_nop 0
	v_mov_b32_e32 v19, v9
	v_pk_add_f32 v[8:9], v[114:115], v[18:19]
	v_lshl_add_u64 v[6:7], v[6:7], 0, s[84:85]
	s_waitcnt vmcnt(32)
	v_bfe_u32 v10, v9, 16, 1
	v_add3_u32 v10, v9, v10, s48
	global_store_short_d16_hi v[6:7], v10, off offset:-512
	v_bfe_u32 v11, v8, 16, 1
	v_add3_u32 v11, v8, v11, s48
	global_store_short_d16_hi v[6:7], v11, off offset:-384
	v_pk_mul_f32 v[16:17], v[0:1], v[8:9] op_sel_hi:[1,0]
	s_nop 0
	v_pk_fma_f32 v[18:19], v[2:3], v[8:9], v[16:17] op_sel:[0,1,0]
	v_pk_fma_f32 v[8:9], v[2:3], v[8:9], v[16:17] op_sel:[0,1,0] neg_lo:[0,0,1] neg_hi:[0,0,1]
	s_nop 0
	v_mov_b32_e32 v19, v9
	v_pk_add_f32 v[8:9], v[116:117], v[18:19]

.LBB0_1157:
	s_or_b64 exec, exec, s[8:9]
	v_lshl_add_u64 v[0:1], s[20:21], 0, v[0:1]
	s_mov_b32 s5, s39
	v_lshl_add_u64 v[0:1], v[0:1], 0, s[4:5]
	v_lshl_add_u64 v[0:1], v[12:13], 1, v[0:1]
	v_add_co_u32_e32 v0, vcc, s74, v0
	v_mov_b32_e32 v65, s86
	s_nop 0
	v_addc_co_u32_e32 v1, vcc, 0, v1, vcc
	global_load_ushort v0, v[0:1], off offset:1536
	s_waitcnt lgkmcnt(0)
	s_lshl_b64 s[6:7], s[38:39], 10
	s_add_i32 s33, s33, 1
	v_lshl_add_u64 v[82:83], v[82:83], 0, s[54:55]
	v_lshl_add_u64 v[84:85], v[84:85], 0, s[96:97]
	s_cmp_eq_u32 s33, 4
	s_waitcnt vmcnt(0)
	v_lshlrev_b32_e32 v86, 16, v0
	ds_read_b128 v[0:3], v65 offset:12288
	ds_read_b128 v[4:7], v65 offset:12304
	ds_read_b128 v[8:11], v65 offset:12320
	ds_read_b128 v[90:93], v65 offset:12336
	ds_read_b128 v[98:101], v65 offset:12544
	ds_read_b128 v[102:105], v65 offset:12800
	s_waitcnt lgkmcnt(0)
	v_pk_mul_f32 v[94:95], v[102:103], v[86:87] op_sel_hi:[1,0]
	s_nop 0
	v_pk_fma_f32 v[20:21], v[20:21], v[98:99], v[94:95]
	s_nop 0
	v_fma_f32 v89, v0, v20, 0
	v_fmac_f32_e32 v89, v1, v21
	v_pk_mul_f32 v[0:1], v[104:105], v[86:87] op_sel_hi:[1,0]
	s_nop 0
	v_pk_fma_f32 v[18:19], v[18:19], v[100:101], v[0:1]
	s_nop 0
	v_fmac_f32_e32 v89, v2, v18
	v_fmac_f32_e32 v89, v3, v19
	ds_read_b128 v[0:3], v65 offset:12560
	ds_read_b128 v[98:101], v65 offset:12816
	s_waitcnt lgkmcnt(0)
	v_pk_mul_f32 v[94:95], v[98:99], v[86:87] op_sel_hi:[1,0]
	s_nop 0
	v_pk_fma_f32 v[16:17], v[16:17], v[0:1], v[94:95]
	v_pk_mul_f32 v[0:1], v[100:101], v[86:87] op_sel_hi:[1,0]
	v_fmac_f32_e32 v89, v4, v16
	v_fmac_f32_e32 v89, v5, v17
	v_pk_fma_f32 v[14:15], v[14:15], v[2:3], v[0:1]
	s_nop 0
	v_fmac_f32_e32 v89, v6, v14
	v_fmac_f32_e32 v89, v7, v15
	ds_read_b128 v[0:3], v65 offset:12576
	ds_read_b128 v[4:7], v65 offset:12832
	s_waitcnt lgkmcnt(0)
	v_pk_mul_f32 v[4:5], v[4:5], v[86:87] op_sel_hi:[1,0]
	s_nop 0
	v_pk_fma_f32 v[34:35], v[34:35], v[0:1], v[4:5]
	v_pk_mul_f32 v[0:1], v[6:7], v[86:87] op_sel_hi:[1,0]
	v_fmac_f32_e32 v89, v8, v34
	v_pk_fma_f32 v[32:33], v[32:33], v[2:3], v[0:1]
	ds_read_b128 v[0:3], v65 offset:12592
	ds_read_b128 v[4:7], v65 offset:12848
	v_fmac_f32_e32 v89, v9, v35
	v_fmac_f32_e32 v89, v10, v32
	v_fmac_f32_e32 v89, v11, v33
	s_waitcnt lgkmcnt(0)
	v_pk_mul_f32 v[4:5], v[4:5], v[86:87] op_sel_hi:[1,0]
	s_nop 0
	v_pk_fma_f32 v[30:31], v[30:31], v[0:1], v[4:5]
	v_pk_mul_f32 v[0:1], v[6:7], v[86:87] op_sel_hi:[1,0]
	v_fmac_f32_e32 v89, v90, v30
	v_pk_fma_f32 v[28:29], v[28:29], v[2:3], v[0:1]
	ds_read_b128 v[0:3], v65 offset:12352
	ds_read_b128 v[4:7], v65 offset:12608
	ds_read_b128 v[8:11], v65 offset:12864
	v_fmac_f32_e32 v89, v91, v31
	v_fmac_f32_e32 v89, v92, v28
	v_fmac_f32_e32 v89, v93, v29
	s_waitcnt lgkmcnt(0)
	v_pk_mul_f32 v[8:9], v[8:9], v[86:87] op_sel_hi:[1,0]
	s_nop 0
	v_pk_fma_f32 v[78:79], v[78:79], v[4:5], v[8:9]
	s_nop 0
	v_fmac_f32_e32 v89, v0, v78
	v_fmac_f32_e32 v89, v1, v79
	v_pk_mul_f32 v[0:1], v[10:11], v[86:87] op_sel_hi:[1,0]
	s_nop 0
	v_pk_fma_f32 v[40:41], v[40:41], v[6:7], v[0:1]
	s_nop 0
	v_fmac_f32_e32 v89, v2, v40
	v_fmac_f32_e32 v89, v3, v41
	ds_read_b128 v[0:3], v65 offset:12368
	ds_read_b128 v[4:7], v65 offset:12624
	ds_read_b128 v[8:11], v65 offset:12880
	s_waitcnt lgkmcnt(0)
	v_pk_mul_f32 v[8:9], v[8:9], v[86:87] op_sel_hi:[1,0]
	s_nop 0
	v_pk_fma_f32 v[38:39], v[38:39], v[4:5], v[8:9]
	s_nop 0
	v_fmac_f32_e32 v89, v0, v38
	v_fmac_f32_e32 v89, v1, v39
	v_pk_mul_f32 v[0:1], v[10:11], v[86:87] op_sel_hi:[1,0]
	s_nop 0
	v_pk_fma_f32 v[36:37], v[36:37], v[6:7], v[0:1]
	s_nop 0
	v_fmac_f32_e32 v89, v2, v36
	v_fmac_f32_e32 v89, v3, v37
	ds_read_b128 v[0:3], v65 offset:12384
	ds_read_b128 v[4:7], v65 offset:12640
	ds_read_b128 v[8:11], v65 offset:12896
	s_waitcnt lgkmcnt(0)
	v_pk_mul_f32 v[8:9], v[8:9], v[86:87] op_sel_hi:[1,0]
	s_nop 0
	v_pk_fma_f32 v[22:23], v[22:23], v[4:5], v[8:9]
	s_nop 0
	v_fmac_f32_e32 v89, v0, v22
	v_fmac_f32_e32 v89, v1, v23
	v_pk_mul_f32 v[0:1], v[10:11], v[86:87] op_sel_hi:[1,0]
	s_nop 0
	v_pk_fma_f32 v[76:77], v[76:77], v[6:7], v[0:1]
	s_nop 0
	v_fmac_f32_e32 v89, v2, v76
	v_fmac_f32_e32 v89, v3, v77
	ds_read_b128 v[0:3], v65 offset:12400
	ds_read_b128 v[4:7], v65 offset:12656
	ds_read_b128 v[8:11], v65 offset:12912
	s_waitcnt lgkmcnt(0)
	v_pk_mul_f32 v[8:9], v[8:9], v[86:87] op_sel_hi:[1,0]
	s_nop 0
	v_pk_fma_f32 v[74:75], v[74:75], v[4:5], v[8:9]
	s_nop 0
	v_fmac_f32_e32 v89, v0, v74
	v_fmac_f32_e32 v89, v1, v75
	v_pk_mul_f32 v[0:1], v[10:11], v[86:87] op_sel_hi:[1,0]
	s_nop 0
	v_pk_fma_f32 v[72:73], v[72:73], v[6:7], v[0:1]
	s_nop 0
	v_fmac_f32_e32 v89, v2, v72
	v_fmac_f32_e32 v89, v3, v73
	ds_read_b128 v[0:3], v65 offset:12416
	ds_read_b128 v[4:7], v65 offset:12672
	ds_read_b128 v[8:11], v65 offset:12928
	s_waitcnt lgkmcnt(0)
	v_pk_mul_f32 v[8:9], v[8:9], v[86:87] op_sel_hi:[1,0]
	s_nop 0
	v_pk_fma_f32 v[24:25], v[24:25], v[4:5], v[8:9]
	s_nop 0
	v_fmac_f32_e32 v89, v0, v24
	v_fmac_f32_e32 v89, v1, v25
	v_pk_mul_f32 v[0:1], v[10:11], v[86:87] op_sel_hi:[1,0]
	s_nop 0
	v_pk_fma_f32 v[56:57], v[56:57], v[6:7], v[0:1]
	s_nop 0
	v_fmac_f32_e32 v89, v2, v56
	v_fmac_f32_e32 v89, v3, v57
	ds_read_b128 v[0:3], v65 offset:12432
	ds_read_b128 v[4:7], v65 offset:12688
	ds_read_b128 v[8:11], v65 offset:12944
	s_waitcnt lgkmcnt(0)
	v_pk_mul_f32 v[8:9], v[8:9], v[86:87] op_sel_hi:[1,0]
	s_nop 0
	v_pk_fma_f32 v[54:55], v[54:55], v[4:5], v[8:9]
	s_nop 0
	v_fmac_f32_e32 v89, v0, v54
	v_fmac_f32_e32 v89, v1, v55
	v_pk_mul_f32 v[0:1], v[10:11], v[86:87] op_sel_hi:[1,0]
	s_nop 0
	v_pk_fma_f32 v[52:53], v[52:53], v[6:7], v[0:1]
	s_nop 0
	v_fmac_f32_e32 v89, v2, v52
	v_fmac_f32_e32 v89, v3, v53
	ds_read_b128 v[0:3], v65 offset:12448
	ds_read_b128 v[4:7], v65 offset:12704
	ds_read_b128 v[8:11], v65 offset:12960
	s_waitcnt lgkmcnt(0)
	v_pk_mul_f32 v[8:9], v[8:9], v[86:87] op_sel_hi:[1,0]
	s_nop 0
	v_pk_fma_f32 v[26:27], v[26:27], v[4:5], v[8:9]
	s_nop 0
	v_fmac_f32_e32 v89, v0, v26
	v_fmac_f32_e32 v89, v1, v27
	v_pk_mul_f32 v[0:1], v[10:11], v[86:87] op_sel_hi:[1,0]
	s_nop 0
	v_pk_fma_f32 v[50:51], v[50:51], v[6:7], v[0:1]
	s_nop 0
	v_fmac_f32_e32 v89, v2, v50
	v_fmac_f32_e32 v89, v3, v51
	ds_read_b128 v[0:3], v65 offset:12464
	ds_read_b128 v[4:7], v65 offset:12720
	ds_read_b128 v[8:11], v65 offset:12976
	s_waitcnt lgkmcnt(0)
	v_pk_mul_f32 v[8:9], v[8:9], v[86:87] op_sel_hi:[1,0]
	s_nop 0
	v_pk_fma_f32 v[70:71], v[70:71], v[4:5], v[8:9]
	s_nop 0
	v_fmac_f32_e32 v89, v0, v70
	v_fmac_f32_e32 v89, v1, v71
	v_pk_mul_f32 v[0:1], v[10:11], v[86:87] op_sel_hi:[1,0]
	s_nop 0
	v_pk_fma_f32 v[68:69], v[68:69], v[6:7], v[0:1]
	s_nop 0
	v_fmac_f32_e32 v89, v2, v68
	v_fmac_f32_e32 v89, v3, v69
	ds_read_b128 v[0:3], v65 offset:12480
	ds_read_b128 v[4:7], v65 offset:12736
	ds_read_b128 v[8:11], v65 offset:12992
	s_waitcnt lgkmcnt(0)
	v_pk_mul_f32 v[8:9], v[8:9], v[86:87] op_sel_hi:[1,0]
	s_nop 0
	v_pk_fma_f32 v[48:49], v[48:49], v[4:5], v[8:9]
	s_nop 0
	v_fmac_f32_e32 v89, v0, v48
	v_fmac_f32_e32 v89, v1, v49
	v_pk_mul_f32 v[0:1], v[10:11], v[86:87] op_sel_hi:[1,0]
	s_nop 0
	v_pk_fma_f32 v[46:47], v[46:47], v[6:7], v[0:1]
	s_nop 0
	v_fmac_f32_e32 v89, v2, v46
	v_fmac_f32_e32 v89, v3, v47
	ds_read_b128 v[0:3], v65 offset:12496
	ds_read_b128 v[4:7], v65 offset:12752
	ds_read_b128 v[8:11], v65 offset:13008
	s_waitcnt lgkmcnt(0)
	v_pk_mul_f32 v[8:9], v[8:9], v[86:87] op_sel_hi:[1,0]
	s_nop 0
	v_pk_fma_f32 v[44:45], v[44:45], v[4:5], v[8:9]
	s_nop 0
	v_fmac_f32_e32 v89, v0, v44
	v_fmac_f32_e32 v89, v1, v45
	v_pk_mul_f32 v[0:1], v[10:11], v[86:87] op_sel_hi:[1,0]
	s_nop 0
	v_pk_fma_f32 v[42:43], v[42:43], v[6:7], v[0:1]
	s_nop 0
	v_fmac_f32_e32 v89, v2, v42
	v_fmac_f32_e32 v89, v3, v43
	ds_read_b128 v[0:3], v65 offset:12768
	ds_read_b128 v[4:7], v65 offset:13024
	ds_read_b128 v[8:11], v65 offset:12512
	s_waitcnt lgkmcnt(1)
	v_pk_mul_f32 v[4:5], v[4:5], v[86:87] op_sel_hi:[1,0]
	s_nop 0
	v_pk_fma_f32 v[60:61], v[60:61], v[0:1], v[4:5]
	s_waitcnt lgkmcnt(0)
	v_pk_mul_f32 v[0:1], v[8:9], v[60:61]
	s_nop 0
	v_add_f32_e32 v0, v89, v0
	v_add_f32_e32 v4, v0, v1
	v_pk_mul_f32 v[0:1], v[6:7], v[86:87] op_sel_hi:[1,0]
	s_nop 0
	v_pk_fma_f32 v[58:59], v[58:59], v[2:3], v[0:1]
	s_nop 0
	v_pk_mul_f32 v[0:1], v[10:11], v[58:59]
	s_nop 0
	v_add_f32_e32 v0, v4, v0
	v_add_f32_e32 v89, v0, v1
	ds_read_b128 v[0:3], v65 offset:12784
	ds_read_b128 v[4:7], v65 offset:13040
	ds_read_b128 v[8:11], v65 offset:12528
	s_waitcnt lgkmcnt(1)
	v_pk_mul_f32 v[4:5], v[4:5], v[86:87] op_sel_hi:[1,0]
	s_nop 0
	v_pk_fma_f32 v[66:67], v[66:67], v[0:1], v[4:5]
	s_waitcnt lgkmcnt(0)
	v_pk_mul_f32 v[0:1], v[8:9], v[66:67]
	s_nop 0
	v_add_f32_e32 v0, v89, v0
	v_add_f32_e32 v4, v0, v1
	v_pk_mul_f32 v[0:1], v[6:7], v[86:87] op_sel_hi:[1,0]
	s_nop 0
	v_pk_fma_f32 v[62:63], v[62:63], v[2:3], v[0:1]
	s_nop 0
	v_pk_mul_f32 v[0:1], v[10:11], v[62:63]
	s_nop 0
	v_add_f32_e32 v0, v4, v0
	v_add_f32_e32 v0, v0, v1
	v_cvt_pk_bf16_f32 v2, v0, v0
	v_lshl_add_u64 v[0:1], v[80:81], 0, s[6:7]
	global_store_short_d16_hi v[0:1], v2, off
	s_cbranch_scc1 .LBB0_1161

.LBB0_1165:
	s_or_b64 exec, exec, s[64:65]
	v_mad_u64_u32 v[0:1], s[64:65], s62, v232, v[142:143]
	global_load_ushort v0, v[0:1], off
	s_waitcnt lgkmcnt(0)
	v_mov_b32_e32 v151, s86
	s_mov_b32 s63, s39
	s_lshl_b64 s[62:63], s[62:63], 10
	s_add_i32 s28, s28, 1
	s_addk_i32 s58, 0x200
	s_cmp_eq_u32 s28, 4
	s_waitcnt vmcnt(0)
	v_lshlrev_b32_e32 v96, 16, v0
	ds_read_b128 v[0:3], v151 offset:12288
	ds_read_b128 v[4:7], v151 offset:12304
	ds_read_b128 v[154:157], v151 offset:12320
	ds_read_b128 v[158:161], v151 offset:12336
	ds_read_b128 v[162:165], v151 offset:12800
	ds_read_b128 v[166:169], v151 offset:13312
	s_waitcnt lgkmcnt(0)
	v_pk_mul_f32 v[152:153], v[166:167], v[96:97] op_sel_hi:[1,0]
	s_nop 0
	v_pk_fma_f32 v[16:17], v[16:17], v[162:163], v[152:153]
	s_nop 0
	v_fma_f32 v152, v0, v16, 0
	v_fmac_f32_e32 v152, v1, v17
	v_pk_mul_f32 v[0:1], v[168:169], v[96:97] op_sel_hi:[1,0]
	s_nop 0
	v_pk_fma_f32 v[14:15], v[14:15], v[164:165], v[0:1]
	s_nop 0
	v_fmac_f32_e32 v152, v2, v14
	v_fmac_f32_e32 v152, v3, v15
	ds_read_b128 v[0:3], v151 offset:12816
	ds_read_b128 v[162:165], v151 offset:13328
	s_waitcnt lgkmcnt(0)
	v_pk_mul_f32 v[162:163], v[162:163], v[96:97] op_sel_hi:[1,0]
	s_nop 0
	v_pk_fma_f32 v[12:13], v[12:13], v[0:1], v[162:163]
	v_pk_mul_f32 v[0:1], v[164:165], v[96:97] op_sel_hi:[1,0]
	v_fmac_f32_e32 v152, v4, v12
	v_fmac_f32_e32 v152, v5, v13
	v_pk_fma_f32 v[10:11], v[10:11], v[2:3], v[0:1]
	s_nop 0
	v_fmac_f32_e32 v152, v6, v10
	v_fmac_f32_e32 v152, v7, v11
	ds_read_b128 v[0:3], v151 offset:12832
	ds_read_b128 v[4:7], v151 offset:13344
	s_waitcnt lgkmcnt(0)
	v_pk_mul_f32 v[4:5], v[4:5], v[96:97] op_sel_hi:[1,0]
	s_nop 0
	v_pk_fma_f32 v[42:43], v[42:43], v[0:1], v[4:5]
	v_pk_mul_f32 v[0:1], v[6:7], v[96:97] op_sel_hi:[1,0]
	v_fmac_f32_e32 v152, v154, v42
	v_pk_fma_f32 v[40:41], v[40:41], v[2:3], v[0:1]
	ds_read_b128 v[0:3], v151 offset:12848
	ds_read_b128 v[4:7], v151 offset:13360
	v_fmac_f32_e32 v152, v155, v43
	v_fmac_f32_e32 v152, v156, v40
	v_fmac_f32_e32 v152, v157, v41
	s_waitcnt lgkmcnt(0)
	v_pk_mul_f32 v[4:5], v[4:5], v[96:97] op_sel_hi:[1,0]
	s_nop 0
	v_pk_fma_f32 v[38:39], v[38:39], v[0:1], v[4:5]
	v_pk_mul_f32 v[0:1], v[6:7], v[96:97] op_sel_hi:[1,0]
	v_fmac_f32_e32 v152, v158, v38
	v_pk_fma_f32 v[36:37], v[36:37], v[2:3], v[0:1]
	ds_read_b128 v[0:3], v151 offset:12352
	ds_read_b128 v[4:7], v151 offset:12864
	ds_read_b128 v[154:157], v151 offset:13376
	v_fmac_f32_e32 v152, v159, v39
	v_fmac_f32_e32 v152, v160, v36
	v_fmac_f32_e32 v152, v161, v37
	s_waitcnt lgkmcnt(0)
	v_pk_mul_f32 v[154:155], v[154:155], v[96:97] op_sel_hi:[1,0]
	s_nop 0
	v_pk_fma_f32 v[140:141], v[140:141], v[4:5], v[154:155]
	s_nop 0
	v_fmac_f32_e32 v152, v0, v140
	v_fmac_f32_e32 v152, v1, v141
	v_pk_mul_f32 v[0:1], v[156:157], v[96:97] op_sel_hi:[1,0]
	s_nop 0
	v_pk_fma_f32 v[138:139], v[138:139], v[6:7], v[0:1]
	s_nop 0
	v_fmac_f32_e32 v152, v2, v138
	v_fmac_f32_e32 v152, v3, v139
	ds_read_b128 v[0:3], v151 offset:12368
	ds_read_b128 v[4:7], v151 offset:12880
	ds_read_b128 v[154:157], v151 offset:13392
	s_waitcnt lgkmcnt(0)
	v_pk_mul_f32 v[154:155], v[154:155], v[96:97] op_sel_hi:[1,0]
	s_nop 0
	v_pk_fma_f32 v[136:137], v[136:137], v[4:5], v[154:155]
	s_nop 0
	v_fmac_f32_e32 v152, v0, v136
	v_fmac_f32_e32 v152, v1, v137
	v_pk_mul_f32 v[0:1], v[156:157], v[96:97] op_sel_hi:[1,0]
	s_nop 0
	v_pk_fma_f32 v[34:35], v[34:35], v[6:7], v[0:1]
	s_nop 0
	v_fmac_f32_e32 v152, v2, v34
	v_fmac_f32_e32 v152, v3, v35
	ds_read_b128 v[0:3], v151 offset:12384
	ds_read_b128 v[4:7], v151 offset:12896
	ds_read_b128 v[154:157], v151 offset:13408
	s_waitcnt lgkmcnt(0)
	v_pk_mul_f32 v[154:155], v[154:155], v[96:97] op_sel_hi:[1,0]
	s_nop 0
	v_pk_fma_f32 v[18:19], v[18:19], v[4:5], v[154:155]
	s_nop 0
	v_fmac_f32_e32 v152, v0, v18
	v_fmac_f32_e32 v152, v1, v19
	v_pk_mul_f32 v[0:1], v[156:157], v[96:97] op_sel_hi:[1,0]
	s_nop 0
	v_pk_fma_f32 v[58:59], v[58:59], v[6:7], v[0:1]
	s_nop 0
	v_fmac_f32_e32 v152, v2, v58
	v_fmac_f32_e32 v152, v3, v59
	ds_read_b128 v[0:3], v151 offset:12400
	ds_read_b128 v[4:7], v151 offset:12912
	ds_read_b128 v[154:157], v151 offset:13424
	s_waitcnt lgkmcnt(0)
	v_pk_mul_f32 v[154:155], v[154:155], v[96:97] op_sel_hi:[1,0]
	s_nop 0
	v_pk_fma_f32 v[56:57], v[56:57], v[4:5], v[154:155]
	s_nop 0
	v_fmac_f32_e32 v152, v0, v56
	v_fmac_f32_e32 v152, v1, v57
	v_pk_mul_f32 v[0:1], v[156:157], v[96:97] op_sel_hi:[1,0]
	s_nop 0
	v_pk_fma_f32 v[54:55], v[54:55], v[6:7], v[0:1]
	s_nop 0
	v_fmac_f32_e32 v152, v2, v54
	v_fmac_f32_e32 v152, v3, v55
	ds_read_b128 v[0:3], v151 offset:12416
	ds_read_b128 v[4:7], v151 offset:12928
	ds_read_b128 v[154:157], v151 offset:13440
	s_waitcnt lgkmcnt(0)
	v_pk_mul_f32 v[154:155], v[154:155], v[96:97] op_sel_hi:[1,0]
	s_nop 0
	v_pk_fma_f32 v[24:25], v[24:25], v[4:5], v[154:155]
	s_nop 0
	v_fmac_f32_e32 v152, v0, v24
	v_fmac_f32_e32 v152, v1, v25
	v_pk_mul_f32 v[0:1], v[156:157], v[96:97] op_sel_hi:[1,0]
	s_nop 0
	v_pk_fma_f32 v[22:23], v[22:23], v[6:7], v[0:1]
	s_nop 0
	v_fmac_f32_e32 v152, v2, v22
	v_fmac_f32_e32 v152, v3, v23
	ds_read_b128 v[0:3], v151 offset:12432
	ds_read_b128 v[4:7], v151 offset:12944
	ds_read_b128 v[154:157], v151 offset:13456
	s_waitcnt lgkmcnt(0)
	v_pk_mul_f32 v[154:155], v[154:155], v[96:97] op_sel_hi:[1,0]
	s_nop 0
	v_pk_fma_f32 v[20:21], v[20:21], v[4:5], v[154:155]
	s_nop 0
	v_fmac_f32_e32 v152, v0, v20
	v_fmac_f32_e32 v152, v1, v21
	v_pk_mul_f32 v[0:1], v[156:157], v[96:97] op_sel_hi:[1,0]
	s_nop 0
	v_pk_fma_f32 v[52:53], v[52:53], v[6:7], v[0:1]
	s_nop 0
	v_fmac_f32_e32 v152, v2, v52
	v_fmac_f32_e32 v152, v3, v53
	ds_read_b128 v[0:3], v151 offset:12448
	ds_read_b128 v[4:7], v151 offset:12960
	ds_read_b128 v[154:157], v151 offset:13472
	s_waitcnt lgkmcnt(0)
	v_pk_mul_f32 v[154:155], v[154:155], v[96:97] op_sel_hi:[1,0]
	s_nop 0
	v_pk_fma_f32 v[28:29], v[28:29], v[4:5], v[154:155]
	s_nop 0
	v_fmac_f32_e32 v152, v0, v28
	v_fmac_f32_e32 v152, v1, v29
	v_pk_mul_f32 v[0:1], v[156:157], v[96:97] op_sel_hi:[1,0]
	s_nop 0
	v_pk_fma_f32 v[26:27], v[26:27], v[6:7], v[0:1]
	s_nop 0
	v_fmac_f32_e32 v152, v2, v26
	v_fmac_f32_e32 v152, v3, v27
	ds_read_b128 v[0:3], v151 offset:12464
	ds_read_b128 v[4:7], v151 offset:12976
	ds_read_b128 v[154:157], v151 offset:13488
	s_waitcnt lgkmcnt(0)
	v_pk_mul_f32 v[154:155], v[154:155], v[96:97] op_sel_hi:[1,0]
	s_nop 0
	v_pk_fma_f32 v[72:73], v[72:73], v[4:5], v[154:155]
	s_nop 0
	v_fmac_f32_e32 v152, v0, v72
	v_fmac_f32_e32 v152, v1, v73
	v_pk_mul_f32 v[0:1], v[156:157], v[96:97] op_sel_hi:[1,0]
	s_nop 0
	v_pk_fma_f32 v[70:71], v[70:71], v[6:7], v[0:1]
	s_nop 0
	v_fmac_f32_e32 v152, v2, v70
	v_fmac_f32_e32 v152, v3, v71
	ds_read_b128 v[0:3], v151 offset:12480
	ds_read_b128 v[4:7], v151 offset:12992
	ds_read_b128 v[154:157], v151 offset:13504
	s_waitcnt lgkmcnt(0)
	v_pk_mul_f32 v[154:155], v[154:155], v[96:97] op_sel_hi:[1,0]
	s_nop 0
	v_pk_fma_f32 v[32:33], v[32:33], v[4:5], v[154:155]
	s_nop 0
	v_fmac_f32_e32 v152, v0, v32
	v_fmac_f32_e32 v152, v1, v33
	v_pk_mul_f32 v[0:1], v[156:157], v[96:97] op_sel_hi:[1,0]
	s_nop 0
	v_pk_fma_f32 v[30:31], v[30:31], v[6:7], v[0:1]
	s_nop 0
	v_fmac_f32_e32 v152, v2, v30
	v_fmac_f32_e32 v152, v3, v31
	ds_read_b128 v[0:3], v151 offset:12496
	ds_read_b128 v[4:7], v151 offset:13008
	ds_read_b128 v[154:157], v151 offset:13520
	s_waitcnt lgkmcnt(0)
	v_pk_mul_f32 v[154:155], v[154:155], v[96:97] op_sel_hi:[1,0]
	s_nop 0
	v_pk_fma_f32 v[80:81], v[80:81], v[4:5], v[154:155]
	s_nop 0
	v_fmac_f32_e32 v152, v0, v80
	v_fmac_f32_e32 v152, v1, v81
	v_pk_mul_f32 v[0:1], v[156:157], v[96:97] op_sel_hi:[1,0]
	s_nop 0
	v_pk_fma_f32 v[78:79], v[78:79], v[6:7], v[0:1]
	s_nop 0
	v_fmac_f32_e32 v152, v2, v78
	v_fmac_f32_e32 v152, v3, v79
	ds_read_b128 v[0:3], v151 offset:12512
	ds_read_b128 v[4:7], v151 offset:13024
	ds_read_b128 v[154:157], v151 offset:13536
	s_waitcnt lgkmcnt(0)
	v_pk_mul_f32 v[154:155], v[154:155], v[96:97] op_sel_hi:[1,0]
	s_nop 0
	v_pk_fma_f32 v[46:47], v[46:47], v[4:5], v[154:155]
	s_nop 0
	v_fmac_f32_e32 v152, v0, v46
	v_fmac_f32_e32 v152, v1, v47
	v_pk_mul_f32 v[0:1], v[156:157], v[96:97] op_sel_hi:[1,0]
	s_nop 0
	v_pk_fma_f32 v[44:45], v[44:45], v[6:7], v[0:1]
	s_nop 0
	v_fmac_f32_e32 v152, v2, v44
	v_fmac_f32_e32 v152, v3, v45
	ds_read_b128 v[0:3], v151 offset:12528
	ds_read_b128 v[4:7], v151 offset:13040
	ds_read_b128 v[154:157], v151 offset:13552
	s_waitcnt lgkmcnt(0)
	v_pk_mul_f32 v[154:155], v[154:155], v[96:97] op_sel_hi:[1,0]
	s_nop 0
	v_pk_fma_f32 v[88:89], v[88:89], v[4:5], v[154:155]
	s_nop 0
	v_fmac_f32_e32 v152, v0, v88
	v_fmac_f32_e32 v152, v1, v89
	v_pk_mul_f32 v[0:1], v[156:157], v[96:97] op_sel_hi:[1,0]
	s_nop 0
	v_pk_fma_f32 v[86:87], v[86:87], v[6:7], v[0:1]
	s_nop 0
	v_fmac_f32_e32 v152, v2, v86
	v_fmac_f32_e32 v152, v3, v87
	ds_read_b128 v[0:3], v151 offset:12544
	ds_read_b128 v[4:7], v151 offset:13056
	ds_read_b128 v[154:157], v151 offset:13568
	s_waitcnt lgkmcnt(0)
	v_pk_mul_f32 v[154:155], v[154:155], v[96:97] op_sel_hi:[1,0]
	s_nop 0
	v_pk_fma_f32 v[50:51], v[50:51], v[4:5], v[154:155]
	s_nop 0
	v_fmac_f32_e32 v152, v0, v50
	v_fmac_f32_e32 v152, v1, v51
	v_pk_mul_f32 v[0:1], v[156:157], v[96:97] op_sel_hi:[1,0]
	s_nop 0
	v_pk_fma_f32 v[48:49], v[48:49], v[6:7], v[0:1]
	s_nop 0
	v_fmac_f32_e32 v152, v2, v48
	v_fmac_f32_e32 v152, v3, v49
	ds_read_b128 v[0:3], v151 offset:12560
	ds_read_b128 v[4:7], v151 offset:13072
	ds_read_b128 v[154:157], v151 offset:13584
	s_waitcnt lgkmcnt(0)
	v_pk_mul_f32 v[154:155], v[154:155], v[96:97] op_sel_hi:[1,0]
	s_nop 0
	v_pk_fma_f32 v[92:93], v[92:93], v[4:5], v[154:155]
	s_nop 0
	v_fmac_f32_e32 v152, v0, v92
	v_fmac_f32_e32 v152, v1, v93
	v_pk_mul_f32 v[0:1], v[156:157], v[96:97] op_sel_hi:[1,0]
	s_nop 0
	v_pk_fma_f32 v[90:91], v[90:91], v[6:7], v[0:1]
	s_nop 0
	v_fmac_f32_e32 v152, v2, v90
	v_fmac_f32_e32 v152, v3, v91
	ds_read_b128 v[0:3], v151 offset:12576
	ds_read_b128 v[4:7], v151 offset:13088
	ds_read_b128 v[154:157], v151 offset:13600
	s_waitcnt lgkmcnt(0)
	v_pk_mul_f32 v[154:155], v[154:155], v[96:97] op_sel_hi:[1,0]
	s_nop 0
	v_pk_fma_f32 v[66:67], v[66:67], v[4:5], v[154:155]
	s_nop 0
	v_fmac_f32_e32 v152, v0, v66
	v_fmac_f32_e32 v152, v1, v67
	v_pk_mul_f32 v[0:1], v[156:157], v[96:97] op_sel_hi:[1,0]
	s_nop 0
	v_pk_fma_f32 v[62:63], v[62:63], v[6:7], v[0:1]
	s_nop 0
	v_fmac_f32_e32 v152, v2, v62
	v_fmac_f32_e32 v152, v3, v63
	ds_read_b128 v[0:3], v151 offset:12592
	ds_read_b128 v[4:7], v151 offset:13104
	ds_read_b128 v[154:157], v151 offset:13616
	s_waitcnt lgkmcnt(0)
	v_pk_mul_f32 v[154:155], v[154:155], v[96:97] op_sel_hi:[1,0]
	s_nop 0
	v_pk_fma_f32 v[60:61], v[60:61], v[4:5], v[154:155]
	s_nop 0
	v_fmac_f32_e32 v152, v0, v60
	v_fmac_f32_e32 v152, v1, v61
	v_pk_mul_f32 v[0:1], v[156:157], v[96:97] op_sel_hi:[1,0]
	s_nop 0
	v_pk_fma_f32 v[120:121], v[120:121], v[6:7], v[0:1]
	s_nop 0
	v_fmac_f32_e32 v152, v2, v120
	v_fmac_f32_e32 v152, v3, v121
	ds_read_b128 v[0:3], v151 offset:12608
	ds_read_b128 v[4:7], v151 offset:13120
	ds_read_b128 v[154:157], v151 offset:13632
	s_waitcnt lgkmcnt(0)
	v_pk_mul_f32 v[154:155], v[154:155], v[96:97] op_sel_hi:[1,0]
	s_nop 0
	v_pk_fma_f32 v[68:69], v[68:69], v[4:5], v[154:155]
	s_nop 0
	v_fmac_f32_e32 v152, v0, v68
	v_fmac_f32_e32 v152, v1, v69
	v_pk_mul_f32 v[0:1], v[156:157], v[96:97] op_sel_hi:[1,0]
	s_nop 0
	v_pk_fma_f32 v[132:133], v[132:133], v[6:7], v[0:1]
	s_nop 0
	v_fmac_f32_e32 v152, v2, v132
	v_fmac_f32_e32 v152, v3, v133
	ds_read_b128 v[0:3], v151 offset:12624
	ds_read_b128 v[4:7], v151 offset:13136
	ds_read_b128 v[154:157], v151 offset:13648
	s_waitcnt lgkmcnt(0)
	v_pk_mul_f32 v[154:155], v[154:155], v[96:97] op_sel_hi:[1,0]
	s_nop 0
	v_pk_fma_f32 v[130:131], v[130:131], v[4:5], v[154:155]
	s_nop 0
	v_fmac_f32_e32 v152, v0, v130
	v_fmac_f32_e32 v152, v1, v131
	v_pk_mul_f32 v[0:1], v[156:157], v[96:97] op_sel_hi:[1,0]
	s_nop 0
	v_pk_fma_f32 v[128:129], v[128:129], v[6:7], v[0:1]
	s_nop 0
	v_fmac_f32_e32 v152, v2, v128
	v_fmac_f32_e32 v152, v3, v129
	ds_read_b128 v[0:3], v151 offset:12640
	ds_read_b128 v[4:7], v151 offset:13152
	ds_read_b128 v[154:157], v151 offset:13664
	s_waitcnt lgkmcnt(0)
	v_pk_mul_f32 v[154:155], v[154:155], v[96:97] op_sel_hi:[1,0]
	s_nop 0
	v_pk_fma_f32 v[82:83], v[82:83], v[4:5], v[154:155]
	s_nop 0
	v_fmac_f32_e32 v152, v0, v82
	v_fmac_f32_e32 v152, v1, v83
	v_pk_mul_f32 v[0:1], v[156:157], v[96:97] op_sel_hi:[1,0]
	s_nop 0
	v_pk_fma_f32 v[76:77], v[76:77], v[6:7], v[0:1]
	s_nop 0
	v_fmac_f32_e32 v152, v2, v76
	v_fmac_f32_e32 v152, v3, v77
	ds_read_b128 v[0:3], v151 offset:12656
	ds_read_b128 v[4:7], v151 offset:13168
	ds_read_b128 v[154:157], v151 offset:13680
	s_waitcnt lgkmcnt(0)
	v_pk_mul_f32 v[154:155], v[154:155], v[96:97] op_sel_hi:[1,0]
	s_nop 0
	v_pk_fma_f32 v[74:75], v[74:75], v[4:5], v[154:155]
	s_nop 0
	v_fmac_f32_e32 v152, v0, v74
	v_fmac_f32_e32 v152, v1, v75
	v_pk_mul_f32 v[0:1], v[156:157], v[96:97] op_sel_hi:[1,0]
	s_nop 0
	v_pk_fma_f32 v[134:135], v[134:135], v[6:7], v[0:1]
	s_nop 0
	v_fmac_f32_e32 v152, v2, v134
	v_fmac_f32_e32 v152, v3, v135
	ds_read_b128 v[0:3], v151 offset:12672
	ds_read_b128 v[4:7], v151 offset:13184
	ds_read_b128 v[154:157], v151 offset:13696
	s_waitcnt lgkmcnt(0)
	v_pk_mul_f32 v[154:155], v[154:155], v[96:97] op_sel_hi:[1,0]
	s_nop 0
	v_pk_fma_f32 v[84:85], v[84:85], v[4:5], v[154:155]
	s_nop 0
	v_fmac_f32_e32 v152, v0, v84
	v_fmac_f32_e32 v152, v1, v85
	v_pk_mul_f32 v[0:1], v[156:157], v[96:97] op_sel_hi:[1,0]
	s_nop 0
	v_pk_fma_f32 v[126:127], v[126:127], v[6:7], v[0:1]
	s_nop 0
	v_fmac_f32_e32 v152, v2, v126
	v_fmac_f32_e32 v152, v3, v127
	ds_read_b128 v[0:3], v151 offset:12688
	ds_read_b128 v[4:7], v151 offset:13200
	ds_read_b128 v[154:157], v151 offset:13712
	s_waitcnt lgkmcnt(0)
	v_pk_mul_f32 v[154:155], v[154:155], v[96:97] op_sel_hi:[1,0]
	s_nop 0
	v_pk_fma_f32 v[124:125], v[124:125], v[4:5], v[154:155]
	s_nop 0
	v_fmac_f32_e32 v152, v0, v124
	v_fmac_f32_e32 v152, v1, v125
	v_pk_mul_f32 v[0:1], v[156:157], v[96:97] op_sel_hi:[1,0]
	s_nop 0
	v_pk_fma_f32 v[122:123], v[122:123], v[6:7], v[0:1]
	s_nop 0
	v_fmac_f32_e32 v152, v2, v122
	v_fmac_f32_e32 v152, v3, v123
	ds_read_b128 v[0:3], v151 offset:12704
	ds_read_b128 v[4:7], v151 offset:13216
	ds_read_b128 v[154:157], v151 offset:13728
	s_waitcnt lgkmcnt(0)
	v_pk_mul_f32 v[154:155], v[154:155], v[96:97] op_sel_hi:[1,0]
	s_nop 0
	v_pk_fma_f32 v[94:95], v[94:95], v[4:5], v[154:155]
	s_nop 0
	v_fmac_f32_e32 v152, v0, v94
	v_fmac_f32_e32 v152, v1, v95
	v_pk_mul_f32 v[0:1], v[156:157], v[96:97] op_sel_hi:[1,0]
	s_nop 0
	v_pk_fma_f32 v[118:119], v[118:119], v[6:7], v[0:1]
	s_nop 0
	v_fmac_f32_e32 v152, v2, v118
	v_fmac_f32_e32 v152, v3, v119
	ds_read_b128 v[0:3], v151 offset:12720
	ds_read_b128 v[4:7], v151 offset:13232
	ds_read_b128 v[154:157], v151 offset:13744
	s_waitcnt lgkmcnt(0)
	v_pk_mul_f32 v[154:155], v[154:155], v[96:97] op_sel_hi:[1,0]
	s_nop 0
	v_pk_fma_f32 v[116:117], v[116:117], v[4:5], v[154:155]
	s_nop 0
	v_fmac_f32_e32 v152, v0, v116
	v_fmac_f32_e32 v152, v1, v117
	v_pk_mul_f32 v[0:1], v[156:157], v[96:97] op_sel_hi:[1,0]
	s_nop 0
	v_pk_fma_f32 v[114:115], v[114:115], v[6:7], v[0:1]
	s_nop 0
	v_fmac_f32_e32 v152, v2, v114
	v_fmac_f32_e32 v152, v3, v115
	ds_read_b128 v[0:3], v151 offset:12736
	ds_read_b128 v[4:7], v151 offset:13248
	ds_read_b128 v[154:157], v151 offset:13760
	s_waitcnt lgkmcnt(0)
	v_pk_mul_f32 v[154:155], v[154:155], v[96:97] op_sel_hi:[1,0]
	s_nop 0
	v_pk_fma_f32 v[112:113], v[112:113], v[4:5], v[154:155]
	s_nop 0
	v_fmac_f32_e32 v152, v0, v112
	v_fmac_f32_e32 v152, v1, v113
	v_pk_mul_f32 v[0:1], v[156:157], v[96:97] op_sel_hi:[1,0]
	s_nop 0
	v_pk_fma_f32 v[110:111], v[110:111], v[6:7], v[0:1]
	s_nop 0
	v_fmac_f32_e32 v152, v2, v110
	v_fmac_f32_e32 v152, v3, v111
	ds_read_b128 v[0:3], v151 offset:12752
	ds_read_b128 v[4:7], v151 offset:13264
	ds_read_b128 v[154:157], v151 offset:13776
	s_waitcnt lgkmcnt(0)
	v_pk_mul_f32 v[154:155], v[154:155], v[96:97] op_sel_hi:[1,0]
	s_nop 0
	v_pk_fma_f32 v[108:109], v[108:109], v[4:5], v[154:155]
	s_nop 0
	v_fmac_f32_e32 v152, v0, v108
	v_fmac_f32_e32 v152, v1, v109
	v_pk_mul_f32 v[0:1], v[156:157], v[96:97] op_sel_hi:[1,0]
	s_nop 0
	v_pk_fma_f32 v[106:107], v[106:107], v[6:7], v[0:1]
	s_nop 0
	v_fmac_f32_e32 v152, v2, v106
	v_fmac_f32_e32 v152, v3, v107
	ds_read_b128 v[0:3], v151 offset:13280
	ds_read_b128 v[4:7], v151 offset:13792
	ds_read_b128 v[154:157], v151 offset:12768
	s_waitcnt lgkmcnt(1)
	v_pk_mul_f32 v[4:5], v[4:5], v[96:97] op_sel_hi:[1,0]
	s_nop 0
	v_pk_fma_f32 v[104:105], v[104:105], v[0:1], v[4:5]
	s_waitcnt lgkmcnt(0)
	v_pk_mul_f32 v[0:1], v[154:155], v[104:105]
	s_nop 0
	v_add_f32_e32 v0, v152, v0
	v_add_f32_e32 v4, v0, v1
	v_pk_mul_f32 v[0:1], v[6:7], v[96:97] op_sel_hi:[1,0]
	s_nop 0
	v_pk_fma_f32 v[102:103], v[102:103], v[2:3], v[0:1]
	s_nop 0
	v_pk_mul_f32 v[0:1], v[156:157], v[102:103]
	s_nop 0
	v_add_f32_e32 v0, v4, v0
	v_add_f32_e32 v156, v0, v1
	ds_read_b128 v[0:3], v151 offset:13296
	ds_read_b128 v[4:7], v151 offset:13808
	ds_read_b128 v[152:155], v151 offset:12784
	s_waitcnt lgkmcnt(1)
	v_pk_mul_f32 v[4:5], v[4:5], v[96:97] op_sel_hi:[1,0]
	s_nop 0
	v_pk_fma_f32 v[100:101], v[100:101], v[0:1], v[4:5]
	s_waitcnt lgkmcnt(0)
	v_pk_mul_f32 v[0:1], v[152:153], v[100:101]
	s_nop 0
	v_add_f32_e32 v0, v156, v0
	v_add_f32_e32 v4, v0, v1
	v_pk_mul_f32 v[0:1], v[6:7], v[96:97] op_sel_hi:[1,0]
	s_nop 0
	v_pk_fma_f32 v[98:99], v[98:99], v[2:3], v[0:1]
	s_nop 0
	v_pk_mul_f32 v[0:1], v[154:155], v[98:99]
	s_nop 0
	v_add_f32_e32 v0, v4, v0
	v_add_f32_e32 v0, v0, v1
	v_cvt_pk_bf16_f32 v2, v0, v0
	v_lshl_add_u64 v[0:1], v[144:145], 0, s[62:63]
	global_store_short_d16_hi v[0:1], v2, off
	s_cbranch_scc1 .LBB0_1181

.LBB0_1193:
	s_ashr_i32 s3, s2, 31
	s_lshl_b64 s[4:5], s[2:3], 11
	v_lshl_add_u64 v[78:79], v[68:69], 0, s[4:5]
	v_add_co_u32_e32 v76, vcc, s91, v78
	global_load_dword v74, v[78:79], off
	s_nop 0
	v_addc_co_u32_e32 v77, vcc, 0, v79, vcc
	global_load_dword v82, v[76:77], off
	v_add_co_u32_e32 v76, vcc, s6, v78
	s_lshl_b64 s[4:5], s[2:3], 12
	s_nop 0
	v_addc_co_u32_e32 v77, vcc, 0, v79, vcc
	v_add_co_u32_e32 v80, vcc, s7, v78
	global_load_dword v76, v[76:77], off
	s_nop 0
	v_addc_co_u32_e32 v81, vcc, 0, v79, vcc
	global_load_dword v66, v[80:81], off
	v_add_co_u32_e32 v80, vcc, s33, v78
	s_add_i32 s9, s9, -1
	s_nop 0
	v_addc_co_u32_e32 v81, vcc, 0, v79, vcc
	global_load_dword v77, v[80:81], off
	v_add_co_u32_e32 v80, vcc, s49, v78
	s_add_i32 s2, s2, 1
	s_nop 0
	v_addc_co_u32_e32 v81, vcc, 0, v79, vcc
	global_load_dword v80, v[80:81], off
	v_add_co_u32_e32 v78, vcc, s28, v78
	s_cmp_lg_u32 s9, 0
	s_nop 0
	v_addc_co_u32_e32 v79, vcc, 0, v79, vcc
	global_load_dword v75, v[78:79], off
	v_cmp_lt_i32_e32 vcc, v246, v252
	s_waitcnt vmcnt(0)
	ds_write2st64_b32 v73, v74, v82 offset0:48 offset1:49
	ds_write2st64_b32 v73, v76, v77 offset0:50 offset1:51
	ds_write_b32 v73, v80 offset:13312
	s_waitcnt lgkmcnt(0)
	v_mov_b32_e32 v77, s86
	ds_read_b128 v[78:81], v77 offset:13056
	v_mul_f32_e32 v74, v74, v76
	v_mul_f32_e32 v76, v72, v74
	s_waitcnt lgkmcnt(0)
	v_fma_f32 v82, v60, v78, 0
	v_fmac_f32_e32 v82, v61, v79
	v_fmac_f32_e32 v82, v62, v80
	v_fmac_f32_e32 v82, v63, v81
	ds_read_b128 v[78:81], v77 offset:13072
	s_waitcnt lgkmcnt(0)
	v_fmac_f32_e32 v82, v56, v78
	v_fmac_f32_e32 v82, v57, v79
	v_fmac_f32_e32 v82, v58, v80
	v_fmac_f32_e32 v82, v59, v81
	ds_read_b128 v[78:81], v77 offset:13088
	s_waitcnt lgkmcnt(0)
	v_fmac_f32_e32 v82, v52, v78
	v_fmac_f32_e32 v82, v53, v79
	v_fmac_f32_e32 v82, v54, v80
	v_fmac_f32_e32 v82, v55, v81
	ds_read_b128 v[78:81], v77 offset:13104
	s_waitcnt lgkmcnt(0)
	v_fmac_f32_e32 v82, v44, v78
	v_fmac_f32_e32 v82, v45, v79
	v_fmac_f32_e32 v82, v46, v80
	v_fmac_f32_e32 v82, v47, v81
	ds_read_b128 v[78:81], v77 offset:13120
	s_waitcnt lgkmcnt(0)
	v_fmac_f32_e32 v82, v48, v78
	v_fmac_f32_e32 v82, v49, v79
	v_fmac_f32_e32 v82, v50, v80
	v_fmac_f32_e32 v82, v51, v81
	ds_read_b128 v[78:81], v77 offset:13136
	s_waitcnt lgkmcnt(0)
	v_fmac_f32_e32 v82, v40, v78
	v_fmac_f32_e32 v82, v41, v79
	v_fmac_f32_e32 v82, v42, v80
	v_fmac_f32_e32 v82, v43, v81
	ds_read_b128 v[78:81], v77 offset:13152
	s_waitcnt lgkmcnt(0)
	v_fmac_f32_e32 v82, v36, v78
	v_fmac_f32_e32 v82, v37, v79
	v_fmac_f32_e32 v82, v38, v80
	v_fmac_f32_e32 v82, v39, v81
	ds_read_b128 v[78:81], v77 offset:13168
	s_waitcnt lgkmcnt(0)
	v_fmac_f32_e32 v82, v28, v78
	v_fmac_f32_e32 v82, v29, v79
	v_fmac_f32_e32 v82, v30, v80
	v_fmac_f32_e32 v82, v31, v81
	ds_read_b128 v[78:81], v77 offset:13184
	s_waitcnt lgkmcnt(0)
	v_fmac_f32_e32 v82, v32, v78
	v_fmac_f32_e32 v82, v33, v79
	v_fmac_f32_e32 v82, v34, v80
	v_fmac_f32_e32 v82, v35, v81
	ds_read_b128 v[78:81], v77 offset:13200
	s_waitcnt lgkmcnt(0)
	v_fmac_f32_e32 v82, v24, v78
	v_fmac_f32_e32 v82, v25, v79
	v_fmac_f32_e32 v82, v26, v80
	v_fmac_f32_e32 v82, v27, v81
	ds_read_b128 v[78:81], v77 offset:13216
	s_waitcnt lgkmcnt(0)
	v_fmac_f32_e32 v82, v20, v78
	v_fmac_f32_e32 v82, v21, v79
	v_fmac_f32_e32 v82, v22, v80
	v_fmac_f32_e32 v82, v23, v81
	ds_read_b128 v[78:81], v77 offset:13232
	s_waitcnt lgkmcnt(0)
	v_fmac_f32_e32 v82, v12, v78
	v_fmac_f32_e32 v82, v13, v79
	v_fmac_f32_e32 v82, v14, v80
	v_fmac_f32_e32 v82, v15, v81
	ds_read_b128 v[78:81], v77 offset:13248
	s_waitcnt lgkmcnt(0)
	v_fmac_f32_e32 v82, v16, v78
	v_fmac_f32_e32 v82, v17, v79
	v_fmac_f32_e32 v82, v18, v80
	v_fmac_f32_e32 v82, v19, v81
	ds_read_b128 v[78:81], v77 offset:13264
	s_waitcnt lgkmcnt(0)
	v_pk_mul_f32 v[78:79], v[8:9], v[78:79]
	s_nop 0
	v_add_f32_e32 v78, v82, v78
	v_add_f32_e32 v82, v78, v79
	v_pk_mul_f32 v[78:79], v[10:11], v[80:81]
	s_nop 0
	v_add_f32_e32 v78, v82, v78
	v_add_f32_e32 v82, v78, v79
	ds_read_b128 v[78:81], v77 offset:13280
	s_waitcnt lgkmcnt(0)
	v_pk_mul_f32 v[78:79], v[4:5], v[78:79]
	s_nop 0
	v_add_f32_e32 v78, v82, v78
	v_add_f32_e32 v82, v78, v79
	v_pk_mul_f32 v[78:79], v[6:7], v[80:81]
	s_nop 0
	v_add_f32_e32 v78, v82, v78
	v_add_f32_e32 v82, v78, v79
	ds_read_b128 v[78:81], v77 offset:13296
	s_waitcnt lgkmcnt(0)
	v_pk_mul_f32 v[78:79], v[0:1], v[78:79]
	s_nop 0
	v_add_f32_e32 v78, v82, v78
	v_add_f32_e32 v82, v78, v79
	v_pk_mul_f32 v[78:79], v[2:3], v[80:81]
	s_nop 0
	v_add_f32_e32 v78, v82, v78
	v_add_f32_e32 v94, v78, v79
	ds_read_b128 v[78:81], v77 offset:12288
	ds_read_b128 v[82:85], v77 offset:12304
	ds_read_b128 v[86:89], v77 offset:12320
	ds_read_b128 v[90:93], v77 offset:12336
	ds_read_b128 v[98:101], v77 offset:12544
	ds_read_b128 v[102:105], v77 offset:13312
	ds_read_b128 v[106:109], v77 offset:12800
	s_waitcnt lgkmcnt(1)
	v_pk_mul_f32 v[102:103], v[94:95], v[102:103] op_sel_hi:[0,1]
	v_pk_fma_f32 v[60:61], v[60:61], v[98:99], v[102:103] neg_lo:[0,0,1] neg_hi:[0,0,1]
	s_waitcnt lgkmcnt(0)
	v_pk_fma_f32 v[60:61], v[66:67], v[106:107], v[60:61] op_sel_hi:[0,1,1]
	v_fma_f32 v95, v78, v60, 0
	v_fmac_f32_e32 v95, v79, v61
	v_pk_mul_f32 v[78:79], v[94:95], v[104:105] op_sel_hi:[0,1]
	v_pk_fma_f32 v[62:63], v[62:63], v[100:101], v[78:79] neg_lo:[0,0,1] neg_hi:[0,0,1]
	s_nop 0
	v_pk_fma_f32 v[62:63], v[66:67], v[108:109], v[62:63] op_sel_hi:[0,1,1]
	v_fmac_f32_e32 v95, v80, v62
	v_fmac_f32_e32 v95, v81, v63
	ds_read_b128 v[78:81], v77 offset:12560
	ds_read_b128 v[98:101], v77 offset:13328
	ds_read_b128 v[102:105], v77 offset:12816
	s_waitcnt lgkmcnt(1)
	v_pk_mul_f32 v[98:99], v[94:95], v[98:99] op_sel_hi:[0,1]
	v_pk_fma_f32 v[56:57], v[56:57], v[78:79], v[98:99] neg_lo:[0,0,1] neg_hi:[0,0,1]
	s_waitcnt lgkmcnt(0)
	v_pk_fma_f32 v[56:57], v[66:67], v[102:103], v[56:57] op_sel_hi:[0,1,1]
	v_fmac_f32_e32 v95, v82, v56
	v_fmac_f32_e32 v95, v83, v57
	v_pk_mul_f32 v[78:79], v[94:95], v[100:101] op_sel_hi:[0,1]
	v_pk_fma_f32 v[58:59], v[58:59], v[80:81], v[78:79] neg_lo:[0,0,1] neg_hi:[0,0,1]
	s_nop 0
	v_pk_fma_f32 v[58:59], v[66:67], v[104:105], v[58:59] op_sel_hi:[0,1,1]
	v_fmac_f32_e32 v95, v84, v58
	v_fmac_f32_e32 v95, v85, v59
	ds_read_b128 v[78:81], v77 offset:12576
	ds_read_b128 v[82:85], v77 offset:13344
	ds_read_b128 v[98:101], v77 offset:12832
	s_waitcnt lgkmcnt(1)
	v_pk_mul_f32 v[82:83], v[94:95], v[82:83] op_sel_hi:[0,1]
	v_pk_fma_f32 v[52:53], v[52:53], v[78:79], v[82:83] neg_lo:[0,0,1] neg_hi:[0,0,1]
	s_waitcnt lgkmcnt(0)
	v_pk_fma_f32 v[52:53], v[66:67], v[98:99], v[52:53] op_sel_hi:[0,1,1]
	v_fmac_f32_e32 v95, v86, v52
	v_fmac_f32_e32 v95, v87, v53
	v_pk_mul_f32 v[78:79], v[94:95], v[84:85] op_sel_hi:[0,1]
	v_pk_fma_f32 v[54:55], v[54:55], v[80:81], v[78:79] neg_lo:[0,0,1] neg_hi:[0,0,1]
	ds_read_b128 v[78:81], v77 offset:12592
	ds_read_b128 v[82:85], v77 offset:13360
	v_pk_fma_f32 v[54:55], v[66:67], v[100:101], v[54:55] op_sel_hi:[0,1,1]
	v_fmac_f32_e32 v95, v88, v54
	v_fmac_f32_e32 v95, v89, v55
	ds_read_b128 v[86:89], v77 offset:12848
	s_waitcnt lgkmcnt(1)
	v_pk_mul_f32 v[82:83], v[94:95], v[82:83] op_sel_hi:[0,1]
	v_pk_fma_f32 v[44:45], v[44:45], v[78:79], v[82:83] neg_lo:[0,0,1] neg_hi:[0,0,1]
	s_waitcnt lgkmcnt(0)
	v_pk_fma_f32 v[44:45], v[66:67], v[86:87], v[44:45] op_sel_hi:[0,1,1]
	v_fmac_f32_e32 v95, v90, v44
	v_fmac_f32_e32 v95, v91, v45
	v_pk_mul_f32 v[78:79], v[94:95], v[84:85] op_sel_hi:[0,1]
	v_pk_fma_f32 v[46:47], v[46:47], v[80:81], v[78:79] neg_lo:[0,0,1] neg_hi:[0,0,1]
	s_nop 0
	v_pk_fma_f32 v[46:47], v[66:67], v[88:89], v[46:47] op_sel_hi:[0,1,1]
	ds_read_b128 v[78:81], v77 offset:12352
	ds_read_b128 v[82:85], v77 offset:12608
	ds_read_b128 v[86:89], v77 offset:13376
	v_fmac_f32_e32 v95, v92, v46
	v_fmac_f32_e32 v95, v93, v47
	ds_read_b128 v[90:93], v77 offset:12864
	s_waitcnt lgkmcnt(1)
	v_pk_mul_f32 v[86:87], v[94:95], v[86:87] op_sel_hi:[0,1]
	v_pk_fma_f32 v[48:49], v[48:49], v[82:83], v[86:87] neg_lo:[0,0,1] neg_hi:[0,0,1]
	s_waitcnt lgkmcnt(0)
	v_pk_fma_f32 v[48:49], v[66:67], v[90:91], v[48:49] op_sel_hi:[0,1,1]
	v_fmac_f32_e32 v95, v78, v48
	v_fmac_f32_e32 v95, v79, v49
	v_pk_mul_f32 v[78:79], v[94:95], v[88:89] op_sel_hi:[0,1]
	v_pk_fma_f32 v[50:51], v[50:51], v[84:85], v[78:79] neg_lo:[0,0,1] neg_hi:[0,0,1]
	s_nop 0
	v_pk_fma_f32 v[50:51], v[66:67], v[92:93], v[50:51] op_sel_hi:[0,1,1]
	v_fmac_f32_e32 v95, v80, v50
	v_fmac_f32_e32 v95, v81, v51
	ds_read_b128 v[78:81], v77 offset:12368
	ds_read_b128 v[82:85], v77 offset:12624
	ds_read_b128 v[86:89], v77 offset:13392
	ds_read_b128 v[90:93], v77 offset:12880
	s_waitcnt lgkmcnt(1)
	v_pk_mul_f32 v[86:87], v[94:95], v[86:87] op_sel_hi:[0,1]
	v_pk_fma_f32 v[40:41], v[40:41], v[82:83], v[86:87] neg_lo:[0,0,1] neg_hi:[0,0,1]
	s_waitcnt lgkmcnt(0)
	v_pk_fma_f32 v[40:41], v[66:67], v[90:91], v[40:41] op_sel_hi:[0,1,1]
	v_fmac_f32_e32 v95, v78, v40
	v_fmac_f32_e32 v95, v79, v41
	v_pk_mul_f32 v[78:79], v[94:95], v[88:89] op_sel_hi:[0,1]
	v_pk_fma_f32 v[42:43], v[42:43], v[84:85], v[78:79] neg_lo:[0,0,1] neg_hi:[0,0,1]
	s_nop 0
	v_pk_fma_f32 v[42:43], v[66:67], v[92:93], v[42:43] op_sel_hi:[0,1,1]
	v_fmac_f32_e32 v95, v80, v42
	v_fmac_f32_e32 v95, v81, v43
	ds_read_b128 v[78:81], v77 offset:12384
	ds_read_b128 v[82:85], v77 offset:12640
	ds_read_b128 v[86:89], v77 offset:13408
	ds_read_b128 v[90:93], v77 offset:12896
	s_waitcnt lgkmcnt(1)
	v_pk_mul_f32 v[86:87], v[94:95], v[86:87] op_sel_hi:[0,1]
	v_pk_fma_f32 v[36:37], v[36:37], v[82:83], v[86:87] neg_lo:[0,0,1] neg_hi:[0,0,1]
	s_waitcnt lgkmcnt(0)
	v_pk_fma_f32 v[36:37], v[66:67], v[90:91], v[36:37] op_sel_hi:[0,1,1]
	v_fmac_f32_e32 v95, v78, v36
	v_fmac_f32_e32 v95, v79, v37
	v_pk_mul_f32 v[78:79], v[94:95], v[88:89] op_sel_hi:[0,1]
	v_pk_fma_f32 v[38:39], v[38:39], v[84:85], v[78:79] neg_lo:[0,0,1] neg_hi:[0,0,1]
	s_nop 0
	v_pk_fma_f32 v[38:39], v[66:67], v[92:93], v[38:39] op_sel_hi:[0,1,1]
	v_fmac_f32_e32 v95, v80, v38
	v_fmac_f32_e32 v95, v81, v39
	ds_read_b128 v[78:81], v77 offset:12400
	ds_read_b128 v[82:85], v77 offset:12656
	ds_read_b128 v[86:89], v77 offset:13424
	ds_read_b128 v[90:93], v77 offset:12912
	s_waitcnt lgkmcnt(1)
	v_pk_mul_f32 v[86:87], v[94:95], v[86:87] op_sel_hi:[0,1]
	v_pk_fma_f32 v[28:29], v[28:29], v[82:83], v[86:87] neg_lo:[0,0,1] neg_hi:[0,0,1]
	s_waitcnt lgkmcnt(0)
	v_pk_fma_f32 v[28:29], v[66:67], v[90:91], v[28:29] op_sel_hi:[0,1,1]
	v_fmac_f32_e32 v95, v78, v28
	v_fmac_f32_e32 v95, v79, v29
	v_pk_mul_f32 v[78:79], v[94:95], v[88:89] op_sel_hi:[0,1]
	v_pk_fma_f32 v[30:31], v[30:31], v[84:85], v[78:79] neg_lo:[0,0,1] neg_hi:[0,0,1]
	s_nop 0
	v_pk_fma_f32 v[30:31], v[66:67], v[92:93], v[30:31] op_sel_hi:[0,1,1]
	v_fmac_f32_e32 v95, v80, v30
	v_fmac_f32_e32 v95, v81, v31
	ds_read_b128 v[78:81], v77 offset:12416
	ds_read_b128 v[82:85], v77 offset:12672
	ds_read_b128 v[86:89], v77 offset:13440
	ds_read_b128 v[90:93], v77 offset:12928
	s_waitcnt lgkmcnt(1)
	v_pk_mul_f32 v[86:87], v[94:95], v[86:87] op_sel_hi:[0,1]
	v_pk_fma_f32 v[32:33], v[32:33], v[82:83], v[86:87] neg_lo:[0,0,1] neg_hi:[0,0,1]
	s_waitcnt lgkmcnt(0)
	v_pk_fma_f32 v[32:33], v[66:67], v[90:91], v[32:33] op_sel_hi:[0,1,1]
	v_fmac_f32_e32 v95, v78, v32
	v_fmac_f32_e32 v95, v79, v33
	v_pk_mul_f32 v[78:79], v[94:95], v[88:89] op_sel_hi:[0,1]
	v_pk_fma_f32 v[34:35], v[34:35], v[84:85], v[78:79] neg_lo:[0,0,1] neg_hi:[0,0,1]
	s_nop 0
	v_pk_fma_f32 v[34:35], v[66:67], v[92:93], v[34:35] op_sel_hi:[0,1,1]
	v_fmac_f32_e32 v95, v80, v34
	v_fmac_f32_e32 v95, v81, v35
	ds_read_b128 v[78:81], v77 offset:12432
	ds_read_b128 v[82:85], v77 offset:12688
	ds_read_b128 v[86:89], v77 offset:13456
	ds_read_b128 v[90:93], v77 offset:12944
	s_waitcnt lgkmcnt(1)
	v_pk_mul_f32 v[86:87], v[94:95], v[86:87] op_sel_hi:[0,1]
	v_pk_fma_f32 v[24:25], v[24:25], v[82:83], v[86:87] neg_lo:[0,0,1] neg_hi:[0,0,1]
	s_waitcnt lgkmcnt(0)
	v_pk_fma_f32 v[24:25], v[66:67], v[90:91], v[24:25] op_sel_hi:[0,1,1]
	v_fmac_f32_e32 v95, v78, v24
	v_fmac_f32_e32 v95, v79, v25
	v_pk_mul_f32 v[78:79], v[94:95], v[88:89] op_sel_hi:[0,1]
	v_pk_fma_f32 v[26:27], v[26:27], v[84:85], v[78:79] neg_lo:[0,0,1] neg_hi:[0,0,1]
	s_nop 0
	v_pk_fma_f32 v[26:27], v[66:67], v[92:93], v[26:27] op_sel_hi:[0,1,1]
	v_fmac_f32_e32 v95, v80, v26
	v_fmac_f32_e32 v95, v81, v27
	ds_read_b128 v[78:81], v77 offset:12448
	ds_read_b128 v[82:85], v77 offset:12704
	ds_read_b128 v[86:89], v77 offset:13472
	ds_read_b128 v[90:93], v77 offset:12960
	s_waitcnt lgkmcnt(1)
	v_pk_mul_f32 v[86:87], v[94:95], v[86:87] op_sel_hi:[0,1]
	v_pk_fma_f32 v[20:21], v[20:21], v[82:83], v[86:87] neg_lo:[0,0,1] neg_hi:[0,0,1]
	s_waitcnt lgkmcnt(0)
	v_pk_fma_f32 v[20:21], v[66:67], v[90:91], v[20:21] op_sel_hi:[0,1,1]
	v_fmac_f32_e32 v95, v78, v20
	v_fmac_f32_e32 v95, v79, v21
	v_pk_mul_f32 v[78:79], v[94:95], v[88:89] op_sel_hi:[0,1]
	v_pk_fma_f32 v[22:23], v[22:23], v[84:85], v[78:79] neg_lo:[0,0,1] neg_hi:[0,0,1]
	s_nop 0
	v_pk_fma_f32 v[22:23], v[66:67], v[92:93], v[22:23] op_sel_hi:[0,1,1]
	v_fmac_f32_e32 v95, v80, v22
	v_fmac_f32_e32 v95, v81, v23
	ds_read_b128 v[78:81], v77 offset:12464
	ds_read_b128 v[82:85], v77 offset:12720
	ds_read_b128 v[86:89], v77 offset:13488
	ds_read_b128 v[90:93], v77 offset:12976
	s_waitcnt lgkmcnt(1)
	v_pk_mul_f32 v[86:87], v[94:95], v[86:87] op_sel_hi:[0,1]
	v_pk_fma_f32 v[12:13], v[12:13], v[82:83], v[86:87] neg_lo:[0,0,1] neg_hi:[0,0,1]
	s_waitcnt lgkmcnt(0)
	v_pk_fma_f32 v[12:13], v[66:67], v[90:91], v[12:13] op_sel_hi:[0,1,1]
	v_fmac_f32_e32 v95, v78, v12
	v_fmac_f32_e32 v95, v79, v13
	v_pk_mul_f32 v[78:79], v[94:95], v[88:89] op_sel_hi:[0,1]
	v_pk_fma_f32 v[14:15], v[14:15], v[84:85], v[78:79] neg_lo:[0,0,1] neg_hi:[0,0,1]
	s_nop 0
	v_pk_fma_f32 v[14:15], v[66:67], v[92:93], v[14:15] op_sel_hi:[0,1,1]
	v_fmac_f32_e32 v95, v80, v14
	v_fmac_f32_e32 v95, v81, v15
	ds_read_b128 v[78:81], v77 offset:12480
	ds_read_b128 v[82:85], v77 offset:12736
	ds_read_b128 v[86:89], v77 offset:13504
	ds_read_b128 v[90:93], v77 offset:12992
	s_waitcnt lgkmcnt(1)
	v_pk_mul_f32 v[86:87], v[94:95], v[86:87] op_sel_hi:[0,1]
	v_pk_fma_f32 v[16:17], v[16:17], v[82:83], v[86:87] neg_lo:[0,0,1] neg_hi:[0,0,1]
	s_waitcnt lgkmcnt(0)
	v_pk_fma_f32 v[16:17], v[66:67], v[90:91], v[16:17] op_sel_hi:[0,1,1]
	v_fmac_f32_e32 v95, v78, v16
	v_fmac_f32_e32 v95, v79, v17
	v_pk_mul_f32 v[78:79], v[94:95], v[88:89] op_sel_hi:[0,1]
	v_pk_fma_f32 v[18:19], v[18:19], v[84:85], v[78:79] neg_lo:[0,0,1] neg_hi:[0,0,1]
	s_nop 0
	v_pk_fma_f32 v[18:19], v[66:67], v[92:93], v[18:19] op_sel_hi:[0,1,1]
	v_fmac_f32_e32 v95, v80, v18
	v_fmac_f32_e32 v95, v81, v19
	ds_read_b128 v[78:81], v77 offset:12496
	ds_read_b128 v[82:85], v77 offset:12752
	ds_read_b128 v[86:89], v77 offset:13520
	ds_read_b128 v[90:93], v77 offset:13008
	s_waitcnt lgkmcnt(1)
	v_pk_mul_f32 v[86:87], v[94:95], v[86:87] op_sel_hi:[0,1]
	v_pk_fma_f32 v[8:9], v[8:9], v[82:83], v[86:87] neg_lo:[0,0,1] neg_hi:[0,0,1]
	s_waitcnt lgkmcnt(0)
	v_pk_fma_f32 v[8:9], v[66:67], v[90:91], v[8:9] op_sel_hi:[0,1,1]
	v_fmac_f32_e32 v95, v78, v8
	v_fmac_f32_e32 v95, v79, v9
	v_pk_mul_f32 v[78:79], v[94:95], v[88:89] op_sel_hi:[0,1]
	v_pk_fma_f32 v[10:11], v[10:11], v[84:85], v[78:79] neg_lo:[0,0,1] neg_hi:[0,0,1]
	s_nop 0
	v_pk_fma_f32 v[10:11], v[66:67], v[92:93], v[10:11] op_sel_hi:[0,1,1]
	v_pk_mul_f32 v[78:79], v[80:81], v[10:11]
	s_nop 0
	v_add_f32_e32 v78, v95, v78
	v_add_f32_e32 v95, v78, v79
	ds_read_b128 v[78:81], v77 offset:12768
	ds_read_b128 v[82:85], v77 offset:13536
	ds_read_b128 v[86:89], v77 offset:13024
	ds_read_b128 v[90:93], v77 offset:12512
	s_waitcnt lgkmcnt(2)
	v_pk_mul_f32 v[82:83], v[94:95], v[82:83] op_sel_hi:[0,1]
	v_pk_fma_f32 v[4:5], v[4:5], v[78:79], v[82:83] neg_lo:[0,0,1] neg_hi:[0,0,1]
	s_waitcnt lgkmcnt(1)
	v_pk_fma_f32 v[4:5], v[66:67], v[86:87], v[4:5] op_sel_hi:[0,1,1]
	s_waitcnt lgkmcnt(0)
	v_pk_mul_f32 v[78:79], v[90:91], v[4:5]
	s_nop 0
	v_add_f32_e32 v78, v95, v78
	v_add_f32_e32 v82, v78, v79
	v_pk_mul_f32 v[78:79], v[94:95], v[84:85] op_sel_hi:[0,1]
	v_pk_fma_f32 v[6:7], v[6:7], v[80:81], v[78:79] neg_lo:[0,0,1] neg_hi:[0,0,1]
	s_nop 0
	v_pk_fma_f32 v[6:7], v[66:67], v[88:89], v[6:7] op_sel_hi:[0,1,1]
	v_pk_mul_f32 v[78:79], v[92:93], v[6:7]
	s_nop 0
	v_add_f32_e32 v78, v82, v78
	v_add_f32_e32 v95, v78, v79
	ds_read_b128 v[78:81], v77 offset:12784
	ds_read_b128 v[82:85], v77 offset:13552
	ds_read_b128 v[86:89], v77 offset:13040
	ds_read_b128 v[90:93], v77 offset:12528
	s_waitcnt lgkmcnt(2)
	v_pk_mul_f32 v[82:83], v[94:95], v[82:83] op_sel_hi:[0,1]
	v_pk_fma_f32 v[0:1], v[0:1], v[78:79], v[82:83] neg_lo:[0,0,1] neg_hi:[0,0,1]
	s_waitcnt lgkmcnt(1)
	v_pk_fma_f32 v[0:1], v[66:67], v[86:87], v[0:1] op_sel_hi:[0,1,1]
	s_waitcnt lgkmcnt(0)
	v_pk_mul_f32 v[78:79], v[90:91], v[0:1]
	s_nop 0
	v_add_f32_e32 v77, v95, v78
	v_add_f32_e32 v77, v77, v79
	v_pk_mul_f32 v[78:79], v[94:95], v[84:85] op_sel_hi:[0,1]
	v_pk_fma_f32 v[2:3], v[2:3], v[80:81], v[78:79] neg_lo:[0,0,1] neg_hi:[0,0,1]
	s_nop 0
	v_pk_fma_f32 v[2:3], v[66:67], v[88:89], v[2:3] op_sel_hi:[0,1,1]
	v_pk_mul_f32 v[78:79], v[92:93], v[2:3]
	s_nop 0
	v_add_f32_e32 v77, v77, v78
	v_cndmask_b32_e32 v78, v217, v246, vcc
	v_add_f32_e32 v77, v77, v79
	v_lshlrev_b32_e32 v78, 2, v78
	ds_bpermute_b32 v79, v78, v77
	v_cmp_lt_i32_e32 vcc, v247, v252
	ds_bpermute_b32 v76, v78, v76
	s_waitcnt lgkmcnt(1)
	v_add_f32_e32 v79, v77, v79
	v_cndmask_b32_e32 v80, v217, v247, vcc
	v_lshlrev_b32_e32 v80, 2, v80
	ds_bpermute_b32 v81, v80, v79
	v_cmp_lt_i32_e32 vcc, v248, v252
	s_waitcnt lgkmcnt(1)
	v_fmac_f32_e32 v76, v72, v74
	ds_bpermute_b32 v74, v80, v76
	s_waitcnt lgkmcnt(1)
	v_add_f32_e32 v79, v79, v81
	v_cndmask_b32_e32 v81, v217, v248, vcc
	v_lshlrev_b32_e32 v81, 2, v81
	ds_bpermute_b32 v82, v81, v79
	v_cmp_lt_i32_e32 vcc, v221, v252
	s_waitcnt lgkmcnt(1)
	v_add_f32_e32 v74, v76, v74
	ds_bpermute_b32 v76, v81, v74
	s_waitcnt lgkmcnt(1)
	v_add_f32_e32 v79, v79, v82
	v_cndmask_b32_e32 v82, v217, v221, vcc
	v_lshlrev_b32_e32 v82, 2, v82
	ds_bpermute_b32 v83, v82, v79
	v_cmp_lt_i32_e32 vcc, v216, v252
	s_waitcnt lgkmcnt(1)
	v_add_f32_e32 v74, v74, v76
	ds_bpermute_b32 v76, v82, v74
	s_waitcnt lgkmcnt(1)
	v_add_f32_e32 v79, v79, v83
	v_cndmask_b32_e32 v83, v217, v216, vcc
	v_lshlrev_b32_e32 v83, 2, v83
	ds_bpermute_b32 v84, v83, v79
	v_cmp_lt_i32_e32 vcc, v218, v252
	s_waitcnt lgkmcnt(1)
	v_add_f32_e32 v74, v74, v76
	ds_bpermute_b32 v76, v83, v74
	s_waitcnt lgkmcnt(1)
	v_add_f32_e32 v79, v79, v84
	v_cndmask_b32_e32 v84, v217, v218, vcc
	v_lshlrev_b32_e32 v84, 2, v84
	ds_bpermute_b32 v85, v84, v79
	s_waitcnt lgkmcnt(1)
	v_add_f32_e32 v74, v74, v76
	ds_bpermute_b32 v76, v84, v74
	s_waitcnt lgkmcnt(1)
	v_add_f32_e32 v79, v79, v85
	v_fmac_f32_e32 v77, 0xbc800000, v79
	v_mul_f32_e32 v79, v77, v77
	ds_bpermute_b32 v79, v78, v79
	s_waitcnt lgkmcnt(1)
	v_add_f32_e32 v76, v74, v76
	s_waitcnt lgkmcnt(0)
	v_fmac_f32_e32 v79, v77, v77
	ds_bpermute_b32 v85, v80, v79
	s_waitcnt lgkmcnt(0)
	v_add_f32_e32 v79, v79, v85
	ds_bpermute_b32 v85, v81, v79
	s_waitcnt lgkmcnt(0)
	v_add_f32_e32 v79, v79, v85
	ds_bpermute_b32 v85, v82, v79
	s_waitcnt lgkmcnt(0)
	v_add_f32_e32 v79, v79, v85
	ds_bpermute_b32 v85, v83, v79
	s_waitcnt lgkmcnt(0)
	v_add_f32_e32 v79, v79, v85
	ds_bpermute_b32 v85, v84, v79
	s_waitcnt lgkmcnt(0)
	v_add_f32_e32 v79, v79, v85
	v_fmamk_f32 v79, v79, 0x3c800000, v231
	v_cmp_gt_f32_e32 vcc, s45, v79
	v_mul_f32_e32 v85, 0x4b800000, v79
	s_nop 0
	v_cndmask_b32_e32 v79, v79, v85, vcc
	v_rsq_f32_e32 v79, v79
	s_nop 0
	v_mul_f32_e32 v85, 0x45800000, v79
	v_cndmask_b32_e32 v79, v79, v85, vcc
	v_mul_f32_e32 v77, v77, v79
	v_pk_mul_f32 v[76:77], v[66:67], v[76:77]
	s_nop 0
	v_add_f32_e32 v66, v76, v77
	v_mul_f32_e32 v66, v75, v66
	v_cvt_pk_bf16_f32 v66, v66, v66
	v_lshl_add_u64 v[74:75], v[70:71], 0, s[4:5]
	global_store_short_d16_hi v[74:75], v66, off
	s_cbranch_scc1 .LBB0_1193
	s_ashr_i32 s4, s8, 31
	s_and_b64 s[2:3], s[0:1], exec
	s_cselect_b32 s3, s4, 0
	s_mov_b32 s4, 0x4400000
	s_cselect_b32 s4, s4, 0x4600000
	s_cselect_b32 s2, s8, s38
	s_add_u32 s4, s10, s4
	s_addc_u32 s5, s11, 0
	s_and_b64 s[0:1], s[0:1], exec
	v_readlane_b32 s6, v255, 40
	s_cselect_b32 s0, 5, 10
	v_readlane_b32 s7, v255, 41
	s_lshl_b64 s[0:1], s[6:7], s0
	s_add_u32 s0, s0, s26
	s_addc_u32 s1, s1, 0
	s_lshl_b64 s[2:3], s[2:3], 17
	s_lshl_b64 s[0:1], s[0:1], 14
	s_add_u32 s2, s4, s2
	s_addc_u32 s3, s5, s3
	s_add_u32 s0, s2, s0
	s_addc_u32 s1, s3, s1
	v_lshlrev_b64 v[66:67], 8, v[64:65]
	v_lshl_add_u64 v[66:67], s[0:1], 0, v[66:67]
	s_movk_i32 s52, 0x4000
	s_movk_i32 s53, 0x6000
	global_store_dwordx4 v[66:67], v[60:63], off
	global_store_dwordx4 v[66:67], v[56:59], off offset:16
	global_store_dwordx4 v[66:67], v[52:55], off offset:32
	global_store_dwordx4 v[66:67], v[44:47], off offset:48
	global_store_dwordx4 v[66:67], v[48:51], off offset:64
	global_store_dwordx4 v[66:67], v[40:43], off offset:80
	global_store_dwordx4 v[66:67], v[36:39], off offset:96
	global_store_dwordx4 v[66:67], v[28:31], off offset:112
	global_store_dwordx4 v[66:67], v[32:35], off offset:128
	global_store_dwordx4 v[66:67], v[24:27], off offset:144
	global_store_dwordx4 v[66:67], v[20:23], off offset:160
	global_store_dwordx4 v[66:67], v[12:15], off offset:176
	global_store_dwordx4 v[66:67], v[16:19], off offset:192
	global_store_dwordx4 v[66:67], v[8:11], off offset:208
	global_store_dwordx4 v[66:67], v[4:7], off offset:224
	global_store_dwordx4 v[66:67], v[0:3], off offset:240
	s_branch .LBB0_1149

.LBB0_1200:
	v_cvt_pk_bf16_f32 v0, v4, v4
	v_lshrrev_b32_e32 v0, 16, v0
	v_cvt_pk_bf16_f32 v1, v5, v5
	v_and_or_b32 v0, v1, s36, v0
	v_cvt_pk_bf16_f32 v1, v6, v6
	v_lshrrev_b32_e32 v1, 16, v1
	v_cvt_pk_bf16_f32 v2, v7, v7
	v_and_or_b32 v1, v2, s36, v1
	ds_write_b64 v56, v[0:1] offset:7392
	s_waitcnt lgkmcnt(0)
	ds_read_u16 v0, v84 offset:132
	ds_read_u16 v1, v84
	ds_read_u16 v10, v84 offset:16
	v_lshl_add_u64 v[4:5], s[20:21], 1, v[74:75]
	s_waitcnt lgkmcnt(1)
	v_lshl_or_b32 v0, v0, 16, v1
	ds_read_u16 v1, v84 offset:264
	ds_read_u16 v2, v84 offset:396
	s_waitcnt lgkmcnt(0)
	v_lshl_or_b32 v1, v2, 16, v1
	ds_read_u16 v2, v84 offset:528
	ds_read_u16 v3, v84 offset:660
	s_waitcnt lgkmcnt(0)
	v_lshl_or_b32 v2, v3, 16, v2
	ds_read_u16 v3, v84 offset:792
	ds_read_u16 v6, v84 offset:924
	s_waitcnt lgkmcnt(0)
	v_lshl_or_b32 v3, v6, 16, v3
	v_add_u32_e32 v6, s28, v83
	v_ashrrev_i32_e32 v7, 31, v6
	v_lshlrev_b64 v[8:9], 12, v[6:7]
	v_lshl_add_u64 v[8:9], v[4:5], 0, v[8:9]
	global_store_dwordx4 v[8:9], v[0:3], off
	ds_read_u16 v0, v84 offset:148
	ds_read_u16 v1, v84 offset:280
	ds_read_u16 v2, v84 offset:412
	v_add_u32_e32 v8, 8, v6
	v_ashrrev_i32_e32 v9, 31, v8
	v_lshlrev_b64 v[8:9], 12, v[8:9]
	s_waitcnt lgkmcnt(2)
	v_lshl_or_b32 v0, v0, 16, v10
	s_waitcnt lgkmcnt(0)
	v_lshl_or_b32 v1, v2, 16, v1
	ds_read_u16 v2, v84 offset:544
	ds_read_u16 v3, v84 offset:676
	v_lshl_add_u64 v[8:9], v[4:5], 0, v[8:9]
	s_waitcnt lgkmcnt(0)
	v_lshl_or_b32 v2, v3, 16, v2
	ds_read_u16 v3, v84 offset:808
	ds_read_u16 v7, v84 offset:940
	s_waitcnt lgkmcnt(0)
	v_lshl_or_b32 v3, v7, 16, v3
	global_store_dwordx4 v[8:9], v[0:3], off
	ds_read_u16 v0, v84 offset:164
	ds_read_u16 v1, v84 offset:32
	ds_read_u16 v7, v84 offset:48
	s_waitcnt lgkmcnt(1)
	v_lshl_or_b32 v0, v0, 16, v1
	ds_read_u16 v1, v84 offset:296
	ds_read_u16 v2, v84 offset:428
	s_waitcnt lgkmcnt(0)
	v_lshl_or_b32 v1, v2, 16, v1
	ds_read_u16 v2, v84 offset:560
	ds_read_u16 v3, v84 offset:692
	s_waitcnt lgkmcnt(0)
	v_lshl_or_b32 v2, v3, 16, v2
	ds_read_u16 v3, v84 offset:824
	ds_read_u16 v8, v84 offset:956
	s_waitcnt lgkmcnt(0)
	v_lshl_or_b32 v3, v8, 16, v3
	v_add_u32_e32 v8, 16, v6
	v_ashrrev_i32_e32 v9, 31, v8
	v_lshlrev_b64 v[8:9], 12, v[8:9]
	v_lshl_add_u64 v[8:9], v[4:5], 0, v[8:9]
	global_store_dwordx4 v[8:9], v[0:3], off
	ds_read_u16 v0, v84 offset:180
	ds_read_u16 v1, v84 offset:312
	ds_read_u16 v2, v84 offset:444
	v_add_u32_e32 v8, 24, v6
	v_ashrrev_i32_e32 v9, 31, v8
	v_lshlrev_b64 v[8:9], 12, v[8:9]
	s_waitcnt lgkmcnt(2)
	v_lshl_or_b32 v0, v0, 16, v7
	s_waitcnt lgkmcnt(0)
	v_lshl_or_b32 v1, v2, 16, v1
	ds_read_u16 v2, v84 offset:576
	ds_read_u16 v3, v84 offset:708
	v_lshl_add_u64 v[8:9], v[4:5], 0, v[8:9]
	s_waitcnt lgkmcnt(0)
	v_lshl_or_b32 v2, v3, 16, v2
	ds_read_u16 v3, v84 offset:840
	ds_read_u16 v7, v84 offset:972
	s_waitcnt lgkmcnt(0)
	v_lshl_or_b32 v3, v7, 16, v3
	global_store_dwordx4 v[8:9], v[0:3], off
	ds_read_u16 v0, v84 offset:64
	ds_read_u16 v1, v84 offset:196
	v_add_u32_e32 v8, 32, v6
	v_ashrrev_i32_e32 v9, 31, v8
	v_lshlrev_b64 v[8:9], 12, v[8:9]
	v_lshl_add_u64 v[8:9], v[4:5], 0, v[8:9]
	s_waitcnt lgkmcnt(0)
	v_lshl_or_b32 v0, v1, 16, v0
	ds_read_u16 v1, v84 offset:328
	ds_read_u16 v2, v84 offset:460
	s_waitcnt lgkmcnt(0)
	v_lshl_or_b32 v1, v2, 16, v1
	ds_read_u16 v2, v84 offset:592
	ds_read_u16 v3, v84 offset:724
	s_waitcnt lgkmcnt(0)
	v_lshl_or_b32 v2, v3, 16, v2
	ds_read_u16 v3, v84 offset:856
	ds_read_u16 v7, v84 offset:988
	s_waitcnt lgkmcnt(0)
	v_lshl_or_b32 v3, v7, 16, v3
	global_store_dwordx4 v[8:9], v[0:3], off
	ds_read_u16 v0, v84 offset:80
	ds_read_u16 v1, v84 offset:212
	v_add_u32_e32 v8, 40, v6
	v_ashrrev_i32_e32 v9, 31, v8
	v_lshlrev_b64 v[8:9], 12, v[8:9]
	v_lshl_add_u64 v[8:9], v[4:5], 0, v[8:9]
	s_waitcnt lgkmcnt(0)
	v_lshl_or_b32 v0, v1, 16, v0
	ds_read_u16 v1, v84 offset:344
	ds_read_u16 v2, v84 offset:476
	s_waitcnt lgkmcnt(0)
	v_lshl_or_b32 v1, v2, 16, v1
	ds_read_u16 v2, v84 offset:608
	ds_read_u16 v3, v84 offset:740
	s_waitcnt lgkmcnt(0)
	v_lshl_or_b32 v2, v3, 16, v2
	ds_read_u16 v3, v84 offset:872
	ds_read_u16 v7, v84 offset:1004
	s_waitcnt lgkmcnt(0)
	v_lshl_or_b32 v3, v7, 16, v3
	global_store_dwordx4 v[8:9], v[0:3], off
	ds_read_u16 v0, v84 offset:96
	ds_read_u16 v1, v84 offset:228
	v_add_u32_e32 v8, 48, v6
	v_ashrrev_i32_e32 v9, 31, v8
	v_lshlrev_b64 v[8:9], 12, v[8:9]
	v_lshl_add_u64 v[8:9], v[4:5], 0, v[8:9]
	s_waitcnt lgkmcnt(0)
	v_lshl_or_b32 v0, v1, 16, v0
	ds_read_u16 v1, v84 offset:360
	ds_read_u16 v2, v84 offset:492
	v_add_u32_e32 v6, 56, v6
	s_waitcnt lgkmcnt(0)
	v_lshl_or_b32 v1, v2, 16, v1
	ds_read_u16 v2, v84 offset:624
	ds_read_u16 v3, v84 offset:756
	s_waitcnt lgkmcnt(0)
	v_lshl_or_b32 v2, v3, 16, v2
	ds_read_u16 v3, v84 offset:888
	ds_read_u16 v7, v84 offset:1020
	s_waitcnt lgkmcnt(0)
	v_lshl_or_b32 v3, v7, 16, v3
	global_store_dwordx4 v[8:9], v[0:3], off
	ds_read_u16 v0, v84 offset:112
	ds_read_u16 v1, v84 offset:244
	s_waitcnt lgkmcnt(0)
	v_lshl_or_b32 v0, v1, 16, v0
	ds_read_u16 v1, v84 offset:376
	ds_read_u16 v2, v84 offset:508
	s_waitcnt lgkmcnt(0)
	v_lshl_or_b32 v1, v2, 16, v1
	ds_read_u16 v2, v84 offset:640
	ds_read_u16 v3, v84 offset:772
	s_waitcnt lgkmcnt(0)
	v_lshl_or_b32 v2, v3, 16, v2
	ds_read_u16 v3, v84 offset:904
	ds_read_u16 v7, v84 offset:1036
	s_waitcnt lgkmcnt(0)
	v_lshl_or_b32 v3, v7, 16, v3
	v_ashrrev_i32_e32 v7, 31, v6
	v_lshlrev_b64 v[6:7], 12, v[6:7]
	v_lshl_add_u64 v[4:5], v[4:5], 0, v[6:7]
	global_store_dwordx4 v[4:5], v[0:3], off
	s_waitcnt lgkmcnt(0)

.LBB0_1202:
	s_cmpk_gt_i32 s95, 0xbff
	s_mov_b64 s[0:1], -1
	s_cbranch_scc0 .LBB0_1248
	s_cmpk_gt_u32 s95, 0xfff
	s_cbranch_scc0 .LBB0_1245
	s_cmpk_gt_u32 s95, 0x257f
	s_cbranch_scc0 .LBB0_1210
	s_cmpk_gt_u32 s95, 0x303f
	s_cbranch_scc0 .LBB0_1207
	s_and_b32 s0, s24, 0x7fffffc0
	s_add_i32 s38, s0, 0xfffe7e00
	s_and_b32 s0, s22, 0x1c0
	v_or_b32_e32 v1, s0, v80
	v_add_u32_e32 v0, s38, v66
	v_lshlrev_b32_e32 v96, 2, v1
	v_ashrrev_i32_e32 v1, 31, v0
	v_lshl_add_u64 v[2:3], s[2:3], 0, v[96:97]
	v_lshlrev_b64 v[0:1], 11, v[0:1]
	v_lshl_add_u64 v[56:57], v[2:3], 0, v[0:1]
	v_add_co_u32_e32 v4, vcc, 0x2000, v56
	s_mov_b32 s1, 0x12000
	s_nop 0
	v_addc_co_u32_e32 v5, vcc, 0, v57, vcc
	global_load_dwordx4 v[0:3], v[56:57], off
	s_nop 0
	global_load_dwordx4 v[4:7], v[4:5], off
	v_add_co_u32_e32 v8, vcc, 0x4000, v56
	s_waitcnt vmcnt(0)
	s_nop 0
	v_addc_co_u32_e32 v9, vcc, 0, v57, vcc
	v_add_co_u32_e32 v12, vcc, 0x6000, v56
	v_cvt_pk_bf16_f32 v0, v0, v0
	s_nop 0
	v_addc_co_u32_e32 v13, vcc, 0, v57, vcc
	global_load_dwordx4 v[8:11], v[8:9], off
	s_nop 0
	global_load_dwordx4 v[12:15], v[12:13], off
	v_add_co_u32_e32 v16, vcc, 0x8000, v56
	s_nop 0
	s_nop 0
	v_addc_co_u32_e32 v17, vcc, 0, v57, vcc
	v_add_co_u32_e32 v20, vcc, 0xa000, v56
	v_lshrrev_b32_e32 v0, 16, v0
	s_nop 0
	v_addc_co_u32_e32 v21, vcc, 0, v57, vcc
	global_load_dwordx4 v[16:19], v[16:17], off
	s_nop 0
	global_load_dwordx4 v[20:23], v[20:21], off
	v_add_co_u32_e32 v24, vcc, 0xc000, v56
	v_cvt_pk_bf16_f32 v1, v1, v1
	s_nop 0
	v_addc_co_u32_e32 v25, vcc, 0, v57, vcc
	v_add_co_u32_e32 v28, vcc, 0xe000, v56
	v_and_or_b32 v0, v1, s36, v0
	s_nop 0
	v_addc_co_u32_e32 v29, vcc, 0, v57, vcc
	global_load_dwordx4 v[24:27], v[24:25], off
	s_nop 0
	global_load_dwordx4 v[28:31], v[28:29], off
	v_add_co_u32_e32 v32, vcc, s75, v56
	v_bfe_u32 v1, v2, 16, 1
	s_nop 0
	v_addc_co_u32_e32 v33, vcc, 0, v57, vcc
	v_add_co_u32_e32 v36, vcc, s1, v56
	s_mov_b32 s1, 0x14000
	s_nop 0
	v_addc_co_u32_e32 v37, vcc, 0, v57, vcc
	global_load_dwordx4 v[32:35], v[32:33], off
	s_nop 0
	global_load_dwordx4 v[36:39], v[36:37], off
	v_add_co_u32_e32 v40, vcc, s1, v56
	s_mov_b32 s1, 0x16000
	s_nop 0
	v_addc_co_u32_e32 v41, vcc, 0, v57, vcc
	v_add_co_u32_e32 v44, vcc, s1, v56
	s_mov_b32 s1, 0x18000
	s_nop 0
	v_addc_co_u32_e32 v45, vcc, 0, v57, vcc
	global_load_dwordx4 v[40:43], v[40:41], off
	s_nop 0
	global_load_dwordx4 v[44:47], v[44:45], off
	v_add_co_u32_e32 v48, vcc, s1, v56
	s_mov_b32 s1, 0x1a000
	s_nop 0
	v_addc_co_u32_e32 v49, vcc, 0, v57, vcc
	v_add_co_u32_e32 v52, vcc, s1, v56
	v_add3_u32 v1, v2, v1, s48
	s_nop 0
	v_addc_co_u32_e32 v53, vcc, 0, v57, vcc
	global_load_dwordx4 v[48:51], v[48:49], off
	s_nop 0
	global_load_dwordx4 v[52:55], v[52:53], off
	v_lshrrev_b32_e32 v1, 16, v1
	v_cvt_pk_bf16_f32 v2, v3, v3
	v_and_or_b32 v1, v2, s36, v1
	s_mov_b32 s1, 0x1c000
	v_cvt_pk_bf16_f32 v2, v4, v4
	v_add_co_u32_e32 v58, vcc, s1, v56
	v_lshrrev_b32_e32 v2, 16, v2
	v_cvt_pk_bf16_f32 v3, v5, v5
	v_addc_co_u32_e32 v59, vcc, 0, v57, vcc
	s_mov_b32 s1, 0x1e000
	v_and_or_b32 v2, v3, s36, v2
	v_add_co_u32_e32 v60, vcc, s1, v56
	v_cvt_pk_bf16_f32 v3, v6, v6
	s_nop 0
	v_addc_co_u32_e32 v61, vcc, 0, v57, vcc
	v_lshrrev_b32_e32 v3, 16, v3
	v_cvt_pk_bf16_f32 v4, v7, v7
	global_load_dwordx4 v[56:59], v[58:59], off
	s_nop 0
	global_load_dwordx4 v[60:63], v[60:61], off
	v_add_u32_e32 v76, v81, v82
	v_and_or_b32 v3, v4, s36, v3
	ds_write2_b64 v76, v[0:1], v[2:3] offset1:66
	s_waitcnt vmcnt(13)
	v_cvt_pk_bf16_f32 v0, v8, v8
	v_lshrrev_b32_e32 v0, 16, v0
	v_cvt_pk_bf16_f32 v1, v9, v9
	v_and_or_b32 v0, v1, s36, v0
	v_cvt_pk_bf16_f32 v1, v10, v10
	v_lshrrev_b32_e32 v1, 16, v1
	v_cvt_pk_bf16_f32 v2, v11, v11
	v_and_or_b32 v1, v2, s36, v1
	s_waitcnt vmcnt(12)
	v_cvt_pk_bf16_f32 v2, v12, v12
	v_lshrrev_b32_e32 v2, 16, v2
	v_cvt_pk_bf16_f32 v3, v13, v13
	v_and_or_b32 v2, v3, s36, v2
	v_cvt_pk_bf16_f32 v3, v14, v14
	v_lshrrev_b32_e32 v3, 16, v3
	v_cvt_pk_bf16_f32 v4, v15, v15
	v_and_or_b32 v3, v4, s36, v3
	ds_write2_b64 v76, v[0:1], v[2:3] offset0:132 offset1:198
	s_waitcnt vmcnt(11)
	v_cvt_pk_bf16_f32 v0, v16, v16
	v_lshrrev_b32_e32 v0, 16, v0
	v_cvt_pk_bf16_f32 v1, v17, v17
	v_and_or_b32 v0, v1, s36, v0
	v_cvt_pk_bf16_f32 v1, v18, v18
	v_lshrrev_b32_e32 v1, 16, v1
	v_cvt_pk_bf16_f32 v2, v19, v19
	v_and_or_b32 v1, v2, s36, v1
	s_waitcnt vmcnt(10)
	v_cvt_pk_bf16_f32 v2, v20, v20
	v_lshrrev_b32_e32 v2, 16, v2
	v_cvt_pk_bf16_f32 v3, v21, v21
	v_and_or_b32 v2, v3, s36, v2
	v_cvt_pk_bf16_f32 v3, v22, v22
	v_lshrrev_b32_e32 v3, 16, v3
	v_cvt_pk_bf16_f32 v4, v23, v23
	v_and_or_b32 v3, v4, s36, v3
	v_add_u32_e32 v4, 0x800, v76
	ds_write2_b64 v4, v[0:1], v[2:3] offset0:8 offset1:74
	s_waitcnt vmcnt(9)
	v_cvt_pk_bf16_f32 v0, v24, v24
	v_lshrrev_b32_e32 v0, 16, v0
	v_cvt_pk_bf16_f32 v1, v25, v25
	v_and_or_b32 v0, v1, s36, v0
	v_cvt_pk_bf16_f32 v1, v26, v26
	v_lshrrev_b32_e32 v1, 16, v1
	v_cvt_pk_bf16_f32 v2, v27, v27
	v_and_or_b32 v1, v2, s36, v1
	s_waitcnt vmcnt(8)
	v_cvt_pk_bf16_f32 v2, v28, v28
	v_lshrrev_b32_e32 v2, 16, v2
	v_cvt_pk_bf16_f32 v3, v29, v29
	v_and_or_b32 v2, v3, s36, v2
	v_cvt_pk_bf16_f32 v3, v30, v30
	v_lshrrev_b32_e32 v3, 16, v3
	v_cvt_pk_bf16_f32 v5, v31, v31
	v_and_or_b32 v3, v5, s36, v3
	ds_write2_b64 v4, v[0:1], v[2:3] offset0:140 offset1:206
	s_waitcnt vmcnt(7)
	v_cvt_pk_bf16_f32 v0, v32, v32
	v_lshrrev_b32_e32 v0, 16, v0
	v_cvt_pk_bf16_f32 v1, v33, v33
	v_and_or_b32 v0, v1, s36, v0
	v_cvt_pk_bf16_f32 v1, v34, v34
	v_lshrrev_b32_e32 v1, 16, v1
	v_cvt_pk_bf16_f32 v2, v35, v35
	v_and_or_b32 v1, v2, s36, v1
	s_waitcnt vmcnt(6)
	v_cvt_pk_bf16_f32 v2, v36, v36
	v_lshrrev_b32_e32 v2, 16, v2
	v_cvt_pk_bf16_f32 v3, v37, v37
	v_and_or_b32 v2, v3, s36, v2
	v_cvt_pk_bf16_f32 v3, v38, v38
	v_lshrrev_b32_e32 v3, 16, v3
	v_cvt_pk_bf16_f32 v4, v39, v39
	v_and_or_b32 v3, v4, s36, v3
	v_add_u32_e32 v4, 0x1000, v76
	ds_write2_b64 v4, v[0:1], v[2:3] offset0:16 offset1:82
	s_waitcnt vmcnt(5)
	v_cvt_pk_bf16_f32 v0, v40, v40
	v_lshrrev_b32_e32 v0, 16, v0
	v_cvt_pk_bf16_f32 v1, v41, v41
	v_and_or_b32 v0, v1, s36, v0
	v_cvt_pk_bf16_f32 v1, v42, v42
	v_lshrrev_b32_e32 v1, 16, v1
	v_cvt_pk_bf16_f32 v2, v43, v43
	v_and_or_b32 v1, v2, s36, v1
	s_waitcnt vmcnt(4)
	v_cvt_pk_bf16_f32 v2, v44, v44
	v_lshrrev_b32_e32 v2, 16, v2
	v_cvt_pk_bf16_f32 v3, v45, v45
	v_and_or_b32 v2, v3, s36, v2
	v_cvt_pk_bf16_f32 v3, v46, v46
	v_lshrrev_b32_e32 v3, 16, v3
	v_cvt_pk_bf16_f32 v5, v47, v47
	v_and_or_b32 v3, v5, s36, v3
	ds_write2_b64 v4, v[0:1], v[2:3] offset0:148 offset1:214
	s_waitcnt vmcnt(3)
	v_cvt_pk_bf16_f32 v0, v48, v48
	v_lshrrev_b32_e32 v0, 16, v0
	v_cvt_pk_bf16_f32 v1, v49, v49
	v_and_or_b32 v0, v1, s36, v0
	v_cvt_pk_bf16_f32 v1, v50, v50
	v_lshrrev_b32_e32 v1, 16, v1
	v_cvt_pk_bf16_f32 v2, v51, v51
	v_and_or_b32 v1, v2, s36, v1
	s_waitcnt vmcnt(2)
	v_cvt_pk_bf16_f32 v2, v52, v52
	v_lshrrev_b32_e32 v2, 16, v2
	v_cvt_pk_bf16_f32 v3, v53, v53
	v_and_or_b32 v2, v3, s36, v2
	v_cvt_pk_bf16_f32 v3, v54, v54
	v_lshrrev_b32_e32 v3, 16, v3
	v_cvt_pk_bf16_f32 v4, v55, v55
	v_and_or_b32 v3, v4, s36, v3
	v_add_u32_e32 v4, 0x1800, v76
	ds_write2_b64 v4, v[0:1], v[2:3] offset0:24 offset1:90
	s_waitcnt vmcnt(1)
	v_cvt_pk_bf16_f32 v0, v56, v56
	v_lshrrev_b32_e32 v0, 16, v0
	v_cvt_pk_bf16_f32 v1, v57, v57
	v_and_or_b32 v0, v1, s36, v0
	v_cvt_pk_bf16_f32 v1, v58, v58
	v_lshrrev_b32_e32 v1, 16, v1
	v_cvt_pk_bf16_f32 v2, v59, v59
	v_and_or_b32 v1, v2, s36, v1
	s_waitcnt vmcnt(0)
	v_cvt_pk_bf16_f32 v2, v60, v60
	v_lshrrev_b32_e32 v2, 16, v2
	v_cvt_pk_bf16_f32 v3, v61, v61
	v_and_or_b32 v2, v3, s36, v2
	v_cvt_pk_bf16_f32 v3, v62, v62
	v_lshrrev_b32_e32 v3, 16, v3
	v_cvt_pk_bf16_f32 v5, v63, v63
	v_and_or_b32 v3, v5, s36, v3
	ds_write2_b64 v4, v[0:1], v[2:3] offset0:156 offset1:222
	s_waitcnt lgkmcnt(0)
	ds_read_u16 v2, v84
	ds_read_u16 v8, v84 offset:16
	ds_read_u16 v9, v84 offset:32
	ds_read_u16 v10, v84 offset:48
	ds_read_u16 v11, v84 offset:64
	ds_read_u16 v12, v84 offset:80
	ds_read_u16 v13, v84 offset:96
	ds_read_u16 v14, v84 offset:112
	ds_read_u16 v3, v84 offset:132
	ds_read_u16 v15, v84 offset:148
	ds_read_u16 v16, v84 offset:164
	ds_read_u16 v17, v84 offset:180
	ds_read_u16 v18, v84 offset:196
	ds_read_u16 v19, v84 offset:212
	ds_read_u16 v20, v84 offset:228
	ds_read_u16 v21, v84 offset:244
	s_waitcnt lgkmcnt(7)
	v_lshl_or_b32 v2, v3, 16, v2
	ds_read_u16 v3, v84 offset:264
	ds_read_u16 v22, v84 offset:280
	ds_read_u16 v23, v84 offset:296
	ds_read_u16 v24, v84 offset:312
	ds_read_u16 v25, v84 offset:328
	ds_read_u16 v26, v84 offset:344
	ds_read_u16 v27, v84 offset:360
	ds_read_u16 v28, v84 offset:376
	ds_read_u16 v4, v84 offset:396
	ds_read_u16 v29, v84 offset:412
	ds_read_u16 v30, v84 offset:428
	ds_read_u16 v31, v84 offset:444
	ds_read_u16 v32, v84 offset:460
	ds_read_u16 v33, v84 offset:476
	ds_read_u16 v34, v84 offset:492
	ds_read_u16 v35, v84 offset:508
	s_waitcnt lgkmcnt(7)
	v_lshl_or_b32 v3, v4, 16, v3
	ds_read_u16 v4, v84 offset:528
	ds_read_u16 v36, v84 offset:544
	ds_read_u16 v37, v84 offset:560
	ds_read_u16 v38, v84 offset:576
	ds_read_u16 v39, v84 offset:592
	ds_read_u16 v40, v84 offset:608
	ds_read_u16 v41, v84 offset:624
	ds_read_u16 v42, v84 offset:640
	ds_read_u16 v5, v84 offset:660
	ds_read_u16 v43, v84 offset:676
	ds_read_u16 v44, v84 offset:692
	ds_read_u16 v45, v84 offset:708
	ds_read_u16 v46, v84 offset:724
	ds_read_u16 v47, v84 offset:740
	ds_read_u16 v48, v84 offset:756
	ds_read_u16 v49, v84 offset:772
	s_waitcnt lgkmcnt(7)
	v_lshl_or_b32 v4, v5, 16, v4
	ds_read_u16 v5, v84 offset:792
	ds_read_u16 v50, v84 offset:808
	ds_read_u16 v51, v84 offset:824
	ds_read_u16 v52, v84 offset:840
	ds_read_u16 v53, v84 offset:856
	ds_read_u16 v54, v84 offset:872
	ds_read_u16 v55, v84 offset:888
	ds_read_u16 v56, v84 offset:904
	ds_read_u16 v6, v84 offset:924
	ds_read_u16 v57, v84 offset:940
	ds_read_u16 v58, v84 offset:956
	ds_read_u16 v59, v84 offset:972
	ds_read_u16 v60, v84 offset:988
	ds_read_u16 v61, v84 offset:1004
	ds_read_u16 v62, v84 offset:1020
	ds_read_u16 v63, v84 offset:1036
	s_waitcnt lgkmcnt(7)
	v_lshl_or_b32 v5, v6, 16, v5
	v_add_u32_e32 v6, s0, v83
	v_ashrrev_i32_e32 v7, 31, v6
	v_lshl_add_u64 v[0:1], s[38:39], 1, v[64:65]
	v_lshlrev_b64 v[6:7], 10, v[6:7]
	v_lshl_add_u64 v[6:7], v[0:1], 0, v[6:7]
	global_store_dwordx4 v[6:7], v[2:5], off
	v_add_u32_e32 v6, s0, v85
	v_ashrrev_i32_e32 v7, 31, v6
	v_lshlrev_b64 v[6:7], 10, v[6:7]
	v_lshl_or_b32 v2, v15, 16, v8
	v_lshl_or_b32 v3, v29, 16, v22
	v_lshl_or_b32 v4, v43, 16, v36
	s_waitcnt lgkmcnt(6)
	v_lshl_or_b32 v5, v57, 16, v50
	v_lshl_add_u64 v[6:7], v[0:1], 0, v[6:7]
	global_store_dwordx4 v[6:7], v[2:5], off
	v_add_u32_e32 v6, s0, v86
	v_ashrrev_i32_e32 v7, 31, v6
	v_lshlrev_b64 v[6:7], 10, v[6:7]
	v_lshl_or_b32 v2, v16, 16, v9
	v_lshl_or_b32 v3, v30, 16, v23
	v_lshl_or_b32 v4, v44, 16, v37
	s_waitcnt lgkmcnt(5)
	v_lshl_or_b32 v5, v58, 16, v51
	v_lshl_add_u64 v[6:7], v[0:1], 0, v[6:7]
	global_store_dwordx4 v[6:7], v[2:5], off
	v_add_u32_e32 v6, s0, v87
	v_ashrrev_i32_e32 v7, 31, v6
	v_lshlrev_b64 v[6:7], 10, v[6:7]
	v_lshl_or_b32 v2, v17, 16, v10
	v_lshl_or_b32 v3, v31, 16, v24
	v_lshl_or_b32 v4, v45, 16, v38
	s_waitcnt lgkmcnt(4)
	v_lshl_or_b32 v5, v59, 16, v52
	v_lshl_add_u64 v[6:7], v[0:1], 0, v[6:7]
	global_store_dwordx4 v[6:7], v[2:5], off
	v_add_u32_e32 v6, s0, v88
	v_ashrrev_i32_e32 v7, 31, v6
	v_lshlrev_b64 v[6:7], 10, v[6:7]
	v_lshl_or_b32 v2, v18, 16, v11
	v_lshl_or_b32 v3, v32, 16, v25
	v_lshl_or_b32 v4, v46, 16, v39
	s_waitcnt lgkmcnt(3)
	v_lshl_or_b32 v5, v60, 16, v53
	v_lshl_add_u64 v[6:7], v[0:1], 0, v[6:7]
	global_store_dwordx4 v[6:7], v[2:5], off
	v_add_u32_e32 v6, s0, v89
	v_ashrrev_i32_e32 v7, 31, v6
	v_lshlrev_b64 v[6:7], 10, v[6:7]
	v_lshl_or_b32 v2, v19, 16, v12
	v_lshl_or_b32 v3, v33, 16, v26
	v_lshl_or_b32 v4, v47, 16, v40
	s_waitcnt lgkmcnt(2)
	v_lshl_or_b32 v5, v61, 16, v54
	v_lshl_add_u64 v[6:7], v[0:1], 0, v[6:7]
	global_store_dwordx4 v[6:7], v[2:5], off
	v_add_u32_e32 v6, s0, v90
	v_ashrrev_i32_e32 v7, 31, v6
	v_lshlrev_b64 v[6:7], 10, v[6:7]
	v_lshl_or_b32 v2, v20, 16, v13
	v_lshl_or_b32 v3, v34, 16, v27
	v_lshl_or_b32 v4, v48, 16, v41
	s_waitcnt lgkmcnt(1)
	v_lshl_or_b32 v5, v62, 16, v55
	v_lshl_add_u64 v[6:7], v[0:1], 0, v[6:7]
	global_store_dwordx4 v[6:7], v[2:5], off
	v_add_u32_e32 v6, s0, v91
	v_ashrrev_i32_e32 v7, 31, v6
	v_lshlrev_b64 v[6:7], 10, v[6:7]
	v_lshl_or_b32 v2, v21, 16, v14
	v_lshl_or_b32 v3, v35, 16, v28
	v_lshl_or_b32 v4, v49, 16, v42
	s_waitcnt lgkmcnt(0)
	v_lshl_or_b32 v5, v63, 16, v56
	v_lshl_add_u64 v[0:1], v[0:1], 0, v[6:7]
	global_store_dwordx4 v[0:1], v[2:5], off
	s_waitcnt lgkmcnt(0)
	s_mov_b64 s[0:1], 0
.LBB0_1207:
	s_andn2_b64 vcc, exec, s[0:1]
	s_cbranch_vccnz .LBB0_1209
	s_and_b32 s0, s26, 0x7fc0
	s_add_i32 s38, s0, 0xffffb500
	s_and_b32 s0, s22, 0x7c0
	v_or_b32_e32 v1, s0, v80
	v_add_u32_e32 v0, s38, v66
	v_lshlrev_b32_e32 v96, 2, v1
	v_ashrrev_i32_e32 v1, 31, v0
	v_lshl_add_u64 v[2:3], s[4:5], 0, v[96:97]
	v_lshlrev_b64 v[0:1], 13, v[0:1]
	v_lshl_add_u64 v[56:57], v[2:3], 0, v[0:1]
	v_add_co_u32_e32 v4, vcc, 0x8000, v56
	s_mov_b32 s1, 0x18000
	s_nop 0
	v_addc_co_u32_e32 v5, vcc, 0, v57, vcc
	global_load_dwordx4 v[0:3], v[56:57], off
	s_nop 0
	global_load_dwordx4 v[4:7], v[4:5], off
	v_add_co_u32_e32 v8, vcc, s75, v56
	s_movk_i32 s43, 0x2b00
	s_nop 0
	v_addc_co_u32_e32 v9, vcc, 0, v57, vcc
	v_add_co_u32_e32 v12, vcc, s1, v56
	s_mov_b32 s1, 0x40000
	s_nop 0
	v_addc_co_u32_e32 v13, vcc, 0, v57, vcc
	global_load_dwordx4 v[8:11], v[8:9], off
	s_nop 0
	global_load_dwordx4 v[12:15], v[12:13], off
	v_add_co_u32_e32 v16, vcc, 0x20000, v56
	s_waitcnt vmcnt(0)
	s_nop 0
	v_addc_co_u32_e32 v17, vcc, 0, v57, vcc
	v_add_co_u32_e32 v20, vcc, 0x28000, v56
	v_cvt_pk_bf16_f32 v0, v0, v0
	s_nop 0
	v_addc_co_u32_e32 v21, vcc, 0, v57, vcc
	global_load_dwordx4 v[16:19], v[16:17], off
	s_nop 0
	global_load_dwordx4 v[20:23], v[20:21], off
	v_add_co_u32_e32 v24, vcc, 0x30000, v56
	s_nop 0
	s_nop 0
	v_addc_co_u32_e32 v25, vcc, 0, v57, vcc
	v_add_co_u32_e32 v28, vcc, 0x38000, v56
	v_lshrrev_b32_e32 v0, 16, v0
	s_nop 0
	v_addc_co_u32_e32 v29, vcc, 0, v57, vcc
	global_load_dwordx4 v[24:27], v[24:25], off
	s_nop 0
	global_load_dwordx4 v[28:31], v[28:29], off
	v_add_co_u32_e32 v32, vcc, s1, v56
	v_cvt_pk_bf16_f32 v1, v1, v1
	s_nop 0
	v_addc_co_u32_e32 v33, vcc, 0, v57, vcc
	v_add_co_u32_e32 v36, vcc, 0x48000, v56
	v_and_or_b32 v0, v1, s36, v0
	s_nop 0
	v_addc_co_u32_e32 v37, vcc, 0, v57, vcc
	global_load_dwordx4 v[32:35], v[32:33], off
	s_nop 0
	global_load_dwordx4 v[36:39], v[36:37], off
	v_add_co_u32_e32 v40, vcc, 0x50000, v56
	s_nop 0
	s_nop 0
	v_addc_co_u32_e32 v41, vcc, 0, v57, vcc
	v_add_co_u32_e32 v44, vcc, 0x58000, v56
	v_cvt_pk_bf16_f32 v1, v2, v2
	s_nop 0
	v_addc_co_u32_e32 v45, vcc, 0, v57, vcc
	global_load_dwordx4 v[40:43], v[40:41], off
	s_nop 0
	global_load_dwordx4 v[44:47], v[44:45], off
	v_add_co_u32_e32 v48, vcc, 0x60000, v56
	s_nop 0
	s_nop 0
	v_addc_co_u32_e32 v49, vcc, 0, v57, vcc
	v_add_co_u32_e32 v52, vcc, 0x68000, v56
	v_lshrrev_b32_e32 v1, 16, v1
	s_nop 0
	v_addc_co_u32_e32 v53, vcc, 0, v57, vcc
	global_load_dwordx4 v[48:51], v[48:49], off
	s_nop 0
	global_load_dwordx4 v[52:55], v[52:53], off
	v_cvt_pk_bf16_f32 v2, v3, v3
	v_and_or_b32 v1, v2, s36, v1
	v_cvt_pk_bf16_f32 v2, v4, v4
	v_add_co_u32_e32 v58, vcc, 0x70000, v56
	v_lshrrev_b32_e32 v2, 16, v2
	v_cvt_pk_bf16_f32 v3, v5, v5
	v_addc_co_u32_e32 v59, vcc, 0, v57, vcc
	v_and_or_b32 v2, v3, s36, v2
	v_add_co_u32_e32 v60, vcc, 0x78000, v56
	v_cvt_pk_bf16_f32 v3, v6, v6
	s_nop 0
	v_addc_co_u32_e32 v61, vcc, 0, v57, vcc
	v_lshrrev_b32_e32 v3, 16, v3
	v_cvt_pk_bf16_f32 v4, v7, v7
	global_load_dwordx4 v[56:59], v[58:59], off
	s_nop 0
	global_load_dwordx4 v[60:63], v[60:61], off
	v_add_u32_e32 v76, v81, v82
	v_and_or_b32 v3, v4, s36, v3
	ds_write2_b64 v76, v[0:1], v[2:3] offset1:66
	v_cvt_pk_bf16_f32 v0, v8, v8
	v_lshrrev_b32_e32 v0, 16, v0
	v_cvt_pk_bf16_f32 v1, v9, v9
	v_and_or_b32 v0, v1, s36, v0
	v_cvt_pk_bf16_f32 v1, v10, v10
	v_lshrrev_b32_e32 v1, 16, v1
	v_cvt_pk_bf16_f32 v2, v11, v11
	v_and_or_b32 v1, v2, s36, v1
	v_cvt_pk_bf16_f32 v2, v12, v12
	v_lshrrev_b32_e32 v2, 16, v2
	v_cvt_pk_bf16_f32 v3, v13, v13
	v_and_or_b32 v2, v3, s36, v2
	v_cvt_pk_bf16_f32 v3, v14, v14
	v_lshrrev_b32_e32 v3, 16, v3
	v_cvt_pk_bf16_f32 v4, v15, v15
	v_and_or_b32 v3, v4, s36, v3
	ds_write2_b64 v76, v[0:1], v[2:3] offset0:132 offset1:198
	s_waitcnt vmcnt(11)
	v_cvt_pk_bf16_f32 v0, v16, v16
	v_lshrrev_b32_e32 v0, 16, v0
	v_cvt_pk_bf16_f32 v1, v17, v17
	v_and_or_b32 v0, v1, s36, v0
	v_cvt_pk_bf16_f32 v1, v18, v18
	v_lshrrev_b32_e32 v1, 16, v1
	v_cvt_pk_bf16_f32 v2, v19, v19
	v_and_or_b32 v1, v2, s36, v1
	s_waitcnt vmcnt(10)
	v_cvt_pk_bf16_f32 v2, v20, v20
	v_lshrrev_b32_e32 v2, 16, v2
	v_cvt_pk_bf16_f32 v3, v21, v21
	v_and_or_b32 v2, v3, s36, v2
	v_cvt_pk_bf16_f32 v3, v22, v22
	v_lshrrev_b32_e32 v3, 16, v3
	v_cvt_pk_bf16_f32 v4, v23, v23
	v_and_or_b32 v3, v4, s36, v3
	v_add_u32_e32 v4, 0x800, v76
	ds_write2_b64 v4, v[0:1], v[2:3] offset0:8 offset1:74
	s_waitcnt vmcnt(9)
	v_cvt_pk_bf16_f32 v0, v24, v24
	v_lshrrev_b32_e32 v0, 16, v0
	v_cvt_pk_bf16_f32 v1, v25, v25
	v_and_or_b32 v0, v1, s36, v0
	v_cvt_pk_bf16_f32 v1, v26, v26
	v_lshrrev_b32_e32 v1, 16, v1
	v_cvt_pk_bf16_f32 v2, v27, v27
	v_and_or_b32 v1, v2, s36, v1
	s_waitcnt vmcnt(8)
	v_cvt_pk_bf16_f32 v2, v28, v28
	v_lshrrev_b32_e32 v2, 16, v2
	v_cvt_pk_bf16_f32 v3, v29, v29
	v_and_or_b32 v2, v3, s36, v2
	v_cvt_pk_bf16_f32 v3, v30, v30
	v_lshrrev_b32_e32 v3, 16, v3
	v_cvt_pk_bf16_f32 v5, v31, v31
	v_and_or_b32 v3, v5, s36, v3
	ds_write2_b64 v4, v[0:1], v[2:3] offset0:140 offset1:206
	s_waitcnt vmcnt(7)
	v_cvt_pk_bf16_f32 v0, v32, v32
	v_lshrrev_b32_e32 v0, 16, v0
	v_cvt_pk_bf16_f32 v1, v33, v33
	v_and_or_b32 v0, v1, s36, v0
	v_cvt_pk_bf16_f32 v1, v34, v34
	v_lshrrev_b32_e32 v1, 16, v1
	v_cvt_pk_bf16_f32 v2, v35, v35
	v_and_or_b32 v1, v2, s36, v1
	s_waitcnt vmcnt(6)
	v_cvt_pk_bf16_f32 v2, v36, v36
	v_lshrrev_b32_e32 v2, 16, v2
	v_cvt_pk_bf16_f32 v3, v37, v37
	v_and_or_b32 v2, v3, s36, v2
	v_cvt_pk_bf16_f32 v3, v38, v38
	v_lshrrev_b32_e32 v3, 16, v3
	v_cvt_pk_bf16_f32 v4, v39, v39
	v_and_or_b32 v3, v4, s36, v3
	v_add_u32_e32 v4, 0x1000, v76
	ds_write2_b64 v4, v[0:1], v[2:3] offset0:16 offset1:82
	s_waitcnt vmcnt(5)
	v_cvt_pk_bf16_f32 v0, v40, v40
	v_lshrrev_b32_e32 v0, 16, v0
	v_cvt_pk_bf16_f32 v1, v41, v41
	v_and_or_b32 v0, v1, s36, v0
	v_cvt_pk_bf16_f32 v1, v42, v42
	v_lshrrev_b32_e32 v1, 16, v1
	v_cvt_pk_bf16_f32 v2, v43, v43
	v_and_or_b32 v1, v2, s36, v1
	s_waitcnt vmcnt(4)
	v_cvt_pk_bf16_f32 v2, v44, v44
	v_lshrrev_b32_e32 v2, 16, v2
	v_cvt_pk_bf16_f32 v3, v45, v45
	v_and_or_b32 v2, v3, s36, v2
	v_cvt_pk_bf16_f32 v3, v46, v46
	v_lshrrev_b32_e32 v3, 16, v3
	v_cvt_pk_bf16_f32 v5, v47, v47
	v_and_or_b32 v3, v5, s36, v3
	ds_write2_b64 v4, v[0:1], v[2:3] offset0:148 offset1:214
	s_waitcnt vmcnt(3)
	v_cvt_pk_bf16_f32 v0, v48, v48
	v_lshrrev_b32_e32 v0, 16, v0
	v_cvt_pk_bf16_f32 v1, v49, v49
	v_and_or_b32 v0, v1, s36, v0
	v_cvt_pk_bf16_f32 v1, v50, v50
	v_lshrrev_b32_e32 v1, 16, v1
	v_cvt_pk_bf16_f32 v2, v51, v51
	v_and_or_b32 v1, v2, s36, v1
	s_waitcnt vmcnt(2)
	v_cvt_pk_bf16_f32 v2, v52, v52
	v_lshrrev_b32_e32 v2, 16, v2
	v_cvt_pk_bf16_f32 v3, v53, v53
	v_and_or_b32 v2, v3, s36, v2
	v_cvt_pk_bf16_f32 v3, v54, v54
	v_lshrrev_b32_e32 v3, 16, v3
	v_cvt_pk_bf16_f32 v4, v55, v55
	v_and_or_b32 v3, v4, s36, v3
	v_add_u32_e32 v4, 0x1800, v76
	ds_write2_b64 v4, v[0:1], v[2:3] offset0:24 offset1:90
	s_waitcnt vmcnt(1)
	v_cvt_pk_bf16_f32 v0, v56, v56
	v_lshrrev_b32_e32 v0, 16, v0
	v_cvt_pk_bf16_f32 v1, v57, v57
	v_and_or_b32 v0, v1, s36, v0
	v_cvt_pk_bf16_f32 v1, v58, v58
	v_lshrrev_b32_e32 v1, 16, v1
	v_cvt_pk_bf16_f32 v2, v59, v59
	v_and_or_b32 v1, v2, s36, v1
	s_waitcnt vmcnt(0)
	v_cvt_pk_bf16_f32 v2, v60, v60
	v_lshrrev_b32_e32 v2, 16, v2
	v_cvt_pk_bf16_f32 v3, v61, v61
	v_and_or_b32 v2, v3, s36, v2
	v_cvt_pk_bf16_f32 v3, v62, v62
	v_lshrrev_b32_e32 v3, 16, v3
	v_cvt_pk_bf16_f32 v5, v63, v63
	v_and_or_b32 v3, v5, s36, v3
	ds_write2_b64 v4, v[0:1], v[2:3] offset0:156 offset1:222
	s_waitcnt lgkmcnt(0)
	ds_read_u16 v2, v84
	ds_read_u16 v8, v84 offset:16
	ds_read_u16 v9, v84 offset:32
	ds_read_u16 v10, v84 offset:48
	ds_read_u16 v11, v84 offset:64
	ds_read_u16 v12, v84 offset:80
	ds_read_u16 v13, v84 offset:96
	ds_read_u16 v14, v84 offset:112
	ds_read_u16 v3, v84 offset:132
	ds_read_u16 v15, v84 offset:148
	ds_read_u16 v16, v84 offset:164
	ds_read_u16 v17, v84 offset:180
	ds_read_u16 v18, v84 offset:196
	ds_read_u16 v19, v84 offset:212
	ds_read_u16 v20, v84 offset:228
	ds_read_u16 v21, v84 offset:244
	s_waitcnt lgkmcnt(7)
	v_lshl_or_b32 v2, v3, 16, v2
	ds_read_u16 v3, v84 offset:264
	ds_read_u16 v22, v84 offset:280
	ds_read_u16 v23, v84 offset:296
	ds_read_u16 v24, v84 offset:312
	ds_read_u16 v25, v84 offset:328
	ds_read_u16 v26, v84 offset:344
	ds_read_u16 v27, v84 offset:360
	ds_read_u16 v28, v84 offset:376
	ds_read_u16 v4, v84 offset:396
	ds_read_u16 v29, v84 offset:412
	ds_read_u16 v30, v84 offset:428
	ds_read_u16 v31, v84 offset:444
	ds_read_u16 v32, v84 offset:460
	ds_read_u16 v33, v84 offset:476
	ds_read_u16 v34, v84 offset:492
	ds_read_u16 v35, v84 offset:508
	s_waitcnt lgkmcnt(7)
	v_lshl_or_b32 v3, v4, 16, v3
	ds_read_u16 v4, v84 offset:528
	ds_read_u16 v36, v84 offset:544
	ds_read_u16 v37, v84 offset:560
	ds_read_u16 v38, v84 offset:576
	ds_read_u16 v39, v84 offset:592
	ds_read_u16 v40, v84 offset:608
	ds_read_u16 v41, v84 offset:624
	ds_read_u16 v42, v84 offset:640
	ds_read_u16 v5, v84 offset:660
	ds_read_u16 v43, v84 offset:676
	ds_read_u16 v44, v84 offset:692
	ds_read_u16 v45, v84 offset:708
	ds_read_u16 v46, v84 offset:724
	ds_read_u16 v47, v84 offset:740
	ds_read_u16 v48, v84 offset:756
	ds_read_u16 v49, v84 offset:772
	s_waitcnt lgkmcnt(7)
	v_lshl_or_b32 v4, v5, 16, v4
	ds_read_u16 v5, v84 offset:792
	ds_read_u16 v50, v84 offset:808
	ds_read_u16 v51, v84 offset:824
	ds_read_u16 v52, v84 offset:840
	ds_read_u16 v53, v84 offset:856
	ds_read_u16 v54, v84 offset:872
	ds_read_u16 v55, v84 offset:888
	ds_read_u16 v56, v84 offset:904
	ds_read_u16 v6, v84 offset:924
	ds_read_u16 v57, v84 offset:940
	ds_read_u16 v58, v84 offset:956
	ds_read_u16 v59, v84 offset:972
	ds_read_u16 v60, v84 offset:988
	ds_read_u16 v61, v84 offset:1004
	ds_read_u16 v62, v84 offset:1020
	ds_read_u16 v63, v84 offset:1036
	v_lshl_add_u64 v[0:1], s[38:39], 1, v[68:69]
	s_waitcnt lgkmcnt(7)
	v_lshl_or_b32 v5, v6, 16, v5
	v_add_u32_e32 v6, s0, v83
	s_movk_i32 s1, 0x2b00
	v_mad_i64_i32 v[6:7], s[20:21], v6, s1, v[0:1]
	global_store_dwordx4 v[6:7], v[2:5], off
	v_add_u32_e32 v6, s0, v85
	v_mad_i64_i32 v[6:7], s[20:21], v6, s1, v[0:1]
	v_lshl_or_b32 v2, v15, 16, v8
	v_lshl_or_b32 v3, v29, 16, v22
	v_lshl_or_b32 v4, v43, 16, v36
	s_waitcnt lgkmcnt(6)
	v_lshl_or_b32 v5, v57, 16, v50
	global_store_dwordx4 v[6:7], v[2:5], off
	v_add_u32_e32 v6, s0, v86
	v_mad_i64_i32 v[6:7], s[20:21], v6, s1, v[0:1]
	v_lshl_or_b32 v2, v16, 16, v9
	v_lshl_or_b32 v3, v30, 16, v23
	v_lshl_or_b32 v4, v44, 16, v37
	s_waitcnt lgkmcnt(5)
	v_lshl_or_b32 v5, v58, 16, v51
	global_store_dwordx4 v[6:7], v[2:5], off
	v_add_u32_e32 v6, s0, v87
	v_mad_i64_i32 v[6:7], s[20:21], v6, s1, v[0:1]
	v_lshl_or_b32 v2, v17, 16, v10
	v_lshl_or_b32 v3, v31, 16, v24
	v_lshl_or_b32 v4, v45, 16, v38
	s_waitcnt lgkmcnt(4)
	v_lshl_or_b32 v5, v59, 16, v52
	global_store_dwordx4 v[6:7], v[2:5], off
	v_add_u32_e32 v6, s0, v88
	v_mad_i64_i32 v[6:7], s[20:21], v6, s1, v[0:1]
	v_lshl_or_b32 v2, v18, 16, v11
	v_lshl_or_b32 v3, v32, 16, v25
	v_lshl_or_b32 v4, v46, 16, v39
	s_waitcnt lgkmcnt(3)
	v_lshl_or_b32 v5, v60, 16, v53
	global_store_dwordx4 v[6:7], v[2:5], off
	v_add_u32_e32 v6, s0, v89
	v_mad_i64_i32 v[6:7], s[20:21], v6, s1, v[0:1]
	v_lshl_or_b32 v2, v19, 16, v12
	v_lshl_or_b32 v3, v33, 16, v26
	v_lshl_or_b32 v4, v47, 16, v40
	s_waitcnt lgkmcnt(2)
	v_lshl_or_b32 v5, v61, 16, v54
	global_store_dwordx4 v[6:7], v[2:5], off
	v_add_u32_e32 v6, s0, v90
	v_mad_i64_i32 v[6:7], s[20:21], v6, s1, v[0:1]
	v_lshl_or_b32 v2, v20, 16, v13
	v_lshl_or_b32 v3, v34, 16, v27
	v_lshl_or_b32 v4, v48, 16, v41
	s_waitcnt lgkmcnt(1)
	v_lshl_or_b32 v5, v62, 16, v55
	global_store_dwordx4 v[6:7], v[2:5], off
	v_add_u32_e32 v6, s0, v91
	v_mad_i64_i32 v[0:1], s[0:1], v6, s1, v[0:1]
	v_lshl_or_b32 v2, v21, 16, v14
	v_lshl_or_b32 v3, v35, 16, v28
	v_lshl_or_b32 v4, v49, 16, v42
	s_waitcnt lgkmcnt(0)
	v_lshl_or_b32 v5, v63, 16, v56
	global_store_dwordx4 v[0:1], v[2:5], off
	s_waitcnt lgkmcnt(0)

.LBB0_1213:
	s_waitcnt vmcnt(0)
	v_cvt_pk_bf16_f32 v60, v60, v60
	v_lshrrev_b32_e32 v60, 16, v60
	v_cvt_pk_bf16_f32 v61, v61, v61
	v_and_or_b32 v60, v61, s36, v60
	v_cvt_pk_bf16_f32 v61, v62, v62
	v_lshrrev_b32_e32 v61, 16, v61
	v_cvt_pk_bf16_f32 v62, v63, v63
	v_and_or_b32 v61, v62, s36, v61
	v_add_u32_e32 v62, v81, v82
	s_and_b64 vcc, exec, s[0:1]
	ds_write_b64 v62, v[60:61]
	s_cbranch_vccnz .LBB0_1215
	global_load_dword v60, v[76:77], off offset:16
	s_waitcnt vmcnt(0)
	v_pk_mul_f32 v[58:59], v[58:59], v[60:61] op_sel_hi:[1,0]
	v_pk_mul_f32 v[56:57], v[56:57], v[60:61] op_sel_hi:[1,0]
.LBB0_1215:
	s_nop 0
	v_cvt_pk_bf16_f32 v56, v56, v56
	v_lshrrev_b32_e32 v56, 16, v56
	v_cvt_pk_bf16_f32 v57, v57, v57
	v_and_or_b32 v60, v57, s36, v56
	v_cvt_pk_bf16_f32 v56, v58, v58
	v_lshrrev_b32_e32 v56, 16, v56
	v_cvt_pk_bf16_f32 v57, v59, v59
	v_and_or_b32 v61, v57, s36, v56
	v_add_u32_e32 v56, v81, v92
	s_and_b64 vcc, exec, s[0:1]
	ds_write_b64 v56, v[60:61]
	s_cbranch_vccnz .LBB0_1217
	global_load_dword v58, v[76:77], off offset:32
	s_waitcnt vmcnt(0)
	v_pk_mul_f32 v[54:55], v[54:55], v[58:59] op_sel_hi:[1,0]
	v_pk_mul_f32 v[52:53], v[52:53], v[58:59] op_sel_hi:[1,0]
.LBB0_1217:
	s_nop 0
	v_cvt_pk_bf16_f32 v52, v52, v52
	v_lshrrev_b32_e32 v52, 16, v52
	v_cvt_pk_bf16_f32 v53, v53, v53
	v_and_or_b32 v52, v53, s36, v52
	v_cvt_pk_bf16_f32 v53, v54, v54
	v_bfe_u32 v54, v55, 16, 1
	v_lshrrev_b32_e32 v53, 16, v53
	v_add3_u32 v54, v55, v54, s48
	v_and_or_b32 v53, v54, s36, v53
	s_and_b64 vcc, exec, s[0:1]
	ds_write_b64 v56, v[52:53] offset:528
	s_cbranch_vccnz .LBB0_1219
	global_load_dword v52, v[76:77], off offset:48
	s_waitcnt vmcnt(0)
	v_pk_mul_f32 v[50:51], v[50:51], v[52:53] op_sel_hi:[1,0]
	v_pk_mul_f32 v[48:49], v[48:49], v[52:53] op_sel_hi:[1,0]
.LBB0_1219:
	s_nop 0
	v_cvt_pk_bf16_f32 v48, v48, v48
	v_lshrrev_b32_e32 v48, 16, v48
	v_cvt_pk_bf16_f32 v49, v49, v49
	v_and_or_b32 v48, v49, s36, v48
	v_cvt_pk_bf16_f32 v49, v50, v50
	v_bfe_u32 v50, v51, 16, 1
	v_lshrrev_b32_e32 v49, 16, v49
	v_add3_u32 v50, v51, v50, s48
	v_and_or_b32 v49, v50, s36, v49
	s_and_b64 vcc, exec, s[0:1]
	ds_write_b64 v56, v[48:49] offset:1056
	s_cbranch_vccnz .LBB0_1221
	global_load_dword v48, v[76:77], off offset:64
	s_waitcnt vmcnt(0)
	v_pk_mul_f32 v[46:47], v[46:47], v[48:49] op_sel_hi:[1,0]
	v_pk_mul_f32 v[44:45], v[44:45], v[48:49] op_sel_hi:[1,0]
.LBB0_1221:
	s_nop 0
	v_cvt_pk_bf16_f32 v44, v44, v44
	v_lshrrev_b32_e32 v44, 16, v44
	v_cvt_pk_bf16_f32 v45, v45, v45
	v_and_or_b32 v44, v45, s36, v44
	v_cvt_pk_bf16_f32 v45, v46, v46
	v_bfe_u32 v46, v47, 16, 1
	v_lshrrev_b32_e32 v45, 16, v45
	v_add3_u32 v46, v47, v46, s48
	v_and_or_b32 v45, v46, s36, v45
	s_and_b64 vcc, exec, s[0:1]
	ds_write_b64 v56, v[44:45] offset:1584
	s_cbranch_vccnz .LBB0_1223
	global_load_dword v44, v[76:77], off offset:80
	s_waitcnt vmcnt(0)
	v_pk_mul_f32 v[42:43], v[42:43], v[44:45] op_sel_hi:[1,0]
	v_pk_mul_f32 v[40:41], v[40:41], v[44:45] op_sel_hi:[1,0]
.LBB0_1223:
	s_nop 0
	v_cvt_pk_bf16_f32 v40, v40, v40
	v_lshrrev_b32_e32 v40, 16, v40
	v_cvt_pk_bf16_f32 v41, v41, v41
	v_and_or_b32 v40, v41, s36, v40
	v_cvt_pk_bf16_f32 v41, v42, v42
	v_bfe_u32 v42, v43, 16, 1
	v_lshrrev_b32_e32 v41, 16, v41
	v_add3_u32 v42, v43, v42, s48
	v_and_or_b32 v41, v42, s36, v41
	s_and_b64 vcc, exec, s[0:1]
	ds_write_b64 v56, v[40:41] offset:2112
	s_cbranch_vccnz .LBB0_1225
	global_load_dword v40, v[76:77], off offset:96
	s_waitcnt vmcnt(0)
	v_pk_mul_f32 v[38:39], v[38:39], v[40:41] op_sel_hi:[1,0]
	v_pk_mul_f32 v[36:37], v[36:37], v[40:41] op_sel_hi:[1,0]
.LBB0_1225:
	s_nop 0
	v_cvt_pk_bf16_f32 v36, v36, v36
	v_lshrrev_b32_e32 v36, 16, v36
	v_cvt_pk_bf16_f32 v37, v37, v37
	v_and_or_b32 v36, v37, s36, v36
	v_cvt_pk_bf16_f32 v37, v38, v38
	v_bfe_u32 v38, v39, 16, 1
	v_lshrrev_b32_e32 v37, 16, v37
	v_add3_u32 v38, v39, v38, s48
	v_and_or_b32 v37, v38, s36, v37
	s_and_b64 vcc, exec, s[0:1]
	ds_write_b64 v56, v[36:37] offset:2640
	s_cbranch_vccnz .LBB0_1227
	global_load_dword v36, v[76:77], off offset:112
	s_waitcnt vmcnt(0)
	v_pk_mul_f32 v[34:35], v[34:35], v[36:37] op_sel_hi:[1,0]
	v_pk_mul_f32 v[32:33], v[32:33], v[36:37] op_sel_hi:[1,0]
.LBB0_1227:
	s_nop 0
	v_cvt_pk_bf16_f32 v32, v32, v32
	v_lshrrev_b32_e32 v32, 16, v32
	v_cvt_pk_bf16_f32 v33, v33, v33
	v_and_or_b32 v32, v33, s36, v32
	v_cvt_pk_bf16_f32 v33, v34, v34
	v_bfe_u32 v34, v35, 16, 1
	v_lshrrev_b32_e32 v33, 16, v33
	v_add3_u32 v34, v35, v34, s48
	v_and_or_b32 v33, v34, s36, v33
	s_and_b64 vcc, exec, s[0:1]
	ds_write_b64 v56, v[32:33] offset:3168
	s_cbranch_vccnz .LBB0_1229
	global_load_dword v32, v[76:77], off offset:128
	s_waitcnt vmcnt(0)
	v_pk_mul_f32 v[30:31], v[30:31], v[32:33] op_sel_hi:[1,0]
	v_pk_mul_f32 v[28:29], v[28:29], v[32:33] op_sel_hi:[1,0]
.LBB0_1229:
	s_nop 0
	v_cvt_pk_bf16_f32 v28, v28, v28
	v_lshrrev_b32_e32 v28, 16, v28
	v_cvt_pk_bf16_f32 v29, v29, v29
	v_and_or_b32 v28, v29, s36, v28
	v_cvt_pk_bf16_f32 v29, v30, v30
	v_bfe_u32 v30, v31, 16, 1
	v_lshrrev_b32_e32 v29, 16, v29
	v_add3_u32 v30, v31, v30, s48
	v_and_or_b32 v29, v30, s36, v29
	s_and_b64 vcc, exec, s[0:1]
	ds_write_b64 v56, v[28:29] offset:3696
	s_cbranch_vccnz .LBB0_1231
	global_load_dword v28, v[76:77], off offset:144
	s_waitcnt vmcnt(0)
	v_pk_mul_f32 v[26:27], v[26:27], v[28:29] op_sel_hi:[1,0]
	v_pk_mul_f32 v[24:25], v[24:25], v[28:29] op_sel_hi:[1,0]
.LBB0_1231:
	s_nop 0
	v_cvt_pk_bf16_f32 v24, v24, v24
	v_lshrrev_b32_e32 v24, 16, v24
	v_cvt_pk_bf16_f32 v25, v25, v25
	v_and_or_b32 v24, v25, s36, v24
	v_cvt_pk_bf16_f32 v25, v26, v26
	v_bfe_u32 v26, v27, 16, 1
	v_lshrrev_b32_e32 v25, 16, v25
	v_add3_u32 v26, v27, v26, s48
	v_and_or_b32 v25, v26, s36, v25
	s_and_b64 vcc, exec, s[0:1]
	ds_write_b64 v56, v[24:25] offset:4224
	s_cbranch_vccnz .LBB0_1233
	global_load_dword v24, v[76:77], off offset:160
	s_waitcnt vmcnt(0)
	v_pk_mul_f32 v[22:23], v[22:23], v[24:25] op_sel_hi:[1,0]
	v_pk_mul_f32 v[20:21], v[20:21], v[24:25] op_sel_hi:[1,0]
.LBB0_1233:
	s_nop 0
	v_cvt_pk_bf16_f32 v20, v20, v20
	v_lshrrev_b32_e32 v20, 16, v20
	v_cvt_pk_bf16_f32 v21, v21, v21
	v_and_or_b32 v20, v21, s36, v20
	v_cvt_pk_bf16_f32 v21, v22, v22
	v_bfe_u32 v22, v23, 16, 1
	v_lshrrev_b32_e32 v21, 16, v21
	v_add3_u32 v22, v23, v22, s48
	v_and_or_b32 v21, v22, s36, v21
	s_and_b64 vcc, exec, s[0:1]
	ds_write_b64 v56, v[20:21] offset:4752
	s_cbranch_vccnz .LBB0_1235
	global_load_dword v20, v[76:77], off offset:176
	s_waitcnt vmcnt(0)
	v_pk_mul_f32 v[18:19], v[18:19], v[20:21] op_sel_hi:[1,0]
	v_pk_mul_f32 v[16:17], v[16:17], v[20:21] op_sel_hi:[1,0]
.LBB0_1235:
	s_nop 0
	v_cvt_pk_bf16_f32 v16, v16, v16
	v_lshrrev_b32_e32 v16, 16, v16
	v_cvt_pk_bf16_f32 v17, v17, v17
	v_and_or_b32 v16, v17, s36, v16
	v_cvt_pk_bf16_f32 v17, v18, v18
	v_bfe_u32 v18, v19, 16, 1
	v_lshrrev_b32_e32 v17, 16, v17
	v_add3_u32 v18, v19, v18, s48
	v_and_or_b32 v17, v18, s36, v17
	s_and_b64 vcc, exec, s[0:1]
	ds_write_b64 v56, v[16:17] offset:5280
	s_cbranch_vccnz .LBB0_1237
	global_load_dword v16, v[76:77], off offset:192
	s_waitcnt vmcnt(0)
	v_pk_mul_f32 v[14:15], v[14:15], v[16:17] op_sel_hi:[1,0]
	v_pk_mul_f32 v[12:13], v[12:13], v[16:17] op_sel_hi:[1,0]
.LBB0_1237:
	s_nop 0
	v_cvt_pk_bf16_f32 v12, v12, v12
	v_lshrrev_b32_e32 v12, 16, v12
	v_cvt_pk_bf16_f32 v13, v13, v13
	v_and_or_b32 v12, v13, s36, v12
	v_cvt_pk_bf16_f32 v13, v14, v14
	v_bfe_u32 v14, v15, 16, 1
	v_lshrrev_b32_e32 v13, 16, v13
	v_add3_u32 v14, v15, v14, s48
	v_and_or_b32 v13, v14, s36, v13
	s_and_b64 vcc, exec, s[0:1]
	ds_write_b64 v56, v[12:13] offset:5808
	s_cbranch_vccnz .LBB0_1239
	global_load_dword v12, v[76:77], off offset:208
	s_waitcnt vmcnt(0)
	v_pk_mul_f32 v[10:11], v[10:11], v[12:13] op_sel_hi:[1,0]
	v_pk_mul_f32 v[8:9], v[8:9], v[12:13] op_sel_hi:[1,0]
.LBB0_1239:
	s_nop 0
	v_cvt_pk_bf16_f32 v8, v8, v8
	v_lshrrev_b32_e32 v8, 16, v8
	v_cvt_pk_bf16_f32 v9, v9, v9
	v_and_or_b32 v8, v9, s36, v8
	v_cvt_pk_bf16_f32 v9, v10, v10
	v_bfe_u32 v10, v11, 16, 1
	v_lshrrev_b32_e32 v9, 16, v9
	v_add3_u32 v10, v11, v10, s48
	v_and_or_b32 v9, v10, s36, v9
	s_and_b64 vcc, exec, s[0:1]
	ds_write_b64 v56, v[8:9] offset:6336
	s_cbranch_vccnz .LBB0_1241
	global_load_dword v8, v[76:77], off offset:224
	s_waitcnt vmcnt(0)
	v_pk_mul_f32 v[6:7], v[6:7], v[8:9] op_sel_hi:[1,0]
	v_pk_mul_f32 v[4:5], v[4:5], v[8:9] op_sel_hi:[1,0]
.LBB0_1241:
	s_nop 0
	v_cvt_pk_bf16_f32 v4, v4, v4
	v_lshrrev_b32_e32 v4, 16, v4
	v_cvt_pk_bf16_f32 v5, v5, v5
	v_and_or_b32 v4, v5, s36, v4
	v_cvt_pk_bf16_f32 v5, v6, v6
	v_lshrrev_b32_e32 v5, 16, v5
	v_cvt_pk_bf16_f32 v6, v7, v7
	v_and_or_b32 v5, v6, s36, v5
	s_and_b64 vcc, exec, s[0:1]
	ds_write_b64 v56, v[4:5] offset:6864
	s_cbranch_vccnz .LBB0_1243
	global_load_dword v4, v[76:77], off offset:240
	s_waitcnt vmcnt(0)
	v_pk_mul_f32 v[2:3], v[2:3], v[4:5] op_sel_hi:[1,0]
	v_pk_mul_f32 v[0:1], v[0:1], v[4:5] op_sel_hi:[1,0]
.LBB0_1243:
	s_nop 0
	v_cvt_pk_bf16_f32 v0, v0, v0
	v_lshrrev_b32_e32 v0, 16, v0
	v_cvt_pk_bf16_f32 v1, v1, v1
	v_and_or_b32 v0, v1, s36, v0
	v_cvt_pk_bf16_f32 v1, v2, v2
	v_lshrrev_b32_e32 v1, 16, v1
	v_cvt_pk_bf16_f32 v2, v3, v3
	v_and_or_b32 v1, v2, s36, v1
	ds_write_b64 v56, v[0:1] offset:7392
	s_waitcnt lgkmcnt(0)
	ds_read_u16 v0, v84 offset:132
	ds_read_u16 v1, v84
	ds_read_u16 v8, v84 offset:16
	s_lshl_b32 s0, s28, 7
	s_or_b32 s1, s0, 0x80
	s_addk_i32 s1, 0xd500
	s_waitcnt lgkmcnt(1)
	v_lshl_or_b32 v0, v0, 16, v1
	ds_read_u16 v1, v84 offset:264
	ds_read_u16 v2, v84 offset:396
	s_and_b32 s0, s0, 0x3f00
	s_cmpk_lt_u32 s28, 0x56
	s_cselect_b32 s0, s0, s1
	s_and_b32 s1, s21, 64
	s_waitcnt lgkmcnt(0)
	v_lshl_or_b32 v1, v2, 16, v1
	ds_read_u16 v2, v84 offset:528
	ds_read_u16 v3, v84 offset:660
	s_or_b32 s0, s0, s1
	s_and_b32 s1, 0xffff, s20
	s_lshl_b32 s38, s1, 1
	v_lshl_add_u64 v[4:5], v[70:71], 0, s[38:39]
	s_waitcnt lgkmcnt(0)
	v_lshl_or_b32 v2, v3, 16, v2
	ds_read_u16 v3, v84 offset:792
	ds_read_u16 v6, v84 offset:924
	s_waitcnt lgkmcnt(0)
	v_lshl_or_b32 v3, v6, 16, v3
	v_add_u32_e32 v6, s0, v83
	v_ashrrev_i32_e32 v7, 31, v6
	v_lshlrev_b64 v[6:7], 12, v[6:7]
	v_lshl_add_u64 v[6:7], v[4:5], 0, v[6:7]
	global_store_dwordx4 v[6:7], v[0:3], off
	ds_read_u16 v0, v84 offset:148
	ds_read_u16 v1, v84 offset:280
	ds_read_u16 v2, v84 offset:412
	s_waitcnt lgkmcnt(2)
	v_lshl_or_b32 v0, v0, 16, v8
	s_waitcnt lgkmcnt(0)
	v_lshl_or_b32 v1, v2, 16, v1
	ds_read_u16 v2, v84 offset:544
	ds_read_u16 v3, v84 offset:676
	s_waitcnt lgkmcnt(0)
	v_lshl_or_b32 v2, v3, 16, v2
	ds_read_u16 v3, v84 offset:808
	ds_read_u16 v6, v84 offset:940
	s_waitcnt lgkmcnt(0)
	v_lshl_or_b32 v3, v6, 16, v3
	v_add_u32_e32 v6, s0, v85
	v_ashrrev_i32_e32 v7, 31, v6
	v_lshlrev_b64 v[6:7], 12, v[6:7]
	v_lshl_add_u64 v[6:7], v[4:5], 0, v[6:7]
	global_store_dwordx4 v[6:7], v[0:3], off
	ds_read_u16 v0, v84 offset:164
	ds_read_u16 v1, v84 offset:32
	ds_read_u16 v8, v84 offset:48
	s_waitcnt lgkmcnt(1)
	v_lshl_or_b32 v0, v0, 16, v1
	ds_read_u16 v1, v84 offset:296
	ds_read_u16 v2, v84 offset:428
	s_waitcnt lgkmcnt(0)
	v_lshl_or_b32 v1, v2, 16, v1
	ds_read_u16 v2, v84 offset:560
	ds_read_u16 v3, v84 offset:692
	s_waitcnt lgkmcnt(0)
	v_lshl_or_b32 v2, v3, 16, v2
	ds_read_u16 v3, v84 offset:824
	ds_read_u16 v6, v84 offset:956
	s_waitcnt lgkmcnt(0)
	v_lshl_or_b32 v3, v6, 16, v3
	v_add_u32_e32 v6, s0, v86
	v_ashrrev_i32_e32 v7, 31, v6
	v_lshlrev_b64 v[6:7], 12, v[6:7]
	v_lshl_add_u64 v[6:7], v[4:5], 0, v[6:7]
	global_store_dwordx4 v[6:7], v[0:3], off
	ds_read_u16 v0, v84 offset:180
	ds_read_u16 v1, v84 offset:312
	ds_read_u16 v2, v84 offset:444
	s_waitcnt lgkmcnt(2)
	v_lshl_or_b32 v0, v0, 16, v8
	s_waitcnt lgkmcnt(0)
	v_lshl_or_b32 v1, v2, 16, v1
	ds_read_u16 v2, v84 offset:576
	ds_read_u16 v3, v84 offset:708
	s_waitcnt lgkmcnt(0)
	v_lshl_or_b32 v2, v3, 16, v2
	ds_read_u16 v3, v84 offset:840
	ds_read_u16 v6, v84 offset:972
	s_waitcnt lgkmcnt(0)
	v_lshl_or_b32 v3, v6, 16, v3
	v_add_u32_e32 v6, s0, v87
	v_ashrrev_i32_e32 v7, 31, v6
	v_lshlrev_b64 v[6:7], 12, v[6:7]
	v_lshl_add_u64 v[6:7], v[4:5], 0, v[6:7]
	global_store_dwordx4 v[6:7], v[0:3], off
	ds_read_u16 v0, v84 offset:64
	ds_read_u16 v1, v84 offset:196
	s_waitcnt lgkmcnt(0)
	v_lshl_or_b32 v0, v1, 16, v0
	ds_read_u16 v1, v84 offset:328
	ds_read_u16 v2, v84 offset:460
	s_waitcnt lgkmcnt(0)
	v_lshl_or_b32 v1, v2, 16, v1
	ds_read_u16 v2, v84 offset:592
	ds_read_u16 v3, v84 offset:724
	s_waitcnt lgkmcnt(0)
	v_lshl_or_b32 v2, v3, 16, v2
	ds_read_u16 v3, v84 offset:856
	ds_read_u16 v6, v84 offset:988
	s_waitcnt lgkmcnt(0)
	v_lshl_or_b32 v3, v6, 16, v3
	v_add_u32_e32 v6, s0, v88
	v_ashrrev_i32_e32 v7, 31, v6
	v_lshlrev_b64 v[6:7], 12, v[6:7]
	v_lshl_add_u64 v[6:7], v[4:5], 0, v[6:7]
	global_store_dwordx4 v[6:7], v[0:3], off
	ds_read_u16 v0, v84 offset:80
	ds_read_u16 v1, v84 offset:212
	s_waitcnt lgkmcnt(0)
	v_lshl_or_b32 v0, v1, 16, v0
	ds_read_u16 v1, v84 offset:344
	ds_read_u16 v2, v84 offset:476
	s_waitcnt lgkmcnt(0)
	v_lshl_or_b32 v1, v2, 16, v1
	ds_read_u16 v2, v84 offset:608
	ds_read_u16 v3, v84 offset:740
	s_waitcnt lgkmcnt(0)
	v_lshl_or_b32 v2, v3, 16, v2
	ds_read_u16 v3, v84 offset:872
	ds_read_u16 v6, v84 offset:1004
	s_waitcnt lgkmcnt(0)
	v_lshl_or_b32 v3, v6, 16, v3
	v_add_u32_e32 v6, s0, v89
	v_ashrrev_i32_e32 v7, 31, v6
	v_lshlrev_b64 v[6:7], 12, v[6:7]
	v_lshl_add_u64 v[6:7], v[4:5], 0, v[6:7]
	global_store_dwordx4 v[6:7], v[0:3], off
	ds_read_u16 v0, v84 offset:96
	ds_read_u16 v1, v84 offset:228
	s_waitcnt lgkmcnt(0)
	v_lshl_or_b32 v0, v1, 16, v0
	ds_read_u16 v1, v84 offset:360
	ds_read_u16 v2, v84 offset:492
	s_waitcnt lgkmcnt(0)
	v_lshl_or_b32 v1, v2, 16, v1
	ds_read_u16 v2, v84 offset:624
	ds_read_u16 v3, v84 offset:756
	s_waitcnt lgkmcnt(0)
	v_lshl_or_b32 v2, v3, 16, v2
	ds_read_u16 v3, v84 offset:888
	ds_read_u16 v6, v84 offset:1020
	s_waitcnt lgkmcnt(0)
	v_lshl_or_b32 v3, v6, 16, v3
	v_add_u32_e32 v6, s0, v90
	v_ashrrev_i32_e32 v7, 31, v6
	v_lshlrev_b64 v[6:7], 12, v[6:7]
	v_lshl_add_u64 v[6:7], v[4:5], 0, v[6:7]
	global_store_dwordx4 v[6:7], v[0:3], off
	ds_read_u16 v0, v84 offset:112
	ds_read_u16 v1, v84 offset:244
	s_waitcnt lgkmcnt(0)
	v_lshl_or_b32 v0, v1, 16, v0
	ds_read_u16 v1, v84 offset:376
	ds_read_u16 v2, v84 offset:508
	s_waitcnt lgkmcnt(0)
	v_lshl_or_b32 v1, v2, 16, v1
	ds_read_u16 v2, v84 offset:640
	ds_read_u16 v3, v84 offset:772
	s_waitcnt lgkmcnt(0)
	v_lshl_or_b32 v2, v3, 16, v2
	ds_read_u16 v3, v84 offset:904
	ds_read_u16 v6, v84 offset:1036
	s_waitcnt lgkmcnt(0)
	v_lshl_or_b32 v3, v6, 16, v3
	v_add_u32_e32 v6, s0, v91
	v_ashrrev_i32_e32 v7, 31, v6
	v_lshlrev_b64 v[6:7], 12, v[6:7]
	v_lshl_add_u64 v[4:5], v[4:5], 0, v[6:7]
	global_store_dwordx4 v[4:5], v[0:3], off
	s_waitcnt lgkmcnt(0)

.LBB0_1245:
	s_andn2_b64 vcc, exec, s[0:1]
	s_cbranch_vccnz .LBB0_1247
	s_and_b32 s0, s26, 0x1fc0
	s_add_i32 s38, s0, 0xffffe800
	s_and_b32 s0, s22, 0x7c0
	v_or_b32_e32 v1, s0, v80
	v_add_u32_e32 v0, s38, v66
	v_lshlrev_b32_e32 v96, 2, v1
	v_ashrrev_i32_e32 v1, 31, v0
	v_lshl_add_u64 v[2:3], s[14:15], 0, v[96:97]
	v_lshlrev_b64 v[0:1], 13, v[0:1]
	v_lshl_add_u64 v[56:57], v[2:3], 0, v[0:1]
	v_add_co_u32_e32 v4, vcc, 0x8000, v56
	s_mov_b32 s1, 0x18000
	s_nop 0
	v_addc_co_u32_e32 v5, vcc, 0, v57, vcc
	global_load_dwordx4 v[0:3], v[56:57], off
	s_nop 0
	global_load_dwordx4 v[4:7], v[4:5], off
	v_add_co_u32_e32 v8, vcc, s75, v56
	s_waitcnt vmcnt(0)
	s_nop 0
	v_addc_co_u32_e32 v9, vcc, 0, v57, vcc
	v_add_co_u32_e32 v12, vcc, s1, v56
	s_mov_b32 s1, 0x40000
	s_nop 0
	v_addc_co_u32_e32 v13, vcc, 0, v57, vcc
	global_load_dwordx4 v[8:11], v[8:9], off
	s_nop 0
	global_load_dwordx4 v[12:15], v[12:13], off
	v_add_co_u32_e32 v16, vcc, 0x20000, v56
	v_cvt_pk_bf16_f32 v0, v0, v0
	s_nop 0
	v_addc_co_u32_e32 v17, vcc, 0, v57, vcc
	v_add_co_u32_e32 v20, vcc, 0x28000, v56
	s_nop 0
	s_nop 0
	v_addc_co_u32_e32 v21, vcc, 0, v57, vcc
	global_load_dwordx4 v[16:19], v[16:17], off
	s_nop 0
	global_load_dwordx4 v[20:23], v[20:21], off
	v_add_co_u32_e32 v24, vcc, 0x30000, v56
	v_lshrrev_b32_e32 v0, 16, v0
	s_nop 0
	v_addc_co_u32_e32 v25, vcc, 0, v57, vcc
	v_add_co_u32_e32 v28, vcc, 0x38000, v56
	v_cvt_pk_bf16_f32 v1, v1, v1
	s_nop 0
	v_addc_co_u32_e32 v29, vcc, 0, v57, vcc
	global_load_dwordx4 v[24:27], v[24:25], off
	s_nop 0
	global_load_dwordx4 v[28:31], v[28:29], off
	v_add_co_u32_e32 v32, vcc, s1, v56
	v_and_or_b32 v0, v1, s36, v0
	s_nop 0
	v_addc_co_u32_e32 v33, vcc, 0, v57, vcc
	v_add_co_u32_e32 v36, vcc, 0x48000, v56
	s_nop 0
	s_nop 0
	v_addc_co_u32_e32 v37, vcc, 0, v57, vcc
	global_load_dwordx4 v[32:35], v[32:33], off
	s_nop 0
	global_load_dwordx4 v[36:39], v[36:37], off
	v_add_co_u32_e32 v40, vcc, 0x50000, v56
	v_cvt_pk_bf16_f32 v1, v2, v2
	s_nop 0
	v_addc_co_u32_e32 v41, vcc, 0, v57, vcc
	v_add_co_u32_e32 v44, vcc, 0x58000, v56
	s_nop 0
	s_nop 0
	v_addc_co_u32_e32 v45, vcc, 0, v57, vcc
	global_load_dwordx4 v[40:43], v[40:41], off
	s_nop 0
	global_load_dwordx4 v[44:47], v[44:45], off
	v_add_co_u32_e32 v48, vcc, 0x60000, v56
	v_lshrrev_b32_e32 v1, 16, v1
	s_nop 0
	v_addc_co_u32_e32 v49, vcc, 0, v57, vcc
	v_add_co_u32_e32 v52, vcc, 0x68000, v56
	v_cvt_pk_bf16_f32 v2, v3, v3
	s_nop 0
	v_addc_co_u32_e32 v53, vcc, 0, v57, vcc
	global_load_dwordx4 v[48:51], v[48:49], off
	s_nop 0
	global_load_dwordx4 v[52:55], v[52:53], off
	v_and_or_b32 v1, v2, s36, v1
	v_cvt_pk_bf16_f32 v2, v4, v4
	v_add_co_u32_e32 v58, vcc, 0x70000, v56
	v_lshrrev_b32_e32 v2, 16, v2
	v_cvt_pk_bf16_f32 v3, v5, v5
	v_addc_co_u32_e32 v59, vcc, 0, v57, vcc
	v_and_or_b32 v2, v3, s36, v2
	v_add_co_u32_e32 v60, vcc, 0x78000, v56
	v_cvt_pk_bf16_f32 v3, v6, v6
	s_nop 0
	v_addc_co_u32_e32 v61, vcc, 0, v57, vcc
	v_lshrrev_b32_e32 v3, 16, v3
	v_cvt_pk_bf16_f32 v4, v7, v7
	global_load_dwordx4 v[56:59], v[58:59], off
	s_nop 0
	global_load_dwordx4 v[60:63], v[60:61], off
	v_add_u32_e32 v76, v81, v82
	v_and_or_b32 v3, v4, s36, v3
	ds_write2_b64 v76, v[0:1], v[2:3] offset1:66
	s_waitcnt vmcnt(13)
	v_cvt_pk_bf16_f32 v0, v8, v8
	v_lshrrev_b32_e32 v0, 16, v0
	v_cvt_pk_bf16_f32 v1, v9, v9
	v_and_or_b32 v0, v1, s36, v0
	v_cvt_pk_bf16_f32 v1, v10, v10
	v_lshrrev_b32_e32 v1, 16, v1
	v_cvt_pk_bf16_f32 v2, v11, v11
	v_and_or_b32 v1, v2, s36, v1
	s_waitcnt vmcnt(12)
	v_cvt_pk_bf16_f32 v2, v12, v12
	v_lshrrev_b32_e32 v2, 16, v2
	v_cvt_pk_bf16_f32 v3, v13, v13
	v_and_or_b32 v2, v3, s36, v2
	v_cvt_pk_bf16_f32 v3, v14, v14
	v_lshrrev_b32_e32 v3, 16, v3
	v_cvt_pk_bf16_f32 v4, v15, v15
	v_and_or_b32 v3, v4, s36, v3
	ds_write2_b64 v76, v[0:1], v[2:3] offset0:132 offset1:198
	s_waitcnt vmcnt(11)
	v_cvt_pk_bf16_f32 v0, v16, v16
	v_lshrrev_b32_e32 v0, 16, v0
	v_cvt_pk_bf16_f32 v1, v17, v17
	v_and_or_b32 v0, v1, s36, v0
	v_cvt_pk_bf16_f32 v1, v18, v18
	v_lshrrev_b32_e32 v1, 16, v1
	v_cvt_pk_bf16_f32 v2, v19, v19
	v_and_or_b32 v1, v2, s36, v1
	s_waitcnt vmcnt(10)
	v_cvt_pk_bf16_f32 v2, v20, v20
	v_lshrrev_b32_e32 v2, 16, v2
	v_cvt_pk_bf16_f32 v3, v21, v21
	v_and_or_b32 v2, v3, s36, v2
	v_cvt_pk_bf16_f32 v3, v22, v22
	v_lshrrev_b32_e32 v3, 16, v3
	v_cvt_pk_bf16_f32 v4, v23, v23
	v_and_or_b32 v3, v4, s36, v3
	v_add_u32_e32 v4, 0x800, v76
	ds_write2_b64 v4, v[0:1], v[2:3] offset0:8 offset1:74
	s_waitcnt vmcnt(9)
	v_cvt_pk_bf16_f32 v0, v24, v24
	v_lshrrev_b32_e32 v0, 16, v0
	v_cvt_pk_bf16_f32 v1, v25, v25
	v_and_or_b32 v0, v1, s36, v0
	v_cvt_pk_bf16_f32 v1, v26, v26
	v_lshrrev_b32_e32 v1, 16, v1
	v_cvt_pk_bf16_f32 v2, v27, v27
	v_and_or_b32 v1, v2, s36, v1
	s_waitcnt vmcnt(8)
	v_cvt_pk_bf16_f32 v2, v28, v28
	v_lshrrev_b32_e32 v2, 16, v2
	v_cvt_pk_bf16_f32 v3, v29, v29
	v_and_or_b32 v2, v3, s36, v2
	v_cvt_pk_bf16_f32 v3, v30, v30
	v_lshrrev_b32_e32 v3, 16, v3
	v_cvt_pk_bf16_f32 v5, v31, v31
	v_and_or_b32 v3, v5, s36, v3
	ds_write2_b64 v4, v[0:1], v[2:3] offset0:140 offset1:206
	s_waitcnt vmcnt(7)
	v_cvt_pk_bf16_f32 v0, v32, v32
	v_lshrrev_b32_e32 v0, 16, v0
	v_cvt_pk_bf16_f32 v1, v33, v33
	v_and_or_b32 v0, v1, s36, v0
	v_cvt_pk_bf16_f32 v1, v34, v34
	v_lshrrev_b32_e32 v1, 16, v1
	v_cvt_pk_bf16_f32 v2, v35, v35
	v_and_or_b32 v1, v2, s36, v1
	s_waitcnt vmcnt(6)
	v_cvt_pk_bf16_f32 v2, v36, v36
	v_lshrrev_b32_e32 v2, 16, v2
	v_cvt_pk_bf16_f32 v3, v37, v37
	v_and_or_b32 v2, v3, s36, v2
	v_cvt_pk_bf16_f32 v3, v38, v38
	v_lshrrev_b32_e32 v3, 16, v3
	v_cvt_pk_bf16_f32 v4, v39, v39
	v_and_or_b32 v3, v4, s36, v3
	v_add_u32_e32 v4, 0x1000, v76
	ds_write2_b64 v4, v[0:1], v[2:3] offset0:16 offset1:82
	s_waitcnt vmcnt(5)
	v_cvt_pk_bf16_f32 v0, v40, v40
	v_lshrrev_b32_e32 v0, 16, v0
	v_cvt_pk_bf16_f32 v1, v41, v41
	v_and_or_b32 v0, v1, s36, v0
	v_cvt_pk_bf16_f32 v1, v42, v42
	v_lshrrev_b32_e32 v1, 16, v1
	v_cvt_pk_bf16_f32 v2, v43, v43
	v_and_or_b32 v1, v2, s36, v1
	s_waitcnt vmcnt(4)
	v_cvt_pk_bf16_f32 v2, v44, v44
	v_lshrrev_b32_e32 v2, 16, v2
	v_cvt_pk_bf16_f32 v3, v45, v45
	v_and_or_b32 v2, v3, s36, v2
	v_cvt_pk_bf16_f32 v3, v46, v46
	v_lshrrev_b32_e32 v3, 16, v3
	v_cvt_pk_bf16_f32 v5, v47, v47
	v_and_or_b32 v3, v5, s36, v3
	ds_write2_b64 v4, v[0:1], v[2:3] offset0:148 offset1:214
	s_waitcnt vmcnt(3)
	v_cvt_pk_bf16_f32 v0, v48, v48
	v_lshrrev_b32_e32 v0, 16, v0
	v_cvt_pk_bf16_f32 v1, v49, v49
	v_and_or_b32 v0, v1, s36, v0
	v_cvt_pk_bf16_f32 v1, v50, v50
	v_lshrrev_b32_e32 v1, 16, v1
	v_cvt_pk_bf16_f32 v2, v51, v51
	v_and_or_b32 v1, v2, s36, v1
	s_waitcnt vmcnt(2)
	v_cvt_pk_bf16_f32 v2, v52, v52
	v_lshrrev_b32_e32 v2, 16, v2
	v_cvt_pk_bf16_f32 v3, v53, v53
	v_and_or_b32 v2, v3, s36, v2
	v_cvt_pk_bf16_f32 v3, v54, v54
	v_lshrrev_b32_e32 v3, 16, v3
	v_cvt_pk_bf16_f32 v4, v55, v55
	v_and_or_b32 v3, v4, s36, v3
	v_add_u32_e32 v4, 0x1800, v76
	ds_write2_b64 v4, v[0:1], v[2:3] offset0:24 offset1:90
	s_waitcnt vmcnt(1)
	v_cvt_pk_bf16_f32 v0, v56, v56
	v_lshrrev_b32_e32 v0, 16, v0
	v_cvt_pk_bf16_f32 v1, v57, v57
	v_and_or_b32 v0, v1, s36, v0
	v_cvt_pk_bf16_f32 v1, v58, v58
	v_lshrrev_b32_e32 v1, 16, v1
	v_cvt_pk_bf16_f32 v2, v59, v59
	v_and_or_b32 v1, v2, s36, v1
	s_waitcnt vmcnt(0)
	v_cvt_pk_bf16_f32 v2, v60, v60
	v_lshrrev_b32_e32 v2, 16, v2
	v_cvt_pk_bf16_f32 v3, v61, v61
	v_and_or_b32 v2, v3, s36, v2
	v_cvt_pk_bf16_f32 v3, v62, v62
	v_lshrrev_b32_e32 v3, 16, v3
	v_cvt_pk_bf16_f32 v5, v63, v63
	v_and_or_b32 v3, v5, s36, v3
	ds_write2_b64 v4, v[0:1], v[2:3] offset0:156 offset1:222
	s_waitcnt lgkmcnt(0)
	ds_read_u16 v2, v84
	ds_read_u16 v8, v84 offset:16
	ds_read_u16 v9, v84 offset:32
	ds_read_u16 v10, v84 offset:48
	ds_read_u16 v11, v84 offset:64
	ds_read_u16 v12, v84 offset:80
	ds_read_u16 v13, v84 offset:96
	ds_read_u16 v14, v84 offset:112
	ds_read_u16 v3, v84 offset:132
	ds_read_u16 v15, v84 offset:148
	ds_read_u16 v16, v84 offset:164
	ds_read_u16 v17, v84 offset:180
	ds_read_u16 v18, v84 offset:196
	ds_read_u16 v19, v84 offset:212
	ds_read_u16 v20, v84 offset:228
	ds_read_u16 v21, v84 offset:244
	s_waitcnt lgkmcnt(7)
	v_lshl_or_b32 v2, v3, 16, v2
	ds_read_u16 v3, v84 offset:264
	ds_read_u16 v22, v84 offset:280
	ds_read_u16 v23, v84 offset:296
	ds_read_u16 v24, v84 offset:312
	ds_read_u16 v25, v84 offset:328
	ds_read_u16 v26, v84 offset:344
	ds_read_u16 v27, v84 offset:360
	ds_read_u16 v28, v84 offset:376
	ds_read_u16 v4, v84 offset:396
	ds_read_u16 v29, v84 offset:412
	ds_read_u16 v30, v84 offset:428
	ds_read_u16 v31, v84 offset:444
	ds_read_u16 v32, v84 offset:460
	ds_read_u16 v33, v84 offset:476
	ds_read_u16 v34, v84 offset:492
	ds_read_u16 v35, v84 offset:508
	s_waitcnt lgkmcnt(7)
	v_lshl_or_b32 v3, v4, 16, v3
	ds_read_u16 v4, v84 offset:528
	ds_read_u16 v36, v84 offset:544
	ds_read_u16 v37, v84 offset:560
	ds_read_u16 v38, v84 offset:576
	ds_read_u16 v39, v84 offset:592
	ds_read_u16 v40, v84 offset:608
	ds_read_u16 v41, v84 offset:624
	ds_read_u16 v42, v84 offset:640
	ds_read_u16 v5, v84 offset:660
	ds_read_u16 v43, v84 offset:676
	ds_read_u16 v44, v84 offset:692
	ds_read_u16 v45, v84 offset:708
	ds_read_u16 v46, v84 offset:724
	ds_read_u16 v47, v84 offset:740
	ds_read_u16 v48, v84 offset:756
	ds_read_u16 v49, v84 offset:772
	s_waitcnt lgkmcnt(7)
	v_lshl_or_b32 v4, v5, 16, v4
	ds_read_u16 v5, v84 offset:792
	ds_read_u16 v50, v84 offset:808
	ds_read_u16 v51, v84 offset:824
	ds_read_u16 v52, v84 offset:840
	ds_read_u16 v53, v84 offset:856
	ds_read_u16 v54, v84 offset:872
	ds_read_u16 v55, v84 offset:888
	ds_read_u16 v56, v84 offset:904
	ds_read_u16 v6, v84 offset:924
	ds_read_u16 v57, v84 offset:940
	ds_read_u16 v58, v84 offset:956
	ds_read_u16 v59, v84 offset:972
	ds_read_u16 v60, v84 offset:988
	ds_read_u16 v61, v84 offset:1004
	ds_read_u16 v62, v84 offset:1020
	ds_read_u16 v63, v84 offset:1036
	s_waitcnt lgkmcnt(7)
	v_lshl_or_b32 v5, v6, 16, v5
	v_add_u32_e32 v6, s0, v83
	v_ashrrev_i32_e32 v7, 31, v6
	v_lshl_add_u64 v[0:1], s[38:39], 1, v[72:73]
	v_lshlrev_b64 v[6:7], 12, v[6:7]
	v_lshl_add_u64 v[6:7], v[0:1], 0, v[6:7]
	global_store_dwordx4 v[6:7], v[2:5], off
	v_add_u32_e32 v6, s0, v85
	v_ashrrev_i32_e32 v7, 31, v6
	v_lshlrev_b64 v[6:7], 12, v[6:7]
	v_lshl_or_b32 v2, v15, 16, v8
	v_lshl_or_b32 v3, v29, 16, v22
	v_lshl_or_b32 v4, v43, 16, v36
	s_waitcnt lgkmcnt(6)
	v_lshl_or_b32 v5, v57, 16, v50
	v_lshl_add_u64 v[6:7], v[0:1], 0, v[6:7]
	global_store_dwordx4 v[6:7], v[2:5], off
	v_add_u32_e32 v6, s0, v86
	v_ashrrev_i32_e32 v7, 31, v6
	v_lshlrev_b64 v[6:7], 12, v[6:7]
	v_lshl_or_b32 v2, v16, 16, v9
	v_lshl_or_b32 v3, v30, 16, v23
	v_lshl_or_b32 v4, v44, 16, v37
	s_waitcnt lgkmcnt(5)
	v_lshl_or_b32 v5, v58, 16, v51
	v_lshl_add_u64 v[6:7], v[0:1], 0, v[6:7]
	global_store_dwordx4 v[6:7], v[2:5], off
	v_add_u32_e32 v6, s0, v87
	v_ashrrev_i32_e32 v7, 31, v6
	v_lshlrev_b64 v[6:7], 12, v[6:7]
	v_lshl_or_b32 v2, v17, 16, v10
	v_lshl_or_b32 v3, v31, 16, v24
	v_lshl_or_b32 v4, v45, 16, v38
	s_waitcnt lgkmcnt(4)
	v_lshl_or_b32 v5, v59, 16, v52
	v_lshl_add_u64 v[6:7], v[0:1], 0, v[6:7]
	global_store_dwordx4 v[6:7], v[2:5], off
	v_add_u32_e32 v6, s0, v88
	v_ashrrev_i32_e32 v7, 31, v6
	v_lshlrev_b64 v[6:7], 12, v[6:7]
	v_lshl_or_b32 v2, v18, 16, v11
	v_lshl_or_b32 v3, v32, 16, v25
	v_lshl_or_b32 v4, v46, 16, v39
	s_waitcnt lgkmcnt(3)
	v_lshl_or_b32 v5, v60, 16, v53
	v_lshl_add_u64 v[6:7], v[0:1], 0, v[6:7]
	global_store_dwordx4 v[6:7], v[2:5], off
	v_add_u32_e32 v6, s0, v89
	v_ashrrev_i32_e32 v7, 31, v6
	v_lshlrev_b64 v[6:7], 12, v[6:7]
	v_lshl_or_b32 v2, v19, 16, v12
	v_lshl_or_b32 v3, v33, 16, v26
	v_lshl_or_b32 v4, v47, 16, v40
	s_waitcnt lgkmcnt(2)
	v_lshl_or_b32 v5, v61, 16, v54
	v_lshl_add_u64 v[6:7], v[0:1], 0, v[6:7]
	global_store_dwordx4 v[6:7], v[2:5], off
	v_add_u32_e32 v6, s0, v90
	v_ashrrev_i32_e32 v7, 31, v6
	v_lshlrev_b64 v[6:7], 12, v[6:7]
	v_lshl_or_b32 v2, v20, 16, v13
	v_lshl_or_b32 v3, v34, 16, v27
	v_lshl_or_b32 v4, v48, 16, v41
	s_waitcnt lgkmcnt(1)
	v_lshl_or_b32 v5, v62, 16, v55
	v_lshl_add_u64 v[6:7], v[0:1], 0, v[6:7]
	global_store_dwordx4 v[6:7], v[2:5], off
	v_add_u32_e32 v6, s0, v91
	v_ashrrev_i32_e32 v7, 31, v6
	v_lshlrev_b64 v[6:7], 12, v[6:7]
	v_lshl_or_b32 v2, v21, 16, v14
	v_lshl_or_b32 v3, v35, 16, v28
	v_lshl_or_b32 v4, v49, 16, v42
	s_waitcnt lgkmcnt(0)
	v_lshl_or_b32 v5, v63, 16, v56
	v_lshl_add_u64 v[0:1], v[0:1], 0, v[6:7]
	global_store_dwordx4 v[0:1], v[2:5], off
	s_waitcnt lgkmcnt(0)

.LBB0_1283:
	s_nop 0
	v_cvt_pk_bf16_f32 v60, v60, v60
	v_lshrrev_b32_e32 v60, 16, v60
	v_cvt_pk_bf16_f32 v61, v61, v61
	v_and_or_b32 v60, v61, s36, v60
	v_cvt_pk_bf16_f32 v61, v62, v62
	v_lshrrev_b32_e32 v61, 16, v61
	v_cvt_pk_bf16_f32 v62, v63, v63
	v_and_or_b32 v61, v62, s36, v61
	v_add_u32_e32 v62, v81, v82
	s_and_b64 vcc, exec, s[0:1]
	ds_write_b64 v62, v[60:61]
	s_cbranch_vccnz .LBB0_1285
	s_ashr_i32 s21, s20, 31
	v_lshl_add_u64 v[60:61], s[20:21], 0, v[66:67]
	v_lshl_add_u64 v[60:61], v[60:61], 2, s[18:19]
	global_load_dword v60, v[60:61], off offset:16
	s_waitcnt vmcnt(0)
	v_pk_mul_f32 v[58:59], v[58:59], v[60:61] op_sel_hi:[1,0]
	v_pk_mul_f32 v[56:57], v[56:57], v[60:61] op_sel_hi:[1,0]
.LBB0_1285:
	s_nop 0
	v_cvt_pk_bf16_f32 v56, v56, v56
	v_lshrrev_b32_e32 v56, 16, v56
	v_cvt_pk_bf16_f32 v57, v57, v57
	v_and_or_b32 v60, v57, s36, v56
	v_cvt_pk_bf16_f32 v56, v58, v58
	v_lshrrev_b32_e32 v56, 16, v56
	v_cvt_pk_bf16_f32 v57, v59, v59
	v_and_or_b32 v61, v57, s36, v56
	v_add_u32_e32 v56, v81, v92
	s_and_b64 vcc, exec, s[0:1]
	ds_write_b64 v56, v[60:61]
	s_cbranch_vccnz .LBB0_1287
	s_ashr_i32 s21, s20, 31
	v_lshl_add_u64 v[58:59], s[20:21], 0, v[66:67]
	v_lshl_add_u64 v[58:59], v[58:59], 2, s[18:19]
	global_load_dword v58, v[58:59], off offset:32
	s_waitcnt vmcnt(0)
	v_pk_mul_f32 v[54:55], v[54:55], v[58:59] op_sel_hi:[1,0]
	v_pk_mul_f32 v[52:53], v[52:53], v[58:59] op_sel_hi:[1,0]
.LBB0_1287:
	s_nop 0
	v_cvt_pk_bf16_f32 v52, v52, v52
	v_lshrrev_b32_e32 v52, 16, v52
	v_cvt_pk_bf16_f32 v53, v53, v53
	v_and_or_b32 v52, v53, s36, v52
	v_cvt_pk_bf16_f32 v53, v54, v54
	v_bfe_u32 v54, v55, 16, 1
	v_lshrrev_b32_e32 v53, 16, v53
	v_add3_u32 v54, v55, v54, s48
	v_and_or_b32 v53, v54, s36, v53
	s_and_b64 vcc, exec, s[0:1]
	ds_write_b64 v56, v[52:53] offset:528
	s_cbranch_vccnz .LBB0_1289
	s_ashr_i32 s21, s20, 31
	v_lshl_add_u64 v[52:53], s[20:21], 0, v[66:67]
	v_lshl_add_u64 v[52:53], v[52:53], 2, s[18:19]
	global_load_dword v52, v[52:53], off offset:48
	s_waitcnt vmcnt(0)
	v_pk_mul_f32 v[50:51], v[50:51], v[52:53] op_sel_hi:[1,0]
	v_pk_mul_f32 v[48:49], v[48:49], v[52:53] op_sel_hi:[1,0]
.LBB0_1289:
	s_nop 0
	v_cvt_pk_bf16_f32 v48, v48, v48
	v_lshrrev_b32_e32 v48, 16, v48
	v_cvt_pk_bf16_f32 v49, v49, v49
	v_and_or_b32 v48, v49, s36, v48
	v_cvt_pk_bf16_f32 v49, v50, v50
	v_bfe_u32 v50, v51, 16, 1
	v_lshrrev_b32_e32 v49, 16, v49
	v_add3_u32 v50, v51, v50, s48
	v_and_or_b32 v49, v50, s36, v49
	s_and_b64 vcc, exec, s[0:1]
	ds_write_b64 v56, v[48:49] offset:1056
	s_cbranch_vccnz .LBB0_1291
	s_ashr_i32 s21, s20, 31
	v_lshl_add_u64 v[48:49], s[20:21], 0, v[66:67]
	v_lshl_add_u64 v[48:49], v[48:49], 2, s[18:19]
	global_load_dword v48, v[48:49], off offset:64
	s_waitcnt vmcnt(0)
	v_pk_mul_f32 v[46:47], v[46:47], v[48:49] op_sel_hi:[1,0]
	v_pk_mul_f32 v[44:45], v[44:45], v[48:49] op_sel_hi:[1,0]
.LBB0_1291:
	s_nop 0
	v_cvt_pk_bf16_f32 v44, v44, v44
	v_lshrrev_b32_e32 v44, 16, v44
	v_cvt_pk_bf16_f32 v45, v45, v45
	v_and_or_b32 v44, v45, s36, v44
	v_cvt_pk_bf16_f32 v45, v46, v46
	v_bfe_u32 v46, v47, 16, 1
	v_lshrrev_b32_e32 v45, 16, v45
	v_add3_u32 v46, v47, v46, s48
	v_and_or_b32 v45, v46, s36, v45
	s_and_b64 vcc, exec, s[0:1]
	ds_write_b64 v56, v[44:45] offset:1584
	s_cbranch_vccnz .LBB0_1293
	s_ashr_i32 s21, s20, 31
	v_lshl_add_u64 v[44:45], s[20:21], 0, v[66:67]
	v_lshl_add_u64 v[44:45], v[44:45], 2, s[18:19]
	global_load_dword v44, v[44:45], off offset:80
	s_waitcnt vmcnt(0)
	v_pk_mul_f32 v[42:43], v[42:43], v[44:45] op_sel_hi:[1,0]
	v_pk_mul_f32 v[40:41], v[40:41], v[44:45] op_sel_hi:[1,0]
.LBB0_1293:
	s_nop 0
	v_cvt_pk_bf16_f32 v40, v40, v40
	v_lshrrev_b32_e32 v40, 16, v40
	v_cvt_pk_bf16_f32 v41, v41, v41
	v_and_or_b32 v40, v41, s36, v40
	v_cvt_pk_bf16_f32 v41, v42, v42
	v_bfe_u32 v42, v43, 16, 1
	v_lshrrev_b32_e32 v41, 16, v41
	v_add3_u32 v42, v43, v42, s48
	v_and_or_b32 v41, v42, s36, v41
	s_and_b64 vcc, exec, s[0:1]
	ds_write_b64 v56, v[40:41] offset:2112
	s_cbranch_vccnz .LBB0_1295
	s_ashr_i32 s21, s20, 31
	v_lshl_add_u64 v[40:41], s[20:21], 0, v[66:67]
	v_lshl_add_u64 v[40:41], v[40:41], 2, s[18:19]
	global_load_dword v40, v[40:41], off offset:96
	s_waitcnt vmcnt(0)
	v_pk_mul_f32 v[38:39], v[38:39], v[40:41] op_sel_hi:[1,0]
	v_pk_mul_f32 v[36:37], v[36:37], v[40:41] op_sel_hi:[1,0]
.LBB0_1295:
	s_nop 0
	v_cvt_pk_bf16_f32 v36, v36, v36
	v_lshrrev_b32_e32 v36, 16, v36
	v_cvt_pk_bf16_f32 v37, v37, v37
	v_and_or_b32 v36, v37, s36, v36
	v_cvt_pk_bf16_f32 v37, v38, v38
	v_bfe_u32 v38, v39, 16, 1
	v_lshrrev_b32_e32 v37, 16, v37
	v_add3_u32 v38, v39, v38, s48
	v_and_or_b32 v37, v38, s36, v37
	s_and_b64 vcc, exec, s[0:1]
	ds_write_b64 v56, v[36:37] offset:2640
	s_cbranch_vccnz .LBB0_1297
	s_ashr_i32 s21, s20, 31
	v_lshl_add_u64 v[36:37], s[20:21], 0, v[66:67]
	v_lshl_add_u64 v[36:37], v[36:37], 2, s[18:19]
	global_load_dword v36, v[36:37], off offset:112
	s_waitcnt vmcnt(0)
	v_pk_mul_f32 v[34:35], v[34:35], v[36:37] op_sel_hi:[1,0]
	v_pk_mul_f32 v[32:33], v[32:33], v[36:37] op_sel_hi:[1,0]
.LBB0_1297:
	s_nop 0
	v_cvt_pk_bf16_f32 v32, v32, v32
	v_lshrrev_b32_e32 v32, 16, v32
	v_cvt_pk_bf16_f32 v33, v33, v33
	v_and_or_b32 v32, v33, s36, v32
	v_cvt_pk_bf16_f32 v33, v34, v34
	v_bfe_u32 v34, v35, 16, 1
	v_lshrrev_b32_e32 v33, 16, v33
	v_add3_u32 v34, v35, v34, s48
	v_and_or_b32 v33, v34, s36, v33
	s_and_b64 vcc, exec, s[0:1]
	ds_write_b64 v56, v[32:33] offset:3168
	s_cbranch_vccnz .LBB0_1299
	s_ashr_i32 s21, s20, 31
	v_lshl_add_u64 v[32:33], s[20:21], 0, v[66:67]
	v_lshl_add_u64 v[32:33], v[32:33], 2, s[18:19]
	global_load_dword v32, v[32:33], off offset:128
	s_waitcnt vmcnt(0)
	v_pk_mul_f32 v[30:31], v[30:31], v[32:33] op_sel_hi:[1,0]
	v_pk_mul_f32 v[28:29], v[28:29], v[32:33] op_sel_hi:[1,0]
.LBB0_1299:
	s_nop 0
	v_cvt_pk_bf16_f32 v28, v28, v28
	v_lshrrev_b32_e32 v28, 16, v28
	v_cvt_pk_bf16_f32 v29, v29, v29
	v_and_or_b32 v28, v29, s36, v28
	v_cvt_pk_bf16_f32 v29, v30, v30
	v_bfe_u32 v30, v31, 16, 1
	v_lshrrev_b32_e32 v29, 16, v29
	v_add3_u32 v30, v31, v30, s48
	v_and_or_b32 v29, v30, s36, v29
	s_and_b64 vcc, exec, s[0:1]
	ds_write_b64 v56, v[28:29] offset:3696
	s_cbranch_vccnz .LBB0_1301
	s_ashr_i32 s21, s20, 31
	v_lshl_add_u64 v[28:29], s[20:21], 0, v[66:67]
	v_lshl_add_u64 v[28:29], v[28:29], 2, s[18:19]
	global_load_dword v28, v[28:29], off offset:144
	s_waitcnt vmcnt(0)
	v_pk_mul_f32 v[26:27], v[26:27], v[28:29] op_sel_hi:[1,0]
	v_pk_mul_f32 v[24:25], v[24:25], v[28:29] op_sel_hi:[1,0]
.LBB0_1301:
	s_nop 0
	v_cvt_pk_bf16_f32 v24, v24, v24
	v_lshrrev_b32_e32 v24, 16, v24
	v_cvt_pk_bf16_f32 v25, v25, v25
	v_and_or_b32 v24, v25, s36, v24
	v_cvt_pk_bf16_f32 v25, v26, v26
	v_bfe_u32 v26, v27, 16, 1
	v_lshrrev_b32_e32 v25, 16, v25
	v_add3_u32 v26, v27, v26, s48
	v_and_or_b32 v25, v26, s36, v25
	s_and_b64 vcc, exec, s[0:1]
	ds_write_b64 v56, v[24:25] offset:4224
	s_cbranch_vccnz .LBB0_1303
	s_ashr_i32 s21, s20, 31
	v_lshl_add_u64 v[24:25], s[20:21], 0, v[66:67]
	v_lshl_add_u64 v[24:25], v[24:25], 2, s[18:19]
	global_load_dword v24, v[24:25], off offset:160
	s_waitcnt vmcnt(0)
	v_pk_mul_f32 v[22:23], v[22:23], v[24:25] op_sel_hi:[1,0]
	v_pk_mul_f32 v[20:21], v[20:21], v[24:25] op_sel_hi:[1,0]
.LBB0_1303:
	s_nop 0
	v_cvt_pk_bf16_f32 v20, v20, v20
	v_lshrrev_b32_e32 v20, 16, v20
	v_cvt_pk_bf16_f32 v21, v21, v21
	v_and_or_b32 v20, v21, s36, v20
	v_cvt_pk_bf16_f32 v21, v22, v22
	v_bfe_u32 v22, v23, 16, 1
	v_lshrrev_b32_e32 v21, 16, v21
	v_add3_u32 v22, v23, v22, s48
	v_and_or_b32 v21, v22, s36, v21
	s_and_b64 vcc, exec, s[0:1]
	ds_write_b64 v56, v[20:21] offset:4752
	s_cbranch_vccnz .LBB0_1305
	s_ashr_i32 s21, s20, 31
	v_lshl_add_u64 v[20:21], s[20:21], 0, v[66:67]
	v_lshl_add_u64 v[20:21], v[20:21], 2, s[18:19]
	global_load_dword v20, v[20:21], off offset:176
	s_waitcnt vmcnt(0)
	v_pk_mul_f32 v[18:19], v[18:19], v[20:21] op_sel_hi:[1,0]
	v_pk_mul_f32 v[16:17], v[16:17], v[20:21] op_sel_hi:[1,0]
.LBB0_1305:
	s_nop 0
	v_cvt_pk_bf16_f32 v16, v16, v16
	v_lshrrev_b32_e32 v16, 16, v16
	v_cvt_pk_bf16_f32 v17, v17, v17
	v_and_or_b32 v16, v17, s36, v16
	v_cvt_pk_bf16_f32 v17, v18, v18
	v_bfe_u32 v18, v19, 16, 1
	v_lshrrev_b32_e32 v17, 16, v17
	v_add3_u32 v18, v19, v18, s48
	v_and_or_b32 v17, v18, s36, v17
	s_and_b64 vcc, exec, s[0:1]
	ds_write_b64 v56, v[16:17] offset:5280
	s_cbranch_vccnz .LBB0_1307
	s_ashr_i32 s21, s20, 31
	v_lshl_add_u64 v[16:17], s[20:21], 0, v[66:67]
	v_lshl_add_u64 v[16:17], v[16:17], 2, s[18:19]
	global_load_dword v16, v[16:17], off offset:192
	s_waitcnt vmcnt(0)
	v_pk_mul_f32 v[14:15], v[14:15], v[16:17] op_sel_hi:[1,0]
	v_pk_mul_f32 v[12:13], v[12:13], v[16:17] op_sel_hi:[1,0]
.LBB0_1307:
	s_waitcnt vmcnt(0)
	v_cvt_pk_bf16_f32 v12, v12, v12
	v_lshrrev_b32_e32 v12, 16, v12
	v_cvt_pk_bf16_f32 v13, v13, v13
	v_and_or_b32 v12, v13, s36, v12
	v_cvt_pk_bf16_f32 v13, v14, v14
	v_bfe_u32 v14, v15, 16, 1
	v_lshrrev_b32_e32 v13, 16, v13
	v_add3_u32 v14, v15, v14, s48
	v_and_or_b32 v13, v14, s36, v13
	s_and_b64 vcc, exec, s[0:1]
	ds_write_b64 v56, v[12:13] offset:5808
	s_cbranch_vccnz .LBB0_1309
	s_ashr_i32 s21, s20, 31
	v_lshl_add_u64 v[12:13], s[20:21], 0, v[66:67]
	v_lshl_add_u64 v[12:13], v[12:13], 2, s[18:19]
	global_load_dword v12, v[12:13], off offset:208
	s_waitcnt vmcnt(0)
	v_pk_mul_f32 v[10:11], v[10:11], v[12:13] op_sel_hi:[1,0]
	v_pk_mul_f32 v[8:9], v[8:9], v[12:13] op_sel_hi:[1,0]
.LBB0_1309:
	s_nop 0
	v_cvt_pk_bf16_f32 v8, v8, v8
	v_lshrrev_b32_e32 v8, 16, v8
	v_cvt_pk_bf16_f32 v9, v9, v9
	v_and_or_b32 v8, v9, s36, v8
	v_cvt_pk_bf16_f32 v9, v10, v10
	v_lshrrev_b32_e32 v9, 16, v9
	v_cvt_pk_bf16_f32 v10, v11, v11
	v_and_or_b32 v9, v10, s36, v9
	s_and_b64 vcc, exec, s[0:1]
	ds_write_b64 v56, v[8:9] offset:6336
	s_cbranch_vccnz .LBB0_1311
	s_ashr_i32 s21, s20, 31
	v_lshl_add_u64 v[8:9], s[20:21], 0, v[66:67]
	v_lshl_add_u64 v[8:9], v[8:9], 2, s[18:19]
	global_load_dword v8, v[8:9], off offset:224
	s_waitcnt vmcnt(0)
	v_pk_mul_f32 v[6:7], v[6:7], v[8:9] op_sel_hi:[1,0]
	v_pk_mul_f32 v[4:5], v[4:5], v[8:9] op_sel_hi:[1,0]
.LBB0_1311:
	s_nop 0
	v_cvt_pk_bf16_f32 v4, v4, v4
	v_lshrrev_b32_e32 v4, 16, v4
	v_cvt_pk_bf16_f32 v5, v5, v5
	v_and_or_b32 v4, v5, s36, v4
	v_cvt_pk_bf16_f32 v5, v6, v6
	v_readlane_b32 s0, v255, 22
	v_lshrrev_b32_e32 v5, 16, v5
	v_cvt_pk_bf16_f32 v6, v7, v7
	v_readlane_b32 s1, v255, 23
	v_and_or_b32 v5, v6, s36, v5
	s_and_b64 vcc, exec, s[0:1]
	ds_write_b64 v56, v[4:5] offset:6864
	s_cbranch_vccz .LBB0_1313
	s_ashr_i32 s21, s20, 31
	v_lshl_add_u64 v[4:5], s[20:21], 0, v[66:67]
	v_lshl_add_u64 v[4:5], v[4:5], 2, s[18:19]
	global_load_dword v4, v[4:5], off offset:240
	s_waitcnt vmcnt(0)
	v_pk_mul_f32 v[6:7], v[2:3], v[4:5] op_sel_hi:[1,0]
	v_pk_mul_f32 v[4:5], v[0:1], v[4:5] op_sel_hi:[1,0]
	s_cbranch_execnz .LBB0_1200
	s_branch .LBB0_1199

.LBB0_1528:
	s_or_b64 exec, exec, s[16:17]
	v_bfi_b32 v1, s49, v2, v1
	v_mul_f32_e32 v0, 0.5, v0
	v_add_f32_e32 v1, 1.0, v1
	v_mul_f32_e32 v0, v0, v1
	s_add_u32 s14, s14, 0x4000
	s_addc_u32 s15, s15, 0
	v_cvt_pk_bf16_f32 v2, v0, v0
	v_lshl_add_u64 v[0:1], s[6:7], 0, v[58:59]
	v_lshl_add_u64 v[62:63], v[62:63], 0, s[50:51]
	v_lshl_add_u64 v[60:61], v[60:61], 0, s[40:41]
	v_lshl_add_u64 v[58:59], v[58:59], 0, s[40:41]
	s_cmp_eq_u32 s14, 0x20000
	v_lshl_add_u64 v[56:57], v[56:57], 0, s[96:97]
	global_store_short_d16_hi v[0:1], v2, off
	s_cbranch_scc1 .LBB0_1526

.LBB0_1535:
	v_lshl_add_u64 v[100:101], s[14:15], 0, v[96:97]
	v_add_co_u32_e32 v98, vcc, 0x33812000, v100
	s_mov_b32 s0, 0x2d772000
	s_nop 1
	v_addc_co_u32_e32 v99, vcc, 0, v101, vcc
	v_add_co_u32_e32 v102, vcc, 0x326f2000, v100
	global_load_dwordx4 v[108:111], v[98:99], off
	s_nop 1
	v_addc_co_u32_e32 v103, vcc, 0, v101, vcc
	global_load_dwordx4 v[112:115], v[102:103], off
	v_add_co_u32_e32 v104, vcc, s5, v100
	s_nop 1
	v_addc_co_u32_e32 v105, vcc, 0, v101, vcc
	global_load_dwordx4 v[116:119], v[104:105], off
	global_load_dwordx4 v[120:123], v[4:5], off offset:16
	global_load_dwordx4 v[124:127], v[4:5], off
	v_add_co_u32_e32 v98, vcc, s3, v100
	s_nop 1
	v_addc_co_u32_e32 v99, vcc, 0, v101, vcc
	global_load_dwordx4 v[128:131], v[98:99], off
	v_add_co_u32_e32 v98, vcc, s0, v100
	s_nop 1
	v_addc_co_u32_e32 v99, vcc, 0, v101, vcc
	global_load_dwordx4 v[132:135], v[98:99], off
	s_mov_b32 s0, 0x2c652000
	v_add_co_u32_e32 v98, vcc, s0, v100
	s_nop 1
	v_addc_co_u32_e32 v99, vcc, 0, v101, vcc
	v_lshl_add_u64 v[100:101], s[6:7], 0, v[96:97]
	s_mov_b32 s0, 0x1ec01000
	v_add_co_u32_e32 v104, vcc, s0, v100
	global_load_dwordx4 v[138:141], v[98:99], off
	s_nop 1
	v_addc_co_u32_e32 v105, vcc, 0, v101, vcc
	s_mov_b32 s0, 0x1ec02000
	v_add_co_u32_e32 v100, vcc, s0, v100
	global_load_dwordx4 v[142:145], v[104:105], off offset:3584
	s_nop 1
	v_addc_co_u32_e32 v101, vcc, 0, v101, vcc
	global_load_dwordx4 v[146:149], v[100:101], off offset:2592
	global_load_dwordx4 v[150:153], v[6:7], off offset:16
	global_load_dwordx4 v[154:157], v[6:7], off
	global_load_dwordx4 v[158:161], v[8:9], off offset:16
	global_load_dwordx4 v[162:165], v[8:9], off
	v_lshl_add_u64 v[10:11], s[14:15], 0, v[96:97]
	v_add_co_u32_e32 v0, vcc, 0x33812000, v10
	s_mov_b32 s0, 0x2d772000
	s_nop 0
	v_addc_co_u32_e32 v1, vcc, 0, v11, vcc
	v_add_co_u32_e32 v12, vcc, 0x326f2000, v10
	s_waitcnt vmcnt(0)
	v_mov_b64_e32 v[0:1], v[108:109]
	v_mov_b64_e32 v[2:3], v[110:111]
	s_nop 0
	v_addc_co_u32_e32 v13, vcc, 0, v11, vcc
	v_mov_b64_e32 v[18:19], v[112:113]
	v_mov_b64_e32 v[20:21], v[114:115]
	s_add_i32 s4, s4, s2
	s_waitcnt vmcnt(1)
	v_lshlrev_b32_e32 v37, 16, v2
	v_lshlrev_b32_e32 v36, 16, v0
	v_and_b32_e32 v39, 0xffff0000, v2
	s_waitcnt vmcnt(0)
	v_lshlrev_b32_e32 v12, 16, v18
	v_and_b32_e32 v13, 0xffff0000, v18
	v_add_co_u32_e32 v18, vcc, s5, v10
	v_lshlrev_b32_e32 v30, 16, v19
	v_and_b32_e32 v31, 0xffff0000, v19
	v_addc_co_u32_e32 v19, vcc, 0, v11, vcc
	v_lshlrev_b32_e32 v32, 16, v20
	v_and_b32_e32 v33, 0xffff0000, v20
	v_lshlrev_b32_e32 v34, 16, v21
	v_and_b32_e32 v35, 0xffff0000, v21
	v_mov_b64_e32 v[18:19], v[116:117]
	v_mov_b64_e32 v[20:21], v[118:119]
	s_nop 0
	v_mov_b64_e32 v[22:23], v[120:121]
	v_mov_b64_e32 v[24:25], v[122:123]
	v_mov_b64_e32 v[26:27], v[124:125]
	v_mov_b64_e32 v[28:29], v[126:127]
	v_and_b32_e32 v38, 0xffff0000, v0
	v_lshlrev_b32_e32 v41, 16, v3
	v_lshlrev_b32_e32 v40, 16, v1
	v_and_b32_e32 v2, 0xffff0000, v1
	v_pk_add_f32 v[0:1], v[36:37], v[38:39]
	v_and_b32_e32 v3, 0xffff0000, v3
	v_pk_add_f32 v[0:1], v[0:1], v[40:41]
	s_nop 0
	v_pk_add_f32 v[0:1], v[0:1], v[2:3]
	s_nop 0
	v_add_f32_e32 v0, v0, v1
	ds_bpermute_b32 v1, v14, v0
	s_waitcnt lgkmcnt(0)
	v_add_f32_e32 v0, v0, v1
	ds_bpermute_b32 v1, v15, v0
	s_waitcnt lgkmcnt(0)
	v_add_f32_e32 v0, v0, v1
	ds_bpermute_b32 v1, v16, v0
	s_waitcnt lgkmcnt(0)
	v_add_f32_e32 v0, v0, v1
	v_fmac_f32_e32 v38, 0xbc800000, v0
	v_fmac_f32_e32 v39, 0xbc800000, v0
	v_fmac_f32_e32 v36, 0xbc800000, v0
	v_fmac_f32_e32 v37, 0xbc800000, v0
	v_mov_b32_e32 v1, v39
	v_mov_b32_e32 v43, v38
	v_pk_mul_f32 v[38:39], v[38:39], v[38:39]
	v_fmac_f32_e32 v2, 0xbc800000, v0
	v_fmac_f32_e32 v40, 0xbc800000, v0
	v_fmac_f32_e32 v3, 0xbc800000, v0
	v_fmac_f32_e32 v41, 0xbc800000, v0
	v_mov_b32_e32 v0, v37
	v_mov_b32_e32 v42, v36
	v_pk_fma_f32 v[36:37], v[36:37], v[36:37], v[38:39]
	v_mov_b32_e32 v39, v3
	v_pk_fma_f32 v[36:37], v[40:41], v[40:41], v[36:37]
	v_mov_b32_e32 v45, v2
	v_pk_fma_f32 v[2:3], v[2:3], v[2:3], v[36:37]
	v_mov_b32_e32 v44, v40
	v_add_f32_e32 v2, v2, v3
	ds_bpermute_b32 v3, v14, v2
	v_mov_b32_e32 v38, v41
	s_waitcnt lgkmcnt(0)
	v_add_f32_e32 v2, v2, v3
	ds_bpermute_b32 v3, v15, v2
	s_waitcnt lgkmcnt(0)
	v_add_f32_e32 v2, v2, v3
	ds_bpermute_b32 v3, v16, v2
	s_waitcnt lgkmcnt(0)
	v_add_f32_e32 v2, v2, v3
	v_fmamk_f32 v2, v2, 0x3c800000, v231
	v_cmp_gt_f32_e32 vcc, s45, v2
	v_mul_f32_e32 v3, 0x4b800000, v2
	s_nop 0
	v_cndmask_b32_e32 v2, v2, v3, vcc
	v_rsq_f32_e32 v2, v2
	s_nop 0
	v_mul_f32_e32 v3, 0x45800000, v2
	v_cndmask_b32_e32 v2, v2, v3, vcc
	v_pk_mul_f32 v[36:37], v[44:45], v[2:3] op_sel_hi:[1,0]
	v_pk_mul_f32 v[40:41], v[42:43], v[2:3] op_sel_hi:[1,0]
	v_pk_mul_f32 v[0:1], v[0:1], v[2:3] op_sel_hi:[1,0]
	s_waitcnt vmcnt(0)
	v_pk_fma_f32 v[12:13], v[26:27], v[40:41], v[12:13]
	v_pk_fma_f32 v[26:27], v[28:29], v[36:37], v[30:31]
	v_pk_mul_f32 v[28:29], v[38:39], v[2:3] op_sel_hi:[1,0]
	v_pk_fma_f32 v[0:1], v[22:23], v[0:1], v[32:33]
	v_pk_fma_f32 v[2:3], v[24:25], v[28:29], v[34:35]
	v_lshlrev_b32_e32 v23, 16, v19
	v_lshlrev_b32_e32 v22, 16, v18
	v_mov_b32_e32 v24, v12
	v_mov_b32_e32 v25, v26
	v_and_b32_e32 v19, 0xffff0000, v19
	v_and_b32_e32 v18, 0xffff0000, v18
	v_mov_b32_e32 v26, v13
	v_pk_mul_f32 v[22:23], v[24:25], v[22:23]
	v_pk_mul_f32 v[12:13], v[26:27], v[18:19]
	v_lshlrev_b32_e32 v19, 16, v21
	v_lshlrev_b32_e32 v18, 16, v20
	v_mov_b32_e32 v25, v2
	v_and_b32_e32 v21, 0xffff0000, v21
	v_and_b32_e32 v20, 0xffff0000, v20
	v_mov_b32_e32 v2, v1
	v_mov_b32_e32 v24, v0
	v_pk_mul_f32 v[0:1], v[2:3], v[20:21]
	v_pk_mul_f32 v[18:19], v[24:25], v[18:19]
	v_cvt_pk_bf16_f32 v12, v12, v12
	v_cvt_pk_bf16_f32 v13, v13, v13
	v_cvt_pk_bf16_f32 v0, v0, v0
	v_cvt_pk_bf16_f32 v1, v1, v1
	v_cvt_pk_bf16_f32 v19, v19, v19
	v_cvt_pk_bf16_f32 v18, v18, v18
	v_cvt_pk_bf16_f32 v3, v23, v23
	v_cvt_pk_bf16_f32 v2, v22, v22
	v_lshrrev_b32_e32 v20, 16, v2
	v_lshrrev_b32_e32 v21, 16, v3
	v_lshrrev_b32_e32 v2, 16, v18
	v_lshrrev_b32_e32 v3, 16, v19
	v_and_or_b32 v3, v1, s36, v3
	v_and_or_b32 v2, v0, s36, v2
	v_and_or_b32 v1, v13, s36, v21
	v_and_or_b32 v0, v12, s36, v20
	v_lshl_add_u64 v[12:13], s[10:11], 0, v[96:97]
	v_add_co_u32_e32 v12, vcc, s18, v12
	s_add_u32 s10, s10, s12
	s_nop 0
	v_addc_co_u32_e32 v13, vcc, 0, v13, vcc
	global_store_dwordx4 v[12:13], v[0:3], off
	s_addc_u32 s11, s11, s13
	s_add_u32 s14, s14, s16
	v_add_co_u32_e32 v0, vcc, s3, v10
	s_addc_u32 s15, s15, s17
	s_nop 0
	v_addc_co_u32_e32 v1, vcc, 0, v11, vcc
	v_mov_b64_e32 v[0:1], v[128:129]
	v_mov_b64_e32 v[2:3], v[130:131]
	s_waitcnt vmcnt(0)
	v_lshlrev_b32_e32 v42, 16, v0
	v_and_b32_e32 v44, 0xffff0000, v0
	v_add_co_u32_e32 v0, vcc, s0, v10
	v_lshlrev_b32_e32 v43, 16, v1
	v_and_b32_e32 v45, 0xffff0000, v1
	v_addc_co_u32_e32 v1, vcc, 0, v11, vcc
	v_lshlrev_b32_e32 v46, 16, v2
	v_and_b32_e32 v48, 0xffff0000, v2
	v_lshlrev_b32_e32 v47, 16, v3
	v_and_b32_e32 v49, 0xffff0000, v3
	v_mov_b64_e32 v[0:1], v[132:133]
	v_mov_b64_e32 v[2:3], v[134:135]
	s_mov_b32 s0, 0x2c652000
	s_waitcnt vmcnt(0)
	v_lshlrev_b32_e32 v50, 16, v0
	v_and_b32_e32 v52, 0xffff0000, v0
	v_add_co_u32_e32 v0, vcc, s0, v10
	v_lshlrev_b32_e32 v51, 16, v1
	v_and_b32_e32 v53, 0xffff0000, v1
	v_addc_co_u32_e32 v1, vcc, 0, v11, vcc
	v_lshl_add_u64 v[10:11], s[6:7], 0, v[96:97]
	s_mov_b32 s0, 0x1ec01000
	v_add_co_u32_e32 v18, vcc, s0, v10
	v_lshlrev_b32_e32 v54, 16, v2
	v_and_b32_e32 v56, 0xffff0000, v2
	v_lshlrev_b32_e32 v55, 16, v3
	v_and_b32_e32 v57, 0xffff0000, v3
	v_mov_b64_e32 v[0:1], v[138:139]
	v_mov_b64_e32 v[2:3], v[140:141]
	v_addc_co_u32_e32 v19, vcc, 0, v11, vcc
	s_mov_b32 s0, 0x1ec02000
	v_add_co_u32_e32 v10, vcc, s0, v10
	v_mov_b64_e32 v[18:19], v[142:143]
	v_mov_b64_e32 v[20:21], v[144:145]
	s_nop 0
	v_addc_co_u32_e32 v11, vcc, 0, v11, vcc
	v_mov_b64_e32 v[22:23], v[146:147]
	v_mov_b64_e32 v[24:25], v[148:149]
	v_mov_b64_e32 v[26:27], v[150:151]
	v_mov_b64_e32 v[28:29], v[152:153]
	v_mov_b64_e32 v[30:31], v[154:155]
	v_mov_b64_e32 v[32:33], v[156:157]
	v_mov_b64_e32 v[34:35], v[158:159]
	v_mov_b64_e32 v[36:37], v[160:161]
	v_mov_b64_e32 v[38:39], v[162:163]
	v_mov_b64_e32 v[40:41], v[164:165]
	v_pk_add_f32 v[10:11], v[42:43], v[50:51]
	v_pk_add_f32 v[42:43], v[44:45], v[52:53]
	v_mov_b32_e32 v73, v10
	v_mov_b32_e32 v75, v42
	v_mov_b32_e32 v50, v43
	v_mov_b32_e32 v51, v11
	v_pk_mul_f32 v[50:51], v[50:51], v[50:51]
	s_add_u32 s6, s6, s8
	s_addc_u32 s7, s7, s9
	s_cmpk_lt_i32 s4, 0xc00
	s_waitcnt vmcnt(6)
	v_and_b32_e32 v69, 0xffff0000, v1
	v_and_b32_e32 v68, 0xffff0000, v0
	v_mov_b32_e32 v74, v68
	v_pk_mul_f32 v[74:75], v[74:75], v[74:75]
	v_and_b32_e32 v80, 0xffff0000, v2
	s_waitcnt vmcnt(4)
	v_lshlrev_b32_e32 v70, 16, v22
	s_waitcnt vmcnt(3)
	v_mov_b32_e32 v67, v28
	v_mov_b32_e32 v28, v27
	v_lshlrev_b32_e32 v27, 16, v1
	v_mov_b32_e32 v66, v26
	v_lshlrev_b32_e32 v26, 16, v0
	v_mov_b32_e32 v0, v69
	v_mov_b32_e32 v1, v27
	v_pk_mul_f32 v[0:1], v[0:1], v[0:1]
	v_mov_b32_e32 v72, v26
	v_pk_fma_f32 v[72:73], v[72:73], v[72:73], v[74:75]
	v_mov_b32_e32 v74, v1
	v_mul_f32_e32 v1, 0xbfb8aa3b, v70
	v_exp_f32_e32 v1, v1
	v_and_b32_e32 v22, 0xffff0000, v22
	v_mov_b32_e32 v75, v51
	v_pk_add_f32 v[72:73], v[74:75], v[72:73]
	v_add_f32_e32 v1, 1.0, v1
	v_rcp_f32_e32 v74, v1
	v_mul_f32_e32 v1, 0xbfb8aa3b, v22
	v_exp_f32_e32 v1, v1
	v_lshlrev_b32_e32 v71, 16, v23
	v_and_b32_e32 v23, 0xffff0000, v23
	v_lshlrev_b32_e32 v82, 16, v24
	v_add_f32_e32 v1, 1.0, v1
	v_rcp_f32_e32 v76, v1
	v_mul_f32_e32 v1, 0xbfb8aa3b, v71
	v_exp_f32_e32 v1, v1
	v_and_b32_e32 v24, 0xffff0000, v24
	v_lshlrev_b32_e32 v45, 16, v19
	v_lshlrev_b32_e32 v44, 16, v18
	v_add_f32_e32 v1, 1.0, v1
	v_rcp_f32_e32 v75, v1
	v_mul_f32_e32 v1, 0xbfb8aa3b, v23
	v_exp_f32_e32 v1, v1
	v_and_b32_e32 v18, 0xffff0000, v18
	v_mul_f32_e32 v53, 0xbfb8aa3b, v18
	s_waitcnt vmcnt(2)
	v_mov_b32_e32 v60, v30
	v_add_f32_e32 v1, 1.0, v1
	v_rcp_f32_e32 v77, v1
	v_mul_f32_e32 v1, 0xbfb8aa3b, v82
	v_exp_f32_e32 v1, v1
	v_mul_f32_e32 v30, 0xbfb8aa3b, v45
	v_exp_f32_e32 v53, v53
	v_exp_f32_e32 v30, v30
	v_add_f32_e32 v1, 1.0, v1
	v_rcp_f32_e32 v86, v1
	v_mul_f32_e32 v1, 0xbfb8aa3b, v24
	v_exp_f32_e32 v1, v1
	v_lshlrev_b32_e32 v83, 16, v25
	v_and_b32_e32 v19, 0xffff0000, v19
	v_add_f32_e32 v53, 1.0, v53
	v_add_f32_e32 v1, 1.0, v1
	v_rcp_f32_e32 v88, v1
	v_mul_f32_e32 v1, 0xbfb8aa3b, v83
	v_exp_f32_e32 v1, v1
	v_add_f32_e32 v30, 1.0, v30
	v_rcp_f32_e32 v58, v53
	v_rcp_f32_e32 v53, v30
	v_mul_f32_e32 v30, 0xbfb8aa3b, v19
	v_exp_f32_e32 v30, v30
	v_and_b32_e32 v25, 0xffff0000, v25
	v_add_f32_e32 v1, 1.0, v1
	v_rcp_f32_e32 v87, v1
	v_mul_f32_e32 v1, 0xbfb8aa3b, v25
	v_exp_f32_e32 v1, v1
	v_add_f32_e32 v30, 1.0, v30
	v_mov_b32_e32 v61, v32
	v_mov_b32_e32 v32, v31
	v_rcp_f32_e32 v59, v30
	v_pk_add_f32 v[30:31], v[46:47], v[54:55]
	v_pk_add_f32 v[46:47], v[48:49], v[56:57]
	s_waitcnt vmcnt(0)
	v_mov_b32_e32 v78, v38
	v_lshlrev_b32_e32 v38, 16, v2
	v_mov_b32_e32 v54, v46
	v_mov_b32_e32 v55, v30
	v_mov_b32_e32 v79, v40
	v_mov_b32_e32 v40, v39
	v_lshlrev_b32_e32 v39, 16, v3
	v_and_b32_e32 v81, 0xffff0000, v3
	v_mov_b32_e32 v2, v80
	v_mov_b32_e32 v3, v38
	v_add_f32_e32 v1, 1.0, v1
	v_pk_mul_f32 v[54:55], v[54:55], v[54:55]
	v_pk_mul_f32 v[2:3], v[2:3], v[2:3]
	v_rcp_f32_e32 v89, v1
	v_mov_b32_e32 v1, v50
	v_mov_b32_e32 v56, v47
	v_mov_b32_e32 v57, v31
	v_mov_b32_e32 v84, v81
	v_mov_b32_e32 v85, v39
	v_pk_add_f32 v[0:1], v[0:1], v[72:73]
	v_mov_b32_e32 v50, v3
	v_mov_b32_e32 v51, v55
	v_pk_mul_f32 v[56:57], v[56:57], v[56:57]
	v_pk_mul_f32 v[84:85], v[84:85], v[84:85]
	v_pk_add_f32 v[0:1], v[50:51], v[0:1]
	v_mov_b32_e32 v3, v54
	v_pk_add_f32 v[0:1], v[2:3], v[0:1]
	v_mov_b32_e32 v2, v85
	v_mov_b32_e32 v3, v57
	v_pk_add_f32 v[0:1], v[2:3], v[0:1]
	v_mov_b32_e32 v85, v56
	v_pk_add_f32 v[0:1], v[84:85], v[0:1]
	ds_bpermute_b32 v3, v14, v1
	ds_bpermute_b32 v2, v14, v0
	v_lshlrev_b32_e32 v48, 16, v20
	v_and_b32_e32 v20, 0xffff0000, v20
	v_mul_f32_e32 v63, 0xbfb8aa3b, v20
	v_exp_f32_e32 v63, v63
	s_waitcnt lgkmcnt(0)
	v_pk_add_f32 v[0:1], v[0:1], v[2:3]
	ds_bpermute_b32 v3, v15, v1
	ds_bpermute_b32 v2, v15, v0
	v_lshlrev_b32_e32 v49, 16, v21
	v_and_b32_e32 v21, 0xffff0000, v21
	v_add_f32_e32 v63, 1.0, v63
	v_mul_f32_e32 v65, 0xbfb8aa3b, v21
	s_waitcnt lgkmcnt(0)
	v_pk_add_f32 v[0:1], v[0:1], v[2:3]
	ds_bpermute_b32 v3, v16, v1
	ds_bpermute_b32 v2, v16, v0
	v_mul_f32_e32 v52, 0xbfb8aa3b, v44
	v_mul_f32_e32 v62, 0xbfb8aa3b, v48
	v_rcp_f32_e32 v64, v63
	v_mul_f32_e32 v63, 0xbfb8aa3b, v49
	s_waitcnt lgkmcnt(0)
	v_pk_add_f32 v[0:1], v[0:1], v[2:3]
	ds_bpermute_b32 v3, v17, v1
	ds_bpermute_b32 v2, v17, v0
	v_exp_f32_e32 v65, v65
	v_exp_f32_e32 v52, v52
	v_exp_f32_e32 v62, v62
	v_exp_f32_e32 v63, v63
	s_waitcnt lgkmcnt(0)
	v_pk_add_f32 v[0:1], v[0:1], v[2:3]
	v_add_f32_e32 v65, 1.0, v65
	v_pk_fma_f32 v[50:51], v[0:1], s[20:21], v[242:243] op_sel_hi:[1,0,0]
	v_add_f32_e32 v52, 1.0, v52
	v_mul_f32_e32 v0, 0x4b800000, v51
	v_cmp_gt_f32_e64 s[0:1], s45, v51
	v_add_f32_e32 v62, 1.0, v62
	v_add_f32_e32 v63, 1.0, v63
	v_cndmask_b32_e64 v0, v51, v0, s[0:1]
	v_rsq_f32_e32 v0, v0
	v_rcp_f32_e32 v65, v65
	v_rcp_f32_e32 v52, v52
	v_rcp_f32_e32 v62, v62
	v_mul_f32_e32 v1, 0x45800000, v0
	v_cndmask_b32_e64 v0, v0, v1, s[0:1]
	v_pk_mul_f32 v[2:3], v[10:11], v[0:1] op_sel_hi:[1,0]
	v_pk_mul_f32 v[10:11], v[42:43], v[0:1] op_sel_hi:[1,0]
	v_rcp_f32_e32 v63, v63
	v_pk_mul_f32 v[10:11], v[32:33], v[10:11]
	v_pk_mul_f32 v[2:3], v[60:61], v[2:3]
	v_pk_mul_f32 v[10:11], v[10:11], v[18:19]
	v_pk_mul_f32 v[18:19], v[30:31], v[0:1] op_sel_hi:[1,0]
	v_pk_mul_f32 v[0:1], v[46:47], v[0:1] op_sel_hi:[1,0]
	v_pk_mul_f32 v[18:19], v[66:67], v[18:19]
	v_pk_mul_f32 v[0:1], v[28:29], v[0:1]
	v_pk_mul_f32 v[2:3], v[2:3], v[44:45]
	v_pk_mul_f32 v[0:1], v[0:1], v[20:21]
	v_pk_mul_f32 v[10:11], v[58:59], v[10:11]
	v_pk_mul_f32 v[18:19], v[18:19], v[48:49]
	v_pk_mul_f32 v[0:1], v[64:65], v[0:1]
	v_pk_mul_f32 v[2:3], v[52:53], v[2:3]
	v_pk_mul_f32 v[18:19], v[62:63], v[18:19]
	v_cvt_pk_bf16_f32 v10, v10, v10
	v_cvt_pk_bf16_f32 v11, v11, v11
	v_cvt_pk_bf16_f32 v0, v0, v0
	v_cvt_pk_bf16_f32 v1, v1, v1
	v_cvt_pk_bf16_f32 v19, v19, v19
	v_cvt_pk_bf16_f32 v18, v18, v18
	v_cvt_pk_bf16_f32 v3, v3, v3
	v_cvt_pk_bf16_f32 v2, v2, v2
	v_lshrrev_b32_e32 v20, 16, v2
	v_lshrrev_b32_e32 v21, 16, v3
	v_lshrrev_b32_e32 v2, 16, v18
	v_lshrrev_b32_e32 v3, 16, v19
	v_and_or_b32 v3, v1, s36, v3
	v_and_or_b32 v2, v0, s36, v2
	v_and_or_b32 v1, v11, s36, v21
	v_and_or_b32 v0, v10, s36, v20
	v_cmp_gt_f32_e32 vcc, s45, v50
	global_store_dwordx4 v[12:13], v[0:3], off offset:2048
	v_mov_b32_e32 v21, v36
	v_mov_b32_e32 v36, v35
	v_mul_f32_e32 v0, 0x4b800000, v50
	v_cndmask_b32_e32 v0, v50, v0, vcc
	v_rsq_f32_e32 v0, v0
	v_mov_b32_e32 v20, v34
	v_mul_f32_e32 v1, 0x45800000, v0
	v_cndmask_b32_e32 v0, v0, v1, vcc
	v_pk_mul_f32 v[2:3], v[0:1], v[26:27] op_sel_hi:[0,1]
	v_pk_mul_f32 v[10:11], v[0:1], v[68:69] op_sel_hi:[0,1]
	v_pk_mul_f32 v[18:19], v[0:1], v[38:39] op_sel_hi:[0,1]
	v_pk_mul_f32 v[0:1], v[0:1], v[80:81] op_sel_hi:[0,1]
	v_pk_mul_f32 v[10:11], v[40:41], v[10:11]
	v_pk_mul_f32 v[0:1], v[36:37], v[0:1]
	v_pk_mul_f32 v[2:3], v[78:79], v[2:3]
	v_pk_mul_f32 v[10:11], v[10:11], v[22:23]
	v_pk_mul_f32 v[18:19], v[20:21], v[18:19]
	v_pk_mul_f32 v[0:1], v[0:1], v[24:25]
	v_pk_mul_f32 v[2:3], v[2:3], v[70:71]
	v_pk_mul_f32 v[10:11], v[76:77], v[10:11]
	v_pk_mul_f32 v[18:19], v[18:19], v[82:83]
	v_pk_mul_f32 v[0:1], v[88:89], v[0:1]
	v_pk_mul_f32 v[2:3], v[74:75], v[2:3]
	v_pk_mul_f32 v[18:19], v[86:87], v[18:19]
	v_bfe_u32 v22, v11, 16, 1
	v_bfe_u32 v23, v10, 16, 1
	v_add3_u32 v10, v10, v23, s48
	v_add3_u32 v11, v11, v22, s48
	v_cvt_pk_bf16_f32 v0, v0, v0
	v_cvt_pk_bf16_f32 v1, v1, v1
	v_bfe_u32 v22, v18, 16, 1
	v_bfe_u32 v23, v19, 16, 1
	v_add3_u32 v19, v19, v23, s48
	v_add3_u32 v18, v18, v22, s48
	v_cvt_pk_bf16_f32 v3, v3, v3
	v_cvt_pk_bf16_f32 v2, v2, v2
	v_lshrrev_b32_e32 v20, 16, v2
	v_lshrrev_b32_e32 v21, 16, v3
	v_lshrrev_b32_e32 v2, 16, v18
	v_lshrrev_b32_e32 v3, 16, v19
	v_and_or_b32 v3, v1, s36, v3
	v_and_or_b32 v2, v0, s36, v2
	v_and_or_b32 v1, v11, s36, v21
	v_and_or_b32 v0, v10, s36, v20
	global_store_dwordx4 v[12:13], v[0:3], off offset:3072
	s_cbranch_scc1 .LBB0_1535

.LBB0_1608:
	v_add_co_u32_e32 v0, vcc, 0x2c652000, v4
	global_load_dwordx4 v[8:11], v[24:25], off offset:16
	global_load_dwordx4 v[12:15], v[24:25], off
	v_addc_co_u32_e32 v1, vcc, 0, v5, vcc
	global_load_dwordx4 v[20:23], v[0:1], off
	v_lshl_add_u64 v[0:1], s[2:3], 0, v[96:97]
	v_add_co_u32_e32 v2, vcc, 0x1ec01000, v0
	v_pk_mul_f32 v[38:39], v[32:33], v[32:33]
	s_nop 0
	v_addc_co_u32_e32 v3, vcc, 0, v1, vcc
	v_add_co_u32_e32 v0, vcc, 0x1ec02000, v0
	global_load_dwordx4 v[54:57], v[2:3], off offset:3584
	s_nop 0
	v_addc_co_u32_e32 v1, vcc, 0, v1, vcc
	global_load_dwordx4 v[16:19], v[0:1], off offset:2592
	s_nop 0
	global_load_dwordx4 v[0:3], v[26:27], off offset:16
	global_load_dwordx4 v[4:7], v[26:27], off
	v_pk_mul_f32 v[44:45], v[48:49], v[48:49]
	v_pk_mul_f32 v[46:47], v[34:35], v[34:35]
	v_mov_b32_e32 v37, v34
	v_mov_b32_e32 v34, v41
	v_mov_b32_e32 v42, v48
	v_mov_b32_e32 v43, v32
	v_mov_b32_e32 v32, v49
	v_mov_b32_e32 v49, v36
	s_brev_b32 s0, 60
	s_add_i32 s6, s6, s4
	s_add_u32 s8, s8, s10
	s_addc_u32 s9, s9, s11
	s_add_u32 s12, s12, s14
	s_addc_u32 s13, s13, s15
	s_waitcnt vmcnt(0)
	v_mov_b32_e32 v60, v8
	v_mov_b32_e32 v59, v14
	v_mov_b32_e32 v14, v13
	v_mov_b32_e32 v61, v10
	v_mov_b32_e32 v10, v9
	v_lshlrev_b32_e32 v13, 16, v21
	v_and_b32_e32 v9, 0xffff0000, v21
	v_and_b32_e32 v8, 0xffff0000, v20
	v_mov_b32_e32 v58, v12
	v_lshlrev_b32_e32 v12, 16, v20
	v_mov_b32_e32 v66, v9
	v_mov_b32_e32 v67, v13
	v_mov_b32_e32 v40, v8
	v_mov_b32_e32 v48, v12
	v_pk_mul_f32 v[66:67], v[66:67], v[66:67]
	v_pk_mul_f32 v[40:41], v[40:41], v[40:41]
	v_lshlrev_b32_e32 v20, 16, v16
	v_lshlrev_b32_e32 v63, 16, v55
	v_lshlrev_b32_e32 v62, 16, v54
	v_and_b32_e32 v54, 0xffff0000, v54
	v_and_b32_e32 v16, 0xffff0000, v16
	v_pk_fma_f32 v[40:41], v[48:49], v[48:49], v[40:41]
	v_pk_mov_b32 v[48:49], v[66:67], v[46:47] op_sel:[1,0]
	v_mul_f32_e32 v46, 0xbfb8aa3b, v20
	v_mul_f32_e32 v69, 0xbfb8aa3b, v54
	v_mul_f32_e32 v70, 0xbfb8aa3b, v63
	v_exp_f32_e32 v46, v46
	v_mul_f32_e32 v67, 0xbfb8aa3b, v16
	v_exp_f32_e32 v69, v69
	v_exp_f32_e32 v70, v70
	v_exp_f32_e32 v67, v67
	v_lshlrev_b32_e32 v21, 16, v17
	v_lshlrev_b32_e32 v65, 16, v57
	v_lshlrev_b32_e32 v64, 16, v56
	v_and_b32_e32 v56, 0xffff0000, v56
	v_and_b32_e32 v17, 0xffff0000, v17
	v_add_f32_e32 v46, 1.0, v46
	v_mov_b32_e32 v78, v4
	v_mul_f32_e32 v4, 0xbfb8aa3b, v21
	v_mul_f32_e32 v73, 0xbfb8aa3b, v56
	v_mul_f32_e32 v74, 0xbfb8aa3b, v65
	v_add_f32_e32 v69, 1.0, v69
	v_add_f32_e32 v76, 1.0, v70
	v_pk_add_f32 v[40:41], v[48:49], v[40:41]
	v_rcp_f32_e32 v48, v46
	v_add_f32_e32 v46, 1.0, v67
	v_exp_f32_e32 v4, v4
	v_mov_b32_e32 v79, v6
	v_mul_f32_e32 v6, 0xbfb8aa3b, v17
	v_exp_f32_e32 v73, v73
	v_exp_f32_e32 v74, v74
	v_rcp_f32_e32 v70, v69
	v_rcp_f32_e32 v69, v76
	v_rcp_f32_e32 v76, v46
	v_exp_f32_e32 v46, v6
	v_add_f32_e32 v4, 1.0, v4
	v_add_f32_e32 v73, 1.0, v73
	v_add_f32_e32 v77, 1.0, v74
	v_rcp_f32_e32 v49, v4
	v_add_f32_e32 v4, 1.0, v46
	v_rcp_f32_e32 v74, v73
	v_rcp_f32_e32 v73, v77
	v_rcp_f32_e32 v77, v4
	v_lshlrev_b32_e32 v4, 16, v22
	v_and_b32_e32 v22, 0xffff0000, v22
	v_mov_b32_e32 v82, v22
	v_mov_b32_e32 v83, v4
	v_mov_b32_e32 v6, v5
	v_lshlrev_b32_e32 v5, 16, v23
	v_and_b32_e32 v23, 0xffff0000, v23
	v_pk_mul_f32 v[82:83], v[82:83], v[82:83]
	v_mov_b32_e32 v67, v47
	v_mov_b32_e32 v84, v23
	v_mov_b32_e32 v85, v5
	v_pk_add_f32 v[40:41], v[66:67], v[40:41]
	v_pk_mov_b32 v[46:47], v[82:83], v[44:45] op_sel:[1,0]
	v_pk_mul_f32 v[84:85], v[84:85], v[84:85]
	v_pk_add_f32 v[40:41], v[46:47], v[40:41]
	v_mov_b32_e32 v83, v45
	v_pk_add_f32 v[40:41], v[82:83], v[40:41]
	v_pk_mov_b32 v[44:45], v[84:85], v[38:39] op_sel:[1,0]
	v_mov_b32_e32 v85, v39
	v_pk_add_f32 v[40:41], v[44:45], v[40:41]
	v_lshlrev_b32_e32 v80, 16, v18
	v_pk_add_f32 v[38:39], v[84:85], v[40:41]
	ds_bpermute_b32 v41, v50, v39
	ds_bpermute_b32 v40, v50, v38
	v_and_b32_e32 v18, 0xffff0000, v18
	v_lshlrev_b32_e32 v81, 16, v19
	v_mul_f32_e32 v45, 0xbfb8aa3b, v18
	v_exp_f32_e32 v45, v45
	s_waitcnt lgkmcnt(0)
	v_pk_add_f32 v[38:39], v[38:39], v[40:41]
	ds_bpermute_b32 v41, v51, v39
	ds_bpermute_b32 v40, v51, v38
	v_mul_f32_e32 v46, 0xbfb8aa3b, v81
	v_exp_f32_e32 v47, v46
	v_and_b32_e32 v19, 0xffff0000, v19
	v_add_f32_e32 v45, 1.0, v45
	s_waitcnt lgkmcnt(0)
	v_pk_add_f32 v[38:39], v[38:39], v[40:41]
	ds_bpermute_b32 v41, v52, v39
	ds_bpermute_b32 v40, v52, v38
	v_and_b32_e32 v55, 0xffff0000, v55
	v_rcp_f32_e32 v46, v45
	v_add_f32_e32 v45, 1.0, v47
	v_mul_f32_e32 v47, 0xbfb8aa3b, v19
	s_waitcnt lgkmcnt(0)
	v_pk_add_f32 v[38:39], v[38:39], v[40:41]
	ds_bpermute_b32 v41, v53, v39
	ds_bpermute_b32 v40, v53, v38
	v_mul_f32_e32 v71, 0xbfb8aa3b, v55
	v_exp_f32_e32 v47, v47
	v_and_b32_e32 v57, 0xffff0000, v57
	v_mul_f32_e32 v72, 0xbfb8aa3b, v64
	s_waitcnt lgkmcnt(0)
	v_pk_add_f32 v[38:39], v[38:39], v[40:41]
	v_exp_f32_e32 v71, v71
	v_pk_fma_f32 v[38:39], v[38:39], s[0:1], v[242:243] op_sel_hi:[1,0,0]
	v_mul_f32_e32 v75, 0xbfb8aa3b, v57
	v_mul_f32_e32 v40, 0x4b800000, v39
	v_cmp_gt_f32_e32 vcc, s45, v39
	v_exp_f32_e32 v72, v72
	v_mul_f32_e32 v68, 0xbfb8aa3b, v62
	v_cndmask_b32_e32 v39, v39, v40, vcc
	v_rsq_f32_e32 v39, v39
	v_exp_f32_e32 v75, v75
	v_exp_f32_e32 v68, v68
	v_add_f32_e32 v40, 1.0, v47
	v_add_f32_e32 v71, 1.0, v71
	v_rcp_f32_e32 v47, v40
	v_mul_f32_e32 v40, 0x45800000, v39
	v_add_f32_e32 v72, 1.0, v72
	v_rcp_f32_e32 v71, v71
	v_cndmask_b32_e32 v40, v39, v40, vcc
	v_add_f32_e32 v75, 1.0, v75
	v_rcp_f32_e32 v72, v72
	v_pk_mul_f32 v[34:35], v[34:35], v[40:41] op_sel_hi:[1,0]
	v_add_f32_e32 v68, 1.0, v68
	v_rcp_f32_e32 v75, v75
	v_pk_mul_f32 v[14:15], v[14:15], v[34:35]
	v_pk_mul_f32 v[34:35], v[42:43], v[40:41] op_sel_hi:[1,0]
	v_rcp_f32_e32 v68, v68
	v_pk_mul_f32 v[14:15], v[14:15], v[54:55]
	v_pk_mul_f32 v[34:35], v[60:61], v[34:35]
	v_pk_mul_f32 v[32:33], v[32:33], v[40:41] op_sel_hi:[1,0]
	v_pk_mul_f32 v[36:37], v[36:37], v[40:41] op_sel_hi:[1,0]
	v_pk_mul_f32 v[14:15], v[70:71], v[14:15]
	v_pk_mul_f32 v[34:35], v[34:35], v[64:65]
	v_pk_mul_f32 v[10:11], v[10:11], v[32:33]
	v_pk_mul_f32 v[36:37], v[58:59], v[36:37]
	v_pk_mul_f32 v[34:35], v[72:73], v[34:35]
	v_pk_mul_f32 v[10:11], v[10:11], v[56:57]
	v_pk_mul_f32 v[36:37], v[36:37], v[62:63]
	v_pk_mul_f32 v[10:11], v[74:75], v[10:11]
	v_cvt_pk_bf16_f32 v15, v15, v15
	v_pk_mul_f32 v[36:37], v[68:69], v[36:37]
	v_cvt_pk_bf16_f32 v34, v34, v34
	v_cvt_pk_bf16_f32 v10, v10, v10
	v_cvt_pk_bf16_f32 v11, v11, v11
	v_lshrrev_b32_e32 v34, 16, v34
	v_cvt_pk_bf16_f32 v32, v36, v36
	v_and_or_b32 v34, v10, s36, v34
	v_mul_f32_e32 v10, 0x4b800000, v38
	v_cmp_gt_f32_e32 vcc, s45, v38
	v_cvt_pk_bf16_f32 v14, v14, v14
	v_lshrrev_b32_e32 v32, 16, v32
	v_cndmask_b32_e32 v10, v38, v10, vcc
	v_and_or_b32 v32, v14, s36, v32
	v_rsq_f32_e32 v14, v10
	v_mul_f32_e32 v44, 0xbfb8aa3b, v80
	v_cvt_pk_bf16_f32 v33, v37, v37
	v_exp_f32_e32 v44, v44
	v_lshrrev_b32_e32 v33, 16, v33
	v_and_or_b32 v33, v15, s36, v33
	v_mul_f32_e32 v15, 0x45800000, v14
	v_cndmask_b32_e32 v14, v14, v15, vcc
	v_pk_mul_f32 v[8:9], v[14:15], v[8:9] op_sel_hi:[0,1]
	v_add_f32_e32 v44, 1.0, v44
	v_pk_mul_f32 v[6:7], v[6:7], v[8:9]
	v_pk_mul_f32 v[4:5], v[14:15], v[4:5] op_sel_hi:[0,1]
	v_mov_b32_e32 v8, v0
	v_mov_b32_e32 v9, v2
	v_rcp_f32_e32 v44, v44
	v_rcp_f32_e32 v45, v45
	v_pk_mul_f32 v[4:5], v[8:9], v[4:5]
	v_pk_mul_f32 v[8:9], v[14:15], v[22:23] op_sel_hi:[0,1]
	v_mov_b32_e32 v2, v1
	v_pk_mul_f32 v[12:13], v[14:15], v[12:13] op_sel_hi:[0,1]
	v_pk_mul_f32 v[0:1], v[2:3], v[8:9]
	v_cvt_pk_bf16_f32 v35, v35, v35
	v_pk_mul_f32 v[12:13], v[78:79], v[12:13]
	v_pk_mul_f32 v[6:7], v[6:7], v[16:17]
	v_pk_mul_f32 v[0:1], v[0:1], v[18:19]
	v_lshrrev_b32_e32 v35, 16, v35
	v_add_co_u32_e64 v10, s[0:1], s7, v30
	v_pk_mul_f32 v[12:13], v[12:13], v[20:21]
	v_pk_mul_f32 v[6:7], v[76:77], v[6:7]
	v_pk_mul_f32 v[4:5], v[4:5], v[80:81]
	v_pk_mul_f32 v[0:1], v[46:47], v[0:1]
	v_and_or_b32 v35, v11, s36, v35
	v_addc_co_u32_e64 v11, s[0:1], 0, v31, s[0:1]
	v_pk_mul_f32 v[12:13], v[48:49], v[12:13]
	v_pk_mul_f32 v[4:5], v[44:45], v[4:5]
	v_bfe_u32 v8, v7, 16, 1
	v_bfe_u32 v9, v6, 16, 1
	v_add3_u32 v6, v6, v9, s48
	v_add3_u32 v7, v7, v8, s48
	v_cvt_pk_bf16_f32 v0, v0, v0
	v_cvt_pk_bf16_f32 v1, v1, v1
	v_bfe_u32 v8, v4, 16, 1
	v_bfe_u32 v9, v5, 16, 1
	s_mul_i32 s0, s4, 0x3000
	v_add3_u32 v5, v5, v9, s48
	v_add3_u32 v4, v4, v8, s48
	v_cvt_pk_bf16_f32 v3, v13, v13
	v_cvt_pk_bf16_f32 v2, v12, v12
	s_add_u32 s2, s2, s0
	s_mul_hi_i32 s0, s4, 0x3000
	v_lshrrev_b32_e32 v8, 16, v2
	v_lshrrev_b32_e32 v9, 16, v3
	v_lshrrev_b32_e32 v2, 16, v4
	v_lshrrev_b32_e32 v3, 16, v5
	s_addc_u32 s3, s3, s0
	v_and_or_b32 v3, v1, s36, v3
	v_and_or_b32 v2, v0, s36, v2
	v_and_or_b32 v1, v7, s36, v9
	v_and_or_b32 v0, v6, s36, v8
	s_cmpk_lt_i32 s6, 0x2240
	global_store_dwordx4 v[10:11], v[32:35], off offset:2048
	global_store_dwordx4 v[10:11], v[0:3], off offset:3072
	s_cbranch_scc0 .LBB0_1613
.LBB0_1609:
	s_cmpk_lt_i32 s6, 0x2040
	s_cselect_b64 s[0:1], -1, 0
	s_cmpk_gt_i32 s6, 0x203f
	v_lshl_add_u64 v[4:5], s[12:13], 0, v[96:97]
	v_lshl_add_u64 v[30:31], s[8:9], 0, v[96:97]
	s_cbranch_scc1 .LBB0_1611
	v_add_co_u32_e32 v98, vcc, 0x33812000, v4
	s_nop 1
	v_addc_co_u32_e32 v99, vcc, 0, v5, vcc
	v_add_co_u32_e32 v100, vcc, 0x326f2000, v4
	global_load_dwordx4 v[102:105], v[98:99], off
	s_nop 1
	v_addc_co_u32_e32 v101, vcc, 0, v5, vcc
	global_load_dwordx4 v[106:109], v[100:101], off
	v_add_co_u32_e32 v100, vcc, s5, v4
	s_nop 1
	v_addc_co_u32_e32 v101, vcc, 0, v5, vcc
	global_load_dwordx4 v[110:113], v[100:101], off
	global_load_dwordx4 v[114:117], v[28:29], off offset:16
	global_load_dwordx4 v[118:121], v[28:29], off
	v_add_co_u32_e32 v0, vcc, 0x33812000, v4
	s_nop 1
	v_addc_co_u32_e32 v1, vcc, 0, v5, vcc
	v_add_co_u32_e32 v6, vcc, 0x326f2000, v4
	s_waitcnt vmcnt(0)
	v_mov_b64_e32 v[0:1], v[102:103]
	v_mov_b64_e32 v[2:3], v[104:105]
	s_nop 0
	v_addc_co_u32_e32 v7, vcc, 0, v5, vcc
	v_mov_b64_e32 v[6:7], v[106:107]
	v_mov_b64_e32 v[8:9], v[108:109]
	s_waitcnt vmcnt(0)
	v_lshlrev_b32_e32 v35, 16, v2
	v_lshlrev_b32_e32 v34, 16, v0
	v_and_b32_e32 v37, 0xffff0000, v2
	v_lshlrev_b32_e32 v18, 16, v6
	v_and_b32_e32 v19, 0xffff0000, v6
	v_add_co_u32_e32 v6, vcc, s5, v4
	v_lshlrev_b32_e32 v20, 16, v7
	v_and_b32_e32 v21, 0xffff0000, v7
	v_addc_co_u32_e32 v7, vcc, 0, v5, vcc
	v_lshlrev_b32_e32 v22, 16, v8
	v_and_b32_e32 v23, 0xffff0000, v8
	v_lshlrev_b32_e32 v32, 16, v9
	v_and_b32_e32 v33, 0xffff0000, v9
	v_mov_b64_e32 v[6:7], v[110:111]
	v_mov_b64_e32 v[8:9], v[112:113]
	s_nop 0
	v_mov_b64_e32 v[10:11], v[114:115]
	v_mov_b64_e32 v[12:13], v[116:117]
	v_mov_b64_e32 v[14:15], v[118:119]
	v_mov_b64_e32 v[16:17], v[120:121]
	v_and_b32_e32 v36, 0xffff0000, v0
	v_lshlrev_b32_e32 v39, 16, v3
	v_lshlrev_b32_e32 v38, 16, v1
	v_and_b32_e32 v2, 0xffff0000, v1
	v_pk_add_f32 v[0:1], v[34:35], v[36:37]
	v_and_b32_e32 v3, 0xffff0000, v3
	v_pk_add_f32 v[0:1], v[0:1], v[38:39]
	s_nop 0
	v_pk_add_f32 v[0:1], v[0:1], v[2:3]
	s_nop 0
	v_add_f32_e32 v0, v0, v1
	ds_bpermute_b32 v1, v50, v0
	s_waitcnt lgkmcnt(0)
	v_add_f32_e32 v0, v0, v1
	ds_bpermute_b32 v1, v51, v0
	s_waitcnt lgkmcnt(0)
	v_add_f32_e32 v0, v0, v1
	ds_bpermute_b32 v1, v52, v0
	s_waitcnt lgkmcnt(0)
	v_add_f32_e32 v0, v0, v1
	v_fmac_f32_e32 v36, 0xbc800000, v0
	v_fmac_f32_e32 v37, 0xbc800000, v0
	v_fmac_f32_e32 v34, 0xbc800000, v0
	v_fmac_f32_e32 v35, 0xbc800000, v0
	v_mov_b32_e32 v1, v37
	v_mov_b32_e32 v41, v36
	v_pk_mul_f32 v[36:37], v[36:37], v[36:37]
	v_fmac_f32_e32 v2, 0xbc800000, v0
	v_fmac_f32_e32 v38, 0xbc800000, v0
	v_fmac_f32_e32 v3, 0xbc800000, v0
	v_fmac_f32_e32 v39, 0xbc800000, v0
	v_mov_b32_e32 v0, v35
	v_mov_b32_e32 v40, v34
	v_pk_fma_f32 v[34:35], v[34:35], v[34:35], v[36:37]
	v_mov_b32_e32 v37, v3
	v_pk_fma_f32 v[34:35], v[38:39], v[38:39], v[34:35]
	v_mov_b32_e32 v43, v2
	v_pk_fma_f32 v[2:3], v[2:3], v[2:3], v[34:35]
	v_mov_b32_e32 v42, v38
	v_add_f32_e32 v2, v2, v3
	ds_bpermute_b32 v3, v50, v2
	v_mov_b32_e32 v36, v39
	s_waitcnt lgkmcnt(0)
	v_add_f32_e32 v2, v2, v3
	ds_bpermute_b32 v3, v51, v2
	s_waitcnt lgkmcnt(0)
	v_add_f32_e32 v2, v2, v3
	ds_bpermute_b32 v3, v52, v2
	s_waitcnt lgkmcnt(0)
	v_add_f32_e32 v2, v2, v3
	v_fmamk_f32 v2, v2, 0x3c800000, v231
	v_cmp_gt_f32_e32 vcc, s45, v2
	v_mul_f32_e32 v3, 0x4b800000, v2
	s_nop 0
	v_cndmask_b32_e32 v2, v2, v3, vcc
	v_rsq_f32_e32 v2, v2
	s_nop 0
	v_mul_f32_e32 v3, 0x45800000, v2
	v_cndmask_b32_e32 v2, v2, v3, vcc
	v_pk_mul_f32 v[34:35], v[42:43], v[2:3] op_sel_hi:[1,0]
	v_pk_mul_f32 v[38:39], v[40:41], v[2:3] op_sel_hi:[1,0]
	s_waitcnt vmcnt(0)
	v_pk_fma_f32 v[16:17], v[16:17], v[34:35], v[20:21]
	v_pk_fma_f32 v[14:15], v[14:15], v[38:39], v[18:19]
	v_pk_mul_f32 v[18:19], v[36:37], v[2:3] op_sel_hi:[1,0]
	v_pk_mul_f32 v[0:1], v[0:1], v[2:3] op_sel_hi:[1,0]
	v_pk_fma_f32 v[2:3], v[12:13], v[18:19], v[32:33]
	v_pk_fma_f32 v[0:1], v[10:11], v[0:1], v[22:23]
	v_lshlrev_b32_e32 v11, 16, v7
	v_lshlrev_b32_e32 v10, 16, v6
	v_mov_b32_e32 v12, v14
	v_mov_b32_e32 v13, v16
	v_pk_mul_f32 v[10:11], v[12:13], v[10:11]
	v_and_b32_e32 v7, 0xffff0000, v7
	v_and_b32_e32 v6, 0xffff0000, v6
	v_mov_b32_e32 v16, v15
	v_lshlrev_b32_e32 v13, 16, v9
	v_lshlrev_b32_e32 v12, 16, v8
	v_mov_b32_e32 v15, v2
	v_and_b32_e32 v9, 0xffff0000, v9
	v_and_b32_e32 v8, 0xffff0000, v8
	v_mov_b32_e32 v2, v1
	v_pk_mul_f32 v[6:7], v[16:17], v[6:7]
	v_mov_b32_e32 v14, v0
	v_pk_mul_f32 v[0:1], v[2:3], v[8:9]
	v_pk_mul_f32 v[12:13], v[14:15], v[12:13]
	v_cvt_pk_bf16_f32 v7, v7, v7
	v_cvt_pk_bf16_f32 v1, v1, v1
	v_cvt_pk_bf16_f32 v6, v6, v6
	v_cvt_pk_bf16_f32 v0, v0, v0
	v_cvt_pk_bf16_f32 v8, v12, v12
	v_cvt_pk_bf16_f32 v2, v10, v10
	v_cvt_pk_bf16_f32 v9, v13, v13
	v_cvt_pk_bf16_f32 v3, v11, v11
	v_lshrrev_b32_e32 v10, 16, v2
	v_lshrrev_b32_e32 v2, 16, v8
	v_lshrrev_b32_e32 v11, 16, v3
	v_lshrrev_b32_e32 v3, 16, v9
	v_and_or_b32 v2, v0, s36, v2
	v_and_or_b32 v0, v6, s36, v10
	v_add_co_u32_e32 v6, vcc, 0x25500000, v30
	v_and_or_b32 v3, v1, s36, v3
	v_and_or_b32 v1, v7, s36, v11
	v_addc_co_u32_e32 v7, vcc, 0, v31, vcc
	global_store_dwordx4 v[6:7], v[0:3], off

.LBB0_2000:
	v_lshlrev_b64 v[8:9], 2, v[68:69]
	v_lshl_add_u64 v[12:13], s[56:57], 0, v[8:9]
	v_lshl_add_u64 v[16:17], s[4:5], 0, v[8:9]
	v_lshl_add_u64 v[20:21], s[6:7], 0, v[8:9]
	v_lshl_add_u64 v[36:37], s[58:59], 0, v[8:9]
	global_load_dwordx4 v[8:11], v[12:13], off offset:16
	global_load_dwordx4 v[24:27], v[12:13], off
	s_nop 0
	global_load_dwordx4 v[12:15], v[16:17], off offset:16
	global_load_dwordx4 v[28:31], v[16:17], off
	s_nop 0
	global_load_dwordx4 v[16:19], v[20:21], off offset:16
	global_load_dwordx4 v[32:35], v[20:21], off
	s_nop 0
	global_load_dwordx4 v[20:23], v[36:37], off offset:16
	s_nop 0
	global_load_dwordx4 v[36:39], v[36:37], off
	s_waitcnt vmcnt(0)
	v_lshlrev_b32_e32 v60, 16, v52
	v_and_b32_e32 v58, 0xffff0000, v52
	v_lshlrev_b32_e32 v61, 16, v53
	v_and_b32_e32 v59, 0xffff0000, v53
	v_lshlrev_b32_e32 v56, 16, v54
	v_and_b32_e32 v52, 0xffff0000, v54
	v_lshlrev_b32_e32 v57, 16, v55
	v_and_b32_e32 v53, 0xffff0000, v55
	v_lshlrev_b32_e32 v63, 16, v49
	v_lshlrev_b32_e32 v62, 16, v48
	v_and_b32_e32 v73, 0xffff0000, v49
	v_and_b32_e32 v72, 0xffff0000, v48
	v_lshl_add_u64 v[48:49], v[68:69], 1, s[8:9]
	v_lshlrev_b32_e32 v69, 16, v41
	v_lshlrev_b32_e32 v68, 16, v40
	v_and_b32_e32 v75, 0xffff0000, v41
	v_and_b32_e32 v74, 0xffff0000, v40
	v_lshlrev_b32_e32 v71, 16, v51
	v_lshlrev_b32_e32 v70, 16, v50
	v_and_b32_e32 v67, 0xffff0000, v51
	v_and_b32_e32 v66, 0xffff0000, v50
	v_lshlrev_b32_e32 v51, 16, v45
	v_lshlrev_b32_e32 v50, 16, v44
	v_and_b32_e32 v45, 0xffff0000, v45
	v_and_b32_e32 v44, 0xffff0000, v44
	v_mov_b32_e32 v40, v24
	v_mov_b32_e32 v41, v26
	v_mov_b32_e32 v26, v25
	v_mov_b32_e32 v64, v28
	v_mov_b32_e32 v65, v30
	v_mov_b32_e32 v30, v29
	v_mov_b32_e32 v54, v36
	v_mov_b32_e32 v55, v38
	v_mov_b32_e32 v38, v37
	v_pk_fma_f32 v[62:63], v[40:41], v[62:63], v[54:55]
	v_pk_fma_f32 v[36:37], v[26:27], v[72:73], v[38:39]
	v_pk_fma_f32 v[76:77], v[64:65], v[60:61], v[62:63]
	v_mov_b32_e32 v63, v34
	v_pk_fma_f32 v[28:29], v[30:31], v[58:59], v[36:37]
	v_mov_b32_e32 v34, v33
	v_pk_fma_f32 v[28:29], v[34:35], v[44:45], v[28:29]
	v_mov_b32_e32 v62, v32
	v_mul_f32_e32 v25, 0x3d372713, v28
	v_mul_f32_e32 v25, v28, v25
	v_fma_f32 v25, v28, v25, v28
	v_mul_f32_e32 v25, 0xbfcc422a, v25
	v_mul_f32_e32 v25, 0x3fb8aa3b, v25
	v_exp_f32_e32 v25, v25
	v_pk_fma_f32 v[76:77], v[62:63], v[50:51], v[76:77]
	v_mul_f32_e32 v33, 0x3d372713, v29
	v_mul_f32_e32 v24, 0x3d372713, v76
	v_add_f32_e32 v25, 1.0, v25
	v_rcp_f32_e32 v32, v25
	v_mul_f32_e32 v25, 0x3d372713, v77
	v_mul_f32_e32 v24, v76, v24
	v_mul_f32_e32 v25, v77, v25
	v_mul_f32_e32 v33, v29, v33
	v_fma_f32 v24, v76, v24, v76
	v_fma_f32 v25, v77, v25, v77
	v_fma_f32 v33, v29, v33, v29
	v_mul_f32_e32 v24, 0xbfcc422a, v24
	v_mul_f32_e32 v25, 0xbfcc422a, v25
	v_mul_f32_e32 v33, 0xbfcc422a, v33
	v_mul_f32_e32 v24, 0x3fb8aa3b, v24
	v_mul_f32_e32 v25, 0x3fb8aa3b, v25
	v_mul_f32_e32 v33, 0x3fb8aa3b, v33
	v_exp_f32_e32 v24, v24
	v_exp_f32_e32 v25, v25
	v_exp_f32_e32 v33, v33
	v_lshlrev_b32_e32 v37, 16, v47
	v_add_f32_e32 v24, 1.0, v24
	v_add_f32_e32 v25, 1.0, v25
	v_add_f32_e32 v33, 1.0, v33
	v_rcp_f32_e32 v24, v24
	v_rcp_f32_e32 v25, v25
	v_rcp_f32_e32 v33, v33
	v_lshlrev_b32_e32 v36, 16, v46
	v_pk_mul_f32 v[24:25], v[76:77], v[24:25]
	v_pk_mul_f32 v[28:29], v[28:29], v[32:33]
	v_pk_mul_f32 v[24:25], v[24:25], v[68:69]
	v_pk_mul_f32 v[28:29], v[28:29], v[74:75]
	v_and_b32_e32 v33, 0xffff0000, v47
	v_and_b32_e32 v32, 0xffff0000, v46
	v_lshlrev_b32_e32 v75, 16, v43
	v_lshlrev_b32_e32 v74, 16, v42
	v_and_b32_e32 v47, 0xffff0000, v43
	v_and_b32_e32 v46, 0xffff0000, v42
	v_mov_b32_e32 v42, v8
	v_mov_b32_e32 v43, v10
	v_mov_b32_e32 v68, v20
	v_mov_b32_e32 v69, v22
	v_mov_b32_e32 v10, v9
	v_mov_b32_e32 v22, v21
	v_pk_fma_f32 v[72:73], v[42:43], v[70:71], v[68:69]
	v_mov_b32_e32 v70, v12
	v_mov_b32_e32 v71, v14
	v_pk_fma_f32 v[20:21], v[10:11], v[66:67], v[22:23]
	v_mov_b32_e32 v14, v13
	v_pk_fma_f32 v[76:77], v[70:71], v[56:57], v[72:73]
	v_mov_b32_e32 v73, v18
	v_pk_fma_f32 v[12:13], v[14:15], v[52:53], v[20:21]
	v_mov_b32_e32 v18, v17
	v_pk_fma_f32 v[12:13], v[18:19], v[32:33], v[12:13]
	v_mov_b32_e32 v72, v16
	v_mul_f32_e32 v9, 0x3d372713, v12
	v_mul_f32_e32 v9, v12, v9
	v_fma_f32 v9, v12, v9, v12
	v_mul_f32_e32 v9, 0xbfcc422a, v9
	v_mul_f32_e32 v9, 0x3fb8aa3b, v9
	v_exp_f32_e32 v9, v9
	v_pk_fma_f32 v[76:77], v[72:73], v[36:37], v[76:77]
	v_mul_f32_e32 v17, 0x3d372713, v13
	v_mul_f32_e32 v8, 0x3d372713, v76
	v_add_f32_e32 v9, 1.0, v9
	v_rcp_f32_e32 v16, v9
	v_mul_f32_e32 v9, 0x3d372713, v77
	v_mul_f32_e32 v17, v13, v17
	v_mul_f32_e32 v8, v76, v8
	v_mul_f32_e32 v9, v77, v9
	v_fma_f32 v17, v13, v17, v13
	v_fma_f32 v8, v76, v8, v76
	v_fma_f32 v9, v77, v9, v77
	v_mul_f32_e32 v17, 0xbfcc422a, v17
	v_mul_f32_e32 v8, 0xbfcc422a, v8
	v_mul_f32_e32 v9, 0xbfcc422a, v9
	v_mul_f32_e32 v17, 0x3fb8aa3b, v17
	v_mul_f32_e32 v8, 0x3fb8aa3b, v8
	v_mul_f32_e32 v9, 0x3fb8aa3b, v9
	v_exp_f32_e32 v17, v17
	v_exp_f32_e32 v8, v8
	v_exp_f32_e32 v9, v9
	v_bfe_u32 v20, v29, 16, 1
	v_add_f32_e32 v17, 1.0, v17
	v_add_f32_e32 v8, 1.0, v8
	v_add_f32_e32 v9, 1.0, v9
	v_rcp_f32_e32 v17, v17
	v_rcp_f32_e32 v8, v8
	v_rcp_f32_e32 v9, v9
	v_pk_mul_f32 v[12:13], v[12:13], v[16:17]
	v_cvt_pk_bf16_f32 v21, v28, v28
	v_pk_mul_f32 v[8:9], v[76:77], v[8:9]
	v_pk_mul_f32 v[12:13], v[12:13], v[46:47]
	v_pk_mul_f32 v[8:9], v[8:9], v[74:75]
	v_add3_u32 v20, v29, v20, s48
	v_cvt_pk_bf16_f32 v12, v12, v12
	v_cvt_pk_bf16_f32 v13, v13, v13
	v_cvt_pk_bf16_f32 v9, v9, v9
	v_cvt_pk_bf16_f32 v8, v8, v8
	v_cvt_pk_bf16_f32 v17, v25, v25
	v_cvt_pk_bf16_f32 v16, v24, v24
	v_lshrrev_b32_e32 v16, 16, v16
	v_lshrrev_b32_e32 v17, 16, v17
	v_lshrrev_b32_e32 v8, 16, v8
	v_lshrrev_b32_e32 v9, 16, v9
	v_mov_b32_e32 v24, 0x2b00
	v_and_or_b32 v77, v13, s36, v9
	v_and_or_b32 v76, v12, s36, v8
	v_and_or_b32 v75, v20, s36, v17
	v_and_or_b32 v74, v21, s36, v16
	v_mad_i64_i32 v[8:9], s[24:25], s12, v24, v[48:49]
	v_pk_fma_f32 v[20:21], v[26:27], v[58:59], v[38:39]
	global_store_dwordx4 v[8:9], v[74:77], off
	v_lshlrev_b32_e32 v9, 16, v5
	v_lshlrev_b32_e32 v8, 16, v4
	v_and_b32_e32 v5, 0xffff0000, v5
	v_and_b32_e32 v4, 0xffff0000, v4
	v_pk_fma_f32 v[16:17], v[40:41], v[60:61], v[54:55]
	v_pk_fma_f32 v[20:21], v[30:31], v[44:45], v[20:21]
	v_pk_fma_f32 v[16:17], v[64:65], v[50:51], v[16:17]
	v_pk_fma_f32 v[4:5], v[34:35], v[4:5], v[20:21]
	v_pk_fma_f32 v[8:9], v[62:63], v[8:9], v[16:17]
	v_mul_f32_e32 v17, 0x3d372713, v4
	v_mul_f32_e32 v17, v4, v17
	v_fma_f32 v17, v4, v17, v4
	v_mul_f32_e32 v17, 0xbfcc422a, v17
	v_mul_f32_e32 v17, 0x3fb8aa3b, v17
	v_exp_f32_e32 v17, v17
	v_mul_f32_e32 v16, 0x3d372713, v8
	v_mul_f32_e32 v16, v8, v16
	v_fma_f32 v16, v8, v16, v8
	v_add_f32_e32 v17, 1.0, v17
	v_rcp_f32_e32 v20, v17
	v_mul_f32_e32 v17, 0x3d372713, v9
	v_mul_f32_e32 v17, v9, v17
	v_fma_f32 v17, v9, v17, v9
	v_mul_f32_e32 v16, 0xbfcc422a, v16
	v_mul_f32_e32 v17, 0xbfcc422a, v17
	v_mul_f32_e32 v16, 0x3fb8aa3b, v16
	v_mul_f32_e32 v17, 0x3fb8aa3b, v17
	v_exp_f32_e32 v16, v16
	v_exp_f32_e32 v17, v17
	v_lshlrev_b32_e32 v13, 16, v1
	v_lshlrev_b32_e32 v12, 16, v0
	v_add_f32_e32 v16, 1.0, v16
	v_add_f32_e32 v17, 1.0, v17
	v_rcp_f32_e32 v16, v16
	v_rcp_f32_e32 v17, v17
	v_and_b32_e32 v1, 0xffff0000, v1
	v_and_b32_e32 v0, 0xffff0000, v0
	v_pk_fma_f32 v[10:11], v[10:11], v[52:53], v[22:23]
	v_pk_mul_f32 v[8:9], v[8:9], v[16:17]
	v_pk_fma_f32 v[16:17], v[42:43], v[56:57], v[68:69]
	v_pk_mul_f32 v[8:9], v[8:9], v[12:13]
	v_mul_f32_e32 v12, 0x3d372713, v5
	v_mul_f32_e32 v12, v5, v12
	v_fma_f32 v12, v5, v12, v5
	v_mul_f32_e32 v12, 0xbfcc422a, v12
	v_mul_f32_e32 v12, 0x3fb8aa3b, v12
	v_exp_f32_e32 v12, v12
	v_pk_fma_f32 v[16:17], v[70:71], v[36:37], v[16:17]
	v_pk_fma_f32 v[10:11], v[14:15], v[32:33], v[10:11]
	v_lshlrev_b32_e32 v13, 16, v3
	v_add_f32_e32 v12, 1.0, v12
	v_rcp_f32_e32 v21, v12
	v_lshlrev_b32_e32 v12, 16, v2
	v_and_b32_e32 v3, 0xffff0000, v3
	v_and_b32_e32 v2, 0xffff0000, v2
	v_pk_mul_f32 v[4:5], v[4:5], v[20:21]
	s_or_b32 s12, s12, 1
	v_pk_mul_f32 v[0:1], v[4:5], v[0:1]
	v_lshlrev_b32_e32 v5, 16, v7
	v_lshlrev_b32_e32 v4, 16, v6
	v_and_b32_e32 v7, 0xffff0000, v7
	v_and_b32_e32 v6, 0xffff0000, v6
	v_pk_fma_f32 v[4:5], v[72:73], v[4:5], v[16:17]
	v_pk_fma_f32 v[6:7], v[18:19], v[6:7], v[10:11]
	v_mul_f32_e32 v11, 0x3d372713, v5
	v_mul_f32_e32 v11, v5, v11
	v_fma_f32 v11, v5, v11, v5
	v_mul_f32_e32 v11, 0xbfcc422a, v11
	v_mul_f32_e32 v11, 0x3fb8aa3b, v11
	v_exp_f32_e32 v11, v11
	v_mul_f32_e32 v10, 0x3d372713, v6
	v_mul_f32_e32 v16, 0x3d372713, v4
	v_mul_f32_e32 v10, v6, v10
	v_add_f32_e32 v11, 1.0, v11
	v_rcp_f32_e32 v17, v11
	v_mul_f32_e32 v11, 0x3d372713, v7
	v_mul_f32_e32 v11, v7, v11
	v_mul_f32_e32 v16, v4, v16
	v_fma_f32 v10, v6, v10, v6
	v_fma_f32 v11, v7, v11, v7
	v_fma_f32 v16, v4, v16, v4
	v_mul_f32_e32 v10, 0xbfcc422a, v10
	v_mul_f32_e32 v11, 0xbfcc422a, v11
	v_mul_f32_e32 v16, 0xbfcc422a, v16
	v_mul_f32_e32 v10, 0x3fb8aa3b, v10
	v_mul_f32_e32 v11, 0x3fb8aa3b, v11
	v_mul_f32_e32 v16, 0x3fb8aa3b, v16
	v_exp_f32_e32 v10, v10
	v_exp_f32_e32 v11, v11
	v_exp_f32_e32 v16, v16
	v_add_f32_e32 v10, 1.0, v10
	v_add_f32_e32 v11, 1.0, v11
	v_add_f32_e32 v16, 1.0, v16
	v_rcp_f32_e32 v10, v10
	v_rcp_f32_e32 v11, v11
	v_rcp_f32_e32 v16, v16
	v_pk_mul_f32 v[6:7], v[6:7], v[10:11]
	v_pk_mul_f32 v[4:5], v[4:5], v[16:17]
	v_pk_mul_f32 v[2:3], v[6:7], v[2:3]
	v_pk_mul_f32 v[4:5], v[4:5], v[12:13]
	v_cvt_pk_bf16_f32 v0, v0, v0
	v_cvt_pk_bf16_f32 v1, v1, v1
	v_cvt_pk_bf16_f32 v2, v2, v2
	v_cvt_pk_bf16_f32 v3, v3, v3
	v_cvt_pk_bf16_f32 v5, v5, v5
	v_cvt_pk_bf16_f32 v4, v4, v4
	v_cvt_pk_bf16_f32 v7, v9, v9
	v_cvt_pk_bf16_f32 v6, v8, v8
	v_lshrrev_b32_e32 v6, 16, v6
	v_lshrrev_b32_e32 v7, 16, v7
	v_lshrrev_b32_e32 v4, 16, v4
	v_lshrrev_b32_e32 v5, 16, v5
	v_and_or_b32 v3, v3, s36, v5
	v_and_or_b32 v2, v2, s36, v4
	v_and_or_b32 v1, v1, s36, v7
	v_and_or_b32 v0, v0, s36, v6
	v_mad_i64_i32 v[4:5], s[12:13], s12, v24, v[48:49]
	global_store_dwordx4 v[4:5], v[0:3], off

.LBB0_2002:
	s_mul_hi_i32 s10, s0, 0x2e8ba2e9
	v_mov_b32_e32 v0, v96
	s_lshr_b32 s11, s10, 31
	s_ashr_i32 s24, s10, 1
	s_add_i32 s24, s24, s11
	v_lshlrev_b32_e32 v0, 3, v0
	s_mul_i32 s10, s24, 0x1600
	v_subrev_u32_e32 v0, s10, v0
	v_add_u32_e32 v68, s22, v0
	v_cmp_gt_i32_e32 vcc, s49, v68
	s_and_saveexec_b64 s[10:11], vcc
	s_cbranch_execz .LBB0_2001
	s_mov_b64 s[12:13], -1
	s_cmpk_gt_i32 s0, 0x58a
	v_ashrrev_i32_e32 v69, 31, v68
	s_cbranch_scc0 .LBB0_2009
	v_lshlrev_b64 v[80:81], 1, v[68:69]
	v_lshlrev_b64 v[82:83], 2, v[68:69]
	s_cmpk_gt_u32 s0, 0x5ab
	v_lshl_add_u64 v[78:79], s[56:57], 0, v[82:83]
	v_lshl_add_u64 v[76:77], s[4:5], 0, v[82:83]
	v_lshl_add_u64 v[74:75], s[6:7], 0, v[82:83]
	v_lshl_add_u64 v[72:73], s[58:59], 0, v[82:83]
	v_lshl_add_u64 v[70:71], s[8:9], 0, v[80:81]
	s_cbranch_scc0 .LBB0_2006
	s_lshl_b32 s25, s24, 2
	s_addk_i32 s25, 0x1e30
	s_mul_i32 s38, s25, 0x2b00
	s_lshl_b64 s[12:13], s[38:39], 1
	s_add_u32 s12, s16, s12
	s_addc_u32 s13, s17, s13
	s_add_i32 s26, s24, 0xffffff7c
	v_lshl_add_u64 v[6:7], s[2:3], 0, v[82:83]
	v_mov_b32_e32 v8, 0xac00
	v_lshl_add_u64 v[40:41], s[12:13], 0, v[80:81]
	v_mad_u64_u32 v[16:17], s[12:13], s26, v8, v[6:7]
	global_load_dwordx4 v[0:3], v[78:79], off
	global_load_dwordx4 v[24:27], v[72:73], off
	global_load_dwordx4 v[98:101], v[16:17], off
	global_load_dwordx4 v[64:67], v[40:41], off
	v_add_co_u32_e32 v4, vcc, s74, v40
	s_movk_i32 s29, 0x5000
	s_nop 0
	v_addc_co_u32_e32 v5, vcc, 0, v41, vcc
	v_add_co_u32_e32 v6, vcc, s29, v16
	s_mov_b32 s12, 0x12000
	s_nop 0
	v_addc_co_u32_e32 v7, vcc, 0, v17, vcc
	global_load_dwordx4 v[56:59], v[6:7], off offset:1536
	global_load_dwordx4 v[102:105], v[4:5], off offset:2816
	global_load_dwordx4 v[32:35], v[76:77], off
	global_load_dwordx4 v[36:39], v[74:75], off
	s_nop 0
	global_load_dwordx4 v[4:7], v[78:79], off offset:16
	global_load_dwordx4 v[8:11], v[76:77], off offset:16
	global_load_dwordx4 v[12:15], v[74:75], off offset:16
	global_load_dwordx4 v[20:23], v[72:73], off offset:16
	v_add_co_u32_e32 v18, vcc, s75, v40
	global_load_dwordx4 v[106:109], v[16:17], off offset:16
	s_nop 0
	v_addc_co_u32_e32 v19, vcc, 0, v41, vcc
	v_add_co_u32_e32 v42, vcc, s12, v40
	s_mov_b64 s[12:13], 0x5600
	s_nop 0
	v_addc_co_u32_e32 v43, vcc, 0, v41, vcc
	v_lshl_add_u64 v[44:45], v[16:17], 0, s[12:13]
	global_load_dwordx4 v[28:31], v[18:19], off offset:512
	s_nop 0
	global_load_dwordx4 v[16:19], v[42:43], off offset:3328
	global_load_dwordx4 v[52:55], v[44:45], off offset:16
	v_add_co_u32_e32 v46, vcc, s29, v40
	s_mov_b32 s28, 0x8000
	s_nop 0
	v_addc_co_u32_e32 v47, vcc, 0, v41, vcc
	v_add_co_u32_e32 v42, vcc, s28, v40
	s_mul_hi_u32 s27, s26, 0xac00
	s_nop 0
	v_addc_co_u32_e32 v43, vcc, 0, v41, vcc
	global_load_dwordx4 v[60:63], v[46:47], off offset:1536
	global_load_dwordx4 v[48:51], v[42:43], off offset:256
	s_mul_i32 s26, s26, 0xac00
	v_add_co_u32_e32 v44, vcc, s79, v40
	s_add_u32 s12, s26, s14
	s_nop 0
	v_addc_co_u32_e32 v45, vcc, 0, v41, vcc
	s_mov_b32 s26, 0xd000
	v_add_co_u32_e32 v40, vcc, s26, v40
	s_mul_i32 s38, s25, 0x1580
	s_nop 0
	v_addc_co_u32_e32 v41, vcc, 0, v41, vcc
	global_load_dwordx4 v[44:47], v[44:45], off offset:3072
	s_nop 0
	global_load_dwordx4 v[40:43], v[40:41], off offset:1792
	s_addc_u32 s13, s27, s1
	s_add_u32 s26, s18, s12
	s_addc_u32 s27, s19, s13
	s_add_u32 s12, s20, s12
	s_addc_u32 s13, s21, s13
	s_waitcnt vmcnt(0)
	v_mov_b32_e32 v85, v2
	v_mov_b32_e32 v86, v24
	v_pk_fma_f32 v[94:95], v[100:101], v[2:3], v[26:27]
	v_pk_fma_f32 v[98:99], v[98:99], v[0:1], v[24:25]
	v_lshlrev_b32_e32 v93, 16, v65
	v_lshlrev_b32_e32 v92, 16, v64
	v_and_b32_e32 v91, 0xffff0000, v65
	v_and_b32_e32 v90, 0xffff0000, v64
	v_mov_b32_e32 v88, v98
	v_mov_b32_e32 v89, v94
	v_mov_b32_e32 v110, v56
	v_mov_b32_e32 v111, v58
	v_mov_b32_e32 v64, v32
	v_mov_b32_e32 v65, v34
	v_mov_b32_e32 v94, v99
	v_mov_b32_e32 v58, v57
	v_mov_b32_e32 v34, v33
	v_pk_fma_f32 v[112:113], v[110:111], v[64:65], v[88:89]
	v_mov_b32_e32 v89, v38
	v_pk_fma_f32 v[32:33], v[58:59], v[34:35], v[94:95]
	v_mov_b32_e32 v38, v37
	v_pk_fma_f32 v[32:33], v[38:39], v[90:91], v[32:33]
	v_mov_b32_e32 v88, v36
	v_mul_f32_e32 v2, 0x3d372713, v32
	v_mul_f32_e32 v2, v32, v2
	v_fma_f32 v2, v32, v2, v32
	v_mul_f32_e32 v2, 0xbfcc422a, v2
	v_mul_f32_e32 v2, 0x3fb8aa3b, v2
	v_exp_f32_e32 v24, v2
	v_pk_fma_f32 v[112:113], v[88:89], v[92:93], v[112:113]
	v_mov_b32_e32 v84, v0
	v_mul_f32_e32 v0, 0x3d372713, v112
	v_mov_b32_e32 v2, v1
	v_add_f32_e32 v1, 1.0, v24
	v_mul_f32_e32 v24, 0x3d372713, v113
	v_mov_b32_e32 v87, v26
	v_mul_f32_e32 v0, v112, v0
	v_mul_f32_e32 v24, v113, v24
	v_mul_f32_e32 v26, 0x3d372713, v33
	v_fma_f32 v0, v112, v0, v112
	v_fma_f32 v24, v113, v24, v113
	v_mul_f32_e32 v26, v33, v26
	v_mul_f32_e32 v0, 0xbfcc422a, v0
	v_mul_f32_e32 v24, 0xbfcc422a, v24
	v_fma_f32 v26, v33, v26, v33
	v_mul_f32_e32 v0, 0x3fb8aa3b, v0
	v_mul_f32_e32 v24, 0x3fb8aa3b, v24
	v_mul_f32_e32 v26, 0xbfcc422a, v26
	v_exp_f32_e32 v0, v0
	v_exp_f32_e32 v24, v24
	v_mul_f32_e32 v26, 0x3fb8aa3b, v26
	v_exp_f32_e32 v26, v26
	v_add_f32_e32 v0, 1.0, v0
	v_rcp_f32_e32 v36, v1
	v_add_f32_e32 v1, 1.0, v24
	v_rcp_f32_e32 v0, v0
	v_rcp_f32_e32 v1, v1
	v_add_f32_e32 v24, 1.0, v26
	v_rcp_f32_e32 v37, v24
	v_lshlrev_b32_e32 v101, 16, v103
	v_lshlrev_b32_e32 v100, 16, v102
	v_pk_mul_f32 v[0:1], v[112:113], v[0:1]
	v_and_b32_e32 v103, 0xffff0000, v103
	v_and_b32_e32 v102, 0xffff0000, v102
	v_pk_mul_f32 v[98:99], v[0:1], v[100:101]
	v_pk_mul_f32 v[0:1], v[32:33], v[36:37]
	v_lshlrev_b32_e32 v95, 16, v67
	v_pk_mul_f32 v[100:101], v[0:1], v[102:103]
	v_lshlrev_b32_e32 v94, 16, v66
	v_and_b32_e32 v57, 0xffff0000, v67
	v_and_b32_e32 v56, 0xffff0000, v66
	v_lshlrev_b32_e32 v67, 16, v105
	v_lshlrev_b32_e32 v66, 16, v104
	v_and_b32_e32 v103, 0xffff0000, v105
	v_and_b32_e32 v102, 0xffff0000, v104
	v_pk_fma_f32 v[104:105], v[108:109], v[6:7], v[22:23]
	v_pk_fma_f32 v[106:107], v[106:107], v[4:5], v[20:21]
	v_mov_b32_e32 v37, v104
	v_mov_b32_e32 v36, v106
	v_mov_b32_e32 v108, v52
	v_mov_b32_e32 v109, v54
	v_mov_b32_e32 v32, v8
	v_mov_b32_e32 v33, v10
	v_mov_b32_e32 v104, v107
	v_mov_b32_e32 v54, v53
	v_mov_b32_e32 v10, v9
	v_pk_fma_f32 v[112:113], v[108:109], v[32:33], v[36:37]
	v_mov_b32_e32 v37, v14
	v_pk_fma_f32 v[8:9], v[54:55], v[10:11], v[104:105]
	v_mov_b32_e32 v14, v13
	v_pk_fma_f32 v[8:9], v[14:15], v[56:57], v[8:9]
	v_mov_b32_e32 v1, v6
	v_mul_f32_e32 v6, 0x3d372713, v8
	v_mul_f32_e32 v6, v8, v6
	v_fma_f32 v6, v8, v6, v8
	v_mul_f32_e32 v6, 0xbfcc422a, v6
	v_mul_f32_e32 v6, 0x3fb8aa3b, v6
	v_mov_b32_e32 v36, v12
	v_exp_f32_e32 v12, v6
	v_pk_fma_f32 v[112:113], v[36:37], v[94:95], v[112:113]
	v_mov_b32_e32 v6, v5
	v_mov_b32_e32 v0, v4
	v_add_f32_e32 v5, 1.0, v12
	v_mul_f32_e32 v12, 0x3d372713, v113
	v_mul_f32_e32 v12, v113, v12
	v_fma_f32 v12, v113, v12, v113
	v_mul_f32_e32 v12, 0xbfcc422a, v12
	v_mul_f32_e32 v12, 0x3fb8aa3b, v12
	v_exp_f32_e32 v13, v12
	v_mul_f32_e32 v12, 0x3d372713, v9
	v_mul_f32_e32 v12, v9, v12
	v_fma_f32 v12, v9, v12, v9
	v_mul_f32_e32 v12, 0xbfcc422a, v12
	v_mul_f32_e32 v4, 0x3d372713, v112
	v_mul_f32_e32 v12, 0x3fb8aa3b, v12
	v_mov_b32_e32 v24, v20
	v_mul_f32_e32 v4, v112, v4
	v_exp_f32_e32 v20, v12
	v_fma_f32 v4, v112, v4, v112
	v_mul_f32_e32 v4, 0xbfcc422a, v4
	v_mul_f32_e32 v4, 0x3fb8aa3b, v4
	v_exp_f32_e32 v4, v4
	v_rcp_f32_e32 v12, v5
	v_add_f32_e32 v5, 1.0, v13
	v_add_f32_e32 v13, 1.0, v20
	v_rcp_f32_e32 v13, v13
	v_add_f32_e32 v4, 1.0, v4
	v_rcp_f32_e32 v4, v4
	v_rcp_f32_e32 v5, v5
	v_pk_mul_f32 v[8:9], v[8:9], v[12:13]
	v_mov_b32_e32 v26, v25
	v_pk_mul_f32 v[8:9], v[8:9], v[102:103]
	v_mov_b32_e32 v25, v22
	v_cvt_pk_bf16_f32 v8, v8, v8
	v_cvt_pk_bf16_f32 v9, v9, v9
	v_mov_b32_e32 v22, v21
	v_pk_mul_f32 v[4:5], v[112:113], v[4:5]
	v_cvt_pk_bf16_f32 v13, v99, v99
	v_cvt_pk_bf16_f32 v12, v98, v98
	v_pk_mul_f32 v[4:5], v[4:5], v[66:67]
	v_cvt_pk_bf16_f32 v21, v100, v100
	v_cvt_pk_bf16_f32 v20, v101, v101
	v_lshrrev_b32_e32 v12, 16, v12
	v_lshrrev_b32_e32 v13, 16, v13
	v_and_or_b32 v99, v20, s36, v13
	v_and_or_b32 v98, v21, s36, v12
	v_pk_fma_f32 v[20:21], v[110:111], v[84:85], v[86:87]
	v_cvt_pk_bf16_f32 v5, v5, v5
	v_cvt_pk_bf16_f32 v4, v4, v4
	v_lshlrev_b32_e32 v53, 16, v61
	v_lshlrev_b32_e32 v52, 16, v60
	v_pk_fma_f32 v[20:21], v[64:65], v[92:93], v[20:21]
	v_lshrrev_b32_e32 v4, 16, v4
	v_pk_fma_f32 v[20:21], v[88:89], v[52:53], v[20:21]
	v_lshrrev_b32_e32 v5, 16, v5
	v_pk_fma_f32 v[58:59], v[58:59], v[2:3], v[26:27]
	v_mul_f32_e32 v66, 0x3d372713, v21
	v_and_or_b32 v101, v9, s36, v5
	v_and_or_b32 v100, v8, s36, v4
	v_and_b32_e32 v9, 0xffff0000, v61
	v_and_b32_e32 v8, 0xffff0000, v60
	v_pk_fma_f32 v[58:59], v[34:35], v[90:91], v[58:59]
	v_mul_f32_e32 v66, v21, v66
	v_pk_fma_f32 v[58:59], v[38:39], v[8:9], v[58:59]
	v_fma_f32 v66, v21, v66, v21
	v_mul_f32_e32 v61, 0x3d372713, v58
	v_mul_f32_e32 v66, 0xbfcc422a, v66
	v_mul_f32_e32 v60, 0x3d372713, v20
	v_mul_f32_e32 v61, v58, v61
	v_mul_f32_e32 v66, 0x3fb8aa3b, v66
	v_mul_f32_e32 v60, v20, v60
	v_fma_f32 v61, v58, v61, v58
	v_exp_f32_e32 v67, v66
	v_mul_f32_e32 v66, 0x3d372713, v59
	v_fma_f32 v60, v20, v60, v20
	v_mul_f32_e32 v61, 0xbfcc422a, v61
	v_mul_f32_e32 v66, v59, v66
	v_mul_f32_e32 v60, 0xbfcc422a, v60
	v_mul_f32_e32 v61, 0x3fb8aa3b, v61
	v_fma_f32 v66, v59, v66, v59
	v_mul_f32_e32 v60, 0x3fb8aa3b, v60
	v_exp_f32_e32 v61, v61
	v_mul_f32_e32 v66, 0xbfcc422a, v66
	v_lshl_add_u64 v[4:5], s[38:39], 1, v[70:71]
	v_exp_f32_e32 v60, v60
	v_mul_f32_e32 v66, 0x3fb8aa3b, v66
	global_store_dwordx4 v[4:5], v[98:101], off
	v_add_f32_e32 v61, 1.0, v61
	v_add_f32_e32 v60, 1.0, v60
	v_exp_f32_e32 v98, v66
	v_rcp_f32_e32 v66, v61
	v_add_f32_e32 v61, 1.0, v67
	v_rcp_f32_e32 v60, v60
	v_rcp_f32_e32 v61, v61
	v_add_f32_e32 v67, 1.0, v98
	v_rcp_f32_e32 v67, v67
	v_lshlrev_b32_e32 v13, 16, v49
	v_lshlrev_b32_e32 v12, 16, v48
	v_pk_mul_f32 v[20:21], v[20:21], v[60:61]
	v_and_b32_e32 v49, 0xffff0000, v49
	v_and_b32_e32 v48, 0xffff0000, v48
	v_pk_mul_f32 v[60:61], v[20:21], v[12:13]
	v_pk_mul_f32 v[12:13], v[58:59], v[66:67]
	v_lshlrev_b32_e32 v21, 16, v63
	v_pk_mul_f32 v[48:49], v[12:13], v[48:49]
	v_lshlrev_b32_e32 v20, 16, v62
	v_and_b32_e32 v13, 0xffff0000, v63
	v_and_b32_e32 v12, 0xffff0000, v62
	v_pk_fma_f32 v[62:63], v[108:109], v[0:1], v[24:25]
	v_pk_fma_f32 v[54:55], v[54:55], v[6:7], v[22:23]
	v_pk_fma_f32 v[62:63], v[32:33], v[94:95], v[62:63]
	v_pk_fma_f32 v[54:55], v[10:11], v[56:57], v[54:55]
	v_pk_fma_f32 v[62:63], v[36:37], v[20:21], v[62:63]
	v_pk_fma_f32 v[54:55], v[14:15], v[12:13], v[54:55]
	v_mul_f32_e32 v98, 0x3d372713, v63
	v_mul_f32_e32 v98, v63, v98
	v_fma_f32 v98, v63, v98, v63
	v_mul_f32_e32 v98, 0xbfcc422a, v98
	v_mul_f32_e32 v67, 0x3d372713, v54
	v_mul_f32_e32 v98, 0x3fb8aa3b, v98
	v_mul_f32_e32 v67, v54, v67
	v_exp_f32_e32 v99, v98
	v_mul_f32_e32 v98, 0x3d372713, v55
	v_mul_f32_e32 v66, 0x3d372713, v62
	v_fma_f32 v67, v54, v67, v54
	v_mul_f32_e32 v98, v55, v98
	v_mul_f32_e32 v66, v62, v66
	v_mul_f32_e32 v67, 0xbfcc422a, v67
	v_fma_f32 v98, v55, v98, v55
	v_fma_f32 v66, v62, v66, v62
	v_mul_f32_e32 v67, 0x3fb8aa3b, v67
	v_mul_f32_e32 v98, 0xbfcc422a, v98
	v_mul_f32_e32 v66, 0xbfcc422a, v66
	v_exp_f32_e32 v67, v67
	v_mul_f32_e32 v98, 0x3fb8aa3b, v98
	v_mul_f32_e32 v66, 0x3fb8aa3b, v66
	v_exp_f32_e32 v100, v98
	v_exp_f32_e32 v66, v66
	v_add_f32_e32 v67, 1.0, v67
	v_rcp_f32_e32 v98, v67
	v_add_f32_e32 v67, 1.0, v99
	v_add_f32_e32 v99, 1.0, v100
	v_add_f32_e32 v66, 1.0, v66
	v_rcp_f32_e32 v99, v99
	v_rcp_f32_e32 v66, v66
	v_rcp_f32_e32 v67, v67
	v_lshlrev_b32_e32 v59, 16, v51
	v_lshlrev_b32_e32 v58, 16, v50
	v_and_b32_e32 v51, 0xffff0000, v51
	v_and_b32_e32 v50, 0xffff0000, v50
	v_pk_mul_f32 v[54:55], v[54:55], v[98:99]
	v_pk_mul_f32 v[62:63], v[62:63], v[66:67]
	v_pk_mul_f32 v[50:51], v[54:55], v[50:51]
	v_pk_mul_f32 v[58:59], v[62:63], v[58:59]
	v_cvt_pk_bf16_f32 v49, v49, v49
	v_cvt_pk_bf16_f32 v48, v48, v48
	v_cvt_pk_bf16_f32 v50, v50, v50
	v_cvt_pk_bf16_f32 v51, v51, v51
	v_cvt_pk_bf16_f32 v54, v60, v60
	v_cvt_pk_bf16_f32 v59, v59, v59
	v_cvt_pk_bf16_f32 v58, v58, v58
	v_cvt_pk_bf16_f32 v55, v61, v61
	v_lshrrev_b32_e32 v54, 16, v54
	v_lshrrev_b32_e32 v55, 16, v55
	v_lshrrev_b32_e32 v58, 16, v58
	v_lshrrev_b32_e32 v59, 16, v59
	v_and_or_b32 v48, v48, s36, v54
	v_add_co_u32_e32 v54, vcc, s74, v4
	v_and_or_b32 v51, v51, s36, v59
	v_and_or_b32 v50, v50, s36, v58
	v_and_or_b32 v49, v49, s36, v55
	v_addc_co_u32_e32 v55, vcc, 0, v5, vcc
	global_store_dwordx4 v[54:55], v[48:51], off offset:2816
	v_pk_fma_f32 v[54:55], v[84:85], v[92:93], v[86:87]
	v_pk_fma_f32 v[56:57], v[6:7], v[56:57], v[22:23]
	v_lshlrev_b32_e32 v49, 16, v45
	v_lshlrev_b32_e32 v48, 16, v44
	v_pk_fma_f32 v[54:55], v[64:65], v[52:53], v[54:55]
	v_and_b32_e32 v45, 0xffff0000, v45
	v_pk_fma_f32 v[54:55], v[88:89], v[48:49], v[54:55]
	v_and_b32_e32 v44, 0xffff0000, v44
	v_mul_f32_e32 v58, 0x3d372713, v54
	v_mul_f32_e32 v58, v54, v58
	v_fma_f32 v58, v54, v58, v54
	v_mul_f32_e32 v58, 0xbfcc422a, v58
	v_mul_f32_e32 v58, 0x3fb8aa3b, v58
	v_exp_f32_e32 v60, v58
	v_pk_fma_f32 v[58:59], v[2:3], v[90:91], v[26:27]
	v_mul_f32_e32 v62, 0x3d372713, v55
	v_pk_fma_f32 v[58:59], v[34:35], v[8:9], v[58:59]
	v_mul_f32_e32 v62, v55, v62
	v_pk_fma_f32 v[58:59], v[38:39], v[44:45], v[58:59]
	v_fma_f32 v62, v55, v62, v55
	v_mul_f32_e32 v61, 0x3d372713, v58
	v_mul_f32_e32 v62, 0xbfcc422a, v62
	v_mul_f32_e32 v61, v58, v61
	v_mul_f32_e32 v62, 0x3fb8aa3b, v62
	v_fma_f32 v61, v58, v61, v58
	v_exp_f32_e32 v63, v62
	v_mul_f32_e32 v62, 0x3d372713, v59
	v_mul_f32_e32 v61, 0xbfcc422a, v61
	v_mul_f32_e32 v62, v59, v62
	v_mul_f32_e32 v61, 0x3fb8aa3b, v61
	v_fma_f32 v62, v59, v62, v59
	v_exp_f32_e32 v61, v61
	v_mul_f32_e32 v62, 0xbfcc422a, v62
	v_mul_f32_e32 v62, 0x3fb8aa3b, v62
	v_exp_f32_e32 v66, v62
	v_add_f32_e32 v61, 1.0, v61
	v_add_f32_e32 v60, 1.0, v60
	v_rcp_f32_e32 v62, v61
	v_add_f32_e32 v61, 1.0, v63
	v_rcp_f32_e32 v60, v60
	v_rcp_f32_e32 v61, v61
	v_add_f32_e32 v63, 1.0, v66
	v_rcp_f32_e32 v63, v63
	v_lshlrev_b32_e32 v51, 16, v41
	v_lshlrev_b32_e32 v50, 16, v40
	v_pk_mul_f32 v[54:55], v[54:55], v[60:61]
	v_and_b32_e32 v41, 0xffff0000, v41
	v_and_b32_e32 v40, 0xffff0000, v40
	v_pk_mul_f32 v[50:51], v[54:55], v[50:51]
	v_pk_mul_f32 v[54:55], v[58:59], v[62:63]
	v_pk_fma_f32 v[60:61], v[0:1], v[94:95], v[24:25]
	v_pk_mul_f32 v[40:41], v[54:55], v[40:41]
	v_lshlrev_b32_e32 v55, 16, v47
	v_lshlrev_b32_e32 v54, 16, v46
	v_pk_fma_f32 v[60:61], v[32:33], v[20:21], v[60:61]
	v_and_b32_e32 v47, 0xffff0000, v47
	v_pk_fma_f32 v[60:61], v[36:37], v[54:55], v[60:61]
	v_and_b32_e32 v46, 0xffff0000, v46
	v_mul_f32_e32 v66, 0x3d372713, v61
	v_mul_f32_e32 v66, v61, v66
	v_pk_fma_f32 v[56:57], v[10:11], v[12:13], v[56:57]
	v_fma_f32 v66, v61, v66, v61
	v_pk_fma_f32 v[56:57], v[14:15], v[46:47], v[56:57]
	v_mul_f32_e32 v66, 0xbfcc422a, v66
	v_mul_f32_e32 v63, 0x3d372713, v56
	v_mul_f32_e32 v66, 0x3fb8aa3b, v66
	v_mul_f32_e32 v63, v56, v63
	v_exp_f32_e32 v67, v66
	v_mul_f32_e32 v66, 0x3d372713, v57
	v_fma_f32 v63, v56, v63, v56
	v_mul_f32_e32 v66, v57, v66
	v_mul_f32_e32 v62, 0x3d372713, v60
	v_mul_f32_e32 v63, 0xbfcc422a, v63
	v_fma_f32 v66, v57, v66, v57
	v_mul_f32_e32 v62, v60, v62
	v_mul_f32_e32 v63, 0x3fb8aa3b, v63
	v_mul_f32_e32 v66, 0xbfcc422a, v66
	v_fma_f32 v62, v60, v62, v60
	v_exp_f32_e32 v63, v63
	v_mul_f32_e32 v66, 0x3fb8aa3b, v66
	v_mul_f32_e32 v62, 0xbfcc422a, v62
	v_exp_f32_e32 v90, v66
	v_mul_f32_e32 v62, 0x3fb8aa3b, v62
	v_exp_f32_e32 v62, v62
	v_add_f32_e32 v63, 1.0, v63
	v_rcp_f32_e32 v66, v63
	v_add_f32_e32 v63, 1.0, v67
	v_add_f32_e32 v67, 1.0, v90
	v_rcp_f32_e32 v67, v67
	v_add_f32_e32 v62, 1.0, v62
	v_rcp_f32_e32 v62, v62
	v_rcp_f32_e32 v63, v63
	v_lshlrev_b32_e32 v59, 16, v43
	v_lshlrev_b32_e32 v58, 16, v42
	v_and_b32_e32 v43, 0xffff0000, v43
	v_and_b32_e32 v42, 0xffff0000, v42
	v_pk_mul_f32 v[56:57], v[56:57], v[66:67]
	v_pk_mul_f32 v[60:61], v[60:61], v[62:63]
	v_pk_mul_f32 v[42:43], v[56:57], v[42:43]
	v_pk_mul_f32 v[58:59], v[60:61], v[58:59]
	v_cvt_pk_bf16_f32 v43, v43, v43
	v_cvt_pk_bf16_f32 v40, v40, v40
	v_cvt_pk_bf16_f32 v41, v41, v41
	v_cvt_pk_bf16_f32 v42, v42, v42
	v_bfe_u32 v60, v58, 16, 1
	v_bfe_u32 v61, v59, 16, 1
	v_cvt_pk_bf16_f32 v50, v50, v50
	v_add3_u32 v59, v59, v61, s48
	v_add3_u32 v58, v58, v60, s48
	v_cvt_pk_bf16_f32 v51, v51, v51
	v_lshrrev_b32_e32 v50, 16, v50
	v_lshrrev_b32_e32 v51, 16, v51
	v_lshrrev_b32_e32 v56, 16, v58
	v_lshrrev_b32_e32 v57, 16, v59
	v_and_or_b32 v40, v40, s36, v50
	v_add_co_u32_e32 v50, vcc, s29, v4
	v_and_or_b32 v43, v43, s36, v57
	v_and_or_b32 v42, v42, s36, v56
	v_and_or_b32 v41, v41, s36, v51
	v_addc_co_u32_e32 v51, vcc, 0, v5, vcc
	global_store_dwordx4 v[50:51], v[40:43], off offset:1536
	v_lshl_add_u64 v[50:51], s[26:27], 0, v[82:83]
	v_pk_fma_f32 v[2:3], v[2:3], v[8:9], v[26:27]
	v_mov_b32_e32 v40, v48
	v_mov_b32_e32 v41, v44
	v_mov_b32_e32 v42, v49
	v_mov_b32_e32 v43, v45
	global_store_dwordx4 v[50:51], v[40:43], off
	v_pk_fma_f32 v[2:3], v[34:35], v[44:45], v[2:3]
	v_and_b32_e32 v9, 0xffff0000, v17
	v_mov_b32_e32 v40, v54
	v_mov_b32_e32 v41, v46
	v_mov_b32_e32 v42, v55
	v_mov_b32_e32 v43, v47
	global_store_dwordx4 v[50:51], v[40:43], off offset:16
	v_pk_fma_f32 v[50:51], v[84:85], v[52:53], v[86:87]
	v_pk_fma_f32 v[6:7], v[6:7], v[12:13], v[22:23]
	v_lshlrev_b32_e32 v41, 16, v29
	v_lshlrev_b32_e32 v40, 16, v28
	v_pk_fma_f32 v[48:49], v[64:65], v[48:49], v[50:51]
	v_and_b32_e32 v29, 0xffff0000, v29
	v_pk_fma_f32 v[48:49], v[88:89], v[40:41], v[48:49]
	v_and_b32_e32 v28, 0xffff0000, v28
	v_mul_f32_e32 v50, 0x3d372713, v48
	v_mul_f32_e32 v50, v48, v50
	v_fma_f32 v50, v48, v50, v48
	v_mul_f32_e32 v50, 0xbfcc422a, v50
	v_mul_f32_e32 v50, 0x3fb8aa3b, v50
	v_exp_f32_e32 v50, v50
	v_pk_fma_f32 v[2:3], v[38:39], v[28:29], v[2:3]
	v_lshlrev_b32_e32 v43, 16, v17
	v_mul_f32_e32 v8, 0x3d372713, v2
	v_add_f32_e32 v17, 1.0, v50
	v_mul_f32_e32 v8, v2, v8
	v_rcp_f32_e32 v26, v17
	v_mul_f32_e32 v17, 0x3d372713, v49
	v_fma_f32 v8, v2, v8, v2
	v_mul_f32_e32 v17, v49, v17
	v_mul_f32_e32 v27, 0x3d372713, v3
	v_mul_f32_e32 v8, 0xbfcc422a, v8
	v_fma_f32 v17, v49, v17, v49
	v_mul_f32_e32 v27, v3, v27
	v_mul_f32_e32 v8, 0x3fb8aa3b, v8
	v_mul_f32_e32 v17, 0xbfcc422a, v17
	v_fma_f32 v27, v3, v27, v3
	v_exp_f32_e32 v8, v8
	v_mul_f32_e32 v17, 0x3fb8aa3b, v17
	v_mul_f32_e32 v27, 0xbfcc422a, v27
	v_exp_f32_e32 v17, v17
	v_mul_f32_e32 v27, 0x3fb8aa3b, v27
	v_exp_f32_e32 v35, v27
	v_add_f32_e32 v8, 1.0, v8
	v_rcp_f32_e32 v34, v8
	v_add_f32_e32 v8, 1.0, v17
	v_rcp_f32_e32 v27, v8
	v_add_f32_e32 v8, 1.0, v35
	v_rcp_f32_e32 v35, v8
	v_and_b32_e32 v8, 0xffff0000, v16
	v_pk_fma_f32 v[0:1], v[0:1], v[20:21], v[24:25]
	v_pk_fma_f32 v[6:7], v[10:11], v[46:47], v[6:7]
	v_pk_mul_f32 v[2:3], v[2:3], v[34:35]
	v_lshlrev_b32_e32 v35, 16, v31
	v_pk_mul_f32 v[8:9], v[2:3], v[8:9]
	v_and_b32_e32 v3, 0xffff0000, v31
	v_and_b32_e32 v2, 0xffff0000, v30
	v_lshlrev_b32_e32 v34, 16, v30
	v_pk_fma_f32 v[0:1], v[32:33], v[54:55], v[0:1]
	v_pk_fma_f32 v[6:7], v[14:15], v[2:3], v[6:7]
	v_pk_fma_f32 v[0:1], v[36:37], v[34:35], v[0:1]
	v_mul_f32_e32 v10, 0x3d372713, v6
	v_mul_f32_e32 v10, v6, v10
	v_mul_f32_e32 v13, 0x3d372713, v1
	v_fma_f32 v10, v6, v10, v6
	v_mul_f32_e32 v13, v1, v13
	v_mul_f32_e32 v14, 0x3d372713, v7
	v_mul_f32_e32 v20, 0x3d372713, v0
	v_mul_f32_e32 v10, 0xbfcc422a, v10
	v_fma_f32 v13, v1, v13, v1
	v_mul_f32_e32 v14, v7, v14
	v_mul_f32_e32 v20, v0, v20
	v_mul_f32_e32 v10, 0x3fb8aa3b, v10
	v_mul_f32_e32 v13, 0xbfcc422a, v13
	v_fma_f32 v14, v7, v14, v7
	v_fma_f32 v20, v0, v20, v0
	v_exp_f32_e32 v10, v10
	v_mul_f32_e32 v13, 0x3fb8aa3b, v13
	v_mul_f32_e32 v14, 0xbfcc422a, v14
	v_mul_f32_e32 v20, 0xbfcc422a, v20
	v_exp_f32_e32 v13, v13
	v_mul_f32_e32 v14, 0x3fb8aa3b, v14
	v_mul_f32_e32 v20, 0x3fb8aa3b, v20
	v_exp_f32_e32 v15, v14
	v_exp_f32_e32 v20, v20
	v_add_f32_e32 v10, 1.0, v10
	v_rcp_f32_e32 v14, v10
	v_add_f32_e32 v10, 1.0, v13
	v_rcp_f32_e32 v13, v10
	v_add_f32_e32 v10, 1.0, v15
	v_add_f32_e32 v12, 1.0, v20
	v_rcp_f32_e32 v15, v10
	v_rcp_f32_e32 v12, v12
	v_and_b32_e32 v11, 0xffff0000, v19
	v_and_b32_e32 v10, 0xffff0000, v18
	v_pk_mul_f32 v[6:7], v[6:7], v[14:15]
	v_lshlrev_b32_e32 v42, 16, v16
	v_pk_mul_f32 v[16:17], v[48:49], v[26:27]
	v_lshlrev_b32_e32 v27, 16, v19
	v_lshlrev_b32_e32 v26, 16, v18
	v_pk_mul_f32 v[0:1], v[0:1], v[12:13]
	v_pk_mul_f32 v[6:7], v[6:7], v[10:11]
	v_pk_mul_f32 v[0:1], v[0:1], v[26:27]
	v_pk_mul_f32 v[16:17], v[16:17], v[42:43]
	v_bfe_u32 v12, v9, 16, 1
	v_bfe_u32 v13, v8, 16, 1
	v_cvt_pk_bf16_f32 v7, v7, v7
	v_add3_u32 v13, v8, v13, s48
	v_add3_u32 v12, v9, v12, s48
	v_cvt_pk_bf16_f32 v6, v6, v6
	v_cvt_pk_bf16_f32 v0, v0, v0
	v_cvt_pk_bf16_f32 v1, v1, v1
	v_cvt_pk_bf16_f32 v9, v17, v17
	v_cvt_pk_bf16_f32 v8, v16, v16
	v_lshrrev_b32_e32 v0, 16, v0
	v_lshrrev_b32_e32 v10, 16, v8
	v_lshrrev_b32_e32 v11, 16, v9
	v_lshrrev_b32_e32 v1, 16, v1
	v_and_or_b32 v8, v6, s36, v0
	v_add_co_u32_e32 v0, vcc, s28, v4
	v_and_or_b32 v9, v7, s36, v1
	v_and_or_b32 v7, v12, s36, v11
	v_and_or_b32 v6, v13, s36, v10
	v_addc_co_u32_e32 v1, vcc, 0, v5, vcc
	global_store_dwordx4 v[0:1], v[6:9], off offset:256
	v_lshl_add_u64 v[4:5], s[12:13], 0, v[82:83]
	v_mov_b32_e32 v26, v40
	v_mov_b32_e32 v27, v28
	v_mov_b32_e32 v28, v41
	v_mov_b32_e32 v0, v34
	v_mov_b32_e32 v1, v2
	v_mov_b32_e32 v2, v35
	global_store_dwordx4 v[4:5], v[26:29], off
	global_store_dwordx4 v[4:5], v[0:3], off offset:16
	s_mov_b64 s[12:13], 0
.LBB0_2006:
	s_andn2_b64 vcc, exec, s[12:13]
	s_cbranch_vccnz .LBB0_2008
	s_mul_i32 s12, s24, 0x810
	s_add_i32 s13, s12, 0xfffbf800
	s_mul_i32 s26, s13, 0x5600
	s_mul_hi_u32 s25, s13, 0x5600
	s_add_u32 s26, s16, s26
	s_addc_u32 s27, s17, s25
	v_lshl_add_u64 v[0:1], s[26:27], 0, v[80:81]
	v_add_co_u32_e32 v2, vcc, s74, v0
	s_movk_i32 s25, 0x5000
	s_nop 0
	v_addc_co_u32_e32 v3, vcc, 0, v1, vcc
	global_load_dwordx4 v[36:39], v[2:3], off offset:2816
	v_add_co_u32_e32 v2, vcc, s25, v0
	s_mov_b32 s25, 0x8000
	s_nop 0
	v_addc_co_u32_e32 v3, vcc, 0, v1, vcc
	global_load_dwordx4 v[32:35], v[0:1], off
	global_load_dwordx4 v[4:7], v[2:3], off offset:1536
	v_add_co_u32_e32 v0, vcc, s25, v0
	s_add_i32 s12, s12, 0xfffbf801
	s_nop 0
	v_addc_co_u32_e32 v1, vcc, 0, v1, vcc
	global_load_dwordx4 v[0:3], v[0:1], off offset:256
	s_nop 0
	global_load_dwordx4 v[24:27], v[78:79], off offset:16
	global_load_dwordx4 v[40:43], v[78:79], off
	global_load_dwordx4 v[8:11], v[76:77], off offset:16
	global_load_dwordx4 v[16:19], v[76:77], off
	global_load_dwordx4 v[12:15], v[74:75], off offset:16
	global_load_dwordx4 v[20:23], v[74:75], off
	global_load_dwordx4 v[28:31], v[72:73], off offset:16
	global_load_dwordx4 v[52:55], v[72:73], off
	s_waitcnt vmcnt(0)
	v_lshlrev_b32_e32 v57, 16, v37
	v_lshlrev_b32_e32 v56, 16, v36
	v_and_b32_e32 v51, 0xffff0000, v37
	v_and_b32_e32 v50, 0xffff0000, v36
	v_lshlrev_b32_e32 v45, 16, v33
	v_mov_b32_e32 v36, v40
	v_mov_b32_e32 v37, v42
	v_mov_b32_e32 v42, v41
	v_lshlrev_b32_e32 v44, 16, v32
	v_and_b32_e32 v33, 0xffff0000, v33
	v_and_b32_e32 v32, 0xffff0000, v32
	v_mov_b32_e32 v46, v52
	v_mov_b32_e32 v47, v54
	v_mov_b32_e32 v54, v53
	v_pk_fma_f32 v[36:37], v[36:37], 0, v[46:47] op_sel_hi:[1,0,1]
	v_mov_b32_e32 v47, v18
	v_pk_fma_f32 v[40:41], v[42:43], 0, v[54:55] op_sel_hi:[1,0,1]
	v_mov_b32_e32 v18, v17
	v_mov_b32_e32 v49, v22
	v_pk_fma_f32 v[42:43], v[18:19], 0, v[40:41] op_sel_hi:[1,0,1]
	v_mov_b32_e32 v22, v21
	v_mov_b32_e32 v48, v20
	v_pk_fma_f32 v[20:21], v[22:23], v[32:33], v[42:43]
	v_mov_b32_e32 v46, v16
	v_mul_f32_e32 v17, 0x3d372713, v20
	v_mul_f32_e32 v17, v20, v17
	v_fma_f32 v17, v20, v17, v20
	v_mul_f32_e32 v17, 0xbfcc422a, v17
	v_mul_f32_e32 v17, 0x3fb8aa3b, v17
	v_exp_f32_e32 v17, v17
	v_pk_fma_f32 v[58:59], v[46:47], 0, v[36:37] op_sel_hi:[1,0,1]
	v_mov_b32_e32 v54, v28
	v_pk_fma_f32 v[58:59], v[48:49], v[44:45], v[58:59]
	v_add_f32_e32 v17, 1.0, v17
	v_mul_f32_e32 v16, 0x3d372713, v58
	v_rcp_f32_e32 v52, v17
	v_mul_f32_e32 v17, 0x3d372713, v59
	v_mul_f32_e32 v16, v58, v16
	v_mul_f32_e32 v17, v59, v17
	v_fma_f32 v16, v58, v16, v58
	v_fma_f32 v17, v59, v17, v59
	v_mul_f32_e32 v16, 0xbfcc422a, v16
	v_mul_f32_e32 v17, 0xbfcc422a, v17
	v_mul_f32_e32 v16, 0x3fb8aa3b, v16
	v_mul_f32_e32 v17, 0x3fb8aa3b, v17
	v_exp_f32_e32 v16, v16
	v_exp_f32_e32 v17, v17
	v_mov_b32_e32 v55, v30
	v_mov_b32_e32 v30, v29
	v_add_f32_e32 v16, 1.0, v16
	v_add_f32_e32 v17, 1.0, v17
	v_rcp_f32_e32 v16, v16
	v_rcp_f32_e32 v17, v17
	v_pk_fma_f32 v[18:19], v[18:19], v[32:33], v[40:41]
	v_pk_mul_f32 v[16:17], v[58:59], v[16:17]
	s_nop 0
	v_pk_mul_f32 v[42:43], v[16:17], v[56:57]
	v_mul_f32_e32 v16, 0x3d372713, v21
	v_mul_f32_e32 v16, v21, v16
	v_fma_f32 v16, v21, v16, v21
	v_mul_f32_e32 v16, 0xbfcc422a, v16
	v_mul_f32_e32 v16, 0x3fb8aa3b, v16
	v_exp_f32_e32 v16, v16
	v_mov_b32_e32 v57, v14
	v_mov_b32_e32 v14, v13
	v_mov_b32_e32 v56, v12
	v_add_f32_e32 v16, 1.0, v16
	v_rcp_f32_e32 v53, v16
	s_nop 0
	v_pk_mul_f32 v[16:17], v[20:21], v[52:53]
	s_nop 0
	v_pk_mul_f32 v[50:51], v[16:17], v[50:51]
	v_lshlrev_b32_e32 v21, 16, v35
	v_lshlrev_b32_e32 v20, 16, v34
	v_and_b32_e32 v17, 0xffff0000, v35
	v_and_b32_e32 v16, 0xffff0000, v34
	v_lshlrev_b32_e32 v53, 16, v39
	v_lshlrev_b32_e32 v52, 16, v38
	v_and_b32_e32 v35, 0xffff0000, v39
	v_and_b32_e32 v34, 0xffff0000, v38
	v_mov_b32_e32 v38, v24
	v_mov_b32_e32 v39, v26
	v_mov_b32_e32 v26, v25
	v_pk_fma_f32 v[38:39], v[38:39], 0, v[54:55] op_sel_hi:[1,0,1]
	v_mov_b32_e32 v55, v10
	v_pk_fma_f32 v[24:25], v[26:27], 0, v[30:31] op_sel_hi:[1,0,1]
	v_mov_b32_e32 v10, v9
	v_pk_fma_f32 v[26:27], v[10:11], 0, v[24:25] op_sel_hi:[1,0,1]
	v_mov_b32_e32 v54, v8
	v_pk_fma_f32 v[12:13], v[14:15], v[16:17], v[26:27]
	v_pk_fma_f32 v[58:59], v[54:55], 0, v[38:39] op_sel_hi:[1,0,1]
	v_mul_f32_e32 v9, 0x3d372713, v12
	v_mul_f32_e32 v9, v12, v9
	v_fma_f32 v9, v12, v9, v12
	v_mul_f32_e32 v9, 0xbfcc422a, v9
	v_mul_f32_e32 v9, 0x3fb8aa3b, v9
	v_exp_f32_e32 v9, v9
	v_mul_f32_e32 v27, 0x3d372713, v13
	v_pk_fma_f32 v[58:59], v[56:57], v[20:21], v[58:59]
	v_mul_f32_e32 v27, v13, v27
	v_add_f32_e32 v9, 1.0, v9
	v_mul_f32_e32 v8, 0x3d372713, v58
	v_rcp_f32_e32 v26, v9
	v_mul_f32_e32 v9, 0x3d372713, v59
	v_fma_f32 v27, v13, v27, v13
	v_mul_f32_e32 v8, v58, v8
	v_mul_f32_e32 v9, v59, v9
	v_mul_f32_e32 v27, 0xbfcc422a, v27
	v_fma_f32 v8, v58, v8, v58
	v_fma_f32 v9, v59, v9, v59
	v_mul_f32_e32 v27, 0x3fb8aa3b, v27
	v_mul_f32_e32 v8, 0xbfcc422a, v8
	v_mul_f32_e32 v9, 0xbfcc422a, v9
	v_exp_f32_e32 v27, v27
	v_mul_f32_e32 v8, 0x3fb8aa3b, v8
	v_mul_f32_e32 v9, 0x3fb8aa3b, v9
	v_exp_f32_e32 v8, v8
	v_exp_f32_e32 v9, v9
	v_add_f32_e32 v27, 1.0, v27
	v_rcp_f32_e32 v27, v27
	v_add_f32_e32 v8, 1.0, v8
	v_add_f32_e32 v9, 1.0, v9
	v_rcp_f32_e32 v8, v8
	v_rcp_f32_e32 v9, v9
	v_pk_mul_f32 v[12:13], v[12:13], v[26:27]
	v_bfe_u32 v28, v51, 16, 1
	v_pk_mul_f32 v[12:13], v[12:13], v[34:35]
	v_pk_mul_f32 v[8:9], v[58:59], v[8:9]
	v_pk_mul_f32 v[8:9], v[8:9], v[52:53]
	v_cvt_pk_bf16_f32 v13, v13, v13
	v_cvt_pk_bf16_f32 v30, v50, v50
	v_add3_u32 v31, v51, v28, s48
	v_cvt_pk_bf16_f32 v12, v12, v12
	v_cvt_pk_bf16_f32 v26, v42, v42
	v_cvt_pk_bf16_f32 v9, v9, v9
	v_cvt_pk_bf16_f32 v8, v8, v8
	v_cvt_pk_bf16_f32 v27, v43, v43
	v_lshrrev_b32_e32 v26, 16, v26
	v_lshrrev_b32_e32 v27, 16, v27
	v_lshrrev_b32_e32 v8, 16, v8
	v_lshrrev_b32_e32 v9, 16, v9
	v_and_or_b32 v26, v30, s36, v26
	v_mov_b32_e32 v30, 0x2b00
	v_and_or_b32 v29, v13, s36, v9
	v_and_or_b32 v28, v12, s36, v8
	v_and_or_b32 v27, v31, s36, v27
	v_mad_u64_u32 v[8:9], s[26:27], s13, v30, v[70:71]
	global_store_dwordx4 v[8:9], v[26:29], off
	v_lshlrev_b32_e32 v9, 16, v5
	v_lshlrev_b32_e32 v8, 16, v4
	v_pk_fma_f32 v[26:27], v[46:47], v[44:45], v[36:37]
	v_and_b32_e32 v5, 0xffff0000, v5
	v_and_b32_e32 v4, 0xffff0000, v4
	v_pk_fma_f32 v[8:9], v[48:49], v[8:9], v[26:27]
	v_pk_fma_f32 v[4:5], v[22:23], v[4:5], v[18:19]
	v_mul_f32_e32 v26, 0x3d372713, v8
	v_mul_f32_e32 v19, 0x3d372713, v9
	v_mul_f32_e32 v26, v8, v26
	v_mul_f32_e32 v19, v9, v19
	v_fma_f32 v26, v8, v26, v8
	v_fma_f32 v19, v9, v19, v9
	v_mul_f32_e32 v26, 0xbfcc422a, v26
	v_mul_f32_e32 v19, 0xbfcc422a, v19
	v_mul_f32_e32 v26, 0x3fb8aa3b, v26
	v_mul_f32_e32 v19, 0x3fb8aa3b, v19
	v_exp_f32_e32 v26, v26
	v_exp_f32_e32 v19, v19
	v_lshlrev_b32_e32 v13, 16, v1
	v_lshlrev_b32_e32 v12, 16, v0
	v_add_f32_e32 v26, 1.0, v26
	v_add_f32_e32 v19, 1.0, v19
	v_rcp_f32_e32 v26, v26
	v_rcp_f32_e32 v27, v19
	v_mul_f32_e32 v18, 0x3d372713, v4
	v_mul_f32_e32 v18, v4, v18
	v_fma_f32 v18, v4, v18, v4
	v_pk_mul_f32 v[8:9], v[8:9], v[26:27]
	v_mul_f32_e32 v18, 0xbfcc422a, v18
	v_pk_mul_f32 v[8:9], v[8:9], v[12:13]
	v_mul_f32_e32 v12, 0x3d372713, v5
	v_mul_f32_e32 v12, v5, v12
	v_fma_f32 v12, v5, v12, v5
	v_mul_f32_e32 v12, 0xbfcc422a, v12
	v_mul_f32_e32 v18, 0x3fb8aa3b, v18
	v_mul_f32_e32 v12, 0x3fb8aa3b, v12
	v_exp_f32_e32 v18, v18
	v_exp_f32_e32 v12, v12
	v_and_b32_e32 v1, 0xffff0000, v1
	v_and_b32_e32 v0, 0xffff0000, v0
	v_add_f32_e32 v18, 1.0, v18
	v_add_f32_e32 v12, 1.0, v12
	v_rcp_f32_e32 v18, v18
	v_rcp_f32_e32 v19, v12
	v_pk_fma_f32 v[10:11], v[10:11], v[16:17], v[24:25]
	v_lshlrev_b32_e32 v13, 16, v3
	v_lshlrev_b32_e32 v12, 16, v2
	v_pk_mul_f32 v[4:5], v[4:5], v[18:19]
	v_pk_fma_f32 v[18:19], v[54:55], v[20:21], v[38:39]
	v_pk_mul_f32 v[0:1], v[4:5], v[0:1]
	v_lshlrev_b32_e32 v5, 16, v7
	v_lshlrev_b32_e32 v4, 16, v6
	v_and_b32_e32 v7, 0xffff0000, v7
	v_and_b32_e32 v6, 0xffff0000, v6
	v_pk_fma_f32 v[4:5], v[56:57], v[4:5], v[18:19]
	v_pk_fma_f32 v[6:7], v[14:15], v[6:7], v[10:11]
	v_mul_f32_e32 v11, 0x3d372713, v5
	v_mul_f32_e32 v11, v5, v11
	v_fma_f32 v11, v5, v11, v5
	v_mul_f32_e32 v11, 0xbfcc422a, v11
	v_mul_f32_e32 v11, 0x3fb8aa3b, v11
	v_exp_f32_e32 v11, v11
	v_mul_f32_e32 v10, 0x3d372713, v6
	v_mul_f32_e32 v18, 0x3d372713, v4
	v_mul_f32_e32 v10, v6, v10
	v_add_f32_e32 v11, 1.0, v11
	v_rcp_f32_e32 v19, v11
	v_mul_f32_e32 v11, 0x3d372713, v7
	v_mul_f32_e32 v11, v7, v11
	v_mul_f32_e32 v18, v4, v18
	v_fma_f32 v10, v6, v10, v6
	v_fma_f32 v11, v7, v11, v7
	v_fma_f32 v18, v4, v18, v4
	v_mul_f32_e32 v10, 0xbfcc422a, v10
	v_mul_f32_e32 v11, 0xbfcc422a, v11
	v_mul_f32_e32 v18, 0xbfcc422a, v18
	v_mul_f32_e32 v10, 0x3fb8aa3b, v10
	v_mul_f32_e32 v11, 0x3fb8aa3b, v11
	v_mul_f32_e32 v18, 0x3fb8aa3b, v18
	v_exp_f32_e32 v10, v10
	v_exp_f32_e32 v11, v11
	v_exp_f32_e32 v18, v18
	v_and_b32_e32 v3, 0xffff0000, v3
	v_add_f32_e32 v10, 1.0, v10
	v_add_f32_e32 v11, 1.0, v11
	v_add_f32_e32 v18, 1.0, v18
	v_rcp_f32_e32 v10, v10
	v_rcp_f32_e32 v11, v11
	v_rcp_f32_e32 v18, v18
	v_and_b32_e32 v2, 0xffff0000, v2
	v_pk_mul_f32 v[6:7], v[6:7], v[10:11]
	v_pk_mul_f32 v[4:5], v[4:5], v[18:19]
	v_pk_mul_f32 v[2:3], v[6:7], v[2:3]
	v_pk_mul_f32 v[4:5], v[4:5], v[12:13]
	v_cvt_pk_bf16_f32 v0, v0, v0
	v_cvt_pk_bf16_f32 v1, v1, v1
	v_cvt_pk_bf16_f32 v2, v2, v2
	v_cvt_pk_bf16_f32 v3, v3, v3
	v_cvt_pk_bf16_f32 v5, v5, v5
	v_cvt_pk_bf16_f32 v4, v4, v4
	v_cvt_pk_bf16_f32 v7, v9, v9
	v_cvt_pk_bf16_f32 v6, v8, v8
	v_lshrrev_b32_e32 v6, 16, v6
	v_lshrrev_b32_e32 v7, 16, v7
	v_lshrrev_b32_e32 v4, 16, v4
	v_lshrrev_b32_e32 v5, 16, v5
	v_and_or_b32 v3, v3, s36, v5
	v_and_or_b32 v2, v2, s36, v4
	v_and_or_b32 v1, v1, s36, v7
	v_and_or_b32 v0, v0, s36, v6
	v_mad_u64_u32 v[4:5], s[12:13], s12, v30, v[70:71]
	global_store_dwordx4 v[4:5], v[0:3], off
